# v81 + EP_RESID and PLE GEMM epilogues: residual/pp loads of the next 16-row group prefetched into free VGPRs with counted vmcnt waits (removed loads keep their issue slot), flat->global
# speedup vs baseline: 1.0917x; 1.0117x over previous
.LBB0_531:
	s_mul_i32 s43, s1, 0x6000
	s_add_i32 s50, s43, 0xffffa000
	s_cmp_lg_u32 s1, 0
	s_cselect_b32 s50, s50, 0xc000
	v_add_u32_e32 v150, s50, v143
	v_lshl_add_u64 v[146:147], v[138:139], 0, s[48:49]
	v_readfirstlane_b32 s50, v150
	v_add_u32_e32 v151, 0x1000, v150
	v_lshl_add_u64 v[148:149], v[146:147], 0, s[24:25]
	s_mov_b32 m0, s50
	v_readfirstlane_b32 s50, v151
	v_add_u32_e32 v151, 0x2000, v150
	s_waitcnt vmcnt(6)
	s_barrier
	global_load_lds_dwordx4 v[148:149], off
	v_lshl_add_u64 v[148:149], v[146:147], 0, s[26:27]
	s_mov_b32 m0, s50
	v_readfirstlane_b32 s50, v151
	global_load_lds_dwordx4 v[148:149], off
	v_lshl_add_u64 v[148:149], v[146:147], 0, s[28:29]
	s_mov_b32 m0, s50
	v_lshl_add_u64 v[146:147], v[146:147], 0, s[30:31]
	global_load_lds_dwordx4 v[148:149], off
	v_add_u32_e32 v148, 0x3000, v150
	v_add_u32_e32 v151, 0x4000, v150
	v_readfirstlane_b32 s50, v148
	s_mov_b32 m0, s50
	v_readfirstlane_b32 s50, v151
	global_load_lds_dwordx4 v[146:147], off
	v_lshl_add_u64 v[146:147], v[136:137], 0, s[48:49]
	v_lshl_add_u64 v[148:149], v[146:147], 0, s[34:35]
	s_mov_b32 m0, s50
	v_lshl_add_u64 v[146:147], v[146:147], 0, s[44:45]
	global_load_lds_dwordx4 v[148:149], off
	v_add_u32_e32 v148, 0x5000, v150
	s_add_i32 s43, s43, 0
	v_readfirstlane_b32 s50, v148
	s_mov_b32 m0, s50
	v_add3_u32 v158, s43, v142, v145
	global_load_lds_dwordx4 v[146:147], off
	v_add3_u32 v178, s43, v144, v145
	ds_read_b128 v[146:149], v158 offset:16384
	ds_read_b128 v[150:153], v158 offset:17408
	ds_read_b128 v[154:157], v158 offset:18432
	ds_read_b128 v[158:161], v158 offset:19456
	ds_read_b128 v[162:165], v178
	ds_read_b128 v[166:169], v178 offset:1024
	ds_read_b128 v[170:173], v178 offset:2048
	ds_read_b128 v[174:177], v178 offset:3072
	s_setprio 1
	s_waitcnt lgkmcnt(0)
	v_mfma_f32_16x16x32_bf16 v[126:129], v[146:149], v[162:165], v[126:129]
	v_mfma_f32_16x16x32_bf16 v[122:125], v[150:153], v[162:165], v[122:125]
	v_mfma_f32_16x16x32_bf16 v[118:121], v[154:157], v[162:165], v[118:121]
	v_mfma_f32_16x16x32_bf16 v[114:117], v[158:161], v[162:165], v[114:117]
	v_mfma_f32_16x16x32_bf16 v[110:113], v[146:149], v[166:169], v[110:113]
	v_mfma_f32_16x16x32_bf16 v[106:109], v[150:153], v[166:169], v[106:109]
	v_mfma_f32_16x16x32_bf16 v[102:105], v[154:157], v[166:169], v[102:105]
	v_mfma_f32_16x16x32_bf16 v[98:101], v[158:161], v[166:169], v[98:101]
	v_mfma_f32_16x16x32_bf16 v[94:97], v[146:149], v[170:173], v[94:97]
	v_mfma_f32_16x16x32_bf16 v[90:93], v[150:153], v[170:173], v[90:93]
	v_mfma_f32_16x16x32_bf16 v[86:89], v[154:157], v[170:173], v[86:89]
	v_mfma_f32_16x16x32_bf16 v[82:85], v[158:161], v[170:173], v[82:85]
	v_mfma_f32_16x16x32_bf16 v[78:81], v[146:149], v[174:177], v[78:81]
	v_mfma_f32_16x16x32_bf16 v[74:77], v[150:153], v[174:177], v[74:77]
	v_mfma_f32_16x16x32_bf16 v[70:73], v[154:157], v[174:177], v[70:73]
	v_mfma_f32_16x16x32_bf16 v[66:69], v[158:161], v[174:177], v[66:69]
	s_setprio 0
	ds_read_b128 v[162:165], v178 offset:4096
	ds_read_b128 v[166:169], v178 offset:5120
	ds_read_b128 v[170:173], v178 offset:6144
	ds_read_b128 v[174:177], v178 offset:7168
	s_setprio 1
	s_waitcnt lgkmcnt(0)
	v_mfma_f32_16x16x32_bf16 v[62:65], v[146:149], v[162:165], v[62:65]
	v_mfma_f32_16x16x32_bf16 v[58:61], v[150:153], v[162:165], v[58:61]
	v_mfma_f32_16x16x32_bf16 v[54:57], v[154:157], v[162:165], v[54:57]
	v_mfma_f32_16x16x32_bf16 v[50:53], v[158:161], v[162:165], v[50:53]
	v_mfma_f32_16x16x32_bf16 v[46:49], v[146:149], v[166:169], v[46:49]
	v_mfma_f32_16x16x32_bf16 v[42:45], v[150:153], v[166:169], v[42:45]
	v_mfma_f32_16x16x32_bf16 v[38:41], v[154:157], v[166:169], v[38:41]
	v_mfma_f32_16x16x32_bf16 v[34:37], v[158:161], v[166:169], v[34:37]
	v_mfma_f32_16x16x32_bf16 v[30:33], v[146:149], v[170:173], v[30:33]
	v_mfma_f32_16x16x32_bf16 v[26:29], v[150:153], v[170:173], v[26:29]
	v_mfma_f32_16x16x32_bf16 v[22:25], v[154:157], v[170:173], v[22:25]
	v_mfma_f32_16x16x32_bf16 v[18:21], v[158:161], v[170:173], v[18:21]
	v_mfma_f32_16x16x32_bf16 v[14:17], v[146:149], v[174:177], v[14:17]
	v_mfma_f32_16x16x32_bf16 v[10:13], v[150:153], v[174:177], v[10:13]
	v_mfma_f32_16x16x32_bf16 v[6:9], v[154:157], v[174:177], v[6:9]
	v_mfma_f32_16x16x32_bf16 v[2:5], v[158:161], v[174:177], v[2:5]
	s_setprio 0
	s_add_i32 s43, s1, 1
	s_cmp_lg_u32 s1, 2
	s_cselect_b32 s1, s43, 0
	s_add_u32 s48, s48, 64
	s_addc_u32 s49, s49, 0
	s_cmpk_eq_i32 s48, 0x780
	s_cbranch_scc0 .LBB0_531
	v_add3_u32 v170, 0, v142, v145
	v_add3_u32 v174, 0, v144, v145
	s_waitcnt vmcnt(6)
	s_barrier
	ds_read_b128 v[136:139], v170 offset:16384
	ds_read_b128 v[146:149], v170 offset:17408
	ds_read_b128 v[150:153], v170 offset:18432
	ds_read_b128 v[154:157], v170 offset:19456
	ds_read_b128 v[142:145], v174
	ds_read_b128 v[158:161], v174 offset:1024
	ds_read_b128 v[162:165], v174 offset:2048
	ds_read_b128 v[166:169], v174 offset:3072
	s_lshl_b64 s[46:47], s[46:47], 8
	s_setprio 1
	s_waitcnt lgkmcnt(0)
	v_mfma_f32_16x16x32_bf16 v[122:125], v[146:149], v[142:145], v[122:125]
	v_mfma_f32_16x16x32_bf16 v[118:121], v[150:153], v[142:145], v[118:121]
	v_mfma_f32_16x16x32_bf16 v[114:117], v[154:157], v[142:145], v[114:117]
	v_mfma_f32_16x16x32_bf16 v[110:113], v[136:139], v[158:161], v[110:113]
	v_mfma_f32_16x16x32_bf16 v[106:109], v[146:149], v[158:161], v[106:109]
	v_mfma_f32_16x16x32_bf16 v[102:105], v[150:153], v[158:161], v[102:105]
	v_mfma_f32_16x16x32_bf16 v[98:101], v[154:157], v[158:161], v[98:101]
	v_mfma_f32_16x16x32_bf16 v[94:97], v[136:139], v[162:165], v[94:97]
	v_mfma_f32_16x16x32_bf16 v[90:93], v[146:149], v[162:165], v[90:93]
	v_mfma_f32_16x16x32_bf16 v[86:89], v[150:153], v[162:165], v[86:89]
	v_mfma_f32_16x16x32_bf16 v[82:85], v[154:157], v[162:165], v[82:85]
	v_mfma_f32_16x16x32_bf16 v[78:81], v[136:139], v[166:169], v[78:81]
	v_mfma_f32_16x16x32_bf16 v[74:77], v[146:149], v[166:169], v[74:77]
	v_mfma_f32_16x16x32_bf16 v[70:73], v[150:153], v[166:169], v[70:73]
	v_mfma_f32_16x16x32_bf16 v[66:69], v[154:157], v[166:169], v[66:69]
	v_mfma_f32_16x16x32_bf16 v[126:129], v[136:139], v[142:145], v[126:129]
	s_setprio 0
	ds_read_b128 v[142:145], v174 offset:4096
	ds_read_b128 v[158:161], v174 offset:5120
	ds_read_b128 v[162:165], v174 offset:6144
	ds_read_b128 v[166:169], v174 offset:7168
	s_setprio 1
	s_waitcnt lgkmcnt(0)
	v_mfma_f32_16x16x32_bf16 v[62:65], v[136:139], v[142:145], v[62:65]
	v_mfma_f32_16x16x32_bf16 v[58:61], v[146:149], v[142:145], v[58:61]
	v_mfma_f32_16x16x32_bf16 v[54:57], v[150:153], v[142:145], v[54:57]
	v_mfma_f32_16x16x32_bf16 v[50:53], v[154:157], v[142:145], v[50:53]
	v_mfma_f32_16x16x32_bf16 v[46:49], v[136:139], v[158:161], v[46:49]
	v_mfma_f32_16x16x32_bf16 v[42:45], v[146:149], v[158:161], v[42:45]
	v_mfma_f32_16x16x32_bf16 v[38:41], v[150:153], v[158:161], v[38:41]
	v_mfma_f32_16x16x32_bf16 v[34:37], v[154:157], v[158:161], v[34:37]
	v_mfma_f32_16x16x32_bf16 v[30:33], v[136:139], v[162:165], v[30:33]
	v_mfma_f32_16x16x32_bf16 v[26:29], v[146:149], v[162:165], v[26:29]
	v_mfma_f32_16x16x32_bf16 v[22:25], v[150:153], v[162:165], v[22:25]
	v_mfma_f32_16x16x32_bf16 v[18:21], v[154:157], v[162:165], v[18:21]
	v_mfma_f32_16x16x32_bf16 v[14:17], v[136:139], v[166:169], v[14:17]
	v_mfma_f32_16x16x32_bf16 v[10:13], v[146:149], v[166:169], v[10:13]
	v_mfma_f32_16x16x32_bf16 v[6:9], v[150:153], v[166:169], v[6:9]
	v_mfma_f32_16x16x32_bf16 v[2:5], v[154:157], v[166:169], v[2:5]
	s_setprio 0
	s_waitcnt vmcnt(0)
	s_barrier
	ds_read_b128 v[136:139], v170 offset:40960
	ds_read_b128 v[142:145], v170 offset:41984
	ds_read_b128 v[146:149], v170 offset:43008
	ds_read_b128 v[150:153], v170 offset:44032
	ds_read_b128 v[154:157], v174 offset:24576
	ds_read_b128 v[158:161], v174 offset:25600
	ds_read_b128 v[162:165], v174 offset:26624
	ds_read_b128 v[166:169], v174 offset:27648
	s_setprio 1
	s_waitcnt lgkmcnt(0)
	v_mfma_f32_16x16x32_bf16 v[122:125], v[142:145], v[154:157], v[122:125]
	v_mfma_f32_16x16x32_bf16 v[110:113], v[136:139], v[158:161], v[110:113]
	v_mfma_f32_16x16x32_bf16 v[106:109], v[142:145], v[158:161], v[106:109]
	v_mfma_f32_16x16x32_bf16 v[102:105], v[146:149], v[158:161], v[102:105]
	v_mfma_f32_16x16x32_bf16 v[98:101], v[150:153], v[158:161], v[98:101]
	v_mfma_f32_16x16x32_bf16 v[94:97], v[136:139], v[162:165], v[94:97]
	v_mfma_f32_16x16x32_bf16 v[90:93], v[142:145], v[162:165], v[90:93]
	v_mfma_f32_16x16x32_bf16 v[86:89], v[146:149], v[162:165], v[86:89]
	v_mfma_f32_16x16x32_bf16 v[82:85], v[150:153], v[162:165], v[82:85]
	v_mfma_f32_16x16x32_bf16 v[78:81], v[136:139], v[166:169], v[78:81]
	v_mfma_f32_16x16x32_bf16 v[74:77], v[142:145], v[166:169], v[74:77]
	v_mfma_f32_16x16x32_bf16 v[70:73], v[146:149], v[166:169], v[70:73]
	v_mfma_f32_16x16x32_bf16 v[66:69], v[150:153], v[166:169], v[66:69]
	v_mfma_f32_16x16x32_bf16 v[126:129], v[136:139], v[154:157], v[126:129]
	v_mfma_f32_16x16x32_bf16 v[170:173], v[146:149], v[154:157], v[118:121]
	v_mfma_f32_16x16x32_bf16 v[154:157], v[150:153], v[154:157], v[114:117]
	s_setprio 0
	s_nop 1
	ds_read_b128 v[114:117], v174 offset:28672
	ds_read_b128 v[118:121], v174 offset:29696
	ds_read_b128 v[158:161], v174 offset:30720
	ds_read_b128 v[162:165], v174 offset:31744
	s_setprio 1
	s_waitcnt lgkmcnt(0)
	v_mfma_f32_16x16x32_bf16 v[62:65], v[136:139], v[114:117], v[62:65]
	v_mfma_f32_16x16x32_bf16 v[58:61], v[142:145], v[114:117], v[58:61]
	v_mfma_f32_16x16x32_bf16 v[54:57], v[146:149], v[114:117], v[54:57]
	v_mfma_f32_16x16x32_bf16 v[50:53], v[150:153], v[114:117], v[50:53]
	v_mfma_f32_16x16x32_bf16 v[46:49], v[136:139], v[118:121], v[46:49]
	v_mfma_f32_16x16x32_bf16 v[42:45], v[142:145], v[118:121], v[42:45]
	v_mfma_f32_16x16x32_bf16 v[38:41], v[146:149], v[118:121], v[38:41]
	v_mfma_f32_16x16x32_bf16 v[34:37], v[150:153], v[118:121], v[34:37]
	v_mfma_f32_16x16x32_bf16 v[30:33], v[136:139], v[158:161], v[30:33]
	v_mfma_f32_16x16x32_bf16 v[26:29], v[142:145], v[158:161], v[26:29]
	v_mfma_f32_16x16x32_bf16 v[22:25], v[146:149], v[158:161], v[22:25]
	v_mfma_f32_16x16x32_bf16 v[18:21], v[150:153], v[158:161], v[18:21]
	v_mfma_f32_16x16x32_bf16 v[14:17], v[136:139], v[162:165], v[14:17]
	v_mfma_f32_16x16x32_bf16 v[10:13], v[142:145], v[162:165], v[10:13]
	v_mfma_f32_16x16x32_bf16 v[6:9], v[146:149], v[162:165], v[6:9]
	v_mfma_f32_16x16x32_bf16 v[2:5], v[150:153], v[162:165], v[2:5]
	s_setprio 0
	v_lshl_add_u64 v[114:115], s[46:47], 0, v[134:135]
	v_lshl_or_b32 v116, s0, 7, v140
	v_lshlrev_b64 v[120:121], 12, v[114:115]
	v_ashrrev_i32_e32 v117, 31, v116
	v_lshl_add_u64 v[136:137], v[132:133], 0, v[120:121]
	v_lshlrev_b64 v[118:119], 2, v[116:117]
	v_lshl_add_u64 v[146:147], v[136:137], 0, v[118:119]
	s_waitcnt vmcnt(0)
	s_barrier
	v_mov_b32_e32 v212, v146
	v_mov_b32_e32 v213, v147
	global_load_dwordx4 v[180:183], v[212:213], off
	global_load_dwordx4 v[184:187], v[212:213], off offset:64
	global_load_dwordx4 v[188:191], v[212:213], off offset:128
	global_load_dwordx4 v[192:195], v[212:213], off offset:192
	s_mov_b32 s98, 0x10000
	s_mov_b32 s99, 0
	v_lshl_add_u64 v[214:215], v[212:213], 0, s[98:99]
	global_load_dwordx4 v[196:199], v[214:215], off
	global_load_dwordx4 v[200:203], v[214:215], off offset:64
	global_load_dwordx4 v[204:207], v[214:215], off offset:128
	global_load_dwordx4 v[208:211], v[214:215], off offset:192
	v_lshlrev_b64 v[142:143], 11, v[114:115]
	v_lshl_add_u64 v[120:121], v[130:131], 0, v[120:121]
	v_lshl_add_u64 v[142:143], s[8:9], 0, v[142:143]
	v_lshl_add_u64 v[150:151], v[120:121], 0, v[118:119]
	v_lshl_add_u64 v[152:153], v[116:117], 1, v[142:143]
	s_waitcnt vmcnt(4) lgkmcnt(0)
	v_mov_b32_e32 v136, v180
	v_mov_b32_e32 v137, v181
	v_mov_b32_e32 v138, v182
	v_mov_b32_e32 v139, v183
	v_pk_add_f32 v[126:127], v[126:127], v[136:137]
	v_pk_add_f32 v[128:129], v[128:129], v[138:139]
	v_cvt_pk_bf16_f32 v120, v126, v127
	v_cvt_pk_bf16_f32 v121, v128, v129
	global_store_dwordx4 v[150:151], v[126:129], off
	global_store_dwordx2 v[152:153], v[120:121], off
	s_nop 0
	s_waitcnt lgkmcnt(0)
	v_mov_b32_e32 v136, v184
	v_mov_b32_e32 v137, v185
	v_mov_b32_e32 v138, v186
	v_mov_b32_e32 v139, v187
	v_pk_add_f32 v[136:137], v[122:123], v[136:137]
	v_pk_add_f32 v[138:139], v[124:125], v[138:139]
	v_cvt_pk_bf16_f32 v120, v136, v137
	v_cvt_pk_bf16_f32 v121, v138, v139
	global_store_dwordx4 v[150:151], v[136:139], off offset:64
	global_store_dwordx2 v[152:153], v[120:121], off offset:32
	s_nop 0
	v_pk_mul_f32 v[124:125], v[128:129], v[128:129]
	s_waitcnt lgkmcnt(0)
	v_mov_b32_e32 v120, v188
	v_mov_b32_e32 v121, v189
	v_mov_b32_e32 v122, v190
	v_mov_b32_e32 v123, v191
	v_pk_add_f32 v[142:143], v[170:171], v[120:121]
	v_pk_add_f32 v[144:145], v[172:173], v[122:123]
	v_cvt_pk_bf16_f32 v120, v142, v143
	v_cvt_pk_bf16_f32 v121, v144, v145
	global_store_dwordx4 v[150:151], v[142:145], off offset:128
	global_store_dwordx2 v[152:153], v[120:121], off offset:64
	s_nop 0
	v_and_b32_e32 v121, 64, v141
	v_xor_b32_e32 v120, 16, v141
	v_add_u32_e32 v123, 64, v121
	v_cmp_lt_i32_e64 s[0:1], v120, v123
	s_nop 1
	v_cndmask_b32_e64 v120, v141, v120, s[0:1]
	v_lshlrev_b32_e32 v122, 2, v120
	v_pk_mul_f32 v[120:121], v[126:127], v[126:127]
	s_nop 0
	v_add_f32_e32 v120, v120, v121
	v_add_f32_e32 v120, v120, v124
	v_add_f32_e32 v126, v120, v125
	v_pk_mul_f32 v[120:121], v[136:137], v[136:137]
	v_pk_mul_f32 v[124:125], v[138:139], v[138:139]
	v_add_f32_e32 v120, v120, v121
	v_add_f32_e32 v120, v120, v124
	v_add_f32_e32 v120, v120, v125
	v_add_f32_e32 v136, v126, v120
	v_pk_mul_f32 v[120:121], v[142:143], v[142:143]
	v_pk_mul_f32 v[124:125], v[144:145], v[144:145]
	v_add_f32_e32 v120, v120, v121
	v_add_f32_e32 v120, v120, v124
	v_add_f32_e32 v137, v120, v125
	v_add_f32_e32 v136, v136, v137
	s_waitcnt lgkmcnt(0)
	v_mov_b32_e32 v146, v192
	v_mov_b32_e32 v147, v193
	v_mov_b32_e32 v148, v194
	v_mov_b32_e32 v149, v195
	v_pk_add_f32 v[124:125], v[154:155], v[146:147]
	v_pk_add_f32 v[126:127], v[156:157], v[148:149]
	v_pk_mul_f32 v[120:121], v[124:125], v[124:125]
	v_pk_mul_f32 v[128:129], v[126:127], v[126:127]
	v_add_f32_e32 v120, v120, v121
	v_add_f32_e32 v120, v120, v128
	v_add_f32_e32 v120, v120, v129
	v_add_f32_e32 v120, v136, v120
	ds_bpermute_b32 v121, v122, v120
	v_xor_b32_e32 v128, 32, v141
	v_cmp_lt_i32_e64 s[0:1], v128, v123
	global_store_dwordx4 v[150:151], v[124:127], off offset:192
	s_waitcnt lgkmcnt(0)
	v_add_f32_e32 v120, v120, v121
	v_cndmask_b32_e64 v123, v141, v128, s[0:1]
	v_lshlrev_b32_e32 v123, 2, v123
	ds_bpermute_b32 v121, v123, v120
	v_cvt_pk_bf16_f32 v124, v124, v125
	v_cvt_pk_bf16_f32 v125, v126, v127
	global_store_dwordx2 v[152:153], v[124:125], off offset:96
	s_and_saveexec_b64 s[0:1], vcc
	s_cbranch_execz .LBB0_534
	s_waitcnt lgkmcnt(0)
	v_add_f32_e32 v124, v120, v121
	v_lshl_add_u64 v[120:121], v[114:115], 2, s[10:11]
	global_atomic_add_f32 v[120:121], v124, off
.LBB0_534:
	s_or_b64 exec, exec, s[0:1]
	v_or_b32_e32 v120, 16, v114
	s_waitcnt lgkmcnt(0)
	v_mov_b32_e32 v121, v115
	v_lshlrev_b64 v[128:129], 12, v[120:121]
	v_lshl_add_u64 v[124:125], v[132:133], 0, v[128:129]
	v_lshl_add_u64 v[136:137], v[124:125], 0, v[118:119]
	s_mov_b32 s98, 0x20000
	s_mov_b32 s99, 0
	v_lshl_add_u64 v[214:215], v[212:213], 0, s[98:99]
	global_load_dwordx4 v[180:183], v[214:215], off
	global_load_dwordx4 v[184:187], v[214:215], off offset:64
	global_load_dwordx4 v[188:191], v[214:215], off offset:128
	global_load_dwordx4 v[192:195], v[214:215], off offset:192
	v_lshlrev_b64 v[138:139], 11, v[120:121]
	v_lshl_add_u64 v[128:129], v[130:131], 0, v[128:129]
	v_lshl_add_u64 v[138:139], s[8:9], 0, v[138:139]
	v_lshl_add_u64 v[128:129], v[128:129], 0, v[118:119]
	v_lshl_add_u64 v[138:139], v[116:117], 1, v[138:139]
	s_waitcnt vmcnt(12) lgkmcnt(0)
	v_mov_b32_e32 v124, v196
	v_mov_b32_e32 v125, v197
	v_mov_b32_e32 v126, v198
	v_mov_b32_e32 v127, v199
	v_pk_add_f32 v[110:111], v[110:111], v[124:125]
	v_pk_add_f32 v[112:113], v[112:113], v[126:127]
	v_cvt_pk_bf16_f32 v124, v110, v111
	v_cvt_pk_bf16_f32 v125, v112, v113
	global_store_dwordx4 v[128:129], v[110:113], off
	global_store_dwordx2 v[138:139], v[124:125], off
	s_nop 0
	v_pk_mul_f32 v[110:111], v[110:111], v[110:111]
	v_pk_mul_f32 v[112:113], v[112:113], v[112:113]
	v_add_f32_e32 v110, v110, v111
	v_add_f32_e32 v110, v110, v112
	v_add_f32_e32 v110, v110, v113
	s_waitcnt lgkmcnt(0)
	v_mov_b32_e32 v124, v200
	v_mov_b32_e32 v125, v201
	v_mov_b32_e32 v126, v202
	v_mov_b32_e32 v127, v203
	v_pk_add_f32 v[106:107], v[106:107], v[124:125]
	v_pk_add_f32 v[108:109], v[108:109], v[126:127]
	v_cvt_pk_bf16_f32 v124, v106, v107
	v_cvt_pk_bf16_f32 v125, v108, v109
	global_store_dwordx4 v[128:129], v[106:109], off offset:64
	global_store_dwordx2 v[138:139], v[124:125], off offset:32
	s_nop 0
	v_pk_mul_f32 v[106:107], v[106:107], v[106:107]
	v_pk_mul_f32 v[108:109], v[108:109], v[108:109]
	v_add_f32_e32 v106, v106, v107
	v_add_f32_e32 v106, v106, v108
	v_add_f32_e32 v106, v106, v109
	v_add_f32_e32 v106, v110, v106
	s_waitcnt lgkmcnt(0)
	v_mov_b32_e32 v124, v204
	v_mov_b32_e32 v125, v205
	v_mov_b32_e32 v126, v206
	v_mov_b32_e32 v127, v207
	v_pk_add_f32 v[102:103], v[102:103], v[124:125]
	v_pk_add_f32 v[104:105], v[104:105], v[126:127]
	v_cvt_pk_bf16_f32 v124, v102, v103
	v_cvt_pk_bf16_f32 v125, v104, v105
	global_store_dwordx4 v[128:129], v[102:105], off offset:128
	global_store_dwordx2 v[138:139], v[124:125], off offset:64
	s_nop 0
	v_pk_mul_f32 v[102:103], v[102:103], v[102:103]
	v_pk_mul_f32 v[104:105], v[104:105], v[104:105]
	v_add_f32_e32 v102, v102, v103
	v_add_f32_e32 v102, v102, v104
	v_add_f32_e32 v107, v102, v105
	v_add_f32_e32 v106, v106, v107
	s_waitcnt lgkmcnt(0)
	v_mov_b32_e32 v124, v208
	v_mov_b32_e32 v125, v209
	v_mov_b32_e32 v126, v210
	v_mov_b32_e32 v127, v211
	v_pk_add_f32 v[102:103], v[98:99], v[124:125]
	v_pk_add_f32 v[104:105], v[100:101], v[126:127]
	v_pk_mul_f32 v[98:99], v[102:103], v[102:103]
	v_pk_mul_f32 v[100:101], v[104:105], v[104:105]
	v_add_f32_e32 v98, v98, v99
	v_add_f32_e32 v98, v98, v100
	v_add_f32_e32 v98, v98, v101
	v_add_f32_e32 v98, v106, v98
	ds_bpermute_b32 v99, v122, v98
	v_cvt_pk_bf16_f32 v100, v102, v103
	v_cvt_pk_bf16_f32 v101, v104, v105
	global_store_dwordx4 v[128:129], v[102:105], off offset:192
	global_store_dwordx2 v[138:139], v[100:101], off offset:96
	s_waitcnt lgkmcnt(0)
	v_add_f32_e32 v98, v98, v99
	ds_bpermute_b32 v99, v123, v98
	s_and_saveexec_b64 s[0:1], vcc
	s_cbranch_execz .LBB0_536
	s_waitcnt lgkmcnt(0)
	v_add_f32_e32 v100, v98, v99
	v_lshl_add_u64 v[98:99], v[120:121], 2, s[10:11]
	global_atomic_add_f32 v[98:99], v100, off
.LBB0_536:
	s_or_b64 exec, exec, s[0:1]
	v_or_b32_e32 v98, 32, v114
	s_waitcnt lgkmcnt(0)
	v_mov_b32_e32 v99, v115
	v_lshlrev_b64 v[104:105], 12, v[98:99]
	v_lshl_add_u64 v[100:101], v[132:133], 0, v[104:105]
	v_lshl_add_u64 v[106:107], v[100:101], 0, v[118:119]
	s_mov_b32 s98, 0x30000
	s_mov_b32 s99, 0
	v_lshl_add_u64 v[214:215], v[212:213], 0, s[98:99]
	global_load_dwordx4 v[196:199], v[214:215], off
	global_load_dwordx4 v[200:203], v[214:215], off offset:64
	global_load_dwordx4 v[204:207], v[214:215], off offset:128
	global_load_dwordx4 v[208:211], v[214:215], off offset:192
	v_lshlrev_b64 v[108:109], 11, v[98:99]
	v_lshl_add_u64 v[104:105], v[130:131], 0, v[104:105]
	v_lshl_add_u64 v[108:109], s[8:9], 0, v[108:109]
	v_lshl_add_u64 v[104:105], v[104:105], 0, v[118:119]
	v_lshl_add_u64 v[108:109], v[116:117], 1, v[108:109]
	s_waitcnt vmcnt(12) lgkmcnt(0)
	v_mov_b32_e32 v100, v180
	v_mov_b32_e32 v101, v181
	v_mov_b32_e32 v102, v182
	v_mov_b32_e32 v103, v183
	v_pk_add_f32 v[94:95], v[94:95], v[100:101]
	v_pk_add_f32 v[96:97], v[96:97], v[102:103]
	v_cvt_pk_bf16_f32 v100, v94, v95
	v_cvt_pk_bf16_f32 v101, v96, v97
	global_store_dwordx4 v[104:105], v[94:97], off
	global_store_dwordx2 v[108:109], v[100:101], off
	s_nop 0
	v_pk_mul_f32 v[94:95], v[94:95], v[94:95]
	v_pk_mul_f32 v[96:97], v[96:97], v[96:97]
	v_add_f32_e32 v94, v94, v95
	v_add_f32_e32 v94, v94, v96
	v_add_f32_e32 v94, v94, v97
	s_waitcnt lgkmcnt(0)
	v_mov_b32_e32 v100, v184
	v_mov_b32_e32 v101, v185
	v_mov_b32_e32 v102, v186
	v_mov_b32_e32 v103, v187
	v_pk_add_f32 v[90:91], v[90:91], v[100:101]
	v_pk_add_f32 v[92:93], v[92:93], v[102:103]
	v_cvt_pk_bf16_f32 v100, v90, v91
	v_cvt_pk_bf16_f32 v101, v92, v93
	global_store_dwordx4 v[104:105], v[90:93], off offset:64
	global_store_dwordx2 v[108:109], v[100:101], off offset:32
	s_nop 0
	v_pk_mul_f32 v[90:91], v[90:91], v[90:91]
	v_pk_mul_f32 v[92:93], v[92:93], v[92:93]
	v_add_f32_e32 v90, v90, v91
	v_add_f32_e32 v90, v90, v92
	v_add_f32_e32 v90, v90, v93
	v_add_f32_e32 v90, v94, v90
	s_waitcnt lgkmcnt(0)
	v_mov_b32_e32 v100, v188
	v_mov_b32_e32 v101, v189
	v_mov_b32_e32 v102, v190
	v_mov_b32_e32 v103, v191
	v_pk_add_f32 v[86:87], v[86:87], v[100:101]
	v_pk_add_f32 v[88:89], v[88:89], v[102:103]
	v_cvt_pk_bf16_f32 v100, v86, v87
	v_cvt_pk_bf16_f32 v101, v88, v89
	global_store_dwordx4 v[104:105], v[86:89], off offset:128
	global_store_dwordx2 v[108:109], v[100:101], off offset:64
	s_nop 0
	v_pk_mul_f32 v[86:87], v[86:87], v[86:87]
	v_pk_mul_f32 v[88:89], v[88:89], v[88:89]
	v_add_f32_e32 v86, v86, v87
	v_add_f32_e32 v86, v86, v88
	v_add_f32_e32 v91, v86, v89
	v_add_f32_e32 v90, v90, v91
	s_waitcnt lgkmcnt(0)
	v_mov_b32_e32 v100, v192
	v_mov_b32_e32 v101, v193
	v_mov_b32_e32 v102, v194
	v_mov_b32_e32 v103, v195
	v_pk_add_f32 v[86:87], v[82:83], v[100:101]
	v_pk_add_f32 v[88:89], v[84:85], v[102:103]
	v_pk_mul_f32 v[82:83], v[86:87], v[86:87]
	v_pk_mul_f32 v[84:85], v[88:89], v[88:89]
	v_add_f32_e32 v82, v82, v83
	v_add_f32_e32 v82, v82, v84
	v_add_f32_e32 v82, v82, v85
	v_add_f32_e32 v82, v90, v82
	ds_bpermute_b32 v83, v122, v82
	v_cvt_pk_bf16_f32 v84, v86, v87
	v_cvt_pk_bf16_f32 v85, v88, v89
	global_store_dwordx4 v[104:105], v[86:89], off offset:192
	global_store_dwordx2 v[108:109], v[84:85], off offset:96
	s_waitcnt lgkmcnt(0)
	v_add_f32_e32 v82, v82, v83
	ds_bpermute_b32 v83, v123, v82
	s_and_saveexec_b64 s[0:1], vcc
	s_cbranch_execz .LBB0_538
	s_waitcnt lgkmcnt(0)
	v_add_f32_e32 v84, v82, v83
	v_lshl_add_u64 v[82:83], v[98:99], 2, s[10:11]
	global_atomic_add_f32 v[82:83], v84, off
.LBB0_538:
	s_or_b64 exec, exec, s[0:1]
	v_or_b32_e32 v82, 48, v114
	s_waitcnt lgkmcnt(0)
	v_mov_b32_e32 v83, v115
	v_lshlrev_b64 v[88:89], 12, v[82:83]
	v_lshl_add_u64 v[84:85], v[132:133], 0, v[88:89]
	v_lshl_add_u64 v[90:91], v[84:85], 0, v[118:119]
	s_mov_b32 s98, 0x40000
	s_mov_b32 s99, 0
	v_lshl_add_u64 v[214:215], v[212:213], 0, s[98:99]
	global_load_dwordx4 v[180:183], v[214:215], off
	global_load_dwordx4 v[184:187], v[214:215], off offset:64
	global_load_dwordx4 v[188:191], v[214:215], off offset:128
	global_load_dwordx4 v[192:195], v[214:215], off offset:192
	v_lshlrev_b64 v[92:93], 11, v[82:83]
	v_lshl_add_u64 v[88:89], v[130:131], 0, v[88:89]
	v_lshl_add_u64 v[92:93], s[8:9], 0, v[92:93]
	v_lshl_add_u64 v[88:89], v[88:89], 0, v[118:119]
	v_lshl_add_u64 v[92:93], v[116:117], 1, v[92:93]
	s_waitcnt vmcnt(12) lgkmcnt(0)
	v_mov_b32_e32 v84, v196
	v_mov_b32_e32 v85, v197
	v_mov_b32_e32 v86, v198
	v_mov_b32_e32 v87, v199
	v_pk_add_f32 v[78:79], v[78:79], v[84:85]
	v_pk_add_f32 v[80:81], v[80:81], v[86:87]
	v_cvt_pk_bf16_f32 v84, v78, v79
	v_cvt_pk_bf16_f32 v85, v80, v81
	global_store_dwordx4 v[88:89], v[78:81], off
	global_store_dwordx2 v[92:93], v[84:85], off
	s_nop 0
	v_pk_mul_f32 v[78:79], v[78:79], v[78:79]
	v_pk_mul_f32 v[80:81], v[80:81], v[80:81]
	v_add_f32_e32 v78, v78, v79
	v_add_f32_e32 v78, v78, v80
	v_add_f32_e32 v78, v78, v81
	s_waitcnt lgkmcnt(0)
	v_mov_b32_e32 v84, v200
	v_mov_b32_e32 v85, v201
	v_mov_b32_e32 v86, v202
	v_mov_b32_e32 v87, v203
	v_pk_add_f32 v[74:75], v[74:75], v[84:85]
	v_pk_add_f32 v[76:77], v[76:77], v[86:87]
	v_cvt_pk_bf16_f32 v84, v74, v75
	v_cvt_pk_bf16_f32 v85, v76, v77
	global_store_dwordx4 v[88:89], v[74:77], off offset:64
	global_store_dwordx2 v[92:93], v[84:85], off offset:32
	s_nop 0
	v_pk_mul_f32 v[74:75], v[74:75], v[74:75]
	v_pk_mul_f32 v[76:77], v[76:77], v[76:77]
	v_add_f32_e32 v74, v74, v75
	v_add_f32_e32 v74, v74, v76
	v_add_f32_e32 v74, v74, v77
	v_add_f32_e32 v74, v78, v74
	s_waitcnt lgkmcnt(0)
	v_mov_b32_e32 v84, v204
	v_mov_b32_e32 v85, v205
	v_mov_b32_e32 v86, v206
	v_mov_b32_e32 v87, v207
	v_pk_add_f32 v[70:71], v[70:71], v[84:85]
	v_pk_add_f32 v[72:73], v[72:73], v[86:87]
	v_cvt_pk_bf16_f32 v84, v70, v71
	v_cvt_pk_bf16_f32 v85, v72, v73
	global_store_dwordx4 v[88:89], v[70:73], off offset:128
	global_store_dwordx2 v[92:93], v[84:85], off offset:64
	s_nop 0
	v_pk_mul_f32 v[70:71], v[70:71], v[70:71]
	v_pk_mul_f32 v[72:73], v[72:73], v[72:73]
	v_add_f32_e32 v70, v70, v71
	v_add_f32_e32 v70, v70, v72
	v_add_f32_e32 v75, v70, v73
	v_add_f32_e32 v74, v74, v75
	s_waitcnt lgkmcnt(0)
	v_mov_b32_e32 v84, v208
	v_mov_b32_e32 v85, v209
	v_mov_b32_e32 v86, v210
	v_mov_b32_e32 v87, v211
	v_pk_add_f32 v[70:71], v[66:67], v[84:85]
	v_pk_add_f32 v[72:73], v[68:69], v[86:87]
	v_pk_mul_f32 v[66:67], v[70:71], v[70:71]
	v_pk_mul_f32 v[68:69], v[72:73], v[72:73]
	v_add_f32_e32 v66, v66, v67
	v_add_f32_e32 v66, v66, v68
	v_add_f32_e32 v66, v66, v69
	v_add_f32_e32 v66, v74, v66
	ds_bpermute_b32 v67, v122, v66
	v_cvt_pk_bf16_f32 v68, v70, v71
	v_cvt_pk_bf16_f32 v69, v72, v73
	global_store_dwordx4 v[88:89], v[70:73], off offset:192
	global_store_dwordx2 v[92:93], v[68:69], off offset:96
	s_waitcnt lgkmcnt(0)
	v_add_f32_e32 v66, v66, v67
	ds_bpermute_b32 v67, v123, v66
	s_and_saveexec_b64 s[0:1], vcc
	s_cbranch_execz .LBB0_540
	s_waitcnt lgkmcnt(0)
	v_add_f32_e32 v68, v66, v67
	v_lshl_add_u64 v[66:67], v[82:83], 2, s[10:11]
	global_atomic_add_f32 v[66:67], v68, off
.LBB0_540:
	s_or_b64 exec, exec, s[0:1]
	v_or_b32_e32 v66, 64, v114
	s_waitcnt lgkmcnt(0)
	v_mov_b32_e32 v67, v115
	v_lshlrev_b64 v[72:73], 12, v[66:67]
	v_lshl_add_u64 v[68:69], v[132:133], 0, v[72:73]
	v_lshl_add_u64 v[74:75], v[68:69], 0, v[118:119]
	s_mov_b32 s98, 0x50000
	s_mov_b32 s99, 0
	v_lshl_add_u64 v[214:215], v[212:213], 0, s[98:99]
	global_load_dwordx4 v[196:199], v[214:215], off
	global_load_dwordx4 v[200:203], v[214:215], off offset:64
	global_load_dwordx4 v[204:207], v[214:215], off offset:128
	global_load_dwordx4 v[208:211], v[214:215], off offset:192
	v_lshlrev_b64 v[76:77], 11, v[66:67]
	v_lshl_add_u64 v[72:73], v[130:131], 0, v[72:73]
	v_lshl_add_u64 v[76:77], s[8:9], 0, v[76:77]
	v_lshl_add_u64 v[72:73], v[72:73], 0, v[118:119]
	v_lshl_add_u64 v[76:77], v[116:117], 1, v[76:77]
	s_waitcnt vmcnt(12) lgkmcnt(0)
	v_mov_b32_e32 v68, v180
	v_mov_b32_e32 v69, v181
	v_mov_b32_e32 v70, v182
	v_mov_b32_e32 v71, v183
	v_pk_add_f32 v[62:63], v[62:63], v[68:69]
	v_pk_add_f32 v[64:65], v[64:65], v[70:71]
	v_cvt_pk_bf16_f32 v68, v62, v63
	v_cvt_pk_bf16_f32 v69, v64, v65
	global_store_dwordx4 v[72:73], v[62:65], off
	global_store_dwordx2 v[76:77], v[68:69], off
	s_nop 0
	v_pk_mul_f32 v[62:63], v[62:63], v[62:63]
	v_pk_mul_f32 v[64:65], v[64:65], v[64:65]
	v_add_f32_e32 v62, v62, v63
	v_add_f32_e32 v62, v62, v64
	v_add_f32_e32 v62, v62, v65
	s_waitcnt lgkmcnt(0)
	v_mov_b32_e32 v68, v184
	v_mov_b32_e32 v69, v185
	v_mov_b32_e32 v70, v186
	v_mov_b32_e32 v71, v187
	v_pk_add_f32 v[58:59], v[58:59], v[68:69]
	v_pk_add_f32 v[60:61], v[60:61], v[70:71]
	v_cvt_pk_bf16_f32 v68, v58, v59
	v_cvt_pk_bf16_f32 v69, v60, v61
	global_store_dwordx4 v[72:73], v[58:61], off offset:64
	global_store_dwordx2 v[76:77], v[68:69], off offset:32
	s_nop 0
	v_pk_mul_f32 v[58:59], v[58:59], v[58:59]
	v_pk_mul_f32 v[60:61], v[60:61], v[60:61]
	v_add_f32_e32 v58, v58, v59
	v_add_f32_e32 v58, v58, v60
	v_add_f32_e32 v58, v58, v61
	v_add_f32_e32 v58, v62, v58
	s_waitcnt lgkmcnt(0)
	v_mov_b32_e32 v68, v188
	v_mov_b32_e32 v69, v189
	v_mov_b32_e32 v70, v190
	v_mov_b32_e32 v71, v191
	v_pk_add_f32 v[54:55], v[54:55], v[68:69]
	v_pk_add_f32 v[56:57], v[56:57], v[70:71]
	v_cvt_pk_bf16_f32 v68, v54, v55
	v_cvt_pk_bf16_f32 v69, v56, v57
	global_store_dwordx4 v[72:73], v[54:57], off offset:128
	global_store_dwordx2 v[76:77], v[68:69], off offset:64
	s_nop 0
	v_pk_mul_f32 v[54:55], v[54:55], v[54:55]
	v_pk_mul_f32 v[56:57], v[56:57], v[56:57]
	v_add_f32_e32 v54, v54, v55
	v_add_f32_e32 v54, v54, v56
	v_add_f32_e32 v59, v54, v57
	v_add_f32_e32 v58, v58, v59
	s_waitcnt lgkmcnt(0)
	v_mov_b32_e32 v68, v192
	v_mov_b32_e32 v69, v193
	v_mov_b32_e32 v70, v194
	v_mov_b32_e32 v71, v195
	v_pk_add_f32 v[54:55], v[50:51], v[68:69]
	v_pk_add_f32 v[56:57], v[52:53], v[70:71]
	v_pk_mul_f32 v[50:51], v[54:55], v[54:55]
	v_pk_mul_f32 v[52:53], v[56:57], v[56:57]
	v_add_f32_e32 v50, v50, v51
	v_add_f32_e32 v50, v50, v52
	v_add_f32_e32 v50, v50, v53
	v_add_f32_e32 v50, v58, v50
	ds_bpermute_b32 v51, v122, v50
	v_cvt_pk_bf16_f32 v52, v54, v55
	v_cvt_pk_bf16_f32 v53, v56, v57
	global_store_dwordx4 v[72:73], v[54:57], off offset:192
	global_store_dwordx2 v[76:77], v[52:53], off offset:96
	s_waitcnt lgkmcnt(0)
	v_add_f32_e32 v50, v50, v51
	ds_bpermute_b32 v51, v123, v50
	s_and_saveexec_b64 s[0:1], vcc
	s_cbranch_execz .LBB0_542
	s_waitcnt lgkmcnt(0)
	v_add_f32_e32 v52, v50, v51
	v_lshl_add_u64 v[50:51], v[66:67], 2, s[10:11]
	global_atomic_add_f32 v[50:51], v52, off
.LBB0_542:
	s_or_b64 exec, exec, s[0:1]
	v_or_b32_e32 v50, 0x50, v114
	s_waitcnt lgkmcnt(0)
	v_mov_b32_e32 v51, v115
	v_lshlrev_b64 v[56:57], 12, v[50:51]
	v_lshl_add_u64 v[52:53], v[132:133], 0, v[56:57]
	v_lshl_add_u64 v[58:59], v[52:53], 0, v[118:119]
	s_mov_b32 s98, 0x60000
	s_mov_b32 s99, 0
	v_lshl_add_u64 v[214:215], v[212:213], 0, s[98:99]
	global_load_dwordx4 v[180:183], v[214:215], off
	global_load_dwordx4 v[184:187], v[214:215], off offset:64
	global_load_dwordx4 v[188:191], v[214:215], off offset:128
	global_load_dwordx4 v[192:195], v[214:215], off offset:192
	v_lshlrev_b64 v[60:61], 11, v[50:51]
	v_lshl_add_u64 v[56:57], v[130:131], 0, v[56:57]
	v_lshl_add_u64 v[60:61], s[8:9], 0, v[60:61]
	v_lshl_add_u64 v[56:57], v[56:57], 0, v[118:119]
	v_lshl_add_u64 v[60:61], v[116:117], 1, v[60:61]
	s_waitcnt vmcnt(12) lgkmcnt(0)
	v_mov_b32_e32 v52, v196
	v_mov_b32_e32 v53, v197
	v_mov_b32_e32 v54, v198
	v_mov_b32_e32 v55, v199
	v_pk_add_f32 v[46:47], v[46:47], v[52:53]
	v_pk_add_f32 v[48:49], v[48:49], v[54:55]
	v_cvt_pk_bf16_f32 v52, v46, v47
	v_cvt_pk_bf16_f32 v53, v48, v49
	global_store_dwordx4 v[56:57], v[46:49], off
	global_store_dwordx2 v[60:61], v[52:53], off
	s_nop 0
	v_pk_mul_f32 v[46:47], v[46:47], v[46:47]
	v_pk_mul_f32 v[48:49], v[48:49], v[48:49]
	v_add_f32_e32 v46, v46, v47
	v_add_f32_e32 v46, v46, v48
	v_add_f32_e32 v46, v46, v49
	s_waitcnt lgkmcnt(0)
	v_mov_b32_e32 v52, v200
	v_mov_b32_e32 v53, v201
	v_mov_b32_e32 v54, v202
	v_mov_b32_e32 v55, v203
	v_pk_add_f32 v[42:43], v[42:43], v[52:53]
	v_pk_add_f32 v[44:45], v[44:45], v[54:55]
	v_cvt_pk_bf16_f32 v52, v42, v43
	v_cvt_pk_bf16_f32 v53, v44, v45
	global_store_dwordx4 v[56:57], v[42:45], off offset:64
	global_store_dwordx2 v[60:61], v[52:53], off offset:32
	s_nop 0
	v_pk_mul_f32 v[42:43], v[42:43], v[42:43]
	v_pk_mul_f32 v[44:45], v[44:45], v[44:45]
	v_add_f32_e32 v42, v42, v43
	v_add_f32_e32 v42, v42, v44
	v_add_f32_e32 v42, v42, v45
	v_add_f32_e32 v42, v46, v42
	s_waitcnt lgkmcnt(0)
	v_mov_b32_e32 v52, v204
	v_mov_b32_e32 v53, v205
	v_mov_b32_e32 v54, v206
	v_mov_b32_e32 v55, v207
	v_pk_add_f32 v[38:39], v[38:39], v[52:53]
	v_pk_add_f32 v[40:41], v[40:41], v[54:55]
	v_cvt_pk_bf16_f32 v52, v38, v39
	v_cvt_pk_bf16_f32 v53, v40, v41
	global_store_dwordx4 v[56:57], v[38:41], off offset:128
	global_store_dwordx2 v[60:61], v[52:53], off offset:64
	s_nop 0
	v_pk_mul_f32 v[38:39], v[38:39], v[38:39]
	v_pk_mul_f32 v[40:41], v[40:41], v[40:41]
	v_add_f32_e32 v38, v38, v39
	v_add_f32_e32 v38, v38, v40
	v_add_f32_e32 v43, v38, v41
	v_add_f32_e32 v42, v42, v43
	s_waitcnt lgkmcnt(0)
	v_mov_b32_e32 v52, v208
	v_mov_b32_e32 v53, v209
	v_mov_b32_e32 v54, v210
	v_mov_b32_e32 v55, v211
	v_pk_add_f32 v[38:39], v[34:35], v[52:53]
	v_pk_add_f32 v[40:41], v[36:37], v[54:55]
	v_pk_mul_f32 v[34:35], v[38:39], v[38:39]
	v_pk_mul_f32 v[36:37], v[40:41], v[40:41]
	v_add_f32_e32 v34, v34, v35
	v_add_f32_e32 v34, v34, v36
	v_add_f32_e32 v34, v34, v37
	v_add_f32_e32 v34, v42, v34
	ds_bpermute_b32 v35, v122, v34
	v_cvt_pk_bf16_f32 v36, v38, v39
	v_cvt_pk_bf16_f32 v37, v40, v41
	global_store_dwordx4 v[56:57], v[38:41], off offset:192
	global_store_dwordx2 v[60:61], v[36:37], off offset:96
	s_waitcnt lgkmcnt(0)
	v_add_f32_e32 v34, v34, v35
	ds_bpermute_b32 v35, v123, v34
	s_and_saveexec_b64 s[0:1], vcc
	s_cbranch_execz .LBB0_544
	s_waitcnt lgkmcnt(0)
	v_add_f32_e32 v36, v34, v35
	v_lshl_add_u64 v[34:35], v[50:51], 2, s[10:11]
	global_atomic_add_f32 v[34:35], v36, off
.LBB0_544:
	s_or_b64 exec, exec, s[0:1]
	v_or_b32_e32 v34, 0x60, v114
	s_waitcnt lgkmcnt(0)
	v_mov_b32_e32 v35, v115
	v_lshlrev_b64 v[40:41], 12, v[34:35]
	v_lshl_add_u64 v[36:37], v[132:133], 0, v[40:41]
	v_lshl_add_u64 v[42:43], v[36:37], 0, v[118:119]
	s_mov_b32 s98, 0x70000
	s_mov_b32 s99, 0
	v_lshl_add_u64 v[214:215], v[212:213], 0, s[98:99]
	global_load_dwordx4 v[196:199], v[214:215], off
	global_load_dwordx4 v[200:203], v[214:215], off offset:64
	global_load_dwordx4 v[204:207], v[214:215], off offset:128
	global_load_dwordx4 v[208:211], v[214:215], off offset:192
	v_lshlrev_b64 v[44:45], 11, v[34:35]
	v_lshl_add_u64 v[40:41], v[130:131], 0, v[40:41]
	v_lshl_add_u64 v[44:45], s[8:9], 0, v[44:45]
	v_lshl_add_u64 v[40:41], v[40:41], 0, v[118:119]
	v_lshl_add_u64 v[44:45], v[116:117], 1, v[44:45]
	s_waitcnt vmcnt(12) lgkmcnt(0)
	v_mov_b32_e32 v36, v180
	v_mov_b32_e32 v37, v181
	v_mov_b32_e32 v38, v182
	v_mov_b32_e32 v39, v183
	v_pk_add_f32 v[30:31], v[30:31], v[36:37]
	v_pk_add_f32 v[32:33], v[32:33], v[38:39]
	v_cvt_pk_bf16_f32 v36, v30, v31
	v_cvt_pk_bf16_f32 v37, v32, v33
	global_store_dwordx4 v[40:41], v[30:33], off
	global_store_dwordx2 v[44:45], v[36:37], off
	s_nop 0
	v_pk_mul_f32 v[30:31], v[30:31], v[30:31]
	v_pk_mul_f32 v[32:33], v[32:33], v[32:33]
	v_add_f32_e32 v30, v30, v31
	v_add_f32_e32 v30, v30, v32
	v_add_f32_e32 v30, v30, v33
	s_waitcnt lgkmcnt(0)
	v_mov_b32_e32 v36, v184
	v_mov_b32_e32 v37, v185
	v_mov_b32_e32 v38, v186
	v_mov_b32_e32 v39, v187
	v_pk_add_f32 v[26:27], v[26:27], v[36:37]
	v_pk_add_f32 v[28:29], v[28:29], v[38:39]
	v_cvt_pk_bf16_f32 v36, v26, v27
	v_cvt_pk_bf16_f32 v37, v28, v29
	global_store_dwordx4 v[40:41], v[26:29], off offset:64
	global_store_dwordx2 v[44:45], v[36:37], off offset:32
	s_nop 0
	v_pk_mul_f32 v[26:27], v[26:27], v[26:27]
	v_pk_mul_f32 v[28:29], v[28:29], v[28:29]
	v_add_f32_e32 v26, v26, v27
	v_add_f32_e32 v26, v26, v28
	v_add_f32_e32 v26, v26, v29
	v_add_f32_e32 v26, v30, v26
	s_waitcnt lgkmcnt(0)
	v_mov_b32_e32 v36, v188
	v_mov_b32_e32 v37, v189
	v_mov_b32_e32 v38, v190
	v_mov_b32_e32 v39, v191
	v_pk_add_f32 v[22:23], v[22:23], v[36:37]
	v_pk_add_f32 v[24:25], v[24:25], v[38:39]
	v_cvt_pk_bf16_f32 v36, v22, v23
	v_cvt_pk_bf16_f32 v37, v24, v25
	global_store_dwordx4 v[40:41], v[22:25], off offset:128
	global_store_dwordx2 v[44:45], v[36:37], off offset:64
	s_nop 0
	v_pk_mul_f32 v[22:23], v[22:23], v[22:23]
	v_pk_mul_f32 v[24:25], v[24:25], v[24:25]
	v_add_f32_e32 v22, v22, v23
	v_add_f32_e32 v22, v22, v24
	v_add_f32_e32 v27, v22, v25
	v_add_f32_e32 v26, v26, v27
	s_waitcnt lgkmcnt(0)
	v_mov_b32_e32 v36, v192
	v_mov_b32_e32 v37, v193
	v_mov_b32_e32 v38, v194
	v_mov_b32_e32 v39, v195
	v_pk_add_f32 v[22:23], v[18:19], v[36:37]
	v_pk_add_f32 v[24:25], v[20:21], v[38:39]
	v_pk_mul_f32 v[18:19], v[22:23], v[22:23]
	v_pk_mul_f32 v[20:21], v[24:25], v[24:25]
	v_add_f32_e32 v18, v18, v19
	v_add_f32_e32 v18, v18, v20
	v_add_f32_e32 v18, v18, v21
	v_add_f32_e32 v18, v26, v18
	ds_bpermute_b32 v19, v122, v18
	v_cvt_pk_bf16_f32 v20, v22, v23
	v_cvt_pk_bf16_f32 v21, v24, v25
	global_store_dwordx4 v[40:41], v[22:25], off offset:192
	global_store_dwordx2 v[44:45], v[20:21], off offset:96
	s_waitcnt lgkmcnt(0)
	v_add_f32_e32 v18, v18, v19
	ds_bpermute_b32 v19, v123, v18
	s_and_saveexec_b64 s[0:1], vcc
	s_cbranch_execz .LBB0_546
	s_waitcnt lgkmcnt(0)
	v_add_f32_e32 v20, v18, v19
	v_lshl_add_u64 v[18:19], v[34:35], 2, s[10:11]
	global_atomic_add_f32 v[18:19], v20, off
.LBB0_546:
	s_or_b64 exec, exec, s[0:1]
	v_or_b32_e32 v114, 0x70, v114
	v_lshlrev_b64 v[22:23], 12, v[114:115]
	s_waitcnt lgkmcnt(0)
	v_lshl_add_u64 v[18:19], v[132:133], 0, v[22:23]
	v_lshl_add_u64 v[24:25], v[18:19], 0, v[118:119]
	s_nop 0
	v_lshlrev_b64 v[26:27], 11, v[114:115]
	v_lshl_add_u64 v[22:23], v[130:131], 0, v[22:23]
	v_lshl_add_u64 v[26:27], s[8:9], 0, v[26:27]
	v_lshl_add_u64 v[22:23], v[22:23], 0, v[118:119]
	v_lshl_add_u64 v[26:27], v[116:117], 1, v[26:27]
	s_waitcnt vmcnt(8) lgkmcnt(0)
	v_mov_b32_e32 v18, v196
	v_mov_b32_e32 v19, v197
	v_mov_b32_e32 v20, v198
	v_mov_b32_e32 v21, v199
	v_pk_add_f32 v[14:15], v[14:15], v[18:19]
	v_pk_add_f32 v[16:17], v[16:17], v[20:21]
	v_cvt_pk_bf16_f32 v18, v14, v15
	v_cvt_pk_bf16_f32 v19, v16, v17
	global_store_dwordx4 v[22:23], v[14:17], off
	global_store_dwordx2 v[26:27], v[18:19], off
	s_nop 0
	v_pk_mul_f32 v[14:15], v[14:15], v[14:15]
	v_pk_mul_f32 v[16:17], v[16:17], v[16:17]
	v_add_f32_e32 v14, v14, v15
	v_add_f32_e32 v14, v14, v16
	v_add_f32_e32 v14, v14, v17
	s_waitcnt lgkmcnt(0)
	v_mov_b32_e32 v18, v200
	v_mov_b32_e32 v19, v201
	v_mov_b32_e32 v20, v202
	v_mov_b32_e32 v21, v203
	v_pk_add_f32 v[10:11], v[10:11], v[18:19]
	v_pk_add_f32 v[12:13], v[12:13], v[20:21]
	v_cvt_pk_bf16_f32 v18, v10, v11
	v_cvt_pk_bf16_f32 v19, v12, v13
	global_store_dwordx4 v[22:23], v[10:13], off offset:64
	global_store_dwordx2 v[26:27], v[18:19], off offset:32
	s_nop 0
	v_pk_mul_f32 v[10:11], v[10:11], v[10:11]
	v_pk_mul_f32 v[12:13], v[12:13], v[12:13]
	v_add_f32_e32 v10, v10, v11
	v_add_f32_e32 v10, v10, v12
	v_add_f32_e32 v10, v10, v13
	v_add_f32_e32 v10, v14, v10
	s_waitcnt lgkmcnt(0)
	v_mov_b32_e32 v18, v204
	v_mov_b32_e32 v19, v205
	v_mov_b32_e32 v20, v206
	v_mov_b32_e32 v21, v207
	v_pk_add_f32 v[6:7], v[6:7], v[18:19]
	v_pk_add_f32 v[8:9], v[8:9], v[20:21]
	v_cvt_pk_bf16_f32 v18, v6, v7
	v_cvt_pk_bf16_f32 v19, v8, v9
	global_store_dwordx4 v[22:23], v[6:9], off offset:128
	global_store_dwordx2 v[26:27], v[18:19], off offset:64
	s_nop 0
	v_pk_mul_f32 v[6:7], v[6:7], v[6:7]
	v_pk_mul_f32 v[8:9], v[8:9], v[8:9]
	v_add_f32_e32 v6, v6, v7
	v_add_f32_e32 v6, v6, v8
	v_add_f32_e32 v11, v6, v9
	v_add_f32_e32 v10, v10, v11
	s_waitcnt lgkmcnt(0)
	v_mov_b32_e32 v18, v208
	v_mov_b32_e32 v19, v209
	v_mov_b32_e32 v20, v210
	v_mov_b32_e32 v21, v211
	v_pk_add_f32 v[6:7], v[2:3], v[18:19]
	v_pk_add_f32 v[8:9], v[4:5], v[20:21]
	v_pk_mul_f32 v[2:3], v[6:7], v[6:7]
	v_pk_mul_f32 v[4:5], v[8:9], v[8:9]
	v_add_f32_e32 v2, v2, v3
	v_add_f32_e32 v2, v2, v4
	v_add_f32_e32 v2, v2, v5
	v_add_f32_e32 v2, v10, v2
	ds_bpermute_b32 v3, v122, v2
	v_cvt_pk_bf16_f32 v4, v6, v7
	v_cvt_pk_bf16_f32 v5, v8, v9
	global_store_dwordx4 v[22:23], v[6:9], off offset:192
	global_store_dwordx2 v[26:27], v[4:5], off offset:96
	s_waitcnt lgkmcnt(0)
	v_add_f32_e32 v2, v2, v3
	ds_bpermute_b32 v3, v123, v2
	s_and_saveexec_b64 s[0:1], vcc
	s_cbranch_execz .LBB0_529
	s_waitcnt lgkmcnt(0)
	v_add_f32_e32 v4, v2, v3
	v_lshl_add_u64 v[2:3], v[114:115], 2, s[10:11]
	global_atomic_add_f32 v[2:3], v4, off
	s_branch .LBB0_529

.LBB0_587:
	s_mul_i32 s43, s1, 0x6000
	s_add_i32 s50, s43, 0xffffa000
	s_cmp_lg_u32 s1, 0
	s_cselect_b32 s50, s50, 0xc000
	v_add_u32_e32 v148, s50, v143
	v_lshl_add_u64 v[144:145], v[136:137], 0, s[48:49]
	v_readfirstlane_b32 s50, v148
	v_add_u32_e32 v149, 0x1000, v148
	v_lshl_add_u64 v[146:147], v[144:145], 0, s[24:25]
	s_mov_b32 m0, s50
	v_readfirstlane_b32 s50, v149
	v_add_u32_e32 v149, 0x2000, v148
	s_waitcnt vmcnt(6)
	s_barrier
	global_load_lds_dwordx4 v[146:147], off
	v_lshl_add_u64 v[146:147], v[144:145], 0, s[26:27]
	s_mov_b32 m0, s50
	v_readfirstlane_b32 s50, v149
	global_load_lds_dwordx4 v[146:147], off
	v_lshl_add_u64 v[146:147], v[144:145], 0, s[28:29]
	s_mov_b32 m0, s50
	v_lshl_add_u64 v[144:145], v[144:145], 0, s[30:31]
	global_load_lds_dwordx4 v[146:147], off
	v_add_u32_e32 v146, 0x3000, v148
	v_add_u32_e32 v149, 0x4000, v148
	v_readfirstlane_b32 s50, v146
	s_mov_b32 m0, s50
	v_readfirstlane_b32 s50, v149
	global_load_lds_dwordx4 v[144:145], off
	v_lshl_add_u64 v[144:145], v[134:135], 0, s[48:49]
	v_lshl_add_u64 v[146:147], v[144:145], 0, s[34:35]
	s_mov_b32 m0, s50
	v_lshl_add_u64 v[144:145], v[144:145], 0, s[44:45]
	global_load_lds_dwordx4 v[146:147], off
	v_add_u32_e32 v146, 0x5000, v148
	s_add_i32 s43, s43, 0
	v_readfirstlane_b32 s50, v146
	s_mov_b32 m0, s50
	v_add3_u32 v156, s43, v140, v142
	global_load_lds_dwordx4 v[144:145], off
	v_add3_u32 v176, s43, v141, v142
	ds_read_b128 v[144:147], v156 offset:16384
	ds_read_b128 v[148:151], v156 offset:17408
	ds_read_b128 v[152:155], v156 offset:18432
	ds_read_b128 v[156:159], v156 offset:19456
	ds_read_b128 v[160:163], v176
	ds_read_b128 v[164:167], v176 offset:1024
	ds_read_b128 v[168:171], v176 offset:2048
	ds_read_b128 v[172:175], v176 offset:3072
	s_setprio 1
	s_waitcnt lgkmcnt(0)
	v_mfma_f32_16x16x32_bf16 v[126:129], v[144:147], v[160:163], v[126:129]
	v_mfma_f32_16x16x32_bf16 v[122:125], v[148:151], v[160:163], v[122:125]
	v_mfma_f32_16x16x32_bf16 v[118:121], v[152:155], v[160:163], v[118:121]
	v_mfma_f32_16x16x32_bf16 v[114:117], v[156:159], v[160:163], v[114:117]
	v_mfma_f32_16x16x32_bf16 v[110:113], v[144:147], v[164:167], v[110:113]
	v_mfma_f32_16x16x32_bf16 v[106:109], v[148:151], v[164:167], v[106:109]
	v_mfma_f32_16x16x32_bf16 v[102:105], v[152:155], v[164:167], v[102:105]
	v_mfma_f32_16x16x32_bf16 v[98:101], v[156:159], v[164:167], v[98:101]
	v_mfma_f32_16x16x32_bf16 v[94:97], v[144:147], v[168:171], v[94:97]
	v_mfma_f32_16x16x32_bf16 v[90:93], v[148:151], v[168:171], v[90:93]
	v_mfma_f32_16x16x32_bf16 v[86:89], v[152:155], v[168:171], v[86:89]
	v_mfma_f32_16x16x32_bf16 v[82:85], v[156:159], v[168:171], v[82:85]
	v_mfma_f32_16x16x32_bf16 v[78:81], v[144:147], v[172:175], v[78:81]
	v_mfma_f32_16x16x32_bf16 v[74:77], v[148:151], v[172:175], v[74:77]
	v_mfma_f32_16x16x32_bf16 v[70:73], v[152:155], v[172:175], v[70:73]
	v_mfma_f32_16x16x32_bf16 v[66:69], v[156:159], v[172:175], v[66:69]
	s_setprio 0
	ds_read_b128 v[160:163], v176 offset:4096
	ds_read_b128 v[164:167], v176 offset:5120
	ds_read_b128 v[168:171], v176 offset:6144
	ds_read_b128 v[172:175], v176 offset:7168
	s_setprio 1
	s_waitcnt lgkmcnt(0)
	v_mfma_f32_16x16x32_bf16 v[62:65], v[144:147], v[160:163], v[62:65]
	v_mfma_f32_16x16x32_bf16 v[58:61], v[148:151], v[160:163], v[58:61]
	v_mfma_f32_16x16x32_bf16 v[54:57], v[152:155], v[160:163], v[54:57]
	v_mfma_f32_16x16x32_bf16 v[50:53], v[156:159], v[160:163], v[50:53]
	v_mfma_f32_16x16x32_bf16 v[46:49], v[144:147], v[164:167], v[46:49]
	v_mfma_f32_16x16x32_bf16 v[42:45], v[148:151], v[164:167], v[42:45]
	v_mfma_f32_16x16x32_bf16 v[38:41], v[152:155], v[164:167], v[38:41]
	v_mfma_f32_16x16x32_bf16 v[34:37], v[156:159], v[164:167], v[34:37]
	v_mfma_f32_16x16x32_bf16 v[30:33], v[144:147], v[168:171], v[30:33]
	v_mfma_f32_16x16x32_bf16 v[26:29], v[148:151], v[168:171], v[26:29]
	v_mfma_f32_16x16x32_bf16 v[22:25], v[152:155], v[168:171], v[22:25]
	v_mfma_f32_16x16x32_bf16 v[18:21], v[156:159], v[168:171], v[18:21]
	v_mfma_f32_16x16x32_bf16 v[14:17], v[144:147], v[172:175], v[14:17]
	v_mfma_f32_16x16x32_bf16 v[10:13], v[148:151], v[172:175], v[10:13]
	v_mfma_f32_16x16x32_bf16 v[6:9], v[152:155], v[172:175], v[6:9]
	v_mfma_f32_16x16x32_bf16 v[2:5], v[156:159], v[172:175], v[2:5]
	s_setprio 0
	s_add_i32 s43, s1, 1
	s_cmp_lg_u32 s1, 2
	s_cselect_b32 s1, s43, 0
	s_add_u32 s48, s48, 64
	s_addc_u32 s49, s49, 0
	s_cmpk_eq_i32 s48, 0x1f80
	s_cbranch_scc0 .LBB0_587
	s_mul_i32 s43, s1, 0x6000
	s_add_i32 s48, s43, 0
	v_add3_u32 v143, s48, v140, v142
	s_waitcnt vmcnt(6)
	s_barrier
	ds_read_b128 v[134:137], v143 offset:16384
	ds_read_b128 v[144:147], v143 offset:17408
	ds_read_b128 v[148:151], v143 offset:18432
	ds_read_b128 v[152:155], v143 offset:19456
	v_add3_u32 v143, s48, v141, v142
	ds_read_b128 v[156:159], v143
	ds_read_b128 v[160:163], v143 offset:1024
	ds_read_b128 v[164:167], v143 offset:2048
	ds_read_b128 v[168:171], v143 offset:3072
	s_lshl_b64 s[46:47], s[46:47], 8
	s_setprio 1
	s_waitcnt lgkmcnt(0)
	v_mfma_f32_16x16x32_bf16 v[118:121], v[148:151], v[156:159], v[118:121]
	v_mfma_f32_16x16x32_bf16 v[114:117], v[152:155], v[156:159], v[114:117]
	v_mfma_f32_16x16x32_bf16 v[110:113], v[134:137], v[160:163], v[110:113]
	v_mfma_f32_16x16x32_bf16 v[106:109], v[144:147], v[160:163], v[106:109]
	v_mfma_f32_16x16x32_bf16 v[102:105], v[148:151], v[160:163], v[102:105]
	v_mfma_f32_16x16x32_bf16 v[98:101], v[152:155], v[160:163], v[98:101]
	v_mfma_f32_16x16x32_bf16 v[94:97], v[134:137], v[164:167], v[94:97]
	v_mfma_f32_16x16x32_bf16 v[90:93], v[144:147], v[164:167], v[90:93]
	v_mfma_f32_16x16x32_bf16 v[86:89], v[148:151], v[164:167], v[86:89]
	v_mfma_f32_16x16x32_bf16 v[82:85], v[152:155], v[164:167], v[82:85]
	v_mfma_f32_16x16x32_bf16 v[78:81], v[134:137], v[168:171], v[78:81]
	v_mfma_f32_16x16x32_bf16 v[74:77], v[144:147], v[168:171], v[74:77]
	v_mfma_f32_16x16x32_bf16 v[70:73], v[148:151], v[168:171], v[70:73]
	v_mfma_f32_16x16x32_bf16 v[66:69], v[152:155], v[168:171], v[66:69]
	v_mfma_f32_16x16x32_bf16 v[126:129], v[134:137], v[156:159], v[126:129]
	v_mfma_f32_16x16x32_bf16 v[122:125], v[144:147], v[156:159], v[122:125]
	s_setprio 0
	ds_read_b128 v[156:159], v143 offset:4096
	ds_read_b128 v[160:163], v143 offset:5120
	ds_read_b128 v[164:167], v143 offset:6144
	ds_read_b128 v[168:171], v143 offset:7168
	s_setprio 1
	s_waitcnt lgkmcnt(0)
	v_mfma_f32_16x16x32_bf16 v[62:65], v[134:137], v[156:159], v[62:65]
	v_mfma_f32_16x16x32_bf16 v[58:61], v[144:147], v[156:159], v[58:61]
	v_mfma_f32_16x16x32_bf16 v[54:57], v[148:151], v[156:159], v[54:57]
	v_mfma_f32_16x16x32_bf16 v[50:53], v[152:155], v[156:159], v[50:53]
	v_mfma_f32_16x16x32_bf16 v[46:49], v[134:137], v[160:163], v[46:49]
	v_mfma_f32_16x16x32_bf16 v[42:45], v[144:147], v[160:163], v[42:45]
	v_mfma_f32_16x16x32_bf16 v[38:41], v[148:151], v[160:163], v[38:41]
	v_mfma_f32_16x16x32_bf16 v[34:37], v[152:155], v[160:163], v[34:37]
	v_mfma_f32_16x16x32_bf16 v[30:33], v[134:137], v[164:167], v[30:33]
	v_mfma_f32_16x16x32_bf16 v[26:29], v[144:147], v[164:167], v[26:29]
	v_mfma_f32_16x16x32_bf16 v[22:25], v[148:151], v[164:167], v[22:25]
	v_mfma_f32_16x16x32_bf16 v[18:21], v[152:155], v[164:167], v[18:21]
	v_mfma_f32_16x16x32_bf16 v[14:17], v[134:137], v[168:171], v[14:17]
	v_mfma_f32_16x16x32_bf16 v[10:13], v[144:147], v[168:171], v[10:13]
	v_mfma_f32_16x16x32_bf16 v[6:9], v[148:151], v[168:171], v[6:9]
	v_mfma_f32_16x16x32_bf16 v[2:5], v[152:155], v[168:171], v[2:5]
	s_setprio 0
	s_addk_i32 s43, 0x6000
	s_cmp_lg_u32 s1, 2
	s_cselect_b32 s1, s43, 0
	s_add_i32 s1, s1, 0
	v_add3_u32 v140, s1, v140, v142
	v_add3_u32 v168, s1, v141, v142
	s_waitcnt vmcnt(0)
	s_barrier
	ds_read_b128 v[134:137], v140 offset:16384
	ds_read_b128 v[144:147], v140 offset:17408
	ds_read_b128 v[148:151], v140 offset:18432
	ds_read_b128 v[152:155], v140 offset:19456
	ds_read_b128 v[140:143], v168
	ds_read_b128 v[156:159], v168 offset:1024
	ds_read_b128 v[160:163], v168 offset:2048
	ds_read_b128 v[164:167], v168 offset:3072
	s_setprio 1
	s_waitcnt lgkmcnt(0)
	v_mfma_f32_16x16x32_bf16 v[118:121], v[148:151], v[140:143], v[118:121]
	v_mfma_f32_16x16x32_bf16 v[110:113], v[134:137], v[156:159], v[110:113]
	v_mfma_f32_16x16x32_bf16 v[106:109], v[144:147], v[156:159], v[106:109]
	v_mfma_f32_16x16x32_bf16 v[102:105], v[148:151], v[156:159], v[102:105]
	v_mfma_f32_16x16x32_bf16 v[98:101], v[152:155], v[156:159], v[98:101]
	v_mfma_f32_16x16x32_bf16 v[94:97], v[134:137], v[160:163], v[94:97]
	v_mfma_f32_16x16x32_bf16 v[90:93], v[144:147], v[160:163], v[90:93]
	v_mfma_f32_16x16x32_bf16 v[86:89], v[148:151], v[160:163], v[86:89]
	v_mfma_f32_16x16x32_bf16 v[82:85], v[152:155], v[160:163], v[82:85]
	v_mfma_f32_16x16x32_bf16 v[78:81], v[134:137], v[164:167], v[78:81]
	v_mfma_f32_16x16x32_bf16 v[74:77], v[144:147], v[164:167], v[74:77]
	v_mfma_f32_16x16x32_bf16 v[70:73], v[148:151], v[164:167], v[70:73]
	v_mfma_f32_16x16x32_bf16 v[66:69], v[152:155], v[164:167], v[66:69]
	v_mfma_f32_16x16x32_bf16 v[126:129], v[134:137], v[140:143], v[126:129]
	v_mfma_f32_16x16x32_bf16 v[122:125], v[144:147], v[140:143], v[122:125]
	v_mfma_f32_16x16x32_bf16 v[140:143], v[152:155], v[140:143], v[114:117]
	s_setprio 0
	s_nop 1
	ds_read_b128 v[114:117], v168 offset:4096
	ds_read_b128 v[156:159], v168 offset:5120
	ds_read_b128 v[160:163], v168 offset:6144
	ds_read_b128 v[164:167], v168 offset:7168
	s_setprio 1
	s_waitcnt lgkmcnt(0)
	v_mfma_f32_16x16x32_bf16 v[62:65], v[134:137], v[114:117], v[62:65]
	v_mfma_f32_16x16x32_bf16 v[58:61], v[144:147], v[114:117], v[58:61]
	v_mfma_f32_16x16x32_bf16 v[54:57], v[148:151], v[114:117], v[54:57]
	v_mfma_f32_16x16x32_bf16 v[50:53], v[152:155], v[114:117], v[50:53]
	v_mfma_f32_16x16x32_bf16 v[46:49], v[134:137], v[156:159], v[46:49]
	v_mfma_f32_16x16x32_bf16 v[42:45], v[144:147], v[156:159], v[42:45]
	v_mfma_f32_16x16x32_bf16 v[38:41], v[148:151], v[156:159], v[38:41]
	v_mfma_f32_16x16x32_bf16 v[34:37], v[152:155], v[156:159], v[34:37]
	v_mfma_f32_16x16x32_bf16 v[30:33], v[134:137], v[160:163], v[30:33]
	v_mfma_f32_16x16x32_bf16 v[26:29], v[144:147], v[160:163], v[26:29]
	v_mfma_f32_16x16x32_bf16 v[22:25], v[148:151], v[160:163], v[22:25]
	v_mfma_f32_16x16x32_bf16 v[18:21], v[152:155], v[160:163], v[18:21]
	v_mfma_f32_16x16x32_bf16 v[14:17], v[134:137], v[164:167], v[14:17]
	v_mfma_f32_16x16x32_bf16 v[10:13], v[144:147], v[164:167], v[10:13]
	v_mfma_f32_16x16x32_bf16 v[6:9], v[148:151], v[164:167], v[6:9]
	v_mfma_f32_16x16x32_bf16 v[2:5], v[152:155], v[164:167], v[2:5]
	s_setprio 0
	v_lshl_add_u64 v[114:115], s[46:47], 0, v[132:133]
	v_lshl_or_b32 v116, s0, 7, v138
	v_lshlrev_b64 v[134:135], 12, v[114:115]
	s_waitcnt vmcnt(0)
	v_lshl_add_u64 v[134:135], v[130:131], 0, v[134:135]
	v_ashrrev_i32_e32 v117, 31, v116
	v_lshl_add_u64 v[148:149], v[116:117], 2, v[134:135]
	s_barrier
	v_mov_b32_e32 v212, v148
	v_mov_b32_e32 v213, v149
	global_load_dwordx4 v[180:183], v[212:213], off
	global_load_dwordx4 v[184:187], v[212:213], off offset:64
	global_load_dwordx4 v[188:191], v[212:213], off offset:128
	global_load_dwordx4 v[192:195], v[212:213], off offset:192
	s_mov_b32 s98, 0x10000
	s_mov_b32 s99, 0
	v_lshl_add_u64 v[214:215], v[212:213], 0, s[98:99]
	global_load_dwordx4 v[196:199], v[214:215], off
	global_load_dwordx4 v[200:203], v[214:215], off offset:64
	global_load_dwordx4 v[204:207], v[214:215], off offset:128
	global_load_dwordx4 v[208:211], v[214:215], off offset:192
	v_lshlrev_b64 v[144:145], 11, v[114:115]
	v_lshl_add_u64 v[144:145], s[8:9], 0, v[144:145]
	v_lshl_add_u64 v[150:151], v[116:117], 1, v[144:145]
	s_waitcnt vmcnt(4) lgkmcnt(0)
	v_mov_b32_e32 v134, v180
	v_mov_b32_e32 v135, v181
	v_mov_b32_e32 v136, v182
	v_mov_b32_e32 v137, v183
	v_pk_add_f32 v[126:127], v[126:127], v[134:135]
	v_pk_add_f32 v[128:129], v[128:129], v[136:137]
	v_cvt_pk_bf16_f32 v134, v126, v127
	v_cvt_pk_bf16_f32 v135, v128, v129
	global_store_dwordx4 v[148:149], v[126:129], off
	global_store_dwordx2 v[150:151], v[134:135], off
	s_nop 0
	s_waitcnt lgkmcnt(0)
	v_mov_b32_e32 v134, v184
	v_mov_b32_e32 v135, v185
	v_mov_b32_e32 v136, v186
	v_mov_b32_e32 v137, v187
	v_pk_add_f32 v[122:123], v[122:123], v[134:135]
	v_pk_add_f32 v[124:125], v[124:125], v[136:137]
	v_cvt_pk_bf16_f32 v134, v122, v123
	v_cvt_pk_bf16_f32 v135, v124, v125
	global_store_dwordx4 v[148:149], v[122:125], off offset:64
	global_store_dwordx2 v[150:151], v[134:135], off offset:32
	s_nop 0
	s_waitcnt lgkmcnt(0)
	v_mov_b32_e32 v134, v188
	v_mov_b32_e32 v135, v189
	v_mov_b32_e32 v136, v190
	v_mov_b32_e32 v137, v191
	v_pk_add_f32 v[134:135], v[118:119], v[134:135]
	v_pk_add_f32 v[136:137], v[120:121], v[136:137]
	v_cvt_pk_bf16_f32 v118, v134, v135
	v_cvt_pk_bf16_f32 v119, v136, v137
	global_store_dwordx4 v[148:149], v[134:137], off offset:128
	global_store_dwordx2 v[150:151], v[118:119], off offset:64
	s_nop 0
	v_and_b32_e32 v119, 64, v139
	v_xor_b32_e32 v118, 16, v139
	v_add_u32_e32 v121, 64, v119
	v_cmp_lt_i32_e64 s[0:1], v118, v121
	s_nop 1
	v_cndmask_b32_e64 v118, v139, v118, s[0:1]
	v_lshlrev_b32_e32 v120, 2, v118
	v_pk_mul_f32 v[118:119], v[126:127], v[126:127]
	v_pk_mul_f32 v[126:127], v[128:129], v[128:129]
	v_add_f32_e32 v118, v118, v119
	v_add_f32_e32 v118, v118, v126
	v_add_f32_e32 v126, v118, v127
	v_pk_mul_f32 v[118:119], v[122:123], v[122:123]
	v_pk_mul_f32 v[122:123], v[124:125], v[124:125]
	v_add_f32_e32 v118, v118, v119
	v_add_f32_e32 v118, v118, v122
	v_add_f32_e32 v118, v118, v123
	v_add_f32_e32 v128, v126, v118
	v_pk_mul_f32 v[118:119], v[134:135], v[134:135]
	v_pk_mul_f32 v[122:123], v[136:137], v[136:137]
	v_add_f32_e32 v118, v118, v119
	v_add_f32_e32 v118, v118, v122
	v_add_f32_e32 v129, v118, v123
	v_add_f32_e32 v128, v128, v129
	s_waitcnt lgkmcnt(0)
	v_mov_b32_e32 v144, v192
	v_mov_b32_e32 v145, v193
	v_mov_b32_e32 v146, v194
	v_mov_b32_e32 v147, v195
	v_pk_add_f32 v[122:123], v[140:141], v[144:145]
	v_pk_add_f32 v[124:125], v[142:143], v[146:147]
	v_pk_mul_f32 v[118:119], v[122:123], v[122:123]
	v_pk_mul_f32 v[126:127], v[124:125], v[124:125]
	v_add_f32_e32 v118, v118, v119
	v_add_f32_e32 v118, v118, v126
	v_add_f32_e32 v118, v118, v127
	v_add_f32_e32 v118, v128, v118
	ds_bpermute_b32 v119, v120, v118
	v_xor_b32_e32 v126, 32, v139
	v_cmp_lt_i32_e64 s[0:1], v126, v121
	global_store_dwordx4 v[148:149], v[122:125], off offset:192
	s_waitcnt lgkmcnt(0)
	v_add_f32_e32 v118, v118, v119
	v_cndmask_b32_e64 v121, v139, v126, s[0:1]
	v_lshlrev_b32_e32 v121, 2, v121
	ds_bpermute_b32 v119, v121, v118
	v_cvt_pk_bf16_f32 v122, v122, v123
	v_cvt_pk_bf16_f32 v123, v124, v125
	global_store_dwordx2 v[150:151], v[122:123], off offset:96
	s_and_saveexec_b64 s[0:1], vcc
	s_cbranch_execz .LBB0_590
	s_waitcnt lgkmcnt(0)
	v_add_f32_e32 v122, v118, v119
	v_lshl_add_u64 v[118:119], v[114:115], 2, s[10:11]
	global_atomic_add_f32 v[118:119], v122, off
.LBB0_590:
	s_or_b64 exec, exec, s[0:1]
	v_or_b32_e32 v118, 16, v114
	s_waitcnt lgkmcnt(0)
	v_mov_b32_e32 v119, v115
	v_lshlrev_b64 v[122:123], 12, v[118:119]
	v_lshl_add_u64 v[122:123], v[130:131], 0, v[122:123]
	v_lshl_add_u64 v[126:127], v[116:117], 2, v[122:123]
	s_mov_b32 s98, 0x20000
	s_mov_b32 s99, 0
	v_lshl_add_u64 v[214:215], v[212:213], 0, s[98:99]
	global_load_dwordx4 v[180:183], v[214:215], off
	global_load_dwordx4 v[184:187], v[214:215], off offset:64
	global_load_dwordx4 v[188:191], v[214:215], off offset:128
	global_load_dwordx4 v[192:195], v[214:215], off offset:192
	v_lshlrev_b64 v[128:129], 11, v[118:119]
	v_lshl_add_u64 v[128:129], s[8:9], 0, v[128:129]
	v_lshl_add_u64 v[128:129], v[116:117], 1, v[128:129]
	s_waitcnt vmcnt(12) lgkmcnt(0)
	v_mov_b32_e32 v122, v196
	v_mov_b32_e32 v123, v197
	v_mov_b32_e32 v124, v198
	v_mov_b32_e32 v125, v199
	v_pk_add_f32 v[110:111], v[110:111], v[122:123]
	v_pk_add_f32 v[112:113], v[112:113], v[124:125]
	v_cvt_pk_bf16_f32 v122, v110, v111
	v_cvt_pk_bf16_f32 v123, v112, v113
	global_store_dwordx4 v[126:127], v[110:113], off
	global_store_dwordx2 v[128:129], v[122:123], off
	s_nop 0
	v_pk_mul_f32 v[110:111], v[110:111], v[110:111]
	v_pk_mul_f32 v[112:113], v[112:113], v[112:113]
	v_add_f32_e32 v110, v110, v111
	v_add_f32_e32 v110, v110, v112
	v_add_f32_e32 v110, v110, v113
	s_waitcnt lgkmcnt(0)
	v_mov_b32_e32 v122, v200
	v_mov_b32_e32 v123, v201
	v_mov_b32_e32 v124, v202
	v_mov_b32_e32 v125, v203
	v_pk_add_f32 v[106:107], v[106:107], v[122:123]
	v_pk_add_f32 v[108:109], v[108:109], v[124:125]
	v_cvt_pk_bf16_f32 v122, v106, v107
	v_cvt_pk_bf16_f32 v123, v108, v109
	global_store_dwordx4 v[126:127], v[106:109], off offset:64
	global_store_dwordx2 v[128:129], v[122:123], off offset:32
	s_nop 0
	v_pk_mul_f32 v[106:107], v[106:107], v[106:107]
	v_pk_mul_f32 v[108:109], v[108:109], v[108:109]
	v_add_f32_e32 v106, v106, v107
	v_add_f32_e32 v106, v106, v108
	v_add_f32_e32 v106, v106, v109
	v_add_f32_e32 v106, v110, v106
	s_waitcnt lgkmcnt(0)
	v_mov_b32_e32 v122, v204
	v_mov_b32_e32 v123, v205
	v_mov_b32_e32 v124, v206
	v_mov_b32_e32 v125, v207
	v_pk_add_f32 v[102:103], v[102:103], v[122:123]
	v_pk_add_f32 v[104:105], v[104:105], v[124:125]
	v_cvt_pk_bf16_f32 v122, v102, v103
	v_cvt_pk_bf16_f32 v123, v104, v105
	global_store_dwordx4 v[126:127], v[102:105], off offset:128
	global_store_dwordx2 v[128:129], v[122:123], off offset:64
	s_nop 0
	v_pk_mul_f32 v[102:103], v[102:103], v[102:103]
	v_pk_mul_f32 v[104:105], v[104:105], v[104:105]
	v_add_f32_e32 v102, v102, v103
	v_add_f32_e32 v102, v102, v104
	v_add_f32_e32 v107, v102, v105
	v_add_f32_e32 v106, v106, v107
	s_waitcnt lgkmcnt(0)
	v_mov_b32_e32 v122, v208
	v_mov_b32_e32 v123, v209
	v_mov_b32_e32 v124, v210
	v_mov_b32_e32 v125, v211
	v_pk_add_f32 v[102:103], v[98:99], v[122:123]
	v_pk_add_f32 v[104:105], v[100:101], v[124:125]
	v_pk_mul_f32 v[98:99], v[102:103], v[102:103]
	v_pk_mul_f32 v[100:101], v[104:105], v[104:105]
	v_add_f32_e32 v98, v98, v99
	v_add_f32_e32 v98, v98, v100
	v_add_f32_e32 v98, v98, v101
	v_add_f32_e32 v98, v106, v98
	ds_bpermute_b32 v99, v120, v98
	v_cvt_pk_bf16_f32 v100, v102, v103
	v_cvt_pk_bf16_f32 v101, v104, v105
	global_store_dwordx4 v[126:127], v[102:105], off offset:192
	global_store_dwordx2 v[128:129], v[100:101], off offset:96
	s_waitcnt lgkmcnt(0)
	v_add_f32_e32 v98, v98, v99
	ds_bpermute_b32 v99, v121, v98
	s_and_saveexec_b64 s[0:1], vcc
	s_cbranch_execz .LBB0_592
	s_waitcnt lgkmcnt(0)
	v_add_f32_e32 v100, v98, v99
	v_lshl_add_u64 v[98:99], v[118:119], 2, s[10:11]
	global_atomic_add_f32 v[98:99], v100, off
.LBB0_592:
	s_or_b64 exec, exec, s[0:1]
	v_or_b32_e32 v98, 32, v114
	s_waitcnt lgkmcnt(0)
	v_mov_b32_e32 v99, v115
	v_lshlrev_b64 v[100:101], 12, v[98:99]
	v_lshl_add_u64 v[100:101], v[130:131], 0, v[100:101]
	v_lshl_add_u64 v[104:105], v[116:117], 2, v[100:101]
	s_mov_b32 s98, 0x30000
	s_mov_b32 s99, 0
	v_lshl_add_u64 v[214:215], v[212:213], 0, s[98:99]
	global_load_dwordx4 v[196:199], v[214:215], off
	global_load_dwordx4 v[200:203], v[214:215], off offset:64
	global_load_dwordx4 v[204:207], v[214:215], off offset:128
	global_load_dwordx4 v[208:211], v[214:215], off offset:192
	v_lshlrev_b64 v[106:107], 11, v[98:99]
	v_lshl_add_u64 v[106:107], s[8:9], 0, v[106:107]
	v_lshl_add_u64 v[106:107], v[116:117], 1, v[106:107]
	s_waitcnt vmcnt(12) lgkmcnt(0)
	v_mov_b32_e32 v100, v180
	v_mov_b32_e32 v101, v181
	v_mov_b32_e32 v102, v182
	v_mov_b32_e32 v103, v183
	v_pk_add_f32 v[94:95], v[94:95], v[100:101]
	v_pk_add_f32 v[96:97], v[96:97], v[102:103]
	v_cvt_pk_bf16_f32 v100, v94, v95
	v_cvt_pk_bf16_f32 v101, v96, v97
	global_store_dwordx4 v[104:105], v[94:97], off
	global_store_dwordx2 v[106:107], v[100:101], off
	s_nop 0
	v_pk_mul_f32 v[94:95], v[94:95], v[94:95]
	v_pk_mul_f32 v[96:97], v[96:97], v[96:97]
	v_add_f32_e32 v94, v94, v95
	v_add_f32_e32 v94, v94, v96
	v_add_f32_e32 v94, v94, v97
	s_waitcnt lgkmcnt(0)
	v_mov_b32_e32 v100, v184
	v_mov_b32_e32 v101, v185
	v_mov_b32_e32 v102, v186
	v_mov_b32_e32 v103, v187
	v_pk_add_f32 v[90:91], v[90:91], v[100:101]
	v_pk_add_f32 v[92:93], v[92:93], v[102:103]
	v_cvt_pk_bf16_f32 v100, v90, v91
	v_cvt_pk_bf16_f32 v101, v92, v93
	global_store_dwordx4 v[104:105], v[90:93], off offset:64
	global_store_dwordx2 v[106:107], v[100:101], off offset:32
	s_nop 0
	v_pk_mul_f32 v[90:91], v[90:91], v[90:91]
	v_pk_mul_f32 v[92:93], v[92:93], v[92:93]
	v_add_f32_e32 v90, v90, v91
	v_add_f32_e32 v90, v90, v92
	v_add_f32_e32 v90, v90, v93
	v_add_f32_e32 v90, v94, v90
	s_waitcnt lgkmcnt(0)
	v_mov_b32_e32 v100, v188
	v_mov_b32_e32 v101, v189
	v_mov_b32_e32 v102, v190
	v_mov_b32_e32 v103, v191
	v_pk_add_f32 v[86:87], v[86:87], v[100:101]
	v_pk_add_f32 v[88:89], v[88:89], v[102:103]
	v_cvt_pk_bf16_f32 v100, v86, v87
	v_cvt_pk_bf16_f32 v101, v88, v89
	global_store_dwordx4 v[104:105], v[86:89], off offset:128
	global_store_dwordx2 v[106:107], v[100:101], off offset:64
	s_nop 0
	v_pk_mul_f32 v[86:87], v[86:87], v[86:87]
	v_pk_mul_f32 v[88:89], v[88:89], v[88:89]
	v_add_f32_e32 v86, v86, v87
	v_add_f32_e32 v86, v86, v88
	v_add_f32_e32 v91, v86, v89
	v_add_f32_e32 v90, v90, v91
	s_waitcnt lgkmcnt(0)
	v_mov_b32_e32 v100, v192
	v_mov_b32_e32 v101, v193
	v_mov_b32_e32 v102, v194
	v_mov_b32_e32 v103, v195
	v_pk_add_f32 v[86:87], v[82:83], v[100:101]
	v_pk_add_f32 v[88:89], v[84:85], v[102:103]
	v_pk_mul_f32 v[82:83], v[86:87], v[86:87]
	v_pk_mul_f32 v[84:85], v[88:89], v[88:89]
	v_add_f32_e32 v82, v82, v83
	v_add_f32_e32 v82, v82, v84
	v_add_f32_e32 v82, v82, v85
	v_add_f32_e32 v82, v90, v82
	ds_bpermute_b32 v83, v120, v82
	v_cvt_pk_bf16_f32 v84, v86, v87
	v_cvt_pk_bf16_f32 v85, v88, v89
	global_store_dwordx4 v[104:105], v[86:89], off offset:192
	global_store_dwordx2 v[106:107], v[84:85], off offset:96
	s_waitcnt lgkmcnt(0)
	v_add_f32_e32 v82, v82, v83
	ds_bpermute_b32 v83, v121, v82
	s_and_saveexec_b64 s[0:1], vcc
	s_cbranch_execz .LBB0_594
	s_waitcnt lgkmcnt(0)
	v_add_f32_e32 v84, v82, v83
	v_lshl_add_u64 v[82:83], v[98:99], 2, s[10:11]
	global_atomic_add_f32 v[82:83], v84, off
.LBB0_594:
	s_or_b64 exec, exec, s[0:1]
	v_or_b32_e32 v82, 48, v114
	s_waitcnt lgkmcnt(0)
	v_mov_b32_e32 v83, v115
	v_lshlrev_b64 v[84:85], 12, v[82:83]
	v_lshl_add_u64 v[84:85], v[130:131], 0, v[84:85]
	v_lshl_add_u64 v[88:89], v[116:117], 2, v[84:85]
	s_mov_b32 s98, 0x40000
	s_mov_b32 s99, 0
	v_lshl_add_u64 v[214:215], v[212:213], 0, s[98:99]
	global_load_dwordx4 v[180:183], v[214:215], off
	global_load_dwordx4 v[184:187], v[214:215], off offset:64
	global_load_dwordx4 v[188:191], v[214:215], off offset:128
	global_load_dwordx4 v[192:195], v[214:215], off offset:192
	v_lshlrev_b64 v[90:91], 11, v[82:83]
	v_lshl_add_u64 v[90:91], s[8:9], 0, v[90:91]
	v_lshl_add_u64 v[90:91], v[116:117], 1, v[90:91]
	s_waitcnt vmcnt(12) lgkmcnt(0)
	v_mov_b32_e32 v84, v196
	v_mov_b32_e32 v85, v197
	v_mov_b32_e32 v86, v198
	v_mov_b32_e32 v87, v199
	v_pk_add_f32 v[78:79], v[78:79], v[84:85]
	v_pk_add_f32 v[80:81], v[80:81], v[86:87]
	v_cvt_pk_bf16_f32 v84, v78, v79
	v_cvt_pk_bf16_f32 v85, v80, v81
	global_store_dwordx4 v[88:89], v[78:81], off
	global_store_dwordx2 v[90:91], v[84:85], off
	s_nop 0
	v_pk_mul_f32 v[78:79], v[78:79], v[78:79]
	v_pk_mul_f32 v[80:81], v[80:81], v[80:81]
	v_add_f32_e32 v78, v78, v79
	v_add_f32_e32 v78, v78, v80
	v_add_f32_e32 v78, v78, v81
	s_waitcnt lgkmcnt(0)
	v_mov_b32_e32 v84, v200
	v_mov_b32_e32 v85, v201
	v_mov_b32_e32 v86, v202
	v_mov_b32_e32 v87, v203
	v_pk_add_f32 v[74:75], v[74:75], v[84:85]
	v_pk_add_f32 v[76:77], v[76:77], v[86:87]
	v_cvt_pk_bf16_f32 v84, v74, v75
	v_cvt_pk_bf16_f32 v85, v76, v77
	global_store_dwordx4 v[88:89], v[74:77], off offset:64
	global_store_dwordx2 v[90:91], v[84:85], off offset:32
	s_nop 0
	v_pk_mul_f32 v[74:75], v[74:75], v[74:75]
	v_pk_mul_f32 v[76:77], v[76:77], v[76:77]
	v_add_f32_e32 v74, v74, v75
	v_add_f32_e32 v74, v74, v76
	v_add_f32_e32 v74, v74, v77
	v_add_f32_e32 v74, v78, v74
	s_waitcnt lgkmcnt(0)
	v_mov_b32_e32 v84, v204
	v_mov_b32_e32 v85, v205
	v_mov_b32_e32 v86, v206
	v_mov_b32_e32 v87, v207
	v_pk_add_f32 v[70:71], v[70:71], v[84:85]
	v_pk_add_f32 v[72:73], v[72:73], v[86:87]
	v_cvt_pk_bf16_f32 v84, v70, v71
	v_cvt_pk_bf16_f32 v85, v72, v73
	global_store_dwordx4 v[88:89], v[70:73], off offset:128
	global_store_dwordx2 v[90:91], v[84:85], off offset:64
	s_nop 0
	v_pk_mul_f32 v[70:71], v[70:71], v[70:71]
	v_pk_mul_f32 v[72:73], v[72:73], v[72:73]
	v_add_f32_e32 v70, v70, v71
	v_add_f32_e32 v70, v70, v72
	v_add_f32_e32 v75, v70, v73
	v_add_f32_e32 v74, v74, v75
	s_waitcnt lgkmcnt(0)
	v_mov_b32_e32 v84, v208
	v_mov_b32_e32 v85, v209
	v_mov_b32_e32 v86, v210
	v_mov_b32_e32 v87, v211
	v_pk_add_f32 v[70:71], v[66:67], v[84:85]
	v_pk_add_f32 v[72:73], v[68:69], v[86:87]
	v_pk_mul_f32 v[66:67], v[70:71], v[70:71]
	v_pk_mul_f32 v[68:69], v[72:73], v[72:73]
	v_add_f32_e32 v66, v66, v67
	v_add_f32_e32 v66, v66, v68
	v_add_f32_e32 v66, v66, v69
	v_add_f32_e32 v66, v74, v66
	ds_bpermute_b32 v67, v120, v66
	v_cvt_pk_bf16_f32 v68, v70, v71
	v_cvt_pk_bf16_f32 v69, v72, v73
	global_store_dwordx4 v[88:89], v[70:73], off offset:192
	global_store_dwordx2 v[90:91], v[68:69], off offset:96
	s_waitcnt lgkmcnt(0)
	v_add_f32_e32 v66, v66, v67
	ds_bpermute_b32 v67, v121, v66
	s_and_saveexec_b64 s[0:1], vcc
	s_cbranch_execz .LBB0_596
	s_waitcnt lgkmcnt(0)
	v_add_f32_e32 v68, v66, v67
	v_lshl_add_u64 v[66:67], v[82:83], 2, s[10:11]
	global_atomic_add_f32 v[66:67], v68, off
.LBB0_596:
	s_or_b64 exec, exec, s[0:1]
	v_or_b32_e32 v66, 64, v114
	s_waitcnt lgkmcnt(0)
	v_mov_b32_e32 v67, v115
	v_lshlrev_b64 v[68:69], 12, v[66:67]
	v_lshl_add_u64 v[68:69], v[130:131], 0, v[68:69]
	v_lshl_add_u64 v[72:73], v[116:117], 2, v[68:69]
	s_mov_b32 s98, 0x50000
	s_mov_b32 s99, 0
	v_lshl_add_u64 v[214:215], v[212:213], 0, s[98:99]
	global_load_dwordx4 v[196:199], v[214:215], off
	global_load_dwordx4 v[200:203], v[214:215], off offset:64
	global_load_dwordx4 v[204:207], v[214:215], off offset:128
	global_load_dwordx4 v[208:211], v[214:215], off offset:192
	v_lshlrev_b64 v[74:75], 11, v[66:67]
	v_lshl_add_u64 v[74:75], s[8:9], 0, v[74:75]
	v_lshl_add_u64 v[74:75], v[116:117], 1, v[74:75]
	s_waitcnt vmcnt(12) lgkmcnt(0)
	v_mov_b32_e32 v68, v180
	v_mov_b32_e32 v69, v181
	v_mov_b32_e32 v70, v182
	v_mov_b32_e32 v71, v183
	v_pk_add_f32 v[62:63], v[62:63], v[68:69]
	v_pk_add_f32 v[64:65], v[64:65], v[70:71]
	v_cvt_pk_bf16_f32 v68, v62, v63
	v_cvt_pk_bf16_f32 v69, v64, v65
	global_store_dwordx4 v[72:73], v[62:65], off
	global_store_dwordx2 v[74:75], v[68:69], off
	s_nop 0
	v_pk_mul_f32 v[62:63], v[62:63], v[62:63]
	v_pk_mul_f32 v[64:65], v[64:65], v[64:65]
	v_add_f32_e32 v62, v62, v63
	v_add_f32_e32 v62, v62, v64
	v_add_f32_e32 v62, v62, v65
	s_waitcnt lgkmcnt(0)
	v_mov_b32_e32 v68, v184
	v_mov_b32_e32 v69, v185
	v_mov_b32_e32 v70, v186
	v_mov_b32_e32 v71, v187
	v_pk_add_f32 v[58:59], v[58:59], v[68:69]
	v_pk_add_f32 v[60:61], v[60:61], v[70:71]
	v_cvt_pk_bf16_f32 v68, v58, v59
	v_cvt_pk_bf16_f32 v69, v60, v61
	global_store_dwordx4 v[72:73], v[58:61], off offset:64
	global_store_dwordx2 v[74:75], v[68:69], off offset:32
	s_nop 0
	v_pk_mul_f32 v[58:59], v[58:59], v[58:59]
	v_pk_mul_f32 v[60:61], v[60:61], v[60:61]
	v_add_f32_e32 v58, v58, v59
	v_add_f32_e32 v58, v58, v60
	v_add_f32_e32 v58, v58, v61
	v_add_f32_e32 v58, v62, v58
	s_waitcnt lgkmcnt(0)
	v_mov_b32_e32 v68, v188
	v_mov_b32_e32 v69, v189
	v_mov_b32_e32 v70, v190
	v_mov_b32_e32 v71, v191
	v_pk_add_f32 v[54:55], v[54:55], v[68:69]
	v_pk_add_f32 v[56:57], v[56:57], v[70:71]
	v_cvt_pk_bf16_f32 v68, v54, v55
	v_cvt_pk_bf16_f32 v69, v56, v57
	global_store_dwordx4 v[72:73], v[54:57], off offset:128
	global_store_dwordx2 v[74:75], v[68:69], off offset:64
	s_nop 0
	v_pk_mul_f32 v[54:55], v[54:55], v[54:55]
	v_pk_mul_f32 v[56:57], v[56:57], v[56:57]
	v_add_f32_e32 v54, v54, v55
	v_add_f32_e32 v54, v54, v56
	v_add_f32_e32 v59, v54, v57
	v_add_f32_e32 v58, v58, v59
	s_waitcnt lgkmcnt(0)
	v_mov_b32_e32 v68, v192
	v_mov_b32_e32 v69, v193
	v_mov_b32_e32 v70, v194
	v_mov_b32_e32 v71, v195
	v_pk_add_f32 v[54:55], v[50:51], v[68:69]
	v_pk_add_f32 v[56:57], v[52:53], v[70:71]
	v_pk_mul_f32 v[50:51], v[54:55], v[54:55]
	v_pk_mul_f32 v[52:53], v[56:57], v[56:57]
	v_add_f32_e32 v50, v50, v51
	v_add_f32_e32 v50, v50, v52
	v_add_f32_e32 v50, v50, v53
	v_add_f32_e32 v50, v58, v50
	ds_bpermute_b32 v51, v120, v50
	v_cvt_pk_bf16_f32 v52, v54, v55
	v_cvt_pk_bf16_f32 v53, v56, v57
	global_store_dwordx4 v[72:73], v[54:57], off offset:192
	global_store_dwordx2 v[74:75], v[52:53], off offset:96
	s_waitcnt lgkmcnt(0)
	v_add_f32_e32 v50, v50, v51
	ds_bpermute_b32 v51, v121, v50
	s_and_saveexec_b64 s[0:1], vcc
	s_cbranch_execz .LBB0_598
	s_waitcnt lgkmcnt(0)
	v_add_f32_e32 v52, v50, v51
	v_lshl_add_u64 v[50:51], v[66:67], 2, s[10:11]
	global_atomic_add_f32 v[50:51], v52, off
.LBB0_598:
	s_or_b64 exec, exec, s[0:1]
	v_or_b32_e32 v50, 0x50, v114
	s_waitcnt lgkmcnt(0)
	v_mov_b32_e32 v51, v115
	v_lshlrev_b64 v[52:53], 12, v[50:51]
	v_lshl_add_u64 v[52:53], v[130:131], 0, v[52:53]
	v_lshl_add_u64 v[56:57], v[116:117], 2, v[52:53]
	s_mov_b32 s98, 0x60000
	s_mov_b32 s99, 0
	v_lshl_add_u64 v[214:215], v[212:213], 0, s[98:99]
	global_load_dwordx4 v[180:183], v[214:215], off
	global_load_dwordx4 v[184:187], v[214:215], off offset:64
	global_load_dwordx4 v[188:191], v[214:215], off offset:128
	global_load_dwordx4 v[192:195], v[214:215], off offset:192
	v_lshlrev_b64 v[58:59], 11, v[50:51]
	v_lshl_add_u64 v[58:59], s[8:9], 0, v[58:59]
	v_lshl_add_u64 v[58:59], v[116:117], 1, v[58:59]
	s_waitcnt vmcnt(12) lgkmcnt(0)
	v_mov_b32_e32 v52, v196
	v_mov_b32_e32 v53, v197
	v_mov_b32_e32 v54, v198
	v_mov_b32_e32 v55, v199
	v_pk_add_f32 v[46:47], v[46:47], v[52:53]
	v_pk_add_f32 v[48:49], v[48:49], v[54:55]
	v_cvt_pk_bf16_f32 v52, v46, v47
	v_cvt_pk_bf16_f32 v53, v48, v49
	global_store_dwordx4 v[56:57], v[46:49], off
	global_store_dwordx2 v[58:59], v[52:53], off
	s_nop 0
	v_pk_mul_f32 v[46:47], v[46:47], v[46:47]
	v_pk_mul_f32 v[48:49], v[48:49], v[48:49]
	v_add_f32_e32 v46, v46, v47
	v_add_f32_e32 v46, v46, v48
	v_add_f32_e32 v46, v46, v49
	s_waitcnt lgkmcnt(0)
	v_mov_b32_e32 v52, v200
	v_mov_b32_e32 v53, v201
	v_mov_b32_e32 v54, v202
	v_mov_b32_e32 v55, v203
	v_pk_add_f32 v[42:43], v[42:43], v[52:53]
	v_pk_add_f32 v[44:45], v[44:45], v[54:55]
	v_cvt_pk_bf16_f32 v52, v42, v43
	v_cvt_pk_bf16_f32 v53, v44, v45
	global_store_dwordx4 v[56:57], v[42:45], off offset:64
	global_store_dwordx2 v[58:59], v[52:53], off offset:32
	s_nop 0
	v_pk_mul_f32 v[42:43], v[42:43], v[42:43]
	v_pk_mul_f32 v[44:45], v[44:45], v[44:45]
	v_add_f32_e32 v42, v42, v43
	v_add_f32_e32 v42, v42, v44
	v_add_f32_e32 v42, v42, v45
	v_add_f32_e32 v42, v46, v42
	s_waitcnt lgkmcnt(0)
	v_mov_b32_e32 v52, v204
	v_mov_b32_e32 v53, v205
	v_mov_b32_e32 v54, v206
	v_mov_b32_e32 v55, v207
	v_pk_add_f32 v[38:39], v[38:39], v[52:53]
	v_pk_add_f32 v[40:41], v[40:41], v[54:55]
	v_cvt_pk_bf16_f32 v52, v38, v39
	v_cvt_pk_bf16_f32 v53, v40, v41
	global_store_dwordx4 v[56:57], v[38:41], off offset:128
	global_store_dwordx2 v[58:59], v[52:53], off offset:64
	s_nop 0
	v_pk_mul_f32 v[38:39], v[38:39], v[38:39]
	v_pk_mul_f32 v[40:41], v[40:41], v[40:41]
	v_add_f32_e32 v38, v38, v39
	v_add_f32_e32 v38, v38, v40
	v_add_f32_e32 v43, v38, v41
	v_add_f32_e32 v42, v42, v43
	s_waitcnt lgkmcnt(0)
	v_mov_b32_e32 v52, v208
	v_mov_b32_e32 v53, v209
	v_mov_b32_e32 v54, v210
	v_mov_b32_e32 v55, v211
	v_pk_add_f32 v[38:39], v[34:35], v[52:53]
	v_pk_add_f32 v[40:41], v[36:37], v[54:55]
	v_pk_mul_f32 v[34:35], v[38:39], v[38:39]
	v_pk_mul_f32 v[36:37], v[40:41], v[40:41]
	v_add_f32_e32 v34, v34, v35
	v_add_f32_e32 v34, v34, v36
	v_add_f32_e32 v34, v34, v37
	v_add_f32_e32 v34, v42, v34
	ds_bpermute_b32 v35, v120, v34
	v_cvt_pk_bf16_f32 v36, v38, v39
	v_cvt_pk_bf16_f32 v37, v40, v41
	global_store_dwordx4 v[56:57], v[38:41], off offset:192
	global_store_dwordx2 v[58:59], v[36:37], off offset:96
	s_waitcnt lgkmcnt(0)
	v_add_f32_e32 v34, v34, v35
	ds_bpermute_b32 v35, v121, v34
	s_and_saveexec_b64 s[0:1], vcc
	s_cbranch_execz .LBB0_600
	s_waitcnt lgkmcnt(0)
	v_add_f32_e32 v36, v34, v35
	v_lshl_add_u64 v[34:35], v[50:51], 2, s[10:11]
	global_atomic_add_f32 v[34:35], v36, off
.LBB0_600:
	s_or_b64 exec, exec, s[0:1]
	v_or_b32_e32 v34, 0x60, v114
	s_waitcnt lgkmcnt(0)
	v_mov_b32_e32 v35, v115
	v_lshlrev_b64 v[36:37], 12, v[34:35]
	v_lshl_add_u64 v[36:37], v[130:131], 0, v[36:37]
	v_lshl_add_u64 v[40:41], v[116:117], 2, v[36:37]
	s_mov_b32 s98, 0x70000
	s_mov_b32 s99, 0
	v_lshl_add_u64 v[214:215], v[212:213], 0, s[98:99]
	global_load_dwordx4 v[196:199], v[214:215], off
	global_load_dwordx4 v[200:203], v[214:215], off offset:64
	global_load_dwordx4 v[204:207], v[214:215], off offset:128
	global_load_dwordx4 v[208:211], v[214:215], off offset:192
	v_lshlrev_b64 v[42:43], 11, v[34:35]
	v_lshl_add_u64 v[42:43], s[8:9], 0, v[42:43]
	v_lshl_add_u64 v[42:43], v[116:117], 1, v[42:43]
	s_waitcnt vmcnt(12) lgkmcnt(0)
	v_mov_b32_e32 v36, v180
	v_mov_b32_e32 v37, v181
	v_mov_b32_e32 v38, v182
	v_mov_b32_e32 v39, v183
	v_pk_add_f32 v[30:31], v[30:31], v[36:37]
	v_pk_add_f32 v[32:33], v[32:33], v[38:39]
	v_cvt_pk_bf16_f32 v36, v30, v31
	v_cvt_pk_bf16_f32 v37, v32, v33
	global_store_dwordx4 v[40:41], v[30:33], off
	global_store_dwordx2 v[42:43], v[36:37], off
	s_nop 0
	v_pk_mul_f32 v[30:31], v[30:31], v[30:31]
	v_pk_mul_f32 v[32:33], v[32:33], v[32:33]
	v_add_f32_e32 v30, v30, v31
	v_add_f32_e32 v30, v30, v32
	v_add_f32_e32 v30, v30, v33
	s_waitcnt lgkmcnt(0)
	v_mov_b32_e32 v36, v184
	v_mov_b32_e32 v37, v185
	v_mov_b32_e32 v38, v186
	v_mov_b32_e32 v39, v187
	v_pk_add_f32 v[26:27], v[26:27], v[36:37]
	v_pk_add_f32 v[28:29], v[28:29], v[38:39]
	v_cvt_pk_bf16_f32 v36, v26, v27
	v_cvt_pk_bf16_f32 v37, v28, v29
	global_store_dwordx4 v[40:41], v[26:29], off offset:64
	global_store_dwordx2 v[42:43], v[36:37], off offset:32
	s_nop 0
	v_pk_mul_f32 v[26:27], v[26:27], v[26:27]
	v_pk_mul_f32 v[28:29], v[28:29], v[28:29]
	v_add_f32_e32 v26, v26, v27
	v_add_f32_e32 v26, v26, v28
	v_add_f32_e32 v26, v26, v29
	v_add_f32_e32 v26, v30, v26
	s_waitcnt lgkmcnt(0)
	v_mov_b32_e32 v36, v188
	v_mov_b32_e32 v37, v189
	v_mov_b32_e32 v38, v190
	v_mov_b32_e32 v39, v191
	v_pk_add_f32 v[22:23], v[22:23], v[36:37]
	v_pk_add_f32 v[24:25], v[24:25], v[38:39]
	v_cvt_pk_bf16_f32 v36, v22, v23
	v_cvt_pk_bf16_f32 v37, v24, v25
	global_store_dwordx4 v[40:41], v[22:25], off offset:128
	global_store_dwordx2 v[42:43], v[36:37], off offset:64
	s_nop 0
	v_pk_mul_f32 v[22:23], v[22:23], v[22:23]
	v_pk_mul_f32 v[24:25], v[24:25], v[24:25]
	v_add_f32_e32 v22, v22, v23
	v_add_f32_e32 v22, v22, v24
	v_add_f32_e32 v27, v22, v25
	v_add_f32_e32 v26, v26, v27
	s_waitcnt lgkmcnt(0)
	v_mov_b32_e32 v36, v192
	v_mov_b32_e32 v37, v193
	v_mov_b32_e32 v38, v194
	v_mov_b32_e32 v39, v195
	v_pk_add_f32 v[22:23], v[18:19], v[36:37]
	v_pk_add_f32 v[24:25], v[20:21], v[38:39]
	v_pk_mul_f32 v[18:19], v[22:23], v[22:23]
	v_pk_mul_f32 v[20:21], v[24:25], v[24:25]
	v_add_f32_e32 v18, v18, v19
	v_add_f32_e32 v18, v18, v20
	v_add_f32_e32 v18, v18, v21
	v_add_f32_e32 v18, v26, v18
	ds_bpermute_b32 v19, v120, v18
	v_cvt_pk_bf16_f32 v20, v22, v23
	v_cvt_pk_bf16_f32 v21, v24, v25
	global_store_dwordx4 v[40:41], v[22:25], off offset:192
	global_store_dwordx2 v[42:43], v[20:21], off offset:96
	s_waitcnt lgkmcnt(0)
	v_add_f32_e32 v18, v18, v19
	ds_bpermute_b32 v19, v121, v18
	s_and_saveexec_b64 s[0:1], vcc
	s_cbranch_execz .LBB0_602
	s_waitcnt lgkmcnt(0)
	v_add_f32_e32 v20, v18, v19
	v_lshl_add_u64 v[18:19], v[34:35], 2, s[10:11]
	global_atomic_add_f32 v[18:19], v20, off
.LBB0_602:
	s_or_b64 exec, exec, s[0:1]
	v_or_b32_e32 v114, 0x70, v114
	s_waitcnt lgkmcnt(0)
	v_lshlrev_b64 v[18:19], 12, v[114:115]
	v_lshl_add_u64 v[18:19], v[130:131], 0, v[18:19]
	v_lshl_add_u64 v[22:23], v[116:117], 2, v[18:19]
	s_nop 0
	v_lshlrev_b64 v[24:25], 11, v[114:115]
	v_lshl_add_u64 v[24:25], s[8:9], 0, v[24:25]
	v_lshl_add_u64 v[24:25], v[116:117], 1, v[24:25]
	s_waitcnt vmcnt(8) lgkmcnt(0)
	v_mov_b32_e32 v18, v196
	v_mov_b32_e32 v19, v197
	v_mov_b32_e32 v20, v198
	v_mov_b32_e32 v21, v199
	v_pk_add_f32 v[14:15], v[14:15], v[18:19]
	v_pk_add_f32 v[16:17], v[16:17], v[20:21]
	v_cvt_pk_bf16_f32 v18, v14, v15
	v_cvt_pk_bf16_f32 v19, v16, v17
	global_store_dwordx4 v[22:23], v[14:17], off
	global_store_dwordx2 v[24:25], v[18:19], off
	s_nop 0
	v_pk_mul_f32 v[14:15], v[14:15], v[14:15]
	v_pk_mul_f32 v[16:17], v[16:17], v[16:17]
	v_add_f32_e32 v14, v14, v15
	v_add_f32_e32 v14, v14, v16
	v_add_f32_e32 v14, v14, v17
	s_waitcnt lgkmcnt(0)
	v_mov_b32_e32 v18, v200
	v_mov_b32_e32 v19, v201
	v_mov_b32_e32 v20, v202
	v_mov_b32_e32 v21, v203
	v_pk_add_f32 v[10:11], v[10:11], v[18:19]
	v_pk_add_f32 v[12:13], v[12:13], v[20:21]
	v_cvt_pk_bf16_f32 v18, v10, v11
	v_cvt_pk_bf16_f32 v19, v12, v13
	global_store_dwordx4 v[22:23], v[10:13], off offset:64
	global_store_dwordx2 v[24:25], v[18:19], off offset:32
	s_nop 0
	v_pk_mul_f32 v[10:11], v[10:11], v[10:11]
	v_pk_mul_f32 v[12:13], v[12:13], v[12:13]
	v_add_f32_e32 v10, v10, v11
	v_add_f32_e32 v10, v10, v12
	v_add_f32_e32 v10, v10, v13
	v_add_f32_e32 v10, v14, v10
	s_waitcnt lgkmcnt(0)
	v_mov_b32_e32 v18, v204
	v_mov_b32_e32 v19, v205
	v_mov_b32_e32 v20, v206
	v_mov_b32_e32 v21, v207
	v_pk_add_f32 v[6:7], v[6:7], v[18:19]
	v_pk_add_f32 v[8:9], v[8:9], v[20:21]
	v_cvt_pk_bf16_f32 v18, v6, v7
	v_cvt_pk_bf16_f32 v19, v8, v9
	global_store_dwordx4 v[22:23], v[6:9], off offset:128
	global_store_dwordx2 v[24:25], v[18:19], off offset:64
	s_nop 0
	v_pk_mul_f32 v[6:7], v[6:7], v[6:7]
	v_pk_mul_f32 v[8:9], v[8:9], v[8:9]
	v_add_f32_e32 v6, v6, v7
	v_add_f32_e32 v6, v6, v8
	v_add_f32_e32 v11, v6, v9
	v_add_f32_e32 v10, v10, v11
	s_waitcnt lgkmcnt(0)
	v_mov_b32_e32 v18, v208
	v_mov_b32_e32 v19, v209
	v_mov_b32_e32 v20, v210
	v_mov_b32_e32 v21, v211
	v_pk_add_f32 v[6:7], v[2:3], v[18:19]
	v_pk_add_f32 v[8:9], v[4:5], v[20:21]
	v_pk_mul_f32 v[2:3], v[6:7], v[6:7]
	v_pk_mul_f32 v[4:5], v[8:9], v[8:9]
	v_add_f32_e32 v2, v2, v3
	v_add_f32_e32 v2, v2, v4
	v_add_f32_e32 v2, v2, v5
	v_add_f32_e32 v2, v10, v2
	ds_bpermute_b32 v3, v120, v2
	v_cvt_pk_bf16_f32 v4, v6, v7
	v_cvt_pk_bf16_f32 v5, v8, v9
	global_store_dwordx4 v[22:23], v[6:9], off offset:192
	global_store_dwordx2 v[24:25], v[4:5], off offset:96
	s_waitcnt lgkmcnt(0)
	v_add_f32_e32 v2, v2, v3
	ds_bpermute_b32 v3, v121, v2
	s_and_saveexec_b64 s[0:1], vcc
	s_cbranch_execz .LBB0_585
	s_waitcnt lgkmcnt(0)
	v_add_f32_e32 v4, v2, v3
	v_lshl_add_u64 v[2:3], v[114:115], 2, s[10:11]
	global_atomic_add_f32 v[2:3], v4, off
	s_branch .LBB0_585

.LBB0_621:
	s_mul_i32 s57, s9, 0x6000
	s_add_i32 s58, s57, 0xffffa000
	s_cmp_lg_u32 s9, 0
	s_cselect_b32 s58, s58, 0xc000
	v_add_u32_e32 v143, s58, v138
	v_lshl_add_u64 v[144:145], v[132:133], 0, s[6:7]
	v_readfirstlane_b32 s58, v143
	v_add_u32_e32 v148, 0x1000, v143
	v_lshl_add_u64 v[146:147], v[144:145], 0, s[44:45]
	s_mov_b32 m0, s58
	v_readfirstlane_b32 s58, v148
	v_add_u32_e32 v148, 0x2000, v143
	s_waitcnt vmcnt(6)
	s_barrier
	global_load_lds_dwordx4 v[146:147], off
	v_lshl_add_u64 v[146:147], v[144:145], 0, s[46:47]
	s_mov_b32 m0, s58
	v_readfirstlane_b32 s58, v148
	global_load_lds_dwordx4 v[146:147], off
	v_lshl_add_u64 v[146:147], v[144:145], 0, s[48:49]
	s_mov_b32 m0, s58
	v_lshl_add_u64 v[144:145], v[144:145], 0, s[50:51]
	global_load_lds_dwordx4 v[146:147], off
	v_add_u32_e32 v146, 0x3000, v143
	v_add_u32_e32 v148, 0x4000, v143
	v_readfirstlane_b32 s58, v146
	s_mov_b32 m0, s58
	v_readfirstlane_b32 s58, v148
	global_load_lds_dwordx4 v[144:145], off
	v_lshl_add_u64 v[144:145], v[130:131], 0, s[6:7]
	v_add_u32_e32 v143, 0x5000, v143
	v_lshl_add_u64 v[146:147], v[144:145], 0, s[52:53]
	s_mov_b32 m0, s58
	v_readfirstlane_b32 s58, v143
	global_load_lds_dwordx4 v[146:147], off
	v_lshl_add_u64 v[144:145], v[144:145], 0, s[54:55]
	s_mov_b32 m0, s58
	s_add_i32 s57, s57, 0
	global_load_lds_dwordx4 v[144:145], off
	v_add3_u32 v143, s57, v140, v142
	ds_read_b128 v[144:147], v143 offset:16384
	ds_read_b128 v[148:151], v143 offset:17408
	ds_read_b128 v[156:159], v143 offset:18432
	ds_read_b128 v[160:163], v143 offset:19456
	v_add3_u32 v143, s57, v141, v142
	ds_read_b128 v[164:167], v143
	ds_read_b128 v[168:171], v143 offset:1024
	ds_read_b128 v[172:175], v143 offset:2048
	ds_read_b128 v[176:179], v143 offset:3072
	s_setprio 1
	s_waitcnt lgkmcnt(0)
	v_mfma_f32_16x16x32_bf16 v[126:129], v[144:147], v[164:167], v[126:129]
	v_mfma_f32_16x16x32_bf16 v[122:125], v[148:151], v[164:167], v[122:125]
	v_mfma_f32_16x16x32_bf16 v[118:121], v[156:159], v[164:167], v[118:121]
	v_mfma_f32_16x16x32_bf16 v[114:117], v[160:163], v[164:167], v[114:117]
	v_mfma_f32_16x16x32_bf16 v[110:113], v[144:147], v[168:171], v[110:113]
	v_mfma_f32_16x16x32_bf16 v[106:109], v[148:151], v[168:171], v[106:109]
	v_mfma_f32_16x16x32_bf16 v[102:105], v[156:159], v[168:171], v[102:105]
	v_mfma_f32_16x16x32_bf16 v[98:101], v[160:163], v[168:171], v[98:101]
	v_mfma_f32_16x16x32_bf16 v[94:97], v[144:147], v[172:175], v[94:97]
	v_mfma_f32_16x16x32_bf16 v[90:93], v[148:151], v[172:175], v[90:93]
	v_mfma_f32_16x16x32_bf16 v[86:89], v[156:159], v[172:175], v[86:89]
	v_mfma_f32_16x16x32_bf16 v[82:85], v[160:163], v[172:175], v[82:85]
	v_mfma_f32_16x16x32_bf16 v[78:81], v[144:147], v[176:179], v[78:81]
	v_mfma_f32_16x16x32_bf16 v[74:77], v[148:151], v[176:179], v[74:77]
	v_mfma_f32_16x16x32_bf16 v[70:73], v[156:159], v[176:179], v[70:73]
	v_mfma_f32_16x16x32_bf16 v[66:69], v[160:163], v[176:179], v[66:69]
	s_setprio 0
	ds_read_b128 v[164:167], v143 offset:4096
	ds_read_b128 v[168:171], v143 offset:5120
	ds_read_b128 v[172:175], v143 offset:6144
	ds_read_b128 v[176:179], v143 offset:7168
	s_setprio 1
	s_waitcnt lgkmcnt(0)
	v_mfma_f32_16x16x32_bf16 v[62:65], v[144:147], v[164:167], v[62:65]
	v_mfma_f32_16x16x32_bf16 v[58:61], v[148:151], v[164:167], v[58:61]
	v_mfma_f32_16x16x32_bf16 v[54:57], v[156:159], v[164:167], v[54:57]
	v_mfma_f32_16x16x32_bf16 v[50:53], v[160:163], v[164:167], v[50:53]
	v_mfma_f32_16x16x32_bf16 v[46:49], v[144:147], v[168:171], v[46:49]
	v_mfma_f32_16x16x32_bf16 v[42:45], v[148:151], v[168:171], v[42:45]
	v_mfma_f32_16x16x32_bf16 v[38:41], v[156:159], v[168:171], v[38:41]
	v_mfma_f32_16x16x32_bf16 v[34:37], v[160:163], v[168:171], v[34:37]
	v_mfma_f32_16x16x32_bf16 v[30:33], v[144:147], v[172:175], v[30:33]
	v_mfma_f32_16x16x32_bf16 v[26:29], v[148:151], v[172:175], v[26:29]
	v_mfma_f32_16x16x32_bf16 v[22:25], v[156:159], v[172:175], v[22:25]
	v_mfma_f32_16x16x32_bf16 v[18:21], v[160:163], v[172:175], v[18:21]
	v_mfma_f32_16x16x32_bf16 v[14:17], v[144:147], v[176:179], v[14:17]
	v_mfma_f32_16x16x32_bf16 v[10:13], v[148:151], v[176:179], v[10:13]
	v_mfma_f32_16x16x32_bf16 v[6:9], v[156:159], v[176:179], v[6:9]
	v_mfma_f32_16x16x32_bf16 v[2:5], v[160:163], v[176:179], v[2:5]
	s_setprio 0
	s_add_i32 s57, s9, 1
	s_cmp_lg_u32 s9, 2
	s_cselect_b32 s9, s57, 0
	s_add_u32 s6, s6, 64
	s_addc_u32 s7, s7, 0
	s_cmpk_eq_i32 s6, 0x780
	s_cbranch_scc0 .LBB0_621
	v_add3_u32 v138, 0, v140, v142
	v_add3_u32 v155, 0, v141, v142
	s_waitcnt vmcnt(6)
	s_barrier
	ds_read_b128 v[130:133], v138 offset:16384
	ds_read_b128 v[144:147], v138 offset:17408
	ds_read_b128 v[148:151], v138 offset:18432
	ds_read_b128 v[156:159], v138 offset:19456
	ds_read_b128 v[140:143], v155
	ds_read_b128 v[160:163], v155 offset:1024
	ds_read_b128 v[164:167], v155 offset:2048
	ds_read_b128 v[168:171], v155 offset:3072
	s_setprio 1
	s_waitcnt lgkmcnt(0)
	v_mfma_f32_16x16x32_bf16 v[126:129], v[130:133], v[140:143], v[126:129]
	v_mfma_f32_16x16x32_bf16 v[114:117], v[156:159], v[140:143], v[114:117]
	v_mfma_f32_16x16x32_bf16 v[110:113], v[130:133], v[160:163], v[110:113]
	v_mfma_f32_16x16x32_bf16 v[106:109], v[144:147], v[160:163], v[106:109]
	v_mfma_f32_16x16x32_bf16 v[102:105], v[148:151], v[160:163], v[102:105]
	v_mfma_f32_16x16x32_bf16 v[98:101], v[156:159], v[160:163], v[98:101]
	v_mfma_f32_16x16x32_bf16 v[94:97], v[130:133], v[164:167], v[94:97]
	v_mfma_f32_16x16x32_bf16 v[90:93], v[144:147], v[164:167], v[90:93]
	v_mfma_f32_16x16x32_bf16 v[86:89], v[148:151], v[164:167], v[86:89]
	v_mfma_f32_16x16x32_bf16 v[82:85], v[156:159], v[164:167], v[82:85]
	v_mfma_f32_16x16x32_bf16 v[78:81], v[130:133], v[168:171], v[78:81]
	v_mfma_f32_16x16x32_bf16 v[74:77], v[144:147], v[168:171], v[74:77]
	v_mfma_f32_16x16x32_bf16 v[70:73], v[148:151], v[168:171], v[70:73]
	v_mfma_f32_16x16x32_bf16 v[66:69], v[156:159], v[168:171], v[66:69]
	v_mfma_f32_16x16x32_bf16 v[122:125], v[144:147], v[140:143], v[122:125]
	v_mfma_f32_16x16x32_bf16 v[118:121], v[148:151], v[140:143], v[118:121]
	s_setprio 0
	ds_read_b128 v[140:143], v155 offset:4096
	ds_read_b128 v[160:163], v155 offset:5120
	ds_read_b128 v[164:167], v155 offset:6144
	ds_read_b128 v[168:171], v155 offset:7168
	s_setprio 1
	s_waitcnt lgkmcnt(0)
	v_mfma_f32_16x16x32_bf16 v[62:65], v[130:133], v[140:143], v[62:65]
	v_mfma_f32_16x16x32_bf16 v[58:61], v[144:147], v[140:143], v[58:61]
	v_mfma_f32_16x16x32_bf16 v[54:57], v[148:151], v[140:143], v[54:57]
	v_mfma_f32_16x16x32_bf16 v[50:53], v[156:159], v[140:143], v[50:53]
	v_mfma_f32_16x16x32_bf16 v[46:49], v[130:133], v[160:163], v[46:49]
	v_mfma_f32_16x16x32_bf16 v[42:45], v[144:147], v[160:163], v[42:45]
	v_mfma_f32_16x16x32_bf16 v[38:41], v[148:151], v[160:163], v[38:41]
	v_mfma_f32_16x16x32_bf16 v[34:37], v[156:159], v[160:163], v[34:37]
	v_mfma_f32_16x16x32_bf16 v[30:33], v[130:133], v[164:167], v[30:33]
	v_mfma_f32_16x16x32_bf16 v[26:29], v[144:147], v[164:167], v[26:29]
	v_mfma_f32_16x16x32_bf16 v[22:25], v[148:151], v[164:167], v[22:25]
	v_mfma_f32_16x16x32_bf16 v[18:21], v[156:159], v[164:167], v[18:21]
	v_mfma_f32_16x16x32_bf16 v[14:17], v[130:133], v[168:171], v[14:17]
	v_mfma_f32_16x16x32_bf16 v[10:13], v[144:147], v[168:171], v[10:13]
	v_mfma_f32_16x16x32_bf16 v[6:9], v[148:151], v[168:171], v[6:9]
	v_mfma_f32_16x16x32_bf16 v[2:5], v[156:159], v[168:171], v[2:5]
	s_setprio 0
	s_waitcnt vmcnt(0)
	s_barrier
	ds_read_b128 v[130:133], v138 offset:40960
	ds_read_b128 v[140:143], v138 offset:41984
	ds_read_b128 v[144:147], v138 offset:43008
	ds_read_b128 v[148:151], v138 offset:44032
	ds_read_b128 v[156:159], v155 offset:24576
	ds_read_b128 v[160:163], v155 offset:25600
	ds_read_b128 v[164:167], v155 offset:26624
	ds_read_b128 v[168:171], v155 offset:27648
	s_lshl_b64 s[4:5], s[4:5], 8
	s_setprio 1
	s_waitcnt lgkmcnt(0)
	v_mfma_f32_16x16x32_bf16 v[172:175], v[130:133], v[156:159], v[126:129]
	v_mfma_f32_16x16x32_bf16 v[126:129], v[140:143], v[156:159], v[122:125]
	v_mfma_f32_16x16x32_bf16 v[114:117], v[148:151], v[156:159], v[114:117]
	v_mfma_f32_16x16x32_bf16 v[110:113], v[130:133], v[160:163], v[110:113]
	v_mfma_f32_16x16x32_bf16 v[106:109], v[140:143], v[160:163], v[106:109]
	v_mfma_f32_16x16x32_bf16 v[102:105], v[144:147], v[160:163], v[102:105]
	v_mfma_f32_16x16x32_bf16 v[98:101], v[148:151], v[160:163], v[98:101]
	v_mfma_f32_16x16x32_bf16 v[94:97], v[130:133], v[164:167], v[94:97]
	v_mfma_f32_16x16x32_bf16 v[90:93], v[140:143], v[164:167], v[90:93]
	v_mfma_f32_16x16x32_bf16 v[86:89], v[144:147], v[164:167], v[86:89]
	v_mfma_f32_16x16x32_bf16 v[82:85], v[148:151], v[164:167], v[82:85]
	v_mfma_f32_16x16x32_bf16 v[78:81], v[130:133], v[168:171], v[78:81]
	v_mfma_f32_16x16x32_bf16 v[74:77], v[140:143], v[168:171], v[74:77]
	v_mfma_f32_16x16x32_bf16 v[70:73], v[144:147], v[168:171], v[70:73]
	v_mfma_f32_16x16x32_bf16 v[66:69], v[148:151], v[168:171], v[66:69]
	v_mfma_f32_16x16x32_bf16 v[122:125], v[144:147], v[156:159], v[118:121]
	s_setprio 0
	s_nop 1
	ds_read_b128 v[118:121], v155 offset:28672
	ds_read_b128 v[156:159], v155 offset:29696
	ds_read_b128 v[160:163], v155 offset:30720
	ds_read_b128 v[164:167], v155 offset:31744
	s_setprio 1
	s_waitcnt lgkmcnt(0)
	v_mfma_f32_16x16x32_bf16 v[62:65], v[130:133], v[118:121], v[62:65]
	v_mfma_f32_16x16x32_bf16 v[58:61], v[140:143], v[118:121], v[58:61]
	v_mfma_f32_16x16x32_bf16 v[54:57], v[144:147], v[118:121], v[54:57]
	v_mfma_f32_16x16x32_bf16 v[50:53], v[148:151], v[118:121], v[50:53]
	v_mfma_f32_16x16x32_bf16 v[46:49], v[130:133], v[156:159], v[46:49]
	v_mfma_f32_16x16x32_bf16 v[42:45], v[140:143], v[156:159], v[42:45]
	v_mfma_f32_16x16x32_bf16 v[38:41], v[144:147], v[156:159], v[38:41]
	v_mfma_f32_16x16x32_bf16 v[34:37], v[148:151], v[156:159], v[34:37]
	v_mfma_f32_16x16x32_bf16 v[30:33], v[130:133], v[160:163], v[30:33]
	v_mfma_f32_16x16x32_bf16 v[26:29], v[140:143], v[160:163], v[26:29]
	v_mfma_f32_16x16x32_bf16 v[22:25], v[144:147], v[160:163], v[22:25]
	v_mfma_f32_16x16x32_bf16 v[18:21], v[148:151], v[160:163], v[18:21]
	v_mfma_f32_16x16x32_bf16 v[14:17], v[130:133], v[164:167], v[14:17]
	v_mfma_f32_16x16x32_bf16 v[10:13], v[140:143], v[164:167], v[10:13]
	v_mfma_f32_16x16x32_bf16 v[6:9], v[144:147], v[164:167], v[6:9]
	v_mfma_f32_16x16x32_bf16 v[2:5], v[148:151], v[164:167], v[2:5]
	s_setprio 0
	v_lshl_add_u64 v[140:141], s[4:5], 0, v[136:137]
	v_lshl_add_u64 v[118:119], v[140:141], 2, s[18:19]
	s_waitcnt vmcnt(0)
	s_barrier
	v_mov_b32_e32 v234, v118
	v_mov_b32_e32 v235, v119
	global_load_dword v228, v[234:235], off
	v_lshl_or_b32 v132, s8, 7, v152
	v_lshlrev_b64 v[118:119], 11, v[140:141]
	v_lshl_add_u64 v[120:121], s[14:15], 0, v[118:119]
	v_lshlrev_b32_e32 v142, 1, v132
	v_mov_b32_e32 v143, v139
	v_lshl_add_u64 v[148:149], v[120:121], 0, v[142:143]
	v_lshlrev_b64 v[120:121], 12, v[140:141]
	v_lshlrev_b32_e32 v138, 2, v132
	v_lshl_add_u64 v[120:121], v[134:135], 0, v[120:121]
	s_nop 0
	v_lshl_add_u64 v[144:145], v[120:121], 0, v[138:139]
	v_lshl_add_u64 v[132:133], s[16:17], 0, v[118:119]
	v_mov_b32_e32 v230, v144
	v_mov_b32_e32 v231, v145
	v_mov_b32_e32 v232, v148
	v_mov_b32_e32 v233, v149
	global_load_dwordx4 v[180:183], v[230:231], off
	global_load_dwordx4 v[184:187], v[230:231], off offset:64
	global_load_dwordx4 v[188:191], v[230:231], off offset:128
	global_load_dwordx4 v[192:195], v[230:231], off offset:192
	global_load_dwordx2 v[196:197], v[232:233], off
	global_load_dwordx2 v[198:199], v[232:233], off offset:32
	global_load_dwordx2 v[200:201], v[232:233], off offset:64
	global_load_dwordx2 v[202:203], v[232:233], off offset:96
	s_mov_b32 s99, 0
	s_mov_b32 s98, 0x10000
	v_lshl_add_u64 v[236:237], v[230:231], 0, s[98:99]
	global_load_dwordx4 v[204:207], v[236:237], off
	global_load_dwordx4 v[208:211], v[236:237], off offset:64
	global_load_dwordx4 v[212:215], v[236:237], off offset:128
	global_load_dwordx4 v[216:219], v[236:237], off offset:192
	s_mov_b32 s98, 0x8000
	v_lshl_add_u64 v[236:237], v[232:233], 0, s[98:99]
	global_load_dwordx2 v[220:221], v[236:237], off
	global_load_dwordx2 v[222:223], v[236:237], off offset:32
	global_load_dwordx2 v[224:225], v[236:237], off offset:64
	global_load_dwordx2 v[226:227], v[236:237], off offset:96
	s_mov_b32 s98, 0x40
	v_lshl_add_u64 v[236:237], v[234:235], 0, s[98:99]
	global_load_dword v229, v[236:237], off
	v_lshl_add_u64 v[146:147], v[132:133], 0, v[142:143]
	s_waitcnt vmcnt(9) lgkmcnt(0)
	v_mov_b32_e32 v150, v228
	v_mov_b32_e32 v130, v196
	v_mov_b32_e32 v131, v197
	v_mov_b32_e32 v118, v180
	v_mov_b32_e32 v119, v181
	v_mov_b32_e32 v120, v182
	v_mov_b32_e32 v121, v183
	v_fmamk_f32 v132, v150, 0x3a800000, v153
	v_mul_f32_e32 v133, 0x4b800000, v132
	v_cmp_gt_f32_e32 vcc, s56, v132
	s_nop 1
	v_cndmask_b32_e32 v132, v132, v133, vcc
	v_rsq_f32_e32 v150, v132
	v_lshlrev_b32_e32 v132, 16, v130
	v_mul_f32_e32 v151, 0x45800000, v150
	v_cndmask_b32_e32 v155, v150, v151, vcc
	v_mul_f32_e32 v150, v172, v155
	v_mul_f32_e32 v151, v173, v155
	v_mul_f32_e32 v150, 0xbfb8aa3b, v150
	v_mul_f32_e32 v151, 0xbfb8aa3b, v151
	v_mul_f32_e32 v156, v174, v155
	v_mul_f32_e32 v157, v175, v155
	v_exp_f32_e32 v150, v150
	v_exp_f32_e32 v151, v151
	v_mul_f32_e32 v156, 0xbfb8aa3b, v156
	v_mul_f32_e32 v157, 0xbfb8aa3b, v157
	v_exp_f32_e32 v156, v156
	v_exp_f32_e32 v157, v157
	v_pk_add_f32 v[150:151], v[150:151], 1.0 op_sel_hi:[1,0]
	v_and_b32_e32 v133, 0xffff0000, v130
	v_div_scale_f32 v158, s[4:5], v151, v151, 1.0
	v_pk_add_f32 v[156:157], v[156:157], 1.0 op_sel_hi:[1,0]
	v_div_scale_f32 v160, s[4:5], v150, v150, 1.0
	v_rcp_f32_e32 v166, v158
	v_div_scale_f32 v162, s[6:7], v157, v157, 1.0
	v_rcp_f32_e32 v167, v160
	v_div_scale_f32 v164, s[8:9], v156, v156, 1.0
	v_rcp_f32_e32 v168, v162
	v_rcp_f32_e32 v169, v164
	v_fma_f32 v170, -v158, v166, 1.0
	v_div_scale_f32 v159, vcc, 1.0, v151, 1.0
	v_fma_f32 v171, -v160, v167, 1.0
	v_fmac_f32_e32 v166, v170, v166
	v_div_scale_f32 v161, s[4:5], 1.0, v150, 1.0
	v_fma_f32 v172, -v162, v168, 1.0
	v_fmac_f32_e32 v167, v171, v167
	v_mul_f32_e32 v170, v159, v166
	v_div_scale_f32 v163, s[6:7], 1.0, v157, 1.0
	v_fma_f32 v173, -v164, v169, 1.0
	v_fmac_f32_e32 v168, v172, v168
	v_mul_f32_e32 v171, v161, v167
	v_fma_f32 v174, -v158, v170, v159
	v_div_scale_f32 v165, s[8:9], 1.0, v156, 1.0
	v_fmac_f32_e32 v169, v173, v169
	v_mul_f32_e32 v172, v163, v168
	v_fma_f32 v175, -v160, v171, v161
	v_fmac_f32_e32 v170, v174, v166
	v_mul_f32_e32 v173, v165, v169
	v_fma_f32 v176, -v162, v172, v163
	v_fmac_f32_e32 v171, v175, v167
	v_fma_f32 v158, -v158, v170, v159
	v_fma_f32 v177, -v164, v173, v165
	v_fmac_f32_e32 v172, v176, v168
	v_fma_f32 v159, -v160, v171, v161
	v_div_fmas_f32 v158, v158, v166, v170
	s_mov_b64 vcc, s[4:5]
	v_fmac_f32_e32 v173, v177, v169
	v_fma_f32 v160, -v162, v172, v163
	v_div_fixup_f32 v151, v158, v151, 1.0
	v_div_fmas_f32 v158, v159, v167, v171
	s_mov_b64 vcc, s[6:7]
	v_fma_f32 v161, -v164, v173, v165
	v_div_fixup_f32 v150, v158, v150, 1.0
	v_div_fmas_f32 v158, v160, v168, v172
	s_mov_b64 vcc, s[8:9]
	v_pk_fma_f32 v[118:119], v[150:151], v[132:133], v[118:119]
	v_div_fmas_f32 v132, v161, v169, v173
	v_lshlrev_b32_e32 v130, 16, v131
	v_and_b32_e32 v131, 0xffff0000, v131
	v_div_fixup_f32 v133, v158, v157, 1.0
	v_div_fixup_f32 v132, v132, v156, 1.0
	v_pk_fma_f32 v[120:121], v[132:133], v[130:131], v[120:121]
	global_store_dwordx4 v[144:145], v[118:121], off
	v_cvt_pk_bf16_f32 v130, v118, v119
	v_cvt_pk_bf16_f32 v131, v120, v121
	s_nop 0
	v_mul_f32_e32 v126, v126, v155
	global_store_dwordx2 v[146:147], v[130:131], off
	s_nop 0
	v_mul_f32_e32 v127, v127, v155
	v_mul_f32_e32 v128, v128, v155
	v_mul_f32_e32 v129, v129, v155
	v_mul_f32_e32 v156, v122, v155
	v_mul_f32_e32 v157, v123, v155
	v_mul_f32_e32 v122, 0xbfb8aa3b, v126
	v_mul_f32_e32 v123, 0xbfb8aa3b, v127
	v_mul_f32_e32 v158, v124, v155
	v_mul_f32_e32 v159, v125, v155
	v_mul_f32_e32 v124, 0xbfb8aa3b, v128
	v_mul_f32_e32 v125, 0xbfb8aa3b, v129
	v_exp_f32_e32 v122, v122
	v_exp_f32_e32 v123, v123
	v_exp_f32_e32 v124, v124
	v_exp_f32_e32 v125, v125
	v_mul_f32_e32 v160, v114, v155
	v_mul_f32_e32 v161, v115, v155
	v_pk_add_f32 v[114:115], v[122:123], 1.0 op_sel_hi:[1,0]
	v_pk_add_f32 v[122:123], v[124:125], 1.0 op_sel_hi:[1,0]
	v_div_scale_f32 v124, s[4:5], v115, v115, 1.0
	v_div_scale_f32 v126, s[4:5], v114, v114, 1.0
	v_rcp_f32_e32 v164, v124
	v_div_scale_f32 v128, s[6:7], v123, v123, 1.0
	v_rcp_f32_e32 v165, v126
	v_div_scale_f32 v162, s[8:9], v122, v122, 1.0
	v_rcp_f32_e32 v166, v128
	v_rcp_f32_e32 v167, v162
	v_fma_f32 v168, -v124, v164, 1.0
	v_div_scale_f32 v125, vcc, 1.0, v115, 1.0
	v_fma_f32 v169, -v126, v165, 1.0
	v_fmac_f32_e32 v164, v168, v164
	v_div_scale_f32 v127, s[4:5], 1.0, v114, 1.0
	v_fma_f32 v170, -v128, v166, 1.0
	v_fmac_f32_e32 v165, v169, v165
	v_mul_f32_e32 v168, v125, v164
	v_div_scale_f32 v129, s[6:7], 1.0, v123, 1.0
	v_fma_f32 v171, -v162, v167, 1.0
	v_fmac_f32_e32 v166, v170, v166
	v_mul_f32_e32 v169, v127, v165
	v_fma_f32 v172, -v124, v168, v125
	v_div_scale_f32 v163, s[8:9], 1.0, v122, 1.0
	v_fmac_f32_e32 v167, v171, v167
	v_mul_f32_e32 v170, v129, v166
	v_fma_f32 v173, -v126, v169, v127
	v_fmac_f32_e32 v168, v172, v164
	v_mul_f32_e32 v171, v163, v167
	v_fma_f32 v174, -v128, v170, v129
	v_fmac_f32_e32 v169, v173, v165
	v_fma_f32 v124, -v124, v168, v125
	v_fma_f32 v175, -v162, v171, v163
	v_fmac_f32_e32 v170, v174, v166
	v_fma_f32 v125, -v126, v169, v127
	v_div_fmas_f32 v124, v124, v164, v168
	s_mov_b64 vcc, s[4:5]
	v_fmac_f32_e32 v171, v175, v167
	v_fma_f32 v126, -v128, v170, v129
	v_div_fixup_f32 v115, v124, v115, 1.0
	v_div_fmas_f32 v124, v125, v165, v169
	s_mov_b64 vcc, s[6:7]
	v_fma_f32 v127, -v162, v171, v163
	v_div_fixup_f32 v114, v124, v114, 1.0
	v_div_fmas_f32 v124, v126, v166, v170
	s_mov_b64 vcc, s[8:9]
	v_div_fixup_f32 v125, v124, v123, 1.0
	v_div_fmas_f32 v123, v127, v167, v171
	v_div_fixup_f32 v124, v123, v122, 1.0
	v_mul_f32_e32 v116, v116, v155
	v_mul_f32_e32 v117, v117, v155
	s_waitcnt lgkmcnt(0)
	v_mov_b32_e32 v150, v198
	v_mov_b32_e32 v151, v199
	v_mov_b32_e32 v130, v184
	v_mov_b32_e32 v131, v185
	v_mov_b32_e32 v132, v186
	v_mov_b32_e32 v133, v187
	v_lshlrev_b32_e32 v122, 16, v150
	v_and_b32_e32 v123, 0xffff0000, v150
	v_lshlrev_b32_e32 v126, 16, v151
	v_and_b32_e32 v127, 0xffff0000, v151
	v_pk_fma_f32 v[122:123], v[114:115], v[122:123], v[130:131]
	v_pk_fma_f32 v[124:125], v[124:125], v[126:127], v[132:133]
	global_store_dwordx4 v[144:145], v[122:125], off offset:64
	v_cvt_pk_bf16_f32 v126, v122, v123
	v_cvt_pk_bf16_f32 v127, v124, v125
	s_nop 0
	v_mul_f32_e32 v130, 0xbfb8aa3b, v156
	global_store_dwordx2 v[146:147], v[126:127], off offset:32
	s_nop 0
	v_mul_f32_e32 v131, 0xbfb8aa3b, v157
	v_mul_f32_e32 v150, 0xbfb8aa3b, v160
	v_mul_f32_e32 v155, 0xbfb8aa3b, v116
	v_mul_f32_e32 v160, 0xbfb8aa3b, v117
	v_exp_f32_e32 v116, v130
	v_exp_f32_e32 v117, v131
	v_mul_f32_e32 v132, 0xbfb8aa3b, v158
	v_mul_f32_e32 v133, 0xbfb8aa3b, v159
	v_exp_f32_e32 v130, v132
	v_exp_f32_e32 v131, v133
	v_mul_f32_e32 v151, 0xbfb8aa3b, v161
	v_pk_add_f32 v[116:117], v[116:117], 1.0 op_sel_hi:[1,0]
	v_exp_f32_e32 v133, v151
	v_div_scale_f32 v151, s[4:5], v117, v117, 1.0
	v_pk_add_f32 v[130:131], v[130:131], 1.0 op_sel_hi:[1,0]
	v_div_scale_f32 v156, s[4:5], v116, v116, 1.0
	v_rcp_f32_e32 v163, v151
	v_div_scale_f32 v158, s[6:7], v131, v131, 1.0
	v_rcp_f32_e32 v164, v156
	v_div_scale_f32 v161, s[8:9], v130, v130, 1.0
	v_rcp_f32_e32 v165, v158
	v_rcp_f32_e32 v166, v161
	v_fma_f32 v167, -v151, v163, 1.0
	v_exp_f32_e32 v132, v150
	v_exp_f32_e32 v150, v155
	v_div_scale_f32 v155, vcc, 1.0, v117, 1.0
	v_fma_f32 v168, -v156, v164, 1.0
	v_fmac_f32_e32 v163, v167, v163
	v_div_scale_f32 v157, s[4:5], 1.0, v116, 1.0
	v_fma_f32 v169, -v158, v165, 1.0
	v_fmac_f32_e32 v164, v168, v164
	v_mul_f32_e32 v167, v155, v163
	v_div_scale_f32 v159, s[6:7], 1.0, v131, 1.0
	v_fma_f32 v170, -v161, v166, 1.0
	v_fmac_f32_e32 v165, v169, v165
	v_mul_f32_e32 v168, v157, v164
	v_fma_f32 v171, -v151, v167, v155
	v_div_scale_f32 v162, s[8:9], 1.0, v130, 1.0
	v_fmac_f32_e32 v166, v170, v166
	v_mul_f32_e32 v169, v159, v165
	v_fma_f32 v172, -v156, v168, v157
	v_fmac_f32_e32 v167, v171, v163
	v_mul_f32_e32 v170, v162, v166
	v_fma_f32 v173, -v158, v169, v159
	v_fmac_f32_e32 v168, v172, v164
	v_fma_f32 v151, -v151, v167, v155
	v_fma_f32 v174, -v161, v170, v162
	v_fmac_f32_e32 v169, v173, v165
	v_fma_f32 v155, -v156, v168, v157
	v_div_fmas_f32 v151, v151, v163, v167
	s_mov_b64 vcc, s[4:5]
	v_fmac_f32_e32 v170, v174, v166
	v_fma_f32 v156, -v158, v169, v159
	v_div_fixup_f32 v117, v151, v117, 1.0
	v_div_fmas_f32 v151, v155, v164, v168
	s_mov_b64 vcc, s[6:7]
	v_fma_f32 v157, -v161, v170, v162
	v_div_fixup_f32 v116, v151, v116, 1.0
	v_div_fmas_f32 v151, v156, v165, v169
	s_mov_b64 vcc, s[8:9]
	v_div_fixup_f32 v131, v151, v131, 1.0
	v_div_fmas_f32 v151, v157, v166, v170
	v_div_fixup_f32 v130, v151, v130, 1.0
	v_exp_f32_e32 v151, v160
	v_pk_add_f32 v[132:133], v[132:133], 1.0 op_sel_hi:[1,0]
	v_pk_mul_f32 v[118:119], v[118:119], v[118:119]
	v_div_scale_f32 v155, s[4:5], v132, v132, 1.0
	s_waitcnt lgkmcnt(0)
	v_mov_b32_e32 v114, v200
	v_mov_b32_e32 v115, v201
	v_mov_b32_e32 v126, v188
	v_mov_b32_e32 v127, v189
	v_mov_b32_e32 v128, v190
	v_mov_b32_e32 v129, v191
	v_lshlrev_b32_e32 v156, 16, v114
	v_and_b32_e32 v157, 0xffff0000, v114
	v_lshlrev_b32_e32 v158, 16, v115
	v_and_b32_e32 v159, 0xffff0000, v115
	v_pk_fma_f32 v[114:115], v[116:117], v[156:157], v[126:127]
	v_pk_fma_f32 v[116:117], v[130:131], v[158:159], v[128:129]
	global_store_dwordx4 v[144:145], v[114:117], off offset:128
	v_cvt_pk_bf16_f32 v126, v114, v115
	v_cvt_pk_bf16_f32 v127, v116, v117
	s_nop 0
	v_pk_add_f32 v[148:149], v[150:151], 1.0 op_sel_hi:[1,0]
	global_store_dwordx2 v[146:147], v[126:127], off offset:64
	s_nop 0
	v_div_scale_f32 v150, s[4:5], v133, v133, 1.0
	v_div_scale_f32 v157, s[6:7], v149, v149, 1.0
	v_rcp_f32_e32 v161, v150
	v_rcp_f32_e32 v162, v155
	v_rcp_f32_e32 v163, v157
	v_div_scale_f32 v159, s[8:9], v148, v148, 1.0
	v_rcp_f32_e32 v164, v159
	v_fma_f32 v165, -v150, v161, 1.0
	v_fma_f32 v166, -v155, v162, 1.0
	v_fma_f32 v167, -v157, v163, 1.0
	v_div_scale_f32 v151, vcc, 1.0, v133, 1.0
	v_div_scale_f32 v156, s[4:5], 1.0, v132, 1.0
	v_div_scale_f32 v158, s[6:7], 1.0, v149, 1.0
	v_fmac_f32_e32 v161, v165, v161
	v_fmac_f32_e32 v162, v166, v162
	v_fmac_f32_e32 v163, v167, v163
	v_mul_f32_e32 v165, v151, v161
	v_mul_f32_e32 v166, v156, v162
	v_mul_f32_e32 v167, v158, v163
	v_fma_f32 v169, -v150, v165, v151
	v_fma_f32 v170, -v155, v166, v156
	v_fma_f32 v171, -v157, v167, v158
	v_fma_f32 v168, -v159, v164, 1.0
	v_fmac_f32_e32 v165, v169, v161
	v_fmac_f32_e32 v166, v170, v162
	v_fmac_f32_e32 v167, v171, v163
	v_div_scale_f32 v160, s[8:9], 1.0, v148, 1.0
	v_fmac_f32_e32 v164, v168, v164
	v_fma_f32 v150, -v150, v165, v151
	v_fma_f32 v151, -v155, v166, v156
	v_fma_f32 v155, -v157, v167, v158
	v_add_f32_e32 v157, v118, v119
	v_pk_mul_f32 v[118:119], v[120:121], v[120:121]
	v_mul_f32_e32 v168, v160, v164
	v_add_f32_e32 v118, v118, v157
	v_fma_f32 v172, -v159, v168, v160
	v_add_f32_e32 v157, v119, v118
	v_div_fmas_f32 v118, v150, v161, v165
	s_mov_b64 vcc, s[4:5]
	v_pk_mul_f32 v[122:123], v[122:123], v[122:123]
	v_fmac_f32_e32 v168, v172, v164
	v_div_fixup_f32 v119, v118, v133, 1.0
	v_div_fmas_f32 v118, v151, v162, v166
	s_mov_b64 vcc, s[6:7]
	v_pk_mul_f32 v[124:125], v[124:125], v[124:125]
	v_add_f32_e32 v122, v122, v123
	v_fma_f32 v156, -v159, v168, v160
	v_div_fmas_f32 v120, v155, v163, v167
	s_mov_b64 vcc, s[8:9]
	v_add_f32_e32 v122, v124, v122
	v_pk_mul_f32 v[114:115], v[114:115], v[114:115]
	v_div_fixup_f32 v118, v118, v132, 1.0
	v_div_fixup_f32 v121, v120, v149, 1.0
	v_div_fmas_f32 v120, v156, v164, v168
	v_add_f32_e32 v122, v125, v122
	v_add_f32_e32 v133, v114, v115
	v_div_fixup_f32 v120, v120, v148, 1.0
	v_add_f32_e32 v132, v157, v122
	v_pk_mul_f32 v[122:123], v[116:117], v[116:117]
	s_waitcnt lgkmcnt(0)
	v_mov_b32_e32 v130, v202
	v_mov_b32_e32 v131, v203
	v_mov_b32_e32 v126, v192
	v_mov_b32_e32 v127, v193
	v_mov_b32_e32 v128, v194
	v_mov_b32_e32 v129, v195
	v_lshlrev_b32_e32 v114, 16, v130
	v_and_b32_e32 v115, 0xffff0000, v130
	v_lshlrev_b32_e32 v124, 16, v131
	v_and_b32_e32 v125, 0xffff0000, v131
	v_pk_fma_f32 v[116:117], v[118:119], v[114:115], v[126:127]
	v_pk_fma_f32 v[118:119], v[120:121], v[124:125], v[128:129]
	v_pk_mul_f32 v[114:115], v[116:117], v[116:117]
	v_pk_mul_f32 v[120:121], v[118:119], v[118:119]
	v_add_f32_e32 v114, v114, v115
	v_add_f32_e32 v114, v120, v114
	v_and_b32_e32 v120, 64, v154
	v_add_f32_e32 v122, v122, v133
	v_xor_b32_e32 v115, 16, v154
	v_add_u32_e32 v120, 64, v120
	v_add_f32_e32 v122, v123, v122
	v_cmp_lt_i32_e32 vcc, v115, v120
	v_add_f32_e32 v122, v132, v122
	v_add_f32_e32 v114, v121, v114
	v_cndmask_b32_e32 v115, v154, v115, vcc
	v_add_f32_e32 v114, v122, v114
	v_lshlrev_b32_e32 v126, 2, v115
	ds_bpermute_b32 v115, v126, v114
	global_store_dwordx4 v[144:145], v[116:119], off offset:192
	s_waitcnt lgkmcnt(0)
	v_add_f32_e32 v114, v114, v115
	v_xor_b32_e32 v115, 32, v154
	v_cmp_lt_i32_e32 vcc, v115, v120
	v_cvt_pk_bf16_f32 v116, v116, v117
	v_cvt_pk_bf16_f32 v117, v118, v119
	v_cndmask_b32_e32 v115, v154, v115, vcc
	v_lshlrev_b32_e32 v127, 2, v115
	ds_bpermute_b32 v115, v127, v114
	global_store_dwordx2 v[146:147], v[116:117], off offset:96
	s_and_saveexec_b64 s[4:5], s[0:1]
	s_cbranch_execz .LBB0_624
	s_waitcnt lgkmcnt(0)
	v_add_f32_e32 v116, v114, v115
	v_lshl_add_u64 v[114:115], v[140:141], 2, s[20:21]
	global_atomic_add_f32 v[114:115], v116, off
.LBB0_624:
	s_or_b64 exec, exec, s[4:5]
	v_or_b32_e32 v118, 16, v140
	v_mov_b32_e32 v119, v141
	s_waitcnt lgkmcnt(0)
	v_lshl_add_u64 v[114:115], v[118:119], 2, s[18:19]
	s_mov_b32 s99, 0
	s_mov_b32 s98, 0x20000
	v_lshl_add_u64 v[236:237], v[230:231], 0, s[98:99]
	global_load_dwordx4 v[180:183], v[236:237], off
	global_load_dwordx4 v[184:187], v[236:237], off offset:64
	global_load_dwordx4 v[188:191], v[236:237], off offset:128
	global_load_dwordx4 v[192:195], v[236:237], off offset:192
	s_mov_b32 s98, 0x10000
	v_lshl_add_u64 v[236:237], v[232:233], 0, s[98:99]
	global_load_dwordx2 v[196:197], v[236:237], off
	global_load_dwordx2 v[198:199], v[236:237], off offset:32
	global_load_dwordx2 v[200:201], v[236:237], off offset:64
	global_load_dwordx2 v[202:203], v[236:237], off offset:96
	s_mov_b32 s98, 0x80
	v_lshl_add_u64 v[236:237], v[234:235], 0, s[98:99]
	global_load_dword v228, v[236:237], off
	v_lshlrev_b64 v[114:115], 11, v[118:119]
	v_lshl_add_u64 v[116:117], s[14:15], 0, v[114:115]
	v_lshl_add_u64 v[124:125], v[116:117], 0, v[142:143]
	v_lshlrev_b64 v[116:117], 12, v[118:119]
	v_lshl_add_u64 v[116:117], v[134:135], 0, v[116:117]
	s_nop 0
	v_lshl_add_u64 v[114:115], s[16:17], 0, v[114:115]
	v_lshl_add_u64 v[120:121], v[116:117], 0, v[138:139]
	v_lshl_add_u64 v[122:123], v[114:115], 0, v[142:143]
	s_nop 0
	s_waitcnt vmcnt(17) lgkmcnt(0)
	v_mov_b32_e32 v130, v229
	v_mov_b32_e32 v128, v220
	v_mov_b32_e32 v129, v221
	v_mov_b32_e32 v114, v204
	v_mov_b32_e32 v115, v205
	v_mov_b32_e32 v116, v206
	v_mov_b32_e32 v117, v207
	v_fmamk_f32 v130, v130, 0x3a800000, v153
	v_mul_f32_e32 v131, 0x4b800000, v130
	v_cmp_gt_f32_e32 vcc, s56, v130
	s_nop 1
	v_cndmask_b32_e32 v131, v130, v131, vcc
	v_rsq_f32_e32 v132, v131
	v_lshlrev_b32_e32 v130, 16, v128
	v_and_b32_e32 v131, 0xffff0000, v128
	v_lshlrev_b32_e32 v128, 16, v129
	v_mul_f32_e32 v133, 0x45800000, v132
	v_cndmask_b32_e32 v132, v132, v133, vcc
	v_mul_f32_e32 v110, v110, v132
	v_mul_f32_e32 v111, v111, v132
	v_mul_f32_e32 v110, 0xbfb8aa3b, v110
	v_mul_f32_e32 v111, 0xbfb8aa3b, v111
	v_mul_f32_e32 v112, v112, v132
	v_mul_f32_e32 v113, v113, v132
	v_exp_f32_e32 v110, v110
	v_exp_f32_e32 v111, v111
	v_mul_f32_e32 v112, 0xbfb8aa3b, v112
	v_mul_f32_e32 v113, 0xbfb8aa3b, v113
	v_exp_f32_e32 v112, v112
	v_exp_f32_e32 v113, v113
	v_mul_f32_e32 v133, v106, v132
	v_mul_f32_e32 v143, v107, v132
	v_pk_add_f32 v[106:107], v[110:111], 1.0 op_sel_hi:[1,0]
	v_pk_add_f32 v[112:113], v[112:113], 1.0 op_sel_hi:[1,0]
	v_div_scale_f32 v110, s[4:5], v107, v107, 1.0
	v_div_scale_f32 v144, s[4:5], v106, v106, 1.0
	v_rcp_f32_e32 v150, v110
	v_div_scale_f32 v146, s[6:7], v113, v113, 1.0
	v_rcp_f32_e32 v151, v144
	v_div_scale_f32 v148, s[8:9], v112, v112, 1.0
	v_rcp_f32_e32 v155, v146
	v_rcp_f32_e32 v156, v148
	v_fma_f32 v157, -v110, v150, 1.0
	v_div_scale_f32 v111, vcc, 1.0, v107, 1.0
	v_fma_f32 v158, -v144, v151, 1.0
	v_fmac_f32_e32 v150, v157, v150
	v_div_scale_f32 v145, s[4:5], 1.0, v106, 1.0
	v_fma_f32 v159, -v146, v155, 1.0
	v_fmac_f32_e32 v151, v158, v151
	v_mul_f32_e32 v157, v111, v150
	v_div_scale_f32 v147, s[6:7], 1.0, v113, 1.0
	v_fma_f32 v160, -v148, v156, 1.0
	v_fmac_f32_e32 v155, v159, v155
	v_mul_f32_e32 v158, v145, v151
	v_fma_f32 v161, -v110, v157, v111
	v_div_scale_f32 v149, s[8:9], 1.0, v112, 1.0
	v_fmac_f32_e32 v156, v160, v156
	v_mul_f32_e32 v159, v147, v155
	v_fma_f32 v162, -v144, v158, v145
	v_fmac_f32_e32 v157, v161, v150
	v_mul_f32_e32 v160, v149, v156
	v_fma_f32 v163, -v146, v159, v147
	v_fmac_f32_e32 v158, v162, v151
	v_fma_f32 v110, -v110, v157, v111
	v_fma_f32 v164, -v148, v160, v149
	v_fmac_f32_e32 v159, v163, v155
	v_fma_f32 v111, -v144, v158, v145
	v_div_fmas_f32 v110, v110, v150, v157
	s_mov_b64 vcc, s[4:5]
	v_fmac_f32_e32 v160, v164, v156
	v_fma_f32 v144, -v146, v159, v147
	v_div_fixup_f32 v107, v110, v107, 1.0
	v_div_fmas_f32 v110, v111, v151, v158
	s_mov_b64 vcc, s[6:7]
	v_fma_f32 v145, -v148, v160, v149
	v_div_fixup_f32 v106, v110, v106, 1.0
	v_div_fmas_f32 v144, v144, v155, v159
	s_mov_b64 vcc, s[8:9]
	v_pk_fma_f32 v[110:111], v[106:107], v[130:131], v[114:115]
	v_div_fmas_f32 v106, v145, v156, v160
	v_and_b32_e32 v129, 0xffff0000, v129
	v_div_fixup_f32 v107, v144, v113, 1.0
	v_div_fixup_f32 v106, v106, v112, 1.0
	v_pk_fma_f32 v[112:113], v[106:107], v[128:129], v[116:117]
	global_store_dwordx4 v[120:121], v[110:113], off
	v_cvt_pk_bf16_f32 v114, v110, v111
	v_cvt_pk_bf16_f32 v115, v112, v113
	s_nop 0
	v_mul_f32_e32 v108, v108, v132
	global_store_dwordx2 v[122:123], v[114:115], off
	s_nop 0
	v_mul_f32_e32 v109, v109, v132
	v_mul_f32_e32 v129, v103, v132
	v_mul_f32_e32 v144, v98, v132
	v_mul_f32_e32 v98, 0xbfb8aa3b, v133
	v_mul_f32_e32 v103, 0xbfb8aa3b, v143
	v_mul_f32_e32 v128, v102, v132
	v_mul_f32_e32 v130, v104, v132
	v_mul_f32_e32 v131, v105, v132
	v_mul_f32_e32 v104, 0xbfb8aa3b, v108
	v_mul_f32_e32 v105, 0xbfb8aa3b, v109
	v_exp_f32_e32 v102, v98
	v_exp_f32_e32 v103, v103
	v_exp_f32_e32 v104, v104
	v_exp_f32_e32 v105, v105
	v_mul_f32_e32 v133, v99, v132
	v_pk_add_f32 v[98:99], v[102:103], 1.0 op_sel_hi:[1,0]
	v_mul_f32_e32 v100, v100, v132
	v_pk_add_f32 v[102:103], v[104:105], 1.0 op_sel_hi:[1,0]
	v_div_scale_f32 v104, s[4:5], v99, v99, 1.0
	v_div_scale_f32 v108, s[4:5], v98, v98, 1.0
	v_rcp_f32_e32 v148, v104
	v_div_scale_f32 v143, s[6:7], v103, v103, 1.0
	v_rcp_f32_e32 v149, v108
	v_div_scale_f32 v146, s[8:9], v102, v102, 1.0
	v_rcp_f32_e32 v150, v143
	v_rcp_f32_e32 v151, v146
	v_fma_f32 v155, -v104, v148, 1.0
	v_div_scale_f32 v105, vcc, 1.0, v99, 1.0
	v_fma_f32 v156, -v108, v149, 1.0
	v_fmac_f32_e32 v148, v155, v148
	v_div_scale_f32 v109, s[4:5], 1.0, v98, 1.0
	v_fma_f32 v157, -v143, v150, 1.0
	v_fmac_f32_e32 v149, v156, v149
	v_mul_f32_e32 v155, v105, v148
	v_div_scale_f32 v145, s[6:7], 1.0, v103, 1.0
	v_fma_f32 v158, -v146, v151, 1.0
	v_fmac_f32_e32 v150, v157, v150
	v_mul_f32_e32 v156, v109, v149
	v_fma_f32 v159, -v104, v155, v105
	v_div_scale_f32 v147, s[8:9], 1.0, v102, 1.0
	v_fmac_f32_e32 v151, v158, v151
	v_mul_f32_e32 v157, v145, v150
	v_fma_f32 v160, -v108, v156, v109
	v_fmac_f32_e32 v155, v159, v148
	v_mul_f32_e32 v158, v147, v151
	v_fma_f32 v161, -v143, v157, v145
	v_fmac_f32_e32 v156, v160, v149
	v_fma_f32 v104, -v104, v155, v105
	v_fma_f32 v162, -v146, v158, v147
	v_fmac_f32_e32 v157, v161, v150
	v_fma_f32 v105, -v108, v156, v109
	v_div_fmas_f32 v104, v104, v148, v155
	s_mov_b64 vcc, s[4:5]
	v_fmac_f32_e32 v158, v162, v151
	v_fma_f32 v108, -v143, v157, v145
	v_div_fixup_f32 v99, v104, v99, 1.0
	v_div_fmas_f32 v104, v105, v149, v156
	s_mov_b64 vcc, s[6:7]
	v_fma_f32 v109, -v146, v158, v147
	v_div_fixup_f32 v98, v104, v98, 1.0
	v_div_fmas_f32 v104, v108, v150, v157
	s_mov_b64 vcc, s[8:9]
	v_div_fixup_f32 v105, v104, v103, 1.0
	v_div_fmas_f32 v103, v109, v151, v158
	v_div_fixup_f32 v104, v103, v102, 1.0
	v_mul_f32_e32 v101, v101, v132
	v_pk_mul_f32 v[110:111], v[110:111], v[110:111]
	s_waitcnt lgkmcnt(0)
	v_mov_b32_e32 v106, v222
	v_mov_b32_e32 v107, v223
	v_mov_b32_e32 v114, v208
	v_mov_b32_e32 v115, v209
	v_mov_b32_e32 v116, v210
	v_mov_b32_e32 v117, v211
	v_lshlrev_b32_e32 v102, 16, v106
	v_and_b32_e32 v103, 0xffff0000, v106
	v_lshlrev_b32_e32 v106, 16, v107
	v_and_b32_e32 v107, 0xffff0000, v107
	v_pk_fma_f32 v[102:103], v[98:99], v[102:103], v[114:115]
	v_pk_fma_f32 v[104:105], v[104:105], v[106:107], v[116:117]
	global_store_dwordx4 v[120:121], v[102:105], off offset:64
	v_cvt_pk_bf16_f32 v106, v102, v103
	v_cvt_pk_bf16_f32 v107, v104, v105
	s_nop 0
	v_mul_f32_e32 v114, 0xbfb8aa3b, v128
	global_store_dwordx2 v[122:123], v[106:107], off offset:32
	s_nop 0
	v_mul_f32_e32 v115, 0xbfb8aa3b, v129
	v_mul_f32_e32 v116, 0xbfb8aa3b, v130
	v_mul_f32_e32 v117, 0xbfb8aa3b, v131
	v_mul_f32_e32 v130, 0xbfb8aa3b, v100
	v_mul_f32_e32 v131, 0xbfb8aa3b, v101
	v_exp_f32_e32 v100, v114
	v_exp_f32_e32 v101, v115
	v_exp_f32_e32 v114, v116
	v_exp_f32_e32 v115, v117
	v_mul_f32_e32 v128, 0xbfb8aa3b, v144
	v_pk_add_f32 v[100:101], v[100:101], 1.0 op_sel_hi:[1,0]
	v_exp_f32_e32 v116, v128
	v_exp_f32_e32 v128, v130
	v_div_scale_f32 v130, s[4:5], v101, v101, 1.0
	v_pk_add_f32 v[114:115], v[114:115], 1.0 op_sel_hi:[1,0]
	v_div_scale_f32 v132, s[4:5], v100, v100, 1.0
	v_rcp_f32_e32 v147, v130
	v_div_scale_f32 v143, s[6:7], v115, v115, 1.0
	v_rcp_f32_e32 v148, v132
	v_div_scale_f32 v145, s[8:9], v114, v114, 1.0
	v_rcp_f32_e32 v149, v143
	v_rcp_f32_e32 v150, v145
	v_mul_f32_e32 v129, 0xbfb8aa3b, v133
	v_fma_f32 v151, -v130, v147, 1.0
	v_exp_f32_e32 v117, v129
	v_exp_f32_e32 v129, v131
	v_div_scale_f32 v131, vcc, 1.0, v101, 1.0
	v_fma_f32 v155, -v132, v148, 1.0
	v_fmac_f32_e32 v147, v151, v147
	v_div_scale_f32 v133, s[4:5], 1.0, v100, 1.0
	v_fma_f32 v156, -v143, v149, 1.0
	v_fmac_f32_e32 v148, v155, v148
	v_mul_f32_e32 v151, v131, v147
	v_div_scale_f32 v144, s[6:7], 1.0, v115, 1.0
	v_fma_f32 v157, -v145, v150, 1.0
	v_fmac_f32_e32 v149, v156, v149
	v_mul_f32_e32 v155, v133, v148
	v_fma_f32 v158, -v130, v151, v131
	v_div_scale_f32 v146, s[8:9], 1.0, v114, 1.0
	v_fmac_f32_e32 v150, v157, v150
	v_mul_f32_e32 v156, v144, v149
	v_fma_f32 v159, -v132, v155, v133
	v_fmac_f32_e32 v151, v158, v147
	v_mul_f32_e32 v157, v146, v150
	v_fma_f32 v160, -v143, v156, v144
	v_fmac_f32_e32 v155, v159, v148
	v_fma_f32 v130, -v130, v151, v131
	v_fma_f32 v161, -v145, v157, v146
	v_fmac_f32_e32 v156, v160, v149
	v_fma_f32 v131, -v132, v155, v133
	v_div_fmas_f32 v130, v130, v147, v151
	s_mov_b64 vcc, s[4:5]
	v_fmac_f32_e32 v157, v161, v150
	v_fma_f32 v132, -v143, v156, v144
	v_div_fixup_f32 v101, v130, v101, 1.0
	v_div_fmas_f32 v130, v131, v148, v155
	s_mov_b64 vcc, s[6:7]
	v_fma_f32 v133, -v145, v157, v146
	v_div_fixup_f32 v100, v130, v100, 1.0
	v_div_fmas_f32 v130, v132, v149, v156
	s_mov_b64 vcc, s[8:9]
	v_div_fixup_f32 v115, v130, v115, 1.0
	v_div_fmas_f32 v130, v133, v150, v157
	v_div_fixup_f32 v114, v130, v114, 1.0
	v_pk_add_f32 v[116:117], v[116:117], 1.0 op_sel_hi:[1,0]
	v_pk_mul_f32 v[102:103], v[102:103], v[102:103]
	v_pk_mul_f32 v[104:105], v[104:105], v[104:105]
	v_add_f32_e32 v102, v102, v103
	s_waitcnt lgkmcnt(0)
	v_mov_b32_e32 v98, v224
	v_mov_b32_e32 v99, v225
	v_mov_b32_e32 v106, v212
	v_mov_b32_e32 v107, v213
	v_mov_b32_e32 v108, v214
	v_mov_b32_e32 v109, v215
	v_lshlrev_b32_e32 v130, 16, v98
	v_and_b32_e32 v131, 0xffff0000, v98
	v_lshlrev_b32_e32 v132, 16, v99
	v_and_b32_e32 v133, 0xffff0000, v99
	v_pk_fma_f32 v[98:99], v[100:101], v[130:131], v[106:107]
	v_pk_fma_f32 v[100:101], v[114:115], v[132:133], v[108:109]
	global_store_dwordx4 v[120:121], v[98:101], off offset:128
	v_cvt_pk_bf16_f32 v106, v98, v99
	v_cvt_pk_bf16_f32 v107, v100, v101
	s_nop 0
	v_pk_add_f32 v[124:125], v[128:129], 1.0 op_sel_hi:[1,0]
	global_store_dwordx2 v[122:123], v[106:107], off offset:64
	s_nop 0
	v_div_scale_f32 v128, s[4:5], v117, v117, 1.0
	v_div_scale_f32 v130, s[4:5], v116, v116, 1.0
	v_div_scale_f32 v132, s[6:7], v125, v125, 1.0
	v_rcp_f32_e32 v145, v128
	v_rcp_f32_e32 v146, v130
	v_rcp_f32_e32 v147, v132
	v_div_scale_f32 v143, s[8:9], v124, v124, 1.0
	v_rcp_f32_e32 v148, v143
	v_fma_f32 v149, -v128, v145, 1.0
	v_fma_f32 v150, -v130, v146, 1.0
	v_fma_f32 v151, -v132, v147, 1.0
	v_div_scale_f32 v129, vcc, 1.0, v117, 1.0
	v_div_scale_f32 v131, s[4:5], 1.0, v116, 1.0
	v_div_scale_f32 v133, s[6:7], 1.0, v125, 1.0
	v_fmac_f32_e32 v145, v149, v145
	v_fmac_f32_e32 v146, v150, v146
	v_fmac_f32_e32 v147, v151, v147
	v_mul_f32_e32 v149, v129, v145
	v_mul_f32_e32 v150, v131, v146
	v_mul_f32_e32 v151, v133, v147
	v_fma_f32 v156, -v128, v149, v129
	v_fma_f32 v157, -v130, v150, v131
	v_fma_f32 v158, -v132, v151, v133
	v_fma_f32 v155, -v143, v148, 1.0
	v_fmac_f32_e32 v149, v156, v145
	v_fmac_f32_e32 v150, v157, v146
	v_fmac_f32_e32 v151, v158, v147
	v_div_scale_f32 v144, s[8:9], 1.0, v124, 1.0
	v_fmac_f32_e32 v148, v155, v148
	v_fma_f32 v128, -v128, v149, v129
	v_fma_f32 v129, -v130, v150, v131
	v_fma_f32 v130, -v132, v151, v133
	v_add_f32_e32 v132, v110, v111
	v_pk_mul_f32 v[110:111], v[112:113], v[112:113]
	v_mul_f32_e32 v155, v144, v148
	v_add_f32_e32 v110, v110, v132
	v_fma_f32 v159, -v143, v155, v144
	v_add_f32_e32 v132, v111, v110
	v_div_fmas_f32 v110, v128, v145, v149
	s_mov_b64 vcc, s[4:5]
	v_pk_mul_f32 v[98:99], v[98:99], v[98:99]
	v_fmac_f32_e32 v155, v159, v148
	v_div_fixup_f32 v111, v110, v117, 1.0
	v_div_fmas_f32 v110, v129, v146, v150
	s_mov_b64 vcc, s[6:7]
	v_pk_mul_f32 v[100:101], v[100:101], v[100:101]
	v_add_f32_e32 v98, v98, v99
	v_fma_f32 v131, -v143, v155, v144
	v_div_fmas_f32 v112, v130, v147, v151
	s_mov_b64 vcc, s[8:9]
	v_add_f32_e32 v102, v104, v102
	v_add_f32_e32 v98, v100, v98
	v_div_fixup_f32 v110, v110, v116, 1.0
	v_div_fixup_f32 v113, v112, v125, 1.0
	v_div_fmas_f32 v112, v131, v148, v155
	v_add_f32_e32 v102, v105, v102
	v_add_f32_e32 v117, v101, v98
	v_div_fixup_f32 v112, v112, v124, 1.0
	v_add_f32_e32 v116, v132, v102
	s_waitcnt lgkmcnt(0)
	v_mov_b32_e32 v114, v226
	v_mov_b32_e32 v115, v227
	v_mov_b32_e32 v106, v216
	v_mov_b32_e32 v107, v217
	v_mov_b32_e32 v108, v218
	v_mov_b32_e32 v109, v219
	v_lshlrev_b32_e32 v98, 16, v114
	v_and_b32_e32 v99, 0xffff0000, v114
	v_lshlrev_b32_e32 v102, 16, v115
	v_and_b32_e32 v103, 0xffff0000, v115
	v_pk_fma_f32 v[100:101], v[110:111], v[98:99], v[106:107]
	v_pk_fma_f32 v[102:103], v[112:113], v[102:103], v[108:109]
	v_pk_mul_f32 v[98:99], v[100:101], v[100:101]
	v_pk_mul_f32 v[104:105], v[102:103], v[102:103]
	v_add_f32_e32 v98, v98, v99
	v_add_f32_e32 v98, v104, v98
	v_add_f32_e32 v106, v116, v117
	v_add_f32_e32 v98, v105, v98
	v_add_f32_e32 v98, v106, v98
	ds_bpermute_b32 v99, v126, v98
	global_store_dwordx4 v[120:121], v[100:103], off offset:192
	s_waitcnt lgkmcnt(0)
	v_add_f32_e32 v98, v98, v99
	ds_bpermute_b32 v99, v127, v98
	v_cvt_pk_bf16_f32 v100, v100, v101
	v_cvt_pk_bf16_f32 v101, v102, v103
	global_store_dwordx2 v[122:123], v[100:101], off offset:96
	s_and_saveexec_b64 s[4:5], s[0:1]
	s_cbranch_execz .LBB0_626
	s_waitcnt lgkmcnt(0)
	v_add_f32_e32 v100, v98, v99
	v_lshl_add_u64 v[98:99], v[118:119], 2, s[20:21]
	global_atomic_add_f32 v[98:99], v100, off
.LBB0_626:
	s_or_b64 exec, exec, s[4:5]
	v_or_b32_e32 v102, 32, v140
	v_mov_b32_e32 v103, v141
	s_waitcnt lgkmcnt(0)
	v_lshl_add_u64 v[98:99], v[102:103], 2, s[18:19]
	s_mov_b32 s99, 0
	s_mov_b32 s98, 0x30000
	v_lshl_add_u64 v[236:237], v[230:231], 0, s[98:99]
	global_load_dwordx4 v[204:207], v[236:237], off
	global_load_dwordx4 v[208:211], v[236:237], off offset:64
	global_load_dwordx4 v[212:215], v[236:237], off offset:128
	global_load_dwordx4 v[216:219], v[236:237], off offset:192
	s_mov_b32 s98, 0x18000
	v_lshl_add_u64 v[236:237], v[232:233], 0, s[98:99]
	global_load_dwordx2 v[220:221], v[236:237], off
	global_load_dwordx2 v[222:223], v[236:237], off offset:32
	global_load_dwordx2 v[224:225], v[236:237], off offset:64
	global_load_dwordx2 v[226:227], v[236:237], off offset:96
	s_mov_b32 s98, 0xc0
	v_lshl_add_u64 v[236:237], v[234:235], 0, s[98:99]
	global_load_dword v229, v[236:237], off
	v_lshlrev_b64 v[98:99], 11, v[102:103]
	v_lshl_add_u64 v[100:101], s[14:15], 0, v[98:99]
	v_mov_b32_e32 v143, v139
	v_lshl_add_u64 v[108:109], v[100:101], 0, v[142:143]
	v_lshlrev_b64 v[100:101], 12, v[102:103]
	v_lshl_add_u64 v[100:101], v[134:135], 0, v[100:101]
	s_nop 0
	v_lshl_add_u64 v[98:99], s[16:17], 0, v[98:99]
	v_lshl_add_u64 v[104:105], v[100:101], 0, v[138:139]
	v_lshl_add_u64 v[106:107], v[98:99], 0, v[142:143]
	s_nop 0
	s_waitcnt vmcnt(17) lgkmcnt(0)
	v_mov_b32_e32 v112, v228
	v_mov_b32_e32 v110, v196
	v_mov_b32_e32 v111, v197
	v_mov_b32_e32 v98, v180
	v_mov_b32_e32 v99, v181
	v_mov_b32_e32 v100, v182
	v_mov_b32_e32 v101, v183
	v_fmamk_f32 v112, v112, 0x3a800000, v153
	v_mul_f32_e32 v113, 0x4b800000, v112
	v_cmp_gt_f32_e32 vcc, s56, v112
	s_nop 1
	v_cndmask_b32_e32 v113, v112, v113, vcc
	v_rsq_f32_e32 v114, v113
	v_lshlrev_b32_e32 v112, 16, v110
	v_and_b32_e32 v113, 0xffff0000, v110
	v_lshlrev_b32_e32 v110, 16, v111
	v_mul_f32_e32 v115, 0x45800000, v114
	v_cndmask_b32_e32 v114, v114, v115, vcc
	v_mul_f32_e32 v94, v94, v114
	v_mul_f32_e32 v95, v95, v114
	v_mul_f32_e32 v94, 0xbfb8aa3b, v94
	v_mul_f32_e32 v95, 0xbfb8aa3b, v95
	v_mul_f32_e32 v96, v96, v114
	v_mul_f32_e32 v97, v97, v114
	v_exp_f32_e32 v94, v94
	v_exp_f32_e32 v95, v95
	v_mul_f32_e32 v96, 0xbfb8aa3b, v96
	v_mul_f32_e32 v97, 0xbfb8aa3b, v97
	v_exp_f32_e32 v96, v96
	v_exp_f32_e32 v97, v97
	v_mul_f32_e32 v115, v90, v114
	v_mul_f32_e32 v116, v91, v114
	v_pk_add_f32 v[90:91], v[94:95], 1.0 op_sel_hi:[1,0]
	v_pk_add_f32 v[96:97], v[96:97], 1.0 op_sel_hi:[1,0]
	v_div_scale_f32 v94, s[4:5], v91, v91, 1.0
	v_div_scale_f32 v117, s[4:5], v90, v90, 1.0
	v_rcp_f32_e32 v123, v94
	v_div_scale_f32 v119, s[6:7], v97, v97, 1.0
	v_rcp_f32_e32 v124, v117
	v_div_scale_f32 v121, s[8:9], v96, v96, 1.0
	v_rcp_f32_e32 v125, v119
	v_rcp_f32_e32 v128, v121
	v_fma_f32 v129, -v94, v123, 1.0
	v_div_scale_f32 v95, vcc, 1.0, v91, 1.0
	v_fma_f32 v130, -v117, v124, 1.0
	v_fmac_f32_e32 v123, v129, v123
	v_div_scale_f32 v118, s[4:5], 1.0, v90, 1.0
	v_fma_f32 v131, -v119, v125, 1.0
	v_fmac_f32_e32 v124, v130, v124
	v_mul_f32_e32 v129, v95, v123
	v_div_scale_f32 v120, s[6:7], 1.0, v97, 1.0
	v_fma_f32 v132, -v121, v128, 1.0
	v_fmac_f32_e32 v125, v131, v125
	v_mul_f32_e32 v130, v118, v124
	v_fma_f32 v133, -v94, v129, v95
	v_div_scale_f32 v122, s[8:9], 1.0, v96, 1.0
	v_fmac_f32_e32 v128, v132, v128
	v_mul_f32_e32 v131, v120, v125
	v_fma_f32 v144, -v117, v130, v118
	v_fmac_f32_e32 v129, v133, v123
	v_mul_f32_e32 v132, v122, v128
	v_fma_f32 v145, -v119, v131, v120
	v_fmac_f32_e32 v130, v144, v124
	v_fma_f32 v94, -v94, v129, v95
	v_fma_f32 v146, -v121, v132, v122
	v_fmac_f32_e32 v131, v145, v125
	v_fma_f32 v95, -v117, v130, v118
	v_div_fmas_f32 v94, v94, v123, v129
	s_mov_b64 vcc, s[4:5]
	v_fmac_f32_e32 v132, v146, v128
	v_fma_f32 v117, -v119, v131, v120
	v_div_fixup_f32 v91, v94, v91, 1.0
	v_div_fmas_f32 v94, v95, v124, v130
	s_mov_b64 vcc, s[6:7]
	v_fma_f32 v118, -v121, v132, v122
	v_div_fixup_f32 v90, v94, v90, 1.0
	v_div_fmas_f32 v117, v117, v125, v131
	s_mov_b64 vcc, s[8:9]
	v_pk_fma_f32 v[94:95], v[90:91], v[112:113], v[98:99]
	v_div_fmas_f32 v90, v118, v128, v132
	v_and_b32_e32 v111, 0xffff0000, v111
	v_div_fixup_f32 v91, v117, v97, 1.0
	v_div_fixup_f32 v90, v90, v96, 1.0
	v_pk_fma_f32 v[96:97], v[90:91], v[110:111], v[100:101]
	global_store_dwordx4 v[104:105], v[94:97], off
	v_cvt_pk_bf16_f32 v98, v94, v95
	v_cvt_pk_bf16_f32 v99, v96, v97
	s_nop 0
	v_mul_f32_e32 v92, v92, v114
	global_store_dwordx2 v[106:107], v[98:99], off
	s_nop 0
	v_mul_f32_e32 v93, v93, v114
	v_mul_f32_e32 v111, v87, v114
	v_mul_f32_e32 v117, v82, v114
	v_mul_f32_e32 v82, 0xbfb8aa3b, v115
	v_mul_f32_e32 v87, 0xbfb8aa3b, v116
	v_mul_f32_e32 v110, v86, v114
	v_mul_f32_e32 v112, v88, v114
	v_mul_f32_e32 v113, v89, v114
	v_mul_f32_e32 v88, 0xbfb8aa3b, v92
	v_mul_f32_e32 v89, 0xbfb8aa3b, v93
	v_exp_f32_e32 v86, v82
	v_exp_f32_e32 v87, v87
	v_exp_f32_e32 v88, v88
	v_exp_f32_e32 v89, v89
	v_mul_f32_e32 v115, v83, v114
	v_pk_add_f32 v[82:83], v[86:87], 1.0 op_sel_hi:[1,0]
	v_mul_f32_e32 v84, v84, v114
	v_pk_add_f32 v[86:87], v[88:89], 1.0 op_sel_hi:[1,0]
	v_div_scale_f32 v88, s[4:5], v83, v83, 1.0
	v_div_scale_f32 v92, s[4:5], v82, v82, 1.0
	v_rcp_f32_e32 v121, v88
	v_div_scale_f32 v116, s[6:7], v87, v87, 1.0
	v_rcp_f32_e32 v122, v92
	v_div_scale_f32 v119, s[8:9], v86, v86, 1.0
	v_rcp_f32_e32 v123, v116
	v_rcp_f32_e32 v124, v119
	v_fma_f32 v125, -v88, v121, 1.0
	v_div_scale_f32 v89, vcc, 1.0, v83, 1.0
	v_fma_f32 v128, -v92, v122, 1.0
	v_fmac_f32_e32 v121, v125, v121
	v_div_scale_f32 v93, s[4:5], 1.0, v82, 1.0
	v_fma_f32 v129, -v116, v123, 1.0
	v_fmac_f32_e32 v122, v128, v122
	v_mul_f32_e32 v125, v89, v121
	v_div_scale_f32 v118, s[6:7], 1.0, v87, 1.0
	v_fma_f32 v130, -v119, v124, 1.0
	v_fmac_f32_e32 v123, v129, v123
	v_mul_f32_e32 v128, v93, v122
	v_fma_f32 v131, -v88, v125, v89
	v_div_scale_f32 v120, s[8:9], 1.0, v86, 1.0
	v_fmac_f32_e32 v124, v130, v124
	v_mul_f32_e32 v129, v118, v123
	v_fma_f32 v132, -v92, v128, v93
	v_fmac_f32_e32 v125, v131, v121
	v_mul_f32_e32 v130, v120, v124
	v_fma_f32 v133, -v116, v129, v118
	v_fmac_f32_e32 v128, v132, v122
	v_fma_f32 v88, -v88, v125, v89
	v_fma_f32 v144, -v119, v130, v120
	v_fmac_f32_e32 v129, v133, v123
	v_fma_f32 v89, -v92, v128, v93
	v_div_fmas_f32 v88, v88, v121, v125
	s_mov_b64 vcc, s[4:5]
	v_fmac_f32_e32 v130, v144, v124
	v_fma_f32 v92, -v116, v129, v118
	v_div_fixup_f32 v83, v88, v83, 1.0
	v_div_fmas_f32 v88, v89, v122, v128
	s_mov_b64 vcc, s[6:7]
	v_fma_f32 v93, -v119, v130, v120
	v_div_fixup_f32 v82, v88, v82, 1.0
	v_div_fmas_f32 v88, v92, v123, v129
	s_mov_b64 vcc, s[8:9]
	v_div_fixup_f32 v89, v88, v87, 1.0
	v_div_fmas_f32 v87, v93, v124, v130
	v_div_fixup_f32 v88, v87, v86, 1.0
	v_mul_f32_e32 v85, v85, v114
	v_pk_mul_f32 v[94:95], v[94:95], v[94:95]
	s_waitcnt lgkmcnt(0)
	v_mov_b32_e32 v90, v198
	v_mov_b32_e32 v91, v199
	v_mov_b32_e32 v98, v184
	v_mov_b32_e32 v99, v185
	v_mov_b32_e32 v100, v186
	v_mov_b32_e32 v101, v187
	v_lshlrev_b32_e32 v86, 16, v90
	v_and_b32_e32 v87, 0xffff0000, v90
	v_lshlrev_b32_e32 v90, 16, v91
	v_and_b32_e32 v91, 0xffff0000, v91
	v_pk_fma_f32 v[86:87], v[82:83], v[86:87], v[98:99]
	v_pk_fma_f32 v[88:89], v[88:89], v[90:91], v[100:101]
	global_store_dwordx4 v[104:105], v[86:89], off offset:64
	v_cvt_pk_bf16_f32 v90, v86, v87
	v_cvt_pk_bf16_f32 v91, v88, v89
	s_nop 0
	v_mul_f32_e32 v98, 0xbfb8aa3b, v110
	global_store_dwordx2 v[106:107], v[90:91], off offset:32
	s_nop 0
	v_mul_f32_e32 v99, 0xbfb8aa3b, v111
	v_mul_f32_e32 v100, 0xbfb8aa3b, v112
	v_mul_f32_e32 v101, 0xbfb8aa3b, v113
	v_mul_f32_e32 v112, 0xbfb8aa3b, v84
	v_mul_f32_e32 v113, 0xbfb8aa3b, v85
	v_exp_f32_e32 v84, v98
	v_exp_f32_e32 v85, v99
	v_exp_f32_e32 v98, v100
	v_exp_f32_e32 v99, v101
	v_mul_f32_e32 v110, 0xbfb8aa3b, v117
	v_pk_add_f32 v[84:85], v[84:85], 1.0 op_sel_hi:[1,0]
	v_exp_f32_e32 v100, v110
	v_exp_f32_e32 v110, v112
	v_div_scale_f32 v112, s[4:5], v85, v85, 1.0
	v_pk_add_f32 v[98:99], v[98:99], 1.0 op_sel_hi:[1,0]
	v_div_scale_f32 v114, s[4:5], v84, v84, 1.0
	v_rcp_f32_e32 v120, v112
	v_div_scale_f32 v116, s[6:7], v99, v99, 1.0
	v_rcp_f32_e32 v121, v114
	v_div_scale_f32 v118, s[8:9], v98, v98, 1.0
	v_rcp_f32_e32 v122, v116
	v_rcp_f32_e32 v123, v118
	v_mul_f32_e32 v111, 0xbfb8aa3b, v115
	v_fma_f32 v124, -v112, v120, 1.0
	v_exp_f32_e32 v101, v111
	v_exp_f32_e32 v111, v113
	v_div_scale_f32 v113, vcc, 1.0, v85, 1.0
	v_fma_f32 v125, -v114, v121, 1.0
	v_fmac_f32_e32 v120, v124, v120
	v_div_scale_f32 v115, s[4:5], 1.0, v84, 1.0
	v_fma_f32 v128, -v116, v122, 1.0
	v_fmac_f32_e32 v121, v125, v121
	v_mul_f32_e32 v124, v113, v120
	v_div_scale_f32 v117, s[6:7], 1.0, v99, 1.0
	v_fma_f32 v129, -v118, v123, 1.0
	v_fmac_f32_e32 v122, v128, v122
	v_mul_f32_e32 v125, v115, v121
	v_fma_f32 v130, -v112, v124, v113
	v_div_scale_f32 v119, s[8:9], 1.0, v98, 1.0
	v_fmac_f32_e32 v123, v129, v123
	v_mul_f32_e32 v128, v117, v122
	v_fma_f32 v131, -v114, v125, v115
	v_fmac_f32_e32 v124, v130, v120
	v_mul_f32_e32 v129, v119, v123
	v_fma_f32 v132, -v116, v128, v117
	v_fmac_f32_e32 v125, v131, v121
	v_fma_f32 v112, -v112, v124, v113
	v_fma_f32 v133, -v118, v129, v119
	v_fmac_f32_e32 v128, v132, v122
	v_fma_f32 v113, -v114, v125, v115
	v_div_fmas_f32 v112, v112, v120, v124
	s_mov_b64 vcc, s[4:5]
	v_fmac_f32_e32 v129, v133, v123
	v_fma_f32 v114, -v116, v128, v117
	v_div_fixup_f32 v85, v112, v85, 1.0
	v_div_fmas_f32 v112, v113, v121, v125
	s_mov_b64 vcc, s[6:7]
	v_fma_f32 v115, -v118, v129, v119
	v_div_fixup_f32 v84, v112, v84, 1.0
	v_div_fmas_f32 v112, v114, v122, v128
	s_mov_b64 vcc, s[8:9]
	v_div_fixup_f32 v99, v112, v99, 1.0
	v_div_fmas_f32 v112, v115, v123, v129
	v_div_fixup_f32 v98, v112, v98, 1.0
	v_pk_add_f32 v[100:101], v[100:101], 1.0 op_sel_hi:[1,0]
	v_pk_mul_f32 v[86:87], v[86:87], v[86:87]
	v_pk_mul_f32 v[88:89], v[88:89], v[88:89]
	v_add_f32_e32 v86, v86, v87
	s_waitcnt lgkmcnt(0)
	v_mov_b32_e32 v82, v200
	v_mov_b32_e32 v83, v201
	v_mov_b32_e32 v90, v188
	v_mov_b32_e32 v91, v189
	v_mov_b32_e32 v92, v190
	v_mov_b32_e32 v93, v191
	v_lshlrev_b32_e32 v112, 16, v82
	v_and_b32_e32 v113, 0xffff0000, v82
	v_lshlrev_b32_e32 v114, 16, v83
	v_and_b32_e32 v115, 0xffff0000, v83
	v_pk_fma_f32 v[82:83], v[84:85], v[112:113], v[90:91]
	v_pk_fma_f32 v[84:85], v[98:99], v[114:115], v[92:93]
	global_store_dwordx4 v[104:105], v[82:85], off offset:128
	v_cvt_pk_bf16_f32 v90, v82, v83
	v_cvt_pk_bf16_f32 v91, v84, v85
	s_nop 0
	v_pk_add_f32 v[108:109], v[110:111], 1.0 op_sel_hi:[1,0]
	global_store_dwordx2 v[106:107], v[90:91], off offset:64
	s_nop 0
	v_div_scale_f32 v110, s[4:5], v101, v101, 1.0
	v_div_scale_f32 v112, s[4:5], v100, v100, 1.0
	v_div_scale_f32 v114, s[6:7], v109, v109, 1.0
	v_rcp_f32_e32 v118, v110
	v_rcp_f32_e32 v119, v112
	v_rcp_f32_e32 v120, v114
	v_div_scale_f32 v116, s[8:9], v108, v108, 1.0
	v_rcp_f32_e32 v121, v116
	v_fma_f32 v122, -v110, v118, 1.0
	v_fma_f32 v123, -v112, v119, 1.0
	v_fma_f32 v124, -v114, v120, 1.0
	v_div_scale_f32 v111, vcc, 1.0, v101, 1.0
	v_div_scale_f32 v113, s[4:5], 1.0, v100, 1.0
	v_div_scale_f32 v115, s[6:7], 1.0, v109, 1.0
	v_fmac_f32_e32 v118, v122, v118
	v_fmac_f32_e32 v119, v123, v119
	v_fmac_f32_e32 v120, v124, v120
	v_mul_f32_e32 v122, v111, v118
	v_mul_f32_e32 v123, v113, v119
	v_mul_f32_e32 v124, v115, v120
	v_fma_f32 v128, -v110, v122, v111
	v_fma_f32 v129, -v112, v123, v113
	v_fma_f32 v130, -v114, v124, v115
	v_fma_f32 v125, -v116, v121, 1.0
	v_fmac_f32_e32 v122, v128, v118
	v_fmac_f32_e32 v123, v129, v119
	v_fmac_f32_e32 v124, v130, v120
	v_div_scale_f32 v117, s[8:9], 1.0, v108, 1.0
	v_fmac_f32_e32 v121, v125, v121
	v_fma_f32 v110, -v110, v122, v111
	v_fma_f32 v111, -v112, v123, v113
	v_fma_f32 v112, -v114, v124, v115
	v_add_f32_e32 v114, v94, v95
	v_pk_mul_f32 v[94:95], v[96:97], v[96:97]
	v_mul_f32_e32 v125, v117, v121
	v_add_f32_e32 v94, v94, v114
	v_fma_f32 v131, -v116, v125, v117
	v_add_f32_e32 v114, v95, v94
	v_div_fmas_f32 v94, v110, v118, v122
	s_mov_b64 vcc, s[4:5]
	v_pk_mul_f32 v[82:83], v[82:83], v[82:83]
	v_fmac_f32_e32 v125, v131, v121
	v_div_fixup_f32 v95, v94, v101, 1.0
	v_div_fmas_f32 v94, v111, v119, v123
	s_mov_b64 vcc, s[6:7]
	v_pk_mul_f32 v[84:85], v[84:85], v[84:85]
	v_add_f32_e32 v82, v82, v83
	v_fma_f32 v113, -v116, v125, v117
	v_div_fmas_f32 v96, v112, v120, v124
	s_mov_b64 vcc, s[8:9]
	v_add_f32_e32 v86, v88, v86
	v_add_f32_e32 v82, v84, v82
	v_div_fixup_f32 v94, v94, v100, 1.0
	v_div_fixup_f32 v97, v96, v109, 1.0
	v_div_fmas_f32 v96, v113, v121, v125
	v_add_f32_e32 v86, v89, v86
	v_add_f32_e32 v101, v85, v82
	v_div_fixup_f32 v96, v96, v108, 1.0
	v_add_f32_e32 v100, v114, v86
	s_waitcnt lgkmcnt(0)
	v_mov_b32_e32 v98, v202
	v_mov_b32_e32 v99, v203
	v_mov_b32_e32 v90, v192
	v_mov_b32_e32 v91, v193
	v_mov_b32_e32 v92, v194
	v_mov_b32_e32 v93, v195
	v_lshlrev_b32_e32 v82, 16, v98
	v_and_b32_e32 v83, 0xffff0000, v98
	v_lshlrev_b32_e32 v86, 16, v99
	v_and_b32_e32 v87, 0xffff0000, v99
	v_pk_fma_f32 v[84:85], v[94:95], v[82:83], v[90:91]
	v_pk_fma_f32 v[86:87], v[96:97], v[86:87], v[92:93]
	v_pk_mul_f32 v[82:83], v[84:85], v[84:85]
	v_pk_mul_f32 v[88:89], v[86:87], v[86:87]
	v_add_f32_e32 v82, v82, v83
	v_add_f32_e32 v82, v88, v82
	v_add_f32_e32 v90, v100, v101
	v_add_f32_e32 v82, v89, v82
	v_add_f32_e32 v82, v90, v82
	ds_bpermute_b32 v83, v126, v82
	global_store_dwordx4 v[104:105], v[84:87], off offset:192
	s_waitcnt lgkmcnt(0)
	v_add_f32_e32 v82, v82, v83
	ds_bpermute_b32 v83, v127, v82
	v_cvt_pk_bf16_f32 v84, v84, v85
	v_cvt_pk_bf16_f32 v85, v86, v87
	global_store_dwordx2 v[106:107], v[84:85], off offset:96
	s_and_saveexec_b64 s[4:5], s[0:1]
	s_cbranch_execz .LBB0_628
	s_waitcnt lgkmcnt(0)
	v_add_f32_e32 v84, v82, v83
	v_lshl_add_u64 v[82:83], v[102:103], 2, s[20:21]
	global_atomic_add_f32 v[82:83], v84, off
.LBB0_628:
	s_or_b64 exec, exec, s[4:5]
	v_or_b32_e32 v86, 48, v140
	v_mov_b32_e32 v87, v141
	s_waitcnt lgkmcnt(0)
	v_lshl_add_u64 v[82:83], v[86:87], 2, s[18:19]
	s_mov_b32 s99, 0
	s_mov_b32 s98, 0x40000
	v_lshl_add_u64 v[236:237], v[230:231], 0, s[98:99]
	global_load_dwordx4 v[180:183], v[236:237], off
	global_load_dwordx4 v[184:187], v[236:237], off offset:64
	global_load_dwordx4 v[188:191], v[236:237], off offset:128
	global_load_dwordx4 v[192:195], v[236:237], off offset:192
	s_mov_b32 s98, 0x20000
	v_lshl_add_u64 v[236:237], v[232:233], 0, s[98:99]
	global_load_dwordx2 v[196:197], v[236:237], off
	global_load_dwordx2 v[198:199], v[236:237], off offset:32
	global_load_dwordx2 v[200:201], v[236:237], off offset:64
	global_load_dwordx2 v[202:203], v[236:237], off offset:96
	s_mov_b32 s98, 0x100
	v_lshl_add_u64 v[236:237], v[234:235], 0, s[98:99]
	global_load_dword v228, v[236:237], off
	v_lshlrev_b64 v[82:83], 11, v[86:87]
	v_lshl_add_u64 v[84:85], s[14:15], 0, v[82:83]
	v_lshl_add_u64 v[92:93], v[84:85], 0, v[142:143]
	v_lshlrev_b64 v[84:85], 12, v[86:87]
	v_lshl_add_u64 v[84:85], v[134:135], 0, v[84:85]
	s_nop 0
	v_lshl_add_u64 v[82:83], s[16:17], 0, v[82:83]
	v_lshl_add_u64 v[88:89], v[84:85], 0, v[138:139]
	v_lshl_add_u64 v[90:91], v[82:83], 0, v[142:143]
	s_nop 0
	s_waitcnt vmcnt(17) lgkmcnt(0)
	v_mov_b32_e32 v96, v229
	v_mov_b32_e32 v94, v220
	v_mov_b32_e32 v95, v221
	v_mov_b32_e32 v82, v204
	v_mov_b32_e32 v83, v205
	v_mov_b32_e32 v84, v206
	v_mov_b32_e32 v85, v207
	v_fmamk_f32 v96, v96, 0x3a800000, v153
	v_mul_f32_e32 v97, 0x4b800000, v96
	v_cmp_gt_f32_e32 vcc, s56, v96
	s_nop 1
	v_cndmask_b32_e32 v97, v96, v97, vcc
	v_rsq_f32_e32 v98, v97
	v_lshlrev_b32_e32 v96, 16, v94
	v_and_b32_e32 v97, 0xffff0000, v94
	v_lshlrev_b32_e32 v94, 16, v95
	v_mul_f32_e32 v99, 0x45800000, v98
	v_cndmask_b32_e32 v98, v98, v99, vcc
	v_mul_f32_e32 v78, v78, v98
	v_mul_f32_e32 v79, v79, v98
	v_mul_f32_e32 v78, 0xbfb8aa3b, v78
	v_mul_f32_e32 v79, 0xbfb8aa3b, v79
	v_mul_f32_e32 v80, v80, v98
	v_mul_f32_e32 v81, v81, v98
	v_exp_f32_e32 v78, v78
	v_exp_f32_e32 v79, v79
	v_mul_f32_e32 v80, 0xbfb8aa3b, v80
	v_mul_f32_e32 v81, 0xbfb8aa3b, v81
	v_exp_f32_e32 v80, v80
	v_exp_f32_e32 v81, v81
	v_mul_f32_e32 v99, v74, v98
	v_mul_f32_e32 v100, v75, v98
	v_pk_add_f32 v[74:75], v[78:79], 1.0 op_sel_hi:[1,0]
	v_pk_add_f32 v[80:81], v[80:81], 1.0 op_sel_hi:[1,0]
	v_div_scale_f32 v78, s[4:5], v75, v75, 1.0
	v_div_scale_f32 v101, s[4:5], v74, v74, 1.0
	v_rcp_f32_e32 v107, v78
	v_div_scale_f32 v103, s[6:7], v81, v81, 1.0
	v_rcp_f32_e32 v108, v101
	v_div_scale_f32 v105, s[8:9], v80, v80, 1.0
	v_rcp_f32_e32 v109, v103
	v_rcp_f32_e32 v110, v105
	v_fma_f32 v111, -v78, v107, 1.0
	v_div_scale_f32 v79, vcc, 1.0, v75, 1.0
	v_fma_f32 v112, -v101, v108, 1.0
	v_fmac_f32_e32 v107, v111, v107
	v_div_scale_f32 v102, s[4:5], 1.0, v74, 1.0
	v_fma_f32 v113, -v103, v109, 1.0
	v_fmac_f32_e32 v108, v112, v108
	v_mul_f32_e32 v111, v79, v107
	v_div_scale_f32 v104, s[6:7], 1.0, v81, 1.0
	v_fma_f32 v114, -v105, v110, 1.0
	v_fmac_f32_e32 v109, v113, v109
	v_mul_f32_e32 v112, v102, v108
	v_fma_f32 v115, -v78, v111, v79
	v_div_scale_f32 v106, s[8:9], 1.0, v80, 1.0
	v_fmac_f32_e32 v110, v114, v110
	v_mul_f32_e32 v113, v104, v109
	v_fma_f32 v116, -v101, v112, v102
	v_fmac_f32_e32 v111, v115, v107
	v_mul_f32_e32 v114, v106, v110
	v_fma_f32 v117, -v103, v113, v104
	v_fmac_f32_e32 v112, v116, v108
	v_fma_f32 v78, -v78, v111, v79
	v_fma_f32 v118, -v105, v114, v106
	v_fmac_f32_e32 v113, v117, v109
	v_fma_f32 v79, -v101, v112, v102
	v_div_fmas_f32 v78, v78, v107, v111
	s_mov_b64 vcc, s[4:5]
	v_fmac_f32_e32 v114, v118, v110
	v_fma_f32 v101, -v103, v113, v104
	v_div_fixup_f32 v75, v78, v75, 1.0
	v_div_fmas_f32 v78, v79, v108, v112
	s_mov_b64 vcc, s[6:7]
	v_fma_f32 v102, -v105, v114, v106
	v_div_fixup_f32 v74, v78, v74, 1.0
	v_div_fmas_f32 v101, v101, v109, v113
	s_mov_b64 vcc, s[8:9]
	v_pk_fma_f32 v[78:79], v[74:75], v[96:97], v[82:83]
	v_div_fmas_f32 v74, v102, v110, v114
	v_and_b32_e32 v95, 0xffff0000, v95
	v_div_fixup_f32 v75, v101, v81, 1.0
	v_div_fixup_f32 v74, v74, v80, 1.0
	v_pk_fma_f32 v[80:81], v[74:75], v[94:95], v[84:85]
	global_store_dwordx4 v[88:89], v[78:81], off
	v_cvt_pk_bf16_f32 v82, v78, v79
	v_cvt_pk_bf16_f32 v83, v80, v81
	s_nop 0
	v_mul_f32_e32 v76, v76, v98
	global_store_dwordx2 v[90:91], v[82:83], off
	s_nop 0
	v_mul_f32_e32 v77, v77, v98
	v_mul_f32_e32 v95, v71, v98
	v_mul_f32_e32 v101, v66, v98
	v_mul_f32_e32 v66, 0xbfb8aa3b, v99
	v_mul_f32_e32 v71, 0xbfb8aa3b, v100
	v_mul_f32_e32 v94, v70, v98
	v_mul_f32_e32 v96, v72, v98
	v_mul_f32_e32 v97, v73, v98
	v_mul_f32_e32 v72, 0xbfb8aa3b, v76
	v_mul_f32_e32 v73, 0xbfb8aa3b, v77
	v_exp_f32_e32 v70, v66
	v_exp_f32_e32 v71, v71
	v_exp_f32_e32 v72, v72
	v_exp_f32_e32 v73, v73
	v_mul_f32_e32 v99, v67, v98
	v_pk_add_f32 v[66:67], v[70:71], 1.0 op_sel_hi:[1,0]
	v_mul_f32_e32 v68, v68, v98
	v_pk_add_f32 v[70:71], v[72:73], 1.0 op_sel_hi:[1,0]
	v_div_scale_f32 v72, s[4:5], v67, v67, 1.0
	v_div_scale_f32 v76, s[4:5], v66, v66, 1.0
	v_rcp_f32_e32 v105, v72
	v_div_scale_f32 v100, s[6:7], v71, v71, 1.0
	v_rcp_f32_e32 v106, v76
	v_div_scale_f32 v103, s[8:9], v70, v70, 1.0
	v_rcp_f32_e32 v107, v100
	v_rcp_f32_e32 v108, v103
	v_fma_f32 v109, -v72, v105, 1.0
	v_div_scale_f32 v73, vcc, 1.0, v67, 1.0
	v_fma_f32 v110, -v76, v106, 1.0
	v_fmac_f32_e32 v105, v109, v105
	v_div_scale_f32 v77, s[4:5], 1.0, v66, 1.0
	v_fma_f32 v111, -v100, v107, 1.0
	v_fmac_f32_e32 v106, v110, v106
	v_mul_f32_e32 v109, v73, v105
	v_div_scale_f32 v102, s[6:7], 1.0, v71, 1.0
	v_fma_f32 v112, -v103, v108, 1.0
	v_fmac_f32_e32 v107, v111, v107
	v_mul_f32_e32 v110, v77, v106
	v_fma_f32 v113, -v72, v109, v73
	v_div_scale_f32 v104, s[8:9], 1.0, v70, 1.0
	v_fmac_f32_e32 v108, v112, v108
	v_mul_f32_e32 v111, v102, v107
	v_fma_f32 v114, -v76, v110, v77
	v_fmac_f32_e32 v109, v113, v105
	v_mul_f32_e32 v112, v104, v108
	v_fma_f32 v115, -v100, v111, v102
	v_fmac_f32_e32 v110, v114, v106
	v_fma_f32 v72, -v72, v109, v73
	v_fma_f32 v116, -v103, v112, v104
	v_fmac_f32_e32 v111, v115, v107
	v_fma_f32 v73, -v76, v110, v77
	v_div_fmas_f32 v72, v72, v105, v109
	s_mov_b64 vcc, s[4:5]
	v_fmac_f32_e32 v112, v116, v108
	v_fma_f32 v76, -v100, v111, v102
	v_div_fixup_f32 v67, v72, v67, 1.0
	v_div_fmas_f32 v72, v73, v106, v110
	s_mov_b64 vcc, s[6:7]
	v_fma_f32 v77, -v103, v112, v104
	v_div_fixup_f32 v66, v72, v66, 1.0
	v_div_fmas_f32 v72, v76, v107, v111
	s_mov_b64 vcc, s[8:9]
	v_div_fixup_f32 v73, v72, v71, 1.0
	v_div_fmas_f32 v71, v77, v108, v112
	v_div_fixup_f32 v72, v71, v70, 1.0
	v_mul_f32_e32 v69, v69, v98
	v_pk_mul_f32 v[78:79], v[78:79], v[78:79]
	s_waitcnt lgkmcnt(0)
	v_mov_b32_e32 v74, v222
	v_mov_b32_e32 v75, v223
	v_mov_b32_e32 v82, v208
	v_mov_b32_e32 v83, v209
	v_mov_b32_e32 v84, v210
	v_mov_b32_e32 v85, v211
	v_lshlrev_b32_e32 v70, 16, v74
	v_and_b32_e32 v71, 0xffff0000, v74
	v_lshlrev_b32_e32 v74, 16, v75
	v_and_b32_e32 v75, 0xffff0000, v75
	v_pk_fma_f32 v[70:71], v[66:67], v[70:71], v[82:83]
	v_pk_fma_f32 v[72:73], v[72:73], v[74:75], v[84:85]
	global_store_dwordx4 v[88:89], v[70:73], off offset:64
	v_cvt_pk_bf16_f32 v74, v70, v71
	v_cvt_pk_bf16_f32 v75, v72, v73
	s_nop 0
	v_mul_f32_e32 v82, 0xbfb8aa3b, v94
	global_store_dwordx2 v[90:91], v[74:75], off offset:32
	s_nop 0
	v_mul_f32_e32 v83, 0xbfb8aa3b, v95
	v_mul_f32_e32 v84, 0xbfb8aa3b, v96
	v_mul_f32_e32 v85, 0xbfb8aa3b, v97
	v_mul_f32_e32 v96, 0xbfb8aa3b, v68
	v_mul_f32_e32 v97, 0xbfb8aa3b, v69
	v_exp_f32_e32 v68, v82
	v_exp_f32_e32 v69, v83
	v_exp_f32_e32 v82, v84
	v_exp_f32_e32 v83, v85
	v_mul_f32_e32 v94, 0xbfb8aa3b, v101
	v_pk_add_f32 v[68:69], v[68:69], 1.0 op_sel_hi:[1,0]
	v_exp_f32_e32 v84, v94
	v_exp_f32_e32 v94, v96
	v_div_scale_f32 v96, s[4:5], v69, v69, 1.0
	v_pk_add_f32 v[82:83], v[82:83], 1.0 op_sel_hi:[1,0]
	v_div_scale_f32 v98, s[4:5], v68, v68, 1.0
	v_rcp_f32_e32 v104, v96
	v_div_scale_f32 v100, s[6:7], v83, v83, 1.0
	v_rcp_f32_e32 v105, v98
	v_div_scale_f32 v102, s[8:9], v82, v82, 1.0
	v_rcp_f32_e32 v106, v100
	v_rcp_f32_e32 v107, v102
	v_mul_f32_e32 v95, 0xbfb8aa3b, v99
	v_fma_f32 v108, -v96, v104, 1.0
	v_exp_f32_e32 v85, v95
	v_exp_f32_e32 v95, v97
	v_div_scale_f32 v97, vcc, 1.0, v69, 1.0
	v_fma_f32 v109, -v98, v105, 1.0
	v_fmac_f32_e32 v104, v108, v104
	v_div_scale_f32 v99, s[4:5], 1.0, v68, 1.0
	v_fma_f32 v110, -v100, v106, 1.0
	v_fmac_f32_e32 v105, v109, v105
	v_mul_f32_e32 v108, v97, v104
	v_div_scale_f32 v101, s[6:7], 1.0, v83, 1.0
	v_fma_f32 v111, -v102, v107, 1.0
	v_fmac_f32_e32 v106, v110, v106
	v_mul_f32_e32 v109, v99, v105
	v_fma_f32 v112, -v96, v108, v97
	v_div_scale_f32 v103, s[8:9], 1.0, v82, 1.0
	v_fmac_f32_e32 v107, v111, v107
	v_mul_f32_e32 v110, v101, v106
	v_fma_f32 v113, -v98, v109, v99
	v_fmac_f32_e32 v108, v112, v104
	v_mul_f32_e32 v111, v103, v107
	v_fma_f32 v114, -v100, v110, v101
	v_fmac_f32_e32 v109, v113, v105
	v_fma_f32 v96, -v96, v108, v97
	v_fma_f32 v115, -v102, v111, v103
	v_fmac_f32_e32 v110, v114, v106
	v_fma_f32 v97, -v98, v109, v99
	v_div_fmas_f32 v96, v96, v104, v108
	s_mov_b64 vcc, s[4:5]
	v_fmac_f32_e32 v111, v115, v107
	v_fma_f32 v98, -v100, v110, v101
	v_div_fixup_f32 v69, v96, v69, 1.0
	v_div_fmas_f32 v96, v97, v105, v109
	s_mov_b64 vcc, s[6:7]
	v_fma_f32 v99, -v102, v111, v103
	v_div_fixup_f32 v68, v96, v68, 1.0
	v_div_fmas_f32 v96, v98, v106, v110
	s_mov_b64 vcc, s[8:9]
	v_div_fixup_f32 v83, v96, v83, 1.0
	v_div_fmas_f32 v96, v99, v107, v111
	v_div_fixup_f32 v82, v96, v82, 1.0
	v_pk_add_f32 v[84:85], v[84:85], 1.0 op_sel_hi:[1,0]
	v_pk_mul_f32 v[70:71], v[70:71], v[70:71]
	v_pk_mul_f32 v[72:73], v[72:73], v[72:73]
	v_add_f32_e32 v70, v70, v71
	s_waitcnt lgkmcnt(0)
	v_mov_b32_e32 v66, v224
	v_mov_b32_e32 v67, v225
	v_mov_b32_e32 v74, v212
	v_mov_b32_e32 v75, v213
	v_mov_b32_e32 v76, v214
	v_mov_b32_e32 v77, v215
	v_lshlrev_b32_e32 v96, 16, v66
	v_and_b32_e32 v97, 0xffff0000, v66
	v_lshlrev_b32_e32 v98, 16, v67
	v_and_b32_e32 v99, 0xffff0000, v67
	v_pk_fma_f32 v[66:67], v[68:69], v[96:97], v[74:75]
	v_pk_fma_f32 v[68:69], v[82:83], v[98:99], v[76:77]
	global_store_dwordx4 v[88:89], v[66:69], off offset:128
	v_cvt_pk_bf16_f32 v74, v66, v67
	v_cvt_pk_bf16_f32 v75, v68, v69
	s_nop 0
	v_pk_add_f32 v[92:93], v[94:95], 1.0 op_sel_hi:[1,0]
	global_store_dwordx2 v[90:91], v[74:75], off offset:64
	s_nop 0
	v_div_scale_f32 v94, s[4:5], v85, v85, 1.0
	v_div_scale_f32 v96, s[4:5], v84, v84, 1.0
	v_div_scale_f32 v98, s[6:7], v93, v93, 1.0
	v_rcp_f32_e32 v102, v94
	v_rcp_f32_e32 v103, v96
	v_rcp_f32_e32 v104, v98
	v_div_scale_f32 v100, s[8:9], v92, v92, 1.0
	v_rcp_f32_e32 v105, v100
	v_fma_f32 v106, -v94, v102, 1.0
	v_fma_f32 v107, -v96, v103, 1.0
	v_fma_f32 v108, -v98, v104, 1.0
	v_div_scale_f32 v95, vcc, 1.0, v85, 1.0
	v_div_scale_f32 v97, s[4:5], 1.0, v84, 1.0
	v_div_scale_f32 v99, s[6:7], 1.0, v93, 1.0
	v_fmac_f32_e32 v102, v106, v102
	v_fmac_f32_e32 v103, v107, v103
	v_fmac_f32_e32 v104, v108, v104
	v_mul_f32_e32 v106, v95, v102
	v_mul_f32_e32 v107, v97, v103
	v_mul_f32_e32 v108, v99, v104
	v_fma_f32 v110, -v94, v106, v95
	v_fma_f32 v111, -v96, v107, v97
	v_fma_f32 v112, -v98, v108, v99
	v_fma_f32 v109, -v100, v105, 1.0
	v_fmac_f32_e32 v106, v110, v102
	v_fmac_f32_e32 v107, v111, v103
	v_fmac_f32_e32 v108, v112, v104
	v_div_scale_f32 v101, s[8:9], 1.0, v92, 1.0
	v_fmac_f32_e32 v105, v109, v105
	v_fma_f32 v94, -v94, v106, v95
	v_fma_f32 v95, -v96, v107, v97
	v_fma_f32 v96, -v98, v108, v99
	v_add_f32_e32 v98, v78, v79
	v_pk_mul_f32 v[78:79], v[80:81], v[80:81]
	v_mul_f32_e32 v109, v101, v105
	v_add_f32_e32 v78, v78, v98
	v_fma_f32 v113, -v100, v109, v101
	v_add_f32_e32 v98, v79, v78
	v_div_fmas_f32 v78, v94, v102, v106
	s_mov_b64 vcc, s[4:5]
	v_pk_mul_f32 v[66:67], v[66:67], v[66:67]
	v_fmac_f32_e32 v109, v113, v105
	v_div_fixup_f32 v79, v78, v85, 1.0
	v_div_fmas_f32 v78, v95, v103, v107
	s_mov_b64 vcc, s[6:7]
	v_pk_mul_f32 v[68:69], v[68:69], v[68:69]
	v_add_f32_e32 v66, v66, v67
	v_fma_f32 v97, -v100, v109, v101
	v_div_fmas_f32 v80, v96, v104, v108
	s_mov_b64 vcc, s[8:9]
	v_add_f32_e32 v70, v72, v70
	v_add_f32_e32 v66, v68, v66
	v_div_fixup_f32 v78, v78, v84, 1.0
	v_div_fixup_f32 v81, v80, v93, 1.0
	v_div_fmas_f32 v80, v97, v105, v109
	v_add_f32_e32 v70, v73, v70
	v_add_f32_e32 v85, v69, v66
	v_div_fixup_f32 v80, v80, v92, 1.0
	v_add_f32_e32 v84, v98, v70
	s_waitcnt lgkmcnt(0)
	v_mov_b32_e32 v82, v226
	v_mov_b32_e32 v83, v227
	v_mov_b32_e32 v74, v216
	v_mov_b32_e32 v75, v217
	v_mov_b32_e32 v76, v218
	v_mov_b32_e32 v77, v219
	v_lshlrev_b32_e32 v66, 16, v82
	v_and_b32_e32 v67, 0xffff0000, v82
	v_lshlrev_b32_e32 v70, 16, v83
	v_and_b32_e32 v71, 0xffff0000, v83
	v_pk_fma_f32 v[68:69], v[78:79], v[66:67], v[74:75]
	v_pk_fma_f32 v[70:71], v[80:81], v[70:71], v[76:77]
	v_pk_mul_f32 v[66:67], v[68:69], v[68:69]
	v_pk_mul_f32 v[72:73], v[70:71], v[70:71]
	v_add_f32_e32 v66, v66, v67
	v_add_f32_e32 v66, v72, v66
	v_add_f32_e32 v74, v84, v85
	v_add_f32_e32 v66, v73, v66
	v_add_f32_e32 v66, v74, v66
	ds_bpermute_b32 v67, v126, v66
	global_store_dwordx4 v[88:89], v[68:71], off offset:192
	s_waitcnt lgkmcnt(0)
	v_add_f32_e32 v66, v66, v67
	ds_bpermute_b32 v67, v127, v66
	v_cvt_pk_bf16_f32 v68, v68, v69
	v_cvt_pk_bf16_f32 v69, v70, v71
	global_store_dwordx2 v[90:91], v[68:69], off offset:96
	s_and_saveexec_b64 s[4:5], s[0:1]
	s_cbranch_execz .LBB0_630
	s_waitcnt lgkmcnt(0)
	v_add_f32_e32 v68, v66, v67
	v_lshl_add_u64 v[66:67], v[86:87], 2, s[20:21]
	global_atomic_add_f32 v[66:67], v68, off
.LBB0_630:
	s_or_b64 exec, exec, s[4:5]
	v_or_b32_e32 v70, 64, v140
	v_mov_b32_e32 v71, v141
	s_waitcnt lgkmcnt(0)
	v_lshl_add_u64 v[66:67], v[70:71], 2, s[18:19]
	s_mov_b32 s99, 0
	s_mov_b32 s98, 0x50000
	v_lshl_add_u64 v[236:237], v[230:231], 0, s[98:99]
	global_load_dwordx4 v[204:207], v[236:237], off
	global_load_dwordx4 v[208:211], v[236:237], off offset:64
	global_load_dwordx4 v[212:215], v[236:237], off offset:128
	global_load_dwordx4 v[216:219], v[236:237], off offset:192
	s_mov_b32 s98, 0x28000
	v_lshl_add_u64 v[236:237], v[232:233], 0, s[98:99]
	global_load_dwordx2 v[220:221], v[236:237], off
	global_load_dwordx2 v[222:223], v[236:237], off offset:32
	global_load_dwordx2 v[224:225], v[236:237], off offset:64
	global_load_dwordx2 v[226:227], v[236:237], off offset:96
	s_mov_b32 s98, 0x140
	v_lshl_add_u64 v[236:237], v[234:235], 0, s[98:99]
	global_load_dword v229, v[236:237], off
	v_lshlrev_b64 v[66:67], 11, v[70:71]
	v_lshl_add_u64 v[68:69], s[14:15], 0, v[66:67]
	v_mov_b32_e32 v143, v139
	v_lshl_add_u64 v[76:77], v[68:69], 0, v[142:143]
	v_lshlrev_b64 v[68:69], 12, v[70:71]
	v_lshl_add_u64 v[68:69], v[134:135], 0, v[68:69]
	s_nop 0
	v_lshl_add_u64 v[66:67], s[16:17], 0, v[66:67]
	v_lshl_add_u64 v[72:73], v[68:69], 0, v[138:139]
	v_lshl_add_u64 v[74:75], v[66:67], 0, v[142:143]
	s_nop 0
	s_waitcnt vmcnt(17) lgkmcnt(0)
	v_mov_b32_e32 v80, v228
	v_mov_b32_e32 v78, v196
	v_mov_b32_e32 v79, v197
	v_mov_b32_e32 v66, v180
	v_mov_b32_e32 v67, v181
	v_mov_b32_e32 v68, v182
	v_mov_b32_e32 v69, v183
	v_fmamk_f32 v80, v80, 0x3a800000, v153
	v_mul_f32_e32 v81, 0x4b800000, v80
	v_cmp_gt_f32_e32 vcc, s56, v80
	s_nop 1
	v_cndmask_b32_e32 v81, v80, v81, vcc
	v_rsq_f32_e32 v82, v81
	v_lshlrev_b32_e32 v80, 16, v78
	v_and_b32_e32 v81, 0xffff0000, v78
	v_lshlrev_b32_e32 v78, 16, v79
	v_mul_f32_e32 v83, 0x45800000, v82
	v_cndmask_b32_e32 v82, v82, v83, vcc
	v_mul_f32_e32 v62, v62, v82
	v_mul_f32_e32 v63, v63, v82
	v_mul_f32_e32 v62, 0xbfb8aa3b, v62
	v_mul_f32_e32 v63, 0xbfb8aa3b, v63
	v_mul_f32_e32 v64, v64, v82
	v_mul_f32_e32 v65, v65, v82
	v_exp_f32_e32 v62, v62
	v_exp_f32_e32 v63, v63
	v_mul_f32_e32 v64, 0xbfb8aa3b, v64
	v_mul_f32_e32 v65, 0xbfb8aa3b, v65
	v_exp_f32_e32 v64, v64
	v_exp_f32_e32 v65, v65
	v_mul_f32_e32 v83, v58, v82
	v_mul_f32_e32 v84, v59, v82
	v_pk_add_f32 v[58:59], v[62:63], 1.0 op_sel_hi:[1,0]
	v_pk_add_f32 v[64:65], v[64:65], 1.0 op_sel_hi:[1,0]
	v_div_scale_f32 v62, s[4:5], v59, v59, 1.0
	v_div_scale_f32 v85, s[4:5], v58, v58, 1.0
	v_rcp_f32_e32 v91, v62
	v_div_scale_f32 v87, s[6:7], v65, v65, 1.0
	v_rcp_f32_e32 v92, v85
	v_div_scale_f32 v89, s[8:9], v64, v64, 1.0
	v_rcp_f32_e32 v93, v87
	v_rcp_f32_e32 v94, v89
	v_fma_f32 v95, -v62, v91, 1.0
	v_div_scale_f32 v63, vcc, 1.0, v59, 1.0
	v_fma_f32 v96, -v85, v92, 1.0
	v_fmac_f32_e32 v91, v95, v91
	v_div_scale_f32 v86, s[4:5], 1.0, v58, 1.0
	v_fma_f32 v97, -v87, v93, 1.0
	v_fmac_f32_e32 v92, v96, v92
	v_mul_f32_e32 v95, v63, v91
	v_div_scale_f32 v88, s[6:7], 1.0, v65, 1.0
	v_fma_f32 v98, -v89, v94, 1.0
	v_fmac_f32_e32 v93, v97, v93
	v_mul_f32_e32 v96, v86, v92
	v_fma_f32 v99, -v62, v95, v63
	v_div_scale_f32 v90, s[8:9], 1.0, v64, 1.0
	v_fmac_f32_e32 v94, v98, v94
	v_mul_f32_e32 v97, v88, v93
	v_fma_f32 v100, -v85, v96, v86
	v_fmac_f32_e32 v95, v99, v91
	v_mul_f32_e32 v98, v90, v94
	v_fma_f32 v101, -v87, v97, v88
	v_fmac_f32_e32 v96, v100, v92
	v_fma_f32 v62, -v62, v95, v63
	v_fma_f32 v102, -v89, v98, v90
	v_fmac_f32_e32 v97, v101, v93
	v_fma_f32 v63, -v85, v96, v86
	v_div_fmas_f32 v62, v62, v91, v95
	s_mov_b64 vcc, s[4:5]
	v_fmac_f32_e32 v98, v102, v94
	v_fma_f32 v85, -v87, v97, v88
	v_div_fixup_f32 v59, v62, v59, 1.0
	v_div_fmas_f32 v62, v63, v92, v96
	s_mov_b64 vcc, s[6:7]
	v_fma_f32 v86, -v89, v98, v90
	v_div_fixup_f32 v58, v62, v58, 1.0
	v_div_fmas_f32 v85, v85, v93, v97
	s_mov_b64 vcc, s[8:9]
	v_pk_fma_f32 v[62:63], v[58:59], v[80:81], v[66:67]
	v_div_fmas_f32 v58, v86, v94, v98
	v_and_b32_e32 v79, 0xffff0000, v79
	v_div_fixup_f32 v59, v85, v65, 1.0
	v_div_fixup_f32 v58, v58, v64, 1.0
	v_pk_fma_f32 v[64:65], v[58:59], v[78:79], v[68:69]
	global_store_dwordx4 v[72:73], v[62:65], off
	v_cvt_pk_bf16_f32 v66, v62, v63
	v_cvt_pk_bf16_f32 v67, v64, v65
	s_nop 0
	v_mul_f32_e32 v60, v60, v82
	global_store_dwordx2 v[74:75], v[66:67], off
	s_nop 0
	v_mul_f32_e32 v61, v61, v82
	v_mul_f32_e32 v79, v55, v82
	v_mul_f32_e32 v85, v50, v82
	v_mul_f32_e32 v50, 0xbfb8aa3b, v83
	v_mul_f32_e32 v55, 0xbfb8aa3b, v84
	v_mul_f32_e32 v78, v54, v82
	v_mul_f32_e32 v80, v56, v82
	v_mul_f32_e32 v81, v57, v82
	v_mul_f32_e32 v56, 0xbfb8aa3b, v60
	v_mul_f32_e32 v57, 0xbfb8aa3b, v61
	v_exp_f32_e32 v54, v50
	v_exp_f32_e32 v55, v55
	v_exp_f32_e32 v56, v56
	v_exp_f32_e32 v57, v57
	v_mul_f32_e32 v83, v51, v82
	v_pk_add_f32 v[50:51], v[54:55], 1.0 op_sel_hi:[1,0]
	v_mul_f32_e32 v52, v52, v82
	v_pk_add_f32 v[54:55], v[56:57], 1.0 op_sel_hi:[1,0]
	v_div_scale_f32 v56, s[4:5], v51, v51, 1.0
	v_div_scale_f32 v60, s[4:5], v50, v50, 1.0
	v_rcp_f32_e32 v89, v56
	v_div_scale_f32 v84, s[6:7], v55, v55, 1.0
	v_rcp_f32_e32 v90, v60
	v_div_scale_f32 v87, s[8:9], v54, v54, 1.0
	v_rcp_f32_e32 v91, v84
	v_rcp_f32_e32 v92, v87
	v_fma_f32 v93, -v56, v89, 1.0
	v_div_scale_f32 v57, vcc, 1.0, v51, 1.0
	v_fma_f32 v94, -v60, v90, 1.0
	v_fmac_f32_e32 v89, v93, v89
	v_div_scale_f32 v61, s[4:5], 1.0, v50, 1.0
	v_fma_f32 v95, -v84, v91, 1.0
	v_fmac_f32_e32 v90, v94, v90
	v_mul_f32_e32 v93, v57, v89
	v_div_scale_f32 v86, s[6:7], 1.0, v55, 1.0
	v_fma_f32 v96, -v87, v92, 1.0
	v_fmac_f32_e32 v91, v95, v91
	v_mul_f32_e32 v94, v61, v90
	v_fma_f32 v97, -v56, v93, v57
	v_div_scale_f32 v88, s[8:9], 1.0, v54, 1.0
	v_fmac_f32_e32 v92, v96, v92
	v_mul_f32_e32 v95, v86, v91
	v_fma_f32 v98, -v60, v94, v61
	v_fmac_f32_e32 v93, v97, v89
	v_mul_f32_e32 v96, v88, v92
	v_fma_f32 v99, -v84, v95, v86
	v_fmac_f32_e32 v94, v98, v90
	v_fma_f32 v56, -v56, v93, v57
	v_fma_f32 v100, -v87, v96, v88
	v_fmac_f32_e32 v95, v99, v91
	v_fma_f32 v57, -v60, v94, v61
	v_div_fmas_f32 v56, v56, v89, v93
	s_mov_b64 vcc, s[4:5]
	v_fmac_f32_e32 v96, v100, v92
	v_fma_f32 v60, -v84, v95, v86
	v_div_fixup_f32 v51, v56, v51, 1.0
	v_div_fmas_f32 v56, v57, v90, v94
	s_mov_b64 vcc, s[6:7]
	v_fma_f32 v61, -v87, v96, v88
	v_div_fixup_f32 v50, v56, v50, 1.0
	v_div_fmas_f32 v56, v60, v91, v95
	s_mov_b64 vcc, s[8:9]
	v_div_fixup_f32 v57, v56, v55, 1.0
	v_div_fmas_f32 v55, v61, v92, v96
	v_div_fixup_f32 v56, v55, v54, 1.0
	v_mul_f32_e32 v53, v53, v82
	v_pk_mul_f32 v[62:63], v[62:63], v[62:63]
	s_waitcnt lgkmcnt(0)
	v_mov_b32_e32 v58, v198
	v_mov_b32_e32 v59, v199
	v_mov_b32_e32 v66, v184
	v_mov_b32_e32 v67, v185
	v_mov_b32_e32 v68, v186
	v_mov_b32_e32 v69, v187
	v_lshlrev_b32_e32 v54, 16, v58
	v_and_b32_e32 v55, 0xffff0000, v58
	v_lshlrev_b32_e32 v58, 16, v59
	v_and_b32_e32 v59, 0xffff0000, v59
	v_pk_fma_f32 v[54:55], v[50:51], v[54:55], v[66:67]
	v_pk_fma_f32 v[56:57], v[56:57], v[58:59], v[68:69]
	global_store_dwordx4 v[72:73], v[54:57], off offset:64
	v_cvt_pk_bf16_f32 v58, v54, v55
	v_cvt_pk_bf16_f32 v59, v56, v57
	s_nop 0
	v_mul_f32_e32 v66, 0xbfb8aa3b, v78
	global_store_dwordx2 v[74:75], v[58:59], off offset:32
	s_nop 0
	v_mul_f32_e32 v67, 0xbfb8aa3b, v79
	v_mul_f32_e32 v68, 0xbfb8aa3b, v80
	v_mul_f32_e32 v69, 0xbfb8aa3b, v81
	v_mul_f32_e32 v80, 0xbfb8aa3b, v52
	v_mul_f32_e32 v81, 0xbfb8aa3b, v53
	v_exp_f32_e32 v52, v66
	v_exp_f32_e32 v53, v67
	v_exp_f32_e32 v66, v68
	v_exp_f32_e32 v67, v69
	v_mul_f32_e32 v78, 0xbfb8aa3b, v85
	v_pk_add_f32 v[52:53], v[52:53], 1.0 op_sel_hi:[1,0]
	v_exp_f32_e32 v68, v78
	v_exp_f32_e32 v78, v80
	v_div_scale_f32 v80, s[4:5], v53, v53, 1.0
	v_pk_add_f32 v[66:67], v[66:67], 1.0 op_sel_hi:[1,0]
	v_div_scale_f32 v82, s[4:5], v52, v52, 1.0
	v_rcp_f32_e32 v88, v80
	v_div_scale_f32 v84, s[6:7], v67, v67, 1.0
	v_rcp_f32_e32 v89, v82
	v_div_scale_f32 v86, s[8:9], v66, v66, 1.0
	v_rcp_f32_e32 v90, v84
	v_rcp_f32_e32 v91, v86
	v_mul_f32_e32 v79, 0xbfb8aa3b, v83
	v_fma_f32 v92, -v80, v88, 1.0
	v_exp_f32_e32 v69, v79
	v_exp_f32_e32 v79, v81
	v_div_scale_f32 v81, vcc, 1.0, v53, 1.0
	v_fma_f32 v93, -v82, v89, 1.0
	v_fmac_f32_e32 v88, v92, v88
	v_div_scale_f32 v83, s[4:5], 1.0, v52, 1.0
	v_fma_f32 v94, -v84, v90, 1.0
	v_fmac_f32_e32 v89, v93, v89
	v_mul_f32_e32 v92, v81, v88
	v_div_scale_f32 v85, s[6:7], 1.0, v67, 1.0
	v_fma_f32 v95, -v86, v91, 1.0
	v_fmac_f32_e32 v90, v94, v90
	v_mul_f32_e32 v93, v83, v89
	v_fma_f32 v96, -v80, v92, v81
	v_div_scale_f32 v87, s[8:9], 1.0, v66, 1.0
	v_fmac_f32_e32 v91, v95, v91
	v_mul_f32_e32 v94, v85, v90
	v_fma_f32 v97, -v82, v93, v83
	v_fmac_f32_e32 v92, v96, v88
	v_mul_f32_e32 v95, v87, v91
	v_fma_f32 v98, -v84, v94, v85
	v_fmac_f32_e32 v93, v97, v89
	v_fma_f32 v80, -v80, v92, v81
	v_fma_f32 v99, -v86, v95, v87
	v_fmac_f32_e32 v94, v98, v90
	v_fma_f32 v81, -v82, v93, v83
	v_div_fmas_f32 v80, v80, v88, v92
	s_mov_b64 vcc, s[4:5]
	v_fmac_f32_e32 v95, v99, v91
	v_fma_f32 v82, -v84, v94, v85
	v_div_fixup_f32 v53, v80, v53, 1.0
	v_div_fmas_f32 v80, v81, v89, v93
	s_mov_b64 vcc, s[6:7]
	v_fma_f32 v83, -v86, v95, v87
	v_div_fixup_f32 v52, v80, v52, 1.0
	v_div_fmas_f32 v80, v82, v90, v94
	s_mov_b64 vcc, s[8:9]
	v_div_fixup_f32 v67, v80, v67, 1.0
	v_div_fmas_f32 v80, v83, v91, v95
	v_div_fixup_f32 v66, v80, v66, 1.0
	v_pk_add_f32 v[68:69], v[68:69], 1.0 op_sel_hi:[1,0]
	v_pk_mul_f32 v[54:55], v[54:55], v[54:55]
	v_pk_mul_f32 v[56:57], v[56:57], v[56:57]
	v_add_f32_e32 v54, v54, v55
	s_waitcnt lgkmcnt(0)
	v_mov_b32_e32 v50, v200
	v_mov_b32_e32 v51, v201
	v_mov_b32_e32 v58, v188
	v_mov_b32_e32 v59, v189
	v_mov_b32_e32 v60, v190
	v_mov_b32_e32 v61, v191
	v_lshlrev_b32_e32 v80, 16, v50
	v_and_b32_e32 v81, 0xffff0000, v50
	v_lshlrev_b32_e32 v82, 16, v51
	v_and_b32_e32 v83, 0xffff0000, v51
	v_pk_fma_f32 v[50:51], v[52:53], v[80:81], v[58:59]
	v_pk_fma_f32 v[52:53], v[66:67], v[82:83], v[60:61]
	global_store_dwordx4 v[72:73], v[50:53], off offset:128
	v_cvt_pk_bf16_f32 v58, v50, v51
	v_cvt_pk_bf16_f32 v59, v52, v53
	s_nop 0
	v_pk_add_f32 v[76:77], v[78:79], 1.0 op_sel_hi:[1,0]
	global_store_dwordx2 v[74:75], v[58:59], off offset:64
	s_nop 0
	v_div_scale_f32 v78, s[4:5], v69, v69, 1.0
	v_div_scale_f32 v80, s[4:5], v68, v68, 1.0
	v_div_scale_f32 v82, s[6:7], v77, v77, 1.0
	v_rcp_f32_e32 v86, v78
	v_rcp_f32_e32 v87, v80
	v_rcp_f32_e32 v88, v82
	v_div_scale_f32 v84, s[8:9], v76, v76, 1.0
	v_rcp_f32_e32 v89, v84
	v_fma_f32 v90, -v78, v86, 1.0
	v_fma_f32 v91, -v80, v87, 1.0
	v_fma_f32 v92, -v82, v88, 1.0
	v_div_scale_f32 v79, vcc, 1.0, v69, 1.0
	v_div_scale_f32 v81, s[4:5], 1.0, v68, 1.0
	v_div_scale_f32 v83, s[6:7], 1.0, v77, 1.0
	v_fmac_f32_e32 v86, v90, v86
	v_fmac_f32_e32 v87, v91, v87
	v_fmac_f32_e32 v88, v92, v88
	v_mul_f32_e32 v90, v79, v86
	v_mul_f32_e32 v91, v81, v87
	v_mul_f32_e32 v92, v83, v88
	v_fma_f32 v94, -v78, v90, v79
	v_fma_f32 v95, -v80, v91, v81
	v_fma_f32 v96, -v82, v92, v83
	v_fma_f32 v93, -v84, v89, 1.0
	v_fmac_f32_e32 v90, v94, v86
	v_fmac_f32_e32 v91, v95, v87
	v_fmac_f32_e32 v92, v96, v88
	v_div_scale_f32 v85, s[8:9], 1.0, v76, 1.0
	v_fmac_f32_e32 v89, v93, v89
	v_fma_f32 v78, -v78, v90, v79
	v_fma_f32 v79, -v80, v91, v81
	v_fma_f32 v80, -v82, v92, v83
	v_add_f32_e32 v82, v62, v63
	v_pk_mul_f32 v[62:63], v[64:65], v[64:65]
	v_mul_f32_e32 v93, v85, v89
	v_add_f32_e32 v62, v62, v82
	v_fma_f32 v97, -v84, v93, v85
	v_add_f32_e32 v82, v63, v62
	v_div_fmas_f32 v62, v78, v86, v90
	s_mov_b64 vcc, s[4:5]
	v_pk_mul_f32 v[50:51], v[50:51], v[50:51]
	v_fmac_f32_e32 v93, v97, v89
	v_div_fixup_f32 v63, v62, v69, 1.0
	v_div_fmas_f32 v62, v79, v87, v91
	s_mov_b64 vcc, s[6:7]
	v_pk_mul_f32 v[52:53], v[52:53], v[52:53]
	v_add_f32_e32 v50, v50, v51
	v_fma_f32 v81, -v84, v93, v85
	v_div_fmas_f32 v64, v80, v88, v92
	s_mov_b64 vcc, s[8:9]
	v_add_f32_e32 v54, v56, v54
	v_add_f32_e32 v50, v52, v50
	v_div_fixup_f32 v62, v62, v68, 1.0
	v_div_fixup_f32 v65, v64, v77, 1.0
	v_div_fmas_f32 v64, v81, v89, v93
	v_add_f32_e32 v54, v57, v54
	v_add_f32_e32 v69, v53, v50
	v_div_fixup_f32 v64, v64, v76, 1.0
	v_add_f32_e32 v68, v82, v54
	s_waitcnt lgkmcnt(0)
	v_mov_b32_e32 v66, v202
	v_mov_b32_e32 v67, v203
	v_mov_b32_e32 v58, v192
	v_mov_b32_e32 v59, v193
	v_mov_b32_e32 v60, v194
	v_mov_b32_e32 v61, v195
	v_lshlrev_b32_e32 v50, 16, v66
	v_and_b32_e32 v51, 0xffff0000, v66
	v_lshlrev_b32_e32 v54, 16, v67
	v_and_b32_e32 v55, 0xffff0000, v67
	v_pk_fma_f32 v[52:53], v[62:63], v[50:51], v[58:59]
	v_pk_fma_f32 v[54:55], v[64:65], v[54:55], v[60:61]
	v_pk_mul_f32 v[50:51], v[52:53], v[52:53]
	v_pk_mul_f32 v[56:57], v[54:55], v[54:55]
	v_add_f32_e32 v50, v50, v51
	v_add_f32_e32 v50, v56, v50
	v_add_f32_e32 v58, v68, v69
	v_add_f32_e32 v50, v57, v50
	v_add_f32_e32 v50, v58, v50
	ds_bpermute_b32 v51, v126, v50
	global_store_dwordx4 v[72:73], v[52:55], off offset:192
	s_waitcnt lgkmcnt(0)
	v_add_f32_e32 v50, v50, v51
	ds_bpermute_b32 v51, v127, v50
	v_cvt_pk_bf16_f32 v52, v52, v53
	v_cvt_pk_bf16_f32 v53, v54, v55
	global_store_dwordx2 v[74:75], v[52:53], off offset:96
	s_and_saveexec_b64 s[4:5], s[0:1]
	s_cbranch_execz .LBB0_632
	s_waitcnt lgkmcnt(0)
	v_add_f32_e32 v52, v50, v51
	v_lshl_add_u64 v[50:51], v[70:71], 2, s[20:21]
	global_atomic_add_f32 v[50:51], v52, off
.LBB0_632:
	s_or_b64 exec, exec, s[4:5]
	v_or_b32_e32 v54, 0x50, v140
	v_mov_b32_e32 v55, v141
	s_waitcnt lgkmcnt(0)
	v_lshl_add_u64 v[50:51], v[54:55], 2, s[18:19]
	s_mov_b32 s99, 0
	s_mov_b32 s98, 0x60000
	v_lshl_add_u64 v[236:237], v[230:231], 0, s[98:99]
	global_load_dwordx4 v[180:183], v[236:237], off
	global_load_dwordx4 v[184:187], v[236:237], off offset:64
	global_load_dwordx4 v[188:191], v[236:237], off offset:128
	global_load_dwordx4 v[192:195], v[236:237], off offset:192
	s_mov_b32 s98, 0x30000
	v_lshl_add_u64 v[236:237], v[232:233], 0, s[98:99]
	global_load_dwordx2 v[196:197], v[236:237], off
	global_load_dwordx2 v[198:199], v[236:237], off offset:32
	global_load_dwordx2 v[200:201], v[236:237], off offset:64
	global_load_dwordx2 v[202:203], v[236:237], off offset:96
	s_mov_b32 s98, 0x180
	v_lshl_add_u64 v[236:237], v[234:235], 0, s[98:99]
	global_load_dword v228, v[236:237], off
	v_lshlrev_b64 v[50:51], 11, v[54:55]
	v_lshl_add_u64 v[52:53], s[14:15], 0, v[50:51]
	v_lshl_add_u64 v[60:61], v[52:53], 0, v[142:143]
	v_lshlrev_b64 v[52:53], 12, v[54:55]
	v_lshl_add_u64 v[52:53], v[134:135], 0, v[52:53]
	s_nop 0
	v_lshl_add_u64 v[50:51], s[16:17], 0, v[50:51]
	v_lshl_add_u64 v[56:57], v[52:53], 0, v[138:139]
	v_lshl_add_u64 v[58:59], v[50:51], 0, v[142:143]
	s_nop 0
	s_waitcnt vmcnt(17) lgkmcnt(0)
	v_mov_b32_e32 v64, v229
	v_mov_b32_e32 v62, v220
	v_mov_b32_e32 v63, v221
	v_mov_b32_e32 v50, v204
	v_mov_b32_e32 v51, v205
	v_mov_b32_e32 v52, v206
	v_mov_b32_e32 v53, v207
	v_fmamk_f32 v64, v64, 0x3a800000, v153
	v_mul_f32_e32 v65, 0x4b800000, v64
	v_cmp_gt_f32_e32 vcc, s56, v64
	s_nop 1
	v_cndmask_b32_e32 v65, v64, v65, vcc
	v_rsq_f32_e32 v66, v65
	v_lshlrev_b32_e32 v64, 16, v62
	v_and_b32_e32 v65, 0xffff0000, v62
	v_lshlrev_b32_e32 v62, 16, v63
	v_mul_f32_e32 v67, 0x45800000, v66
	v_cndmask_b32_e32 v66, v66, v67, vcc
	v_mul_f32_e32 v46, v46, v66
	v_mul_f32_e32 v47, v47, v66
	v_mul_f32_e32 v46, 0xbfb8aa3b, v46
	v_mul_f32_e32 v47, 0xbfb8aa3b, v47
	v_mul_f32_e32 v48, v48, v66
	v_mul_f32_e32 v49, v49, v66
	v_exp_f32_e32 v46, v46
	v_exp_f32_e32 v47, v47
	v_mul_f32_e32 v48, 0xbfb8aa3b, v48
	v_mul_f32_e32 v49, 0xbfb8aa3b, v49
	v_exp_f32_e32 v48, v48
	v_exp_f32_e32 v49, v49
	v_mul_f32_e32 v67, v42, v66
	v_mul_f32_e32 v68, v43, v66
	v_pk_add_f32 v[42:43], v[46:47], 1.0 op_sel_hi:[1,0]
	v_pk_add_f32 v[48:49], v[48:49], 1.0 op_sel_hi:[1,0]
	v_div_scale_f32 v46, s[4:5], v43, v43, 1.0
	v_div_scale_f32 v69, s[4:5], v42, v42, 1.0
	v_rcp_f32_e32 v75, v46
	v_div_scale_f32 v71, s[6:7], v49, v49, 1.0
	v_rcp_f32_e32 v76, v69
	v_div_scale_f32 v73, s[8:9], v48, v48, 1.0
	v_rcp_f32_e32 v77, v71
	v_rcp_f32_e32 v78, v73
	v_fma_f32 v79, -v46, v75, 1.0
	v_div_scale_f32 v47, vcc, 1.0, v43, 1.0
	v_fma_f32 v80, -v69, v76, 1.0
	v_fmac_f32_e32 v75, v79, v75
	v_div_scale_f32 v70, s[4:5], 1.0, v42, 1.0
	v_fma_f32 v81, -v71, v77, 1.0
	v_fmac_f32_e32 v76, v80, v76
	v_mul_f32_e32 v79, v47, v75
	v_div_scale_f32 v72, s[6:7], 1.0, v49, 1.0
	v_fma_f32 v82, -v73, v78, 1.0
	v_fmac_f32_e32 v77, v81, v77
	v_mul_f32_e32 v80, v70, v76
	v_fma_f32 v83, -v46, v79, v47
	v_div_scale_f32 v74, s[8:9], 1.0, v48, 1.0
	v_fmac_f32_e32 v78, v82, v78
	v_mul_f32_e32 v81, v72, v77
	v_fma_f32 v84, -v69, v80, v70
	v_fmac_f32_e32 v79, v83, v75
	v_mul_f32_e32 v82, v74, v78
	v_fma_f32 v85, -v71, v81, v72
	v_fmac_f32_e32 v80, v84, v76
	v_fma_f32 v46, -v46, v79, v47
	v_fma_f32 v86, -v73, v82, v74
	v_fmac_f32_e32 v81, v85, v77
	v_fma_f32 v47, -v69, v80, v70
	v_div_fmas_f32 v46, v46, v75, v79
	s_mov_b64 vcc, s[4:5]
	v_fmac_f32_e32 v82, v86, v78
	v_fma_f32 v69, -v71, v81, v72
	v_div_fixup_f32 v43, v46, v43, 1.0
	v_div_fmas_f32 v46, v47, v76, v80
	s_mov_b64 vcc, s[6:7]
	v_fma_f32 v70, -v73, v82, v74
	v_div_fixup_f32 v42, v46, v42, 1.0
	v_div_fmas_f32 v69, v69, v77, v81
	s_mov_b64 vcc, s[8:9]
	v_pk_fma_f32 v[46:47], v[42:43], v[64:65], v[50:51]
	v_div_fmas_f32 v42, v70, v78, v82
	v_and_b32_e32 v63, 0xffff0000, v63
	v_div_fixup_f32 v43, v69, v49, 1.0
	v_div_fixup_f32 v42, v42, v48, 1.0
	v_pk_fma_f32 v[48:49], v[42:43], v[62:63], v[52:53]
	global_store_dwordx4 v[56:57], v[46:49], off
	v_cvt_pk_bf16_f32 v50, v46, v47
	v_cvt_pk_bf16_f32 v51, v48, v49
	s_nop 0
	v_mul_f32_e32 v44, v44, v66
	global_store_dwordx2 v[58:59], v[50:51], off
	s_nop 0
	v_mul_f32_e32 v45, v45, v66
	v_mul_f32_e32 v63, v39, v66
	v_mul_f32_e32 v69, v34, v66
	v_mul_f32_e32 v34, 0xbfb8aa3b, v67
	v_mul_f32_e32 v39, 0xbfb8aa3b, v68
	v_mul_f32_e32 v62, v38, v66
	v_mul_f32_e32 v64, v40, v66
	v_mul_f32_e32 v65, v41, v66
	v_mul_f32_e32 v40, 0xbfb8aa3b, v44
	v_mul_f32_e32 v41, 0xbfb8aa3b, v45
	v_exp_f32_e32 v38, v34
	v_exp_f32_e32 v39, v39
	v_exp_f32_e32 v40, v40
	v_exp_f32_e32 v41, v41
	v_mul_f32_e32 v67, v35, v66
	v_pk_add_f32 v[34:35], v[38:39], 1.0 op_sel_hi:[1,0]
	v_mul_f32_e32 v36, v36, v66
	v_pk_add_f32 v[38:39], v[40:41], 1.0 op_sel_hi:[1,0]
	v_div_scale_f32 v40, s[4:5], v35, v35, 1.0
	v_div_scale_f32 v44, s[4:5], v34, v34, 1.0
	v_rcp_f32_e32 v73, v40
	v_div_scale_f32 v68, s[6:7], v39, v39, 1.0
	v_rcp_f32_e32 v74, v44
	v_div_scale_f32 v71, s[8:9], v38, v38, 1.0
	v_rcp_f32_e32 v75, v68
	v_rcp_f32_e32 v76, v71
	v_fma_f32 v77, -v40, v73, 1.0
	v_div_scale_f32 v41, vcc, 1.0, v35, 1.0
	v_fma_f32 v78, -v44, v74, 1.0
	v_fmac_f32_e32 v73, v77, v73
	v_div_scale_f32 v45, s[4:5], 1.0, v34, 1.0
	v_fma_f32 v79, -v68, v75, 1.0
	v_fmac_f32_e32 v74, v78, v74
	v_mul_f32_e32 v77, v41, v73
	v_div_scale_f32 v70, s[6:7], 1.0, v39, 1.0
	v_fma_f32 v80, -v71, v76, 1.0
	v_fmac_f32_e32 v75, v79, v75
	v_mul_f32_e32 v78, v45, v74
	v_fma_f32 v81, -v40, v77, v41
	v_div_scale_f32 v72, s[8:9], 1.0, v38, 1.0
	v_fmac_f32_e32 v76, v80, v76
	v_mul_f32_e32 v79, v70, v75
	v_fma_f32 v82, -v44, v78, v45
	v_fmac_f32_e32 v77, v81, v73
	v_mul_f32_e32 v80, v72, v76
	v_fma_f32 v83, -v68, v79, v70
	v_fmac_f32_e32 v78, v82, v74
	v_fma_f32 v40, -v40, v77, v41
	v_fma_f32 v84, -v71, v80, v72
	v_fmac_f32_e32 v79, v83, v75
	v_fma_f32 v41, -v44, v78, v45
	v_div_fmas_f32 v40, v40, v73, v77
	s_mov_b64 vcc, s[4:5]
	v_fmac_f32_e32 v80, v84, v76
	v_fma_f32 v44, -v68, v79, v70
	v_div_fixup_f32 v35, v40, v35, 1.0
	v_div_fmas_f32 v40, v41, v74, v78
	s_mov_b64 vcc, s[6:7]
	v_fma_f32 v45, -v71, v80, v72
	v_div_fixup_f32 v34, v40, v34, 1.0
	v_div_fmas_f32 v40, v44, v75, v79
	s_mov_b64 vcc, s[8:9]
	v_div_fixup_f32 v41, v40, v39, 1.0
	v_div_fmas_f32 v39, v45, v76, v80
	v_div_fixup_f32 v40, v39, v38, 1.0
	v_mul_f32_e32 v37, v37, v66
	v_pk_mul_f32 v[46:47], v[46:47], v[46:47]
	s_waitcnt lgkmcnt(0)
	v_mov_b32_e32 v42, v222
	v_mov_b32_e32 v43, v223
	v_mov_b32_e32 v50, v208
	v_mov_b32_e32 v51, v209
	v_mov_b32_e32 v52, v210
	v_mov_b32_e32 v53, v211
	v_lshlrev_b32_e32 v38, 16, v42
	v_and_b32_e32 v39, 0xffff0000, v42
	v_lshlrev_b32_e32 v42, 16, v43
	v_and_b32_e32 v43, 0xffff0000, v43
	v_pk_fma_f32 v[38:39], v[34:35], v[38:39], v[50:51]
	v_pk_fma_f32 v[40:41], v[40:41], v[42:43], v[52:53]
	global_store_dwordx4 v[56:57], v[38:41], off offset:64
	v_cvt_pk_bf16_f32 v42, v38, v39
	v_cvt_pk_bf16_f32 v43, v40, v41
	s_nop 0
	v_mul_f32_e32 v50, 0xbfb8aa3b, v62
	global_store_dwordx2 v[58:59], v[42:43], off offset:32
	s_nop 0
	v_mul_f32_e32 v51, 0xbfb8aa3b, v63
	v_mul_f32_e32 v52, 0xbfb8aa3b, v64
	v_mul_f32_e32 v53, 0xbfb8aa3b, v65
	v_mul_f32_e32 v64, 0xbfb8aa3b, v36
	v_mul_f32_e32 v65, 0xbfb8aa3b, v37
	v_exp_f32_e32 v36, v50
	v_exp_f32_e32 v37, v51
	v_exp_f32_e32 v50, v52
	v_exp_f32_e32 v51, v53
	v_mul_f32_e32 v62, 0xbfb8aa3b, v69
	v_pk_add_f32 v[36:37], v[36:37], 1.0 op_sel_hi:[1,0]
	v_exp_f32_e32 v52, v62
	v_exp_f32_e32 v62, v64
	v_div_scale_f32 v64, s[4:5], v37, v37, 1.0
	v_pk_add_f32 v[50:51], v[50:51], 1.0 op_sel_hi:[1,0]
	v_div_scale_f32 v66, s[4:5], v36, v36, 1.0
	v_rcp_f32_e32 v72, v64
	v_div_scale_f32 v68, s[6:7], v51, v51, 1.0
	v_rcp_f32_e32 v73, v66
	v_div_scale_f32 v70, s[8:9], v50, v50, 1.0
	v_rcp_f32_e32 v74, v68
	v_rcp_f32_e32 v75, v70
	v_mul_f32_e32 v63, 0xbfb8aa3b, v67
	v_fma_f32 v76, -v64, v72, 1.0
	v_exp_f32_e32 v53, v63
	v_exp_f32_e32 v63, v65
	v_div_scale_f32 v65, vcc, 1.0, v37, 1.0
	v_fma_f32 v77, -v66, v73, 1.0
	v_fmac_f32_e32 v72, v76, v72
	v_div_scale_f32 v67, s[4:5], 1.0, v36, 1.0
	v_fma_f32 v78, -v68, v74, 1.0
	v_fmac_f32_e32 v73, v77, v73
	v_mul_f32_e32 v76, v65, v72
	v_div_scale_f32 v69, s[6:7], 1.0, v51, 1.0
	v_fma_f32 v79, -v70, v75, 1.0
	v_fmac_f32_e32 v74, v78, v74
	v_mul_f32_e32 v77, v67, v73
	v_fma_f32 v80, -v64, v76, v65
	v_div_scale_f32 v71, s[8:9], 1.0, v50, 1.0
	v_fmac_f32_e32 v75, v79, v75
	v_mul_f32_e32 v78, v69, v74
	v_fma_f32 v81, -v66, v77, v67
	v_fmac_f32_e32 v76, v80, v72
	v_mul_f32_e32 v79, v71, v75
	v_fma_f32 v82, -v68, v78, v69
	v_fmac_f32_e32 v77, v81, v73
	v_fma_f32 v64, -v64, v76, v65
	v_fma_f32 v83, -v70, v79, v71
	v_fmac_f32_e32 v78, v82, v74
	v_fma_f32 v65, -v66, v77, v67
	v_div_fmas_f32 v64, v64, v72, v76
	s_mov_b64 vcc, s[4:5]
	v_fmac_f32_e32 v79, v83, v75
	v_fma_f32 v66, -v68, v78, v69
	v_div_fixup_f32 v37, v64, v37, 1.0
	v_div_fmas_f32 v64, v65, v73, v77
	s_mov_b64 vcc, s[6:7]
	v_fma_f32 v67, -v70, v79, v71
	v_div_fixup_f32 v36, v64, v36, 1.0
	v_div_fmas_f32 v64, v66, v74, v78
	s_mov_b64 vcc, s[8:9]
	v_div_fixup_f32 v51, v64, v51, 1.0
	v_div_fmas_f32 v64, v67, v75, v79
	v_div_fixup_f32 v50, v64, v50, 1.0
	v_pk_add_f32 v[52:53], v[52:53], 1.0 op_sel_hi:[1,0]
	v_pk_mul_f32 v[38:39], v[38:39], v[38:39]
	v_pk_mul_f32 v[40:41], v[40:41], v[40:41]
	v_add_f32_e32 v38, v38, v39
	s_waitcnt lgkmcnt(0)
	v_mov_b32_e32 v34, v224
	v_mov_b32_e32 v35, v225
	v_mov_b32_e32 v42, v212
	v_mov_b32_e32 v43, v213
	v_mov_b32_e32 v44, v214
	v_mov_b32_e32 v45, v215
	v_lshlrev_b32_e32 v64, 16, v34
	v_and_b32_e32 v65, 0xffff0000, v34
	v_lshlrev_b32_e32 v66, 16, v35
	v_and_b32_e32 v67, 0xffff0000, v35
	v_pk_fma_f32 v[34:35], v[36:37], v[64:65], v[42:43]
	v_pk_fma_f32 v[36:37], v[50:51], v[66:67], v[44:45]
	global_store_dwordx4 v[56:57], v[34:37], off offset:128
	v_cvt_pk_bf16_f32 v42, v34, v35
	v_cvt_pk_bf16_f32 v43, v36, v37
	s_nop 0
	v_pk_add_f32 v[60:61], v[62:63], 1.0 op_sel_hi:[1,0]
	global_store_dwordx2 v[58:59], v[42:43], off offset:64
	s_nop 0
	v_div_scale_f32 v62, s[4:5], v53, v53, 1.0
	v_div_scale_f32 v64, s[4:5], v52, v52, 1.0
	v_div_scale_f32 v66, s[6:7], v61, v61, 1.0
	v_rcp_f32_e32 v70, v62
	v_rcp_f32_e32 v71, v64
	v_rcp_f32_e32 v72, v66
	v_div_scale_f32 v68, s[8:9], v60, v60, 1.0
	v_rcp_f32_e32 v73, v68
	v_fma_f32 v74, -v62, v70, 1.0
	v_fma_f32 v75, -v64, v71, 1.0
	v_fma_f32 v76, -v66, v72, 1.0
	v_div_scale_f32 v63, vcc, 1.0, v53, 1.0
	v_div_scale_f32 v65, s[4:5], 1.0, v52, 1.0
	v_div_scale_f32 v67, s[6:7], 1.0, v61, 1.0
	v_fmac_f32_e32 v70, v74, v70
	v_fmac_f32_e32 v71, v75, v71
	v_fmac_f32_e32 v72, v76, v72
	v_mul_f32_e32 v74, v63, v70
	v_mul_f32_e32 v75, v65, v71
	v_mul_f32_e32 v76, v67, v72
	v_fma_f32 v78, -v62, v74, v63
	v_fma_f32 v79, -v64, v75, v65
	v_fma_f32 v80, -v66, v76, v67
	v_fma_f32 v77, -v68, v73, 1.0
	v_fmac_f32_e32 v74, v78, v70
	v_fmac_f32_e32 v75, v79, v71
	v_fmac_f32_e32 v76, v80, v72
	v_div_scale_f32 v69, s[8:9], 1.0, v60, 1.0
	v_fmac_f32_e32 v73, v77, v73
	v_fma_f32 v62, -v62, v74, v63
	v_fma_f32 v63, -v64, v75, v65
	v_fma_f32 v64, -v66, v76, v67
	v_add_f32_e32 v66, v46, v47
	v_pk_mul_f32 v[46:47], v[48:49], v[48:49]
	v_mul_f32_e32 v77, v69, v73
	v_add_f32_e32 v46, v46, v66
	v_fma_f32 v81, -v68, v77, v69
	v_add_f32_e32 v66, v47, v46
	v_div_fmas_f32 v46, v62, v70, v74
	s_mov_b64 vcc, s[4:5]
	v_pk_mul_f32 v[34:35], v[34:35], v[34:35]
	v_fmac_f32_e32 v77, v81, v73
	v_div_fixup_f32 v47, v46, v53, 1.0
	v_div_fmas_f32 v46, v63, v71, v75
	s_mov_b64 vcc, s[6:7]
	v_pk_mul_f32 v[36:37], v[36:37], v[36:37]
	v_add_f32_e32 v34, v34, v35
	v_fma_f32 v65, -v68, v77, v69
	v_div_fmas_f32 v48, v64, v72, v76
	s_mov_b64 vcc, s[8:9]
	v_add_f32_e32 v38, v40, v38
	v_add_f32_e32 v34, v36, v34
	v_div_fixup_f32 v46, v46, v52, 1.0
	v_div_fixup_f32 v49, v48, v61, 1.0
	v_div_fmas_f32 v48, v65, v73, v77
	v_add_f32_e32 v38, v41, v38
	v_add_f32_e32 v53, v37, v34
	v_div_fixup_f32 v48, v48, v60, 1.0
	v_add_f32_e32 v52, v66, v38
	s_waitcnt lgkmcnt(0)
	v_mov_b32_e32 v50, v226
	v_mov_b32_e32 v51, v227
	v_mov_b32_e32 v42, v216
	v_mov_b32_e32 v43, v217
	v_mov_b32_e32 v44, v218
	v_mov_b32_e32 v45, v219
	v_lshlrev_b32_e32 v34, 16, v50
	v_and_b32_e32 v35, 0xffff0000, v50
	v_lshlrev_b32_e32 v38, 16, v51
	v_and_b32_e32 v39, 0xffff0000, v51
	v_pk_fma_f32 v[36:37], v[46:47], v[34:35], v[42:43]
	v_pk_fma_f32 v[38:39], v[48:49], v[38:39], v[44:45]
	v_pk_mul_f32 v[34:35], v[36:37], v[36:37]
	v_pk_mul_f32 v[40:41], v[38:39], v[38:39]
	v_add_f32_e32 v34, v34, v35
	v_add_f32_e32 v34, v40, v34
	v_add_f32_e32 v42, v52, v53
	v_add_f32_e32 v34, v41, v34
	v_add_f32_e32 v34, v42, v34
	ds_bpermute_b32 v35, v126, v34
	global_store_dwordx4 v[56:57], v[36:39], off offset:192
	s_waitcnt lgkmcnt(0)
	v_add_f32_e32 v34, v34, v35
	ds_bpermute_b32 v35, v127, v34
	v_cvt_pk_bf16_f32 v36, v36, v37
	v_cvt_pk_bf16_f32 v37, v38, v39
	global_store_dwordx2 v[58:59], v[36:37], off offset:96
	s_and_saveexec_b64 s[4:5], s[0:1]
	s_cbranch_execz .LBB0_634
	s_waitcnt lgkmcnt(0)
	v_add_f32_e32 v36, v34, v35
	v_lshl_add_u64 v[34:35], v[54:55], 2, s[20:21]
	global_atomic_add_f32 v[34:35], v36, off
.LBB0_634:
	s_or_b64 exec, exec, s[4:5]
	v_or_b32_e32 v38, 0x60, v140
	v_mov_b32_e32 v39, v141
	s_waitcnt lgkmcnt(0)
	v_lshl_add_u64 v[34:35], v[38:39], 2, s[18:19]
	s_mov_b32 s99, 0
	s_mov_b32 s98, 0x70000
	v_lshl_add_u64 v[236:237], v[230:231], 0, s[98:99]
	global_load_dwordx4 v[204:207], v[236:237], off
	global_load_dwordx4 v[208:211], v[236:237], off offset:64
	global_load_dwordx4 v[212:215], v[236:237], off offset:128
	global_load_dwordx4 v[216:219], v[236:237], off offset:192
	s_mov_b32 s98, 0x38000
	v_lshl_add_u64 v[236:237], v[232:233], 0, s[98:99]
	global_load_dwordx2 v[220:221], v[236:237], off
	global_load_dwordx2 v[222:223], v[236:237], off offset:32
	global_load_dwordx2 v[224:225], v[236:237], off offset:64
	global_load_dwordx2 v[226:227], v[236:237], off offset:96
	s_mov_b32 s98, 0x1c0
	v_lshl_add_u64 v[236:237], v[234:235], 0, s[98:99]
	global_load_dword v229, v[236:237], off
	v_lshlrev_b64 v[34:35], 11, v[38:39]
	v_lshl_add_u64 v[36:37], s[14:15], 0, v[34:35]
	v_mov_b32_e32 v143, v139
	v_lshl_add_u64 v[44:45], v[36:37], 0, v[142:143]
	v_lshlrev_b64 v[36:37], 12, v[38:39]
	v_lshl_add_u64 v[36:37], v[134:135], 0, v[36:37]
	s_nop 0
	v_lshl_add_u64 v[34:35], s[16:17], 0, v[34:35]
	v_lshl_add_u64 v[40:41], v[36:37], 0, v[138:139]
	v_lshl_add_u64 v[42:43], v[34:35], 0, v[142:143]
	s_nop 0
	s_waitcnt vmcnt(17) lgkmcnt(0)
	v_mov_b32_e32 v48, v228
	v_mov_b32_e32 v46, v196
	v_mov_b32_e32 v47, v197
	v_mov_b32_e32 v34, v180
	v_mov_b32_e32 v35, v181
	v_mov_b32_e32 v36, v182
	v_mov_b32_e32 v37, v183
	v_fmamk_f32 v48, v48, 0x3a800000, v153
	v_mul_f32_e32 v49, 0x4b800000, v48
	v_cmp_gt_f32_e32 vcc, s56, v48
	s_nop 1
	v_cndmask_b32_e32 v49, v48, v49, vcc
	v_rsq_f32_e32 v50, v49
	v_lshlrev_b32_e32 v48, 16, v46
	v_and_b32_e32 v49, 0xffff0000, v46
	v_lshlrev_b32_e32 v46, 16, v47
	v_mul_f32_e32 v51, 0x45800000, v50
	v_cndmask_b32_e32 v50, v50, v51, vcc
	v_mul_f32_e32 v30, v30, v50
	v_mul_f32_e32 v31, v31, v50
	v_mul_f32_e32 v30, 0xbfb8aa3b, v30
	v_mul_f32_e32 v31, 0xbfb8aa3b, v31
	v_mul_f32_e32 v32, v32, v50
	v_mul_f32_e32 v33, v33, v50
	v_exp_f32_e32 v30, v30
	v_exp_f32_e32 v31, v31
	v_mul_f32_e32 v32, 0xbfb8aa3b, v32
	v_mul_f32_e32 v33, 0xbfb8aa3b, v33
	v_exp_f32_e32 v32, v32
	v_exp_f32_e32 v33, v33
	v_mul_f32_e32 v51, v26, v50
	v_mul_f32_e32 v52, v27, v50
	v_pk_add_f32 v[26:27], v[30:31], 1.0 op_sel_hi:[1,0]
	v_pk_add_f32 v[32:33], v[32:33], 1.0 op_sel_hi:[1,0]
	v_div_scale_f32 v30, s[4:5], v27, v27, 1.0
	v_div_scale_f32 v53, s[4:5], v26, v26, 1.0
	v_rcp_f32_e32 v59, v30
	v_div_scale_f32 v55, s[6:7], v33, v33, 1.0
	v_rcp_f32_e32 v60, v53
	v_div_scale_f32 v57, s[8:9], v32, v32, 1.0
	v_rcp_f32_e32 v61, v55
	v_rcp_f32_e32 v62, v57
	v_fma_f32 v63, -v30, v59, 1.0
	v_div_scale_f32 v31, vcc, 1.0, v27, 1.0
	v_fma_f32 v64, -v53, v60, 1.0
	v_fmac_f32_e32 v59, v63, v59
	v_div_scale_f32 v54, s[4:5], 1.0, v26, 1.0
	v_fma_f32 v65, -v55, v61, 1.0
	v_fmac_f32_e32 v60, v64, v60
	v_mul_f32_e32 v63, v31, v59
	v_div_scale_f32 v56, s[6:7], 1.0, v33, 1.0
	v_fma_f32 v66, -v57, v62, 1.0
	v_fmac_f32_e32 v61, v65, v61
	v_mul_f32_e32 v64, v54, v60
	v_fma_f32 v67, -v30, v63, v31
	v_div_scale_f32 v58, s[8:9], 1.0, v32, 1.0
	v_fmac_f32_e32 v62, v66, v62
	v_mul_f32_e32 v65, v56, v61
	v_fma_f32 v68, -v53, v64, v54
	v_fmac_f32_e32 v63, v67, v59
	v_mul_f32_e32 v66, v58, v62
	v_fma_f32 v69, -v55, v65, v56
	v_fmac_f32_e32 v64, v68, v60
	v_fma_f32 v30, -v30, v63, v31
	v_fma_f32 v70, -v57, v66, v58
	v_fmac_f32_e32 v65, v69, v61
	v_fma_f32 v31, -v53, v64, v54
	v_div_fmas_f32 v30, v30, v59, v63
	s_mov_b64 vcc, s[4:5]
	v_fmac_f32_e32 v66, v70, v62
	v_fma_f32 v53, -v55, v65, v56
	v_div_fixup_f32 v27, v30, v27, 1.0
	v_div_fmas_f32 v30, v31, v60, v64
	s_mov_b64 vcc, s[6:7]
	v_fma_f32 v54, -v57, v66, v58
	v_div_fixup_f32 v26, v30, v26, 1.0
	v_div_fmas_f32 v53, v53, v61, v65
	s_mov_b64 vcc, s[8:9]
	v_pk_fma_f32 v[30:31], v[26:27], v[48:49], v[34:35]
	v_div_fmas_f32 v26, v54, v62, v66
	v_and_b32_e32 v47, 0xffff0000, v47
	v_div_fixup_f32 v27, v53, v33, 1.0
	v_div_fixup_f32 v26, v26, v32, 1.0
	v_pk_fma_f32 v[32:33], v[26:27], v[46:47], v[36:37]
	global_store_dwordx4 v[40:41], v[30:33], off
	v_cvt_pk_bf16_f32 v34, v30, v31
	v_cvt_pk_bf16_f32 v35, v32, v33
	s_nop 0
	v_mul_f32_e32 v28, v28, v50
	global_store_dwordx2 v[42:43], v[34:35], off
	s_nop 0
	v_mul_f32_e32 v29, v29, v50
	v_mul_f32_e32 v47, v23, v50
	v_mul_f32_e32 v53, v18, v50
	v_mul_f32_e32 v18, 0xbfb8aa3b, v51
	v_mul_f32_e32 v23, 0xbfb8aa3b, v52
	v_mul_f32_e32 v46, v22, v50
	v_mul_f32_e32 v48, v24, v50
	v_mul_f32_e32 v49, v25, v50
	v_mul_f32_e32 v24, 0xbfb8aa3b, v28
	v_mul_f32_e32 v25, 0xbfb8aa3b, v29
	v_exp_f32_e32 v22, v18
	v_exp_f32_e32 v23, v23
	v_exp_f32_e32 v24, v24
	v_exp_f32_e32 v25, v25
	v_mul_f32_e32 v51, v19, v50
	v_pk_add_f32 v[18:19], v[22:23], 1.0 op_sel_hi:[1,0]
	v_mul_f32_e32 v20, v20, v50
	v_pk_add_f32 v[22:23], v[24:25], 1.0 op_sel_hi:[1,0]
	v_div_scale_f32 v24, s[4:5], v19, v19, 1.0
	v_div_scale_f32 v28, s[4:5], v18, v18, 1.0
	v_rcp_f32_e32 v57, v24
	v_div_scale_f32 v52, s[6:7], v23, v23, 1.0
	v_rcp_f32_e32 v58, v28
	v_div_scale_f32 v55, s[8:9], v22, v22, 1.0
	v_rcp_f32_e32 v59, v52
	v_rcp_f32_e32 v60, v55
	v_fma_f32 v61, -v24, v57, 1.0
	v_div_scale_f32 v25, vcc, 1.0, v19, 1.0
	v_fma_f32 v62, -v28, v58, 1.0
	v_fmac_f32_e32 v57, v61, v57
	v_div_scale_f32 v29, s[4:5], 1.0, v18, 1.0
	v_fma_f32 v63, -v52, v59, 1.0
	v_fmac_f32_e32 v58, v62, v58
	v_mul_f32_e32 v61, v25, v57
	v_div_scale_f32 v54, s[6:7], 1.0, v23, 1.0
	v_fma_f32 v64, -v55, v60, 1.0
	v_fmac_f32_e32 v59, v63, v59
	v_mul_f32_e32 v62, v29, v58
	v_fma_f32 v65, -v24, v61, v25
	v_div_scale_f32 v56, s[8:9], 1.0, v22, 1.0
	v_fmac_f32_e32 v60, v64, v60
	v_mul_f32_e32 v63, v54, v59
	v_fma_f32 v66, -v28, v62, v29
	v_fmac_f32_e32 v61, v65, v57
	v_mul_f32_e32 v64, v56, v60
	v_fma_f32 v67, -v52, v63, v54
	v_fmac_f32_e32 v62, v66, v58
	v_fma_f32 v24, -v24, v61, v25
	v_fma_f32 v68, -v55, v64, v56
	v_fmac_f32_e32 v63, v67, v59
	v_fma_f32 v25, -v28, v62, v29
	v_div_fmas_f32 v24, v24, v57, v61
	s_mov_b64 vcc, s[4:5]
	v_fmac_f32_e32 v64, v68, v60
	v_fma_f32 v28, -v52, v63, v54
	v_div_fixup_f32 v19, v24, v19, 1.0
	v_div_fmas_f32 v24, v25, v58, v62
	s_mov_b64 vcc, s[6:7]
	v_fma_f32 v29, -v55, v64, v56
	v_div_fixup_f32 v18, v24, v18, 1.0
	v_div_fmas_f32 v24, v28, v59, v63
	s_mov_b64 vcc, s[8:9]
	v_div_fixup_f32 v25, v24, v23, 1.0
	v_div_fmas_f32 v23, v29, v60, v64
	v_div_fixup_f32 v24, v23, v22, 1.0
	v_mul_f32_e32 v21, v21, v50
	v_pk_mul_f32 v[30:31], v[30:31], v[30:31]
	s_waitcnt lgkmcnt(0)
	v_mov_b32_e32 v26, v198
	v_mov_b32_e32 v27, v199
	v_mov_b32_e32 v34, v184
	v_mov_b32_e32 v35, v185
	v_mov_b32_e32 v36, v186
	v_mov_b32_e32 v37, v187
	v_lshlrev_b32_e32 v22, 16, v26
	v_and_b32_e32 v23, 0xffff0000, v26
	v_lshlrev_b32_e32 v26, 16, v27
	v_and_b32_e32 v27, 0xffff0000, v27
	v_pk_fma_f32 v[22:23], v[18:19], v[22:23], v[34:35]
	v_pk_fma_f32 v[24:25], v[24:25], v[26:27], v[36:37]
	global_store_dwordx4 v[40:41], v[22:25], off offset:64
	v_cvt_pk_bf16_f32 v26, v22, v23
	v_cvt_pk_bf16_f32 v27, v24, v25
	s_nop 0
	v_mul_f32_e32 v34, 0xbfb8aa3b, v46
	global_store_dwordx2 v[42:43], v[26:27], off offset:32
	s_nop 0
	v_mul_f32_e32 v35, 0xbfb8aa3b, v47
	v_mul_f32_e32 v36, 0xbfb8aa3b, v48
	v_mul_f32_e32 v37, 0xbfb8aa3b, v49
	v_mul_f32_e32 v48, 0xbfb8aa3b, v20
	v_mul_f32_e32 v49, 0xbfb8aa3b, v21
	v_exp_f32_e32 v20, v34
	v_exp_f32_e32 v21, v35
	v_exp_f32_e32 v34, v36
	v_exp_f32_e32 v35, v37
	v_mul_f32_e32 v46, 0xbfb8aa3b, v53
	v_pk_add_f32 v[20:21], v[20:21], 1.0 op_sel_hi:[1,0]
	v_exp_f32_e32 v36, v46
	v_exp_f32_e32 v46, v48
	v_div_scale_f32 v48, s[4:5], v21, v21, 1.0
	v_pk_add_f32 v[34:35], v[34:35], 1.0 op_sel_hi:[1,0]
	v_div_scale_f32 v50, s[4:5], v20, v20, 1.0
	v_rcp_f32_e32 v56, v48
	v_div_scale_f32 v52, s[6:7], v35, v35, 1.0
	v_rcp_f32_e32 v57, v50
	v_div_scale_f32 v54, s[8:9], v34, v34, 1.0
	v_rcp_f32_e32 v58, v52
	v_rcp_f32_e32 v59, v54
	v_mul_f32_e32 v47, 0xbfb8aa3b, v51
	v_fma_f32 v60, -v48, v56, 1.0
	v_exp_f32_e32 v37, v47
	v_exp_f32_e32 v47, v49
	v_div_scale_f32 v49, vcc, 1.0, v21, 1.0
	v_fma_f32 v61, -v50, v57, 1.0
	v_fmac_f32_e32 v56, v60, v56
	v_div_scale_f32 v51, s[4:5], 1.0, v20, 1.0
	v_fma_f32 v62, -v52, v58, 1.0
	v_fmac_f32_e32 v57, v61, v57
	v_mul_f32_e32 v60, v49, v56
	v_div_scale_f32 v53, s[6:7], 1.0, v35, 1.0
	v_fma_f32 v63, -v54, v59, 1.0
	v_fmac_f32_e32 v58, v62, v58
	v_mul_f32_e32 v61, v51, v57
	v_fma_f32 v64, -v48, v60, v49
	v_div_scale_f32 v55, s[8:9], 1.0, v34, 1.0
	v_fmac_f32_e32 v59, v63, v59
	v_mul_f32_e32 v62, v53, v58
	v_fma_f32 v65, -v50, v61, v51
	v_fmac_f32_e32 v60, v64, v56
	v_mul_f32_e32 v63, v55, v59
	v_fma_f32 v66, -v52, v62, v53
	v_fmac_f32_e32 v61, v65, v57
	v_fma_f32 v48, -v48, v60, v49
	v_fma_f32 v67, -v54, v63, v55
	v_fmac_f32_e32 v62, v66, v58
	v_fma_f32 v49, -v50, v61, v51
	v_div_fmas_f32 v48, v48, v56, v60
	s_mov_b64 vcc, s[4:5]
	v_fmac_f32_e32 v63, v67, v59
	v_fma_f32 v50, -v52, v62, v53
	v_div_fixup_f32 v21, v48, v21, 1.0
	v_div_fmas_f32 v48, v49, v57, v61
	s_mov_b64 vcc, s[6:7]
	v_fma_f32 v51, -v54, v63, v55
	v_div_fixup_f32 v20, v48, v20, 1.0
	v_div_fmas_f32 v48, v50, v58, v62
	s_mov_b64 vcc, s[8:9]
	v_div_fixup_f32 v35, v48, v35, 1.0
	v_div_fmas_f32 v48, v51, v59, v63
	v_div_fixup_f32 v34, v48, v34, 1.0
	v_pk_add_f32 v[36:37], v[36:37], 1.0 op_sel_hi:[1,0]
	v_pk_mul_f32 v[22:23], v[22:23], v[22:23]
	v_pk_mul_f32 v[24:25], v[24:25], v[24:25]
	v_add_f32_e32 v22, v22, v23
	s_waitcnt lgkmcnt(0)
	v_mov_b32_e32 v18, v200
	v_mov_b32_e32 v19, v201
	v_mov_b32_e32 v26, v188
	v_mov_b32_e32 v27, v189
	v_mov_b32_e32 v28, v190
	v_mov_b32_e32 v29, v191
	v_lshlrev_b32_e32 v48, 16, v18
	v_and_b32_e32 v49, 0xffff0000, v18
	v_lshlrev_b32_e32 v50, 16, v19
	v_and_b32_e32 v51, 0xffff0000, v19
	v_pk_fma_f32 v[18:19], v[20:21], v[48:49], v[26:27]
	v_pk_fma_f32 v[20:21], v[34:35], v[50:51], v[28:29]
	global_store_dwordx4 v[40:41], v[18:21], off offset:128
	v_cvt_pk_bf16_f32 v26, v18, v19
	v_cvt_pk_bf16_f32 v27, v20, v21
	s_nop 0
	v_pk_add_f32 v[44:45], v[46:47], 1.0 op_sel_hi:[1,0]
	global_store_dwordx2 v[42:43], v[26:27], off offset:64
	s_nop 0
	v_div_scale_f32 v46, s[4:5], v37, v37, 1.0
	v_div_scale_f32 v48, s[4:5], v36, v36, 1.0
	v_div_scale_f32 v50, s[6:7], v45, v45, 1.0
	v_rcp_f32_e32 v54, v46
	v_rcp_f32_e32 v55, v48
	v_rcp_f32_e32 v56, v50
	v_div_scale_f32 v52, s[8:9], v44, v44, 1.0
	v_rcp_f32_e32 v57, v52
	v_fma_f32 v58, -v46, v54, 1.0
	v_fma_f32 v59, -v48, v55, 1.0
	v_fma_f32 v60, -v50, v56, 1.0
	v_div_scale_f32 v47, vcc, 1.0, v37, 1.0
	v_div_scale_f32 v49, s[4:5], 1.0, v36, 1.0
	v_div_scale_f32 v51, s[6:7], 1.0, v45, 1.0
	v_fmac_f32_e32 v54, v58, v54
	v_fmac_f32_e32 v55, v59, v55
	v_fmac_f32_e32 v56, v60, v56
	v_mul_f32_e32 v58, v47, v54
	v_mul_f32_e32 v59, v49, v55
	v_mul_f32_e32 v60, v51, v56
	v_fma_f32 v62, -v46, v58, v47
	v_fma_f32 v63, -v48, v59, v49
	v_fma_f32 v64, -v50, v60, v51
	v_fma_f32 v61, -v52, v57, 1.0
	v_fmac_f32_e32 v58, v62, v54
	v_fmac_f32_e32 v59, v63, v55
	v_fmac_f32_e32 v60, v64, v56
	v_div_scale_f32 v53, s[8:9], 1.0, v44, 1.0
	v_fmac_f32_e32 v57, v61, v57
	v_fma_f32 v46, -v46, v58, v47
	v_fma_f32 v47, -v48, v59, v49
	v_fma_f32 v48, -v50, v60, v51
	v_add_f32_e32 v50, v30, v31
	v_pk_mul_f32 v[30:31], v[32:33], v[32:33]
	v_mul_f32_e32 v61, v53, v57
	v_add_f32_e32 v30, v30, v50
	v_fma_f32 v65, -v52, v61, v53
	v_add_f32_e32 v50, v31, v30
	v_div_fmas_f32 v30, v46, v54, v58
	s_mov_b64 vcc, s[4:5]
	v_pk_mul_f32 v[18:19], v[18:19], v[18:19]
	v_fmac_f32_e32 v61, v65, v57
	v_div_fixup_f32 v31, v30, v37, 1.0
	v_div_fmas_f32 v30, v47, v55, v59
	s_mov_b64 vcc, s[6:7]
	v_pk_mul_f32 v[20:21], v[20:21], v[20:21]
	v_add_f32_e32 v18, v18, v19
	v_fma_f32 v49, -v52, v61, v53
	v_div_fmas_f32 v32, v48, v56, v60
	s_mov_b64 vcc, s[8:9]
	v_add_f32_e32 v22, v24, v22
	v_add_f32_e32 v18, v20, v18
	v_div_fixup_f32 v30, v30, v36, 1.0
	v_div_fixup_f32 v33, v32, v45, 1.0
	v_div_fmas_f32 v32, v49, v57, v61
	v_add_f32_e32 v22, v25, v22
	v_add_f32_e32 v37, v21, v18
	v_div_fixup_f32 v32, v32, v44, 1.0
	v_add_f32_e32 v36, v50, v22
	s_waitcnt lgkmcnt(0)
	v_mov_b32_e32 v34, v202
	v_mov_b32_e32 v35, v203
	v_mov_b32_e32 v26, v192
	v_mov_b32_e32 v27, v193
	v_mov_b32_e32 v28, v194
	v_mov_b32_e32 v29, v195
	v_lshlrev_b32_e32 v18, 16, v34
	v_and_b32_e32 v19, 0xffff0000, v34
	v_lshlrev_b32_e32 v22, 16, v35
	v_and_b32_e32 v23, 0xffff0000, v35
	v_pk_fma_f32 v[20:21], v[30:31], v[18:19], v[26:27]
	v_pk_fma_f32 v[22:23], v[32:33], v[22:23], v[28:29]
	v_pk_mul_f32 v[18:19], v[20:21], v[20:21]
	v_pk_mul_f32 v[24:25], v[22:23], v[22:23]
	v_add_f32_e32 v18, v18, v19
	v_add_f32_e32 v18, v24, v18
	v_add_f32_e32 v26, v36, v37
	v_add_f32_e32 v18, v25, v18
	v_add_f32_e32 v18, v26, v18
	ds_bpermute_b32 v19, v126, v18
	global_store_dwordx4 v[40:41], v[20:23], off offset:192
	s_waitcnt lgkmcnt(0)
	v_add_f32_e32 v18, v18, v19
	ds_bpermute_b32 v19, v127, v18
	v_cvt_pk_bf16_f32 v20, v20, v21
	v_cvt_pk_bf16_f32 v21, v22, v23
	global_store_dwordx2 v[42:43], v[20:21], off offset:96
	s_and_saveexec_b64 s[4:5], s[0:1]
	s_cbranch_execz .LBB0_636
	s_waitcnt lgkmcnt(0)
	v_add_f32_e32 v20, v18, v19
	v_lshl_add_u64 v[18:19], v[38:39], 2, s[20:21]
	global_atomic_add_f32 v[18:19], v20, off
.LBB0_636:
	s_or_b64 exec, exec, s[4:5]
	v_or_b32_e32 v140, 0x70, v140
	s_waitcnt lgkmcnt(0)
	v_lshl_add_u64 v[18:19], v[140:141], 2, s[18:19]
	s_nop 0
	v_lshlrev_b64 v[18:19], 11, v[140:141]
	v_lshl_add_u64 v[20:21], s[14:15], 0, v[18:19]
	v_lshl_add_u64 v[26:27], v[20:21], 0, v[142:143]
	v_lshlrev_b64 v[20:21], 12, v[140:141]
	v_lshl_add_u64 v[20:21], v[134:135], 0, v[20:21]
	s_nop 0
	v_lshl_add_u64 v[18:19], s[16:17], 0, v[18:19]
	v_lshl_add_u64 v[22:23], v[20:21], 0, v[138:139]
	v_lshl_add_u64 v[24:25], v[18:19], 0, v[142:143]
	s_nop 0
	s_waitcnt vmcnt(8) lgkmcnt(0)
	v_mov_b32_e32 v30, v229
	v_mov_b32_e32 v28, v220
	v_mov_b32_e32 v29, v221
	v_mov_b32_e32 v18, v204
	v_mov_b32_e32 v19, v205
	v_mov_b32_e32 v20, v206
	v_mov_b32_e32 v21, v207
	v_fmamk_f32 v30, v30, 0x3a800000, v153
	v_mul_f32_e32 v31, 0x4b800000, v30
	v_cmp_gt_f32_e32 vcc, s56, v30
	s_nop 1
	v_cndmask_b32_e32 v31, v30, v31, vcc
	v_rsq_f32_e32 v32, v31
	v_lshlrev_b32_e32 v30, 16, v28
	v_and_b32_e32 v31, 0xffff0000, v28
	v_lshlrev_b32_e32 v28, 16, v29
	v_mul_f32_e32 v33, 0x45800000, v32
	v_cndmask_b32_e32 v32, v32, v33, vcc
	v_mul_f32_e32 v14, v14, v32
	v_mul_f32_e32 v15, v15, v32
	v_mul_f32_e32 v14, 0xbfb8aa3b, v14
	v_mul_f32_e32 v15, 0xbfb8aa3b, v15
	v_mul_f32_e32 v16, v16, v32
	v_mul_f32_e32 v17, v17, v32
	v_exp_f32_e32 v14, v14
	v_exp_f32_e32 v15, v15
	v_mul_f32_e32 v16, 0xbfb8aa3b, v16
	v_mul_f32_e32 v17, 0xbfb8aa3b, v17
	v_exp_f32_e32 v16, v16
	v_exp_f32_e32 v17, v17
	v_mul_f32_e32 v33, v10, v32
	v_mul_f32_e32 v34, v11, v32
	v_pk_add_f32 v[10:11], v[14:15], 1.0 op_sel_hi:[1,0]
	v_pk_add_f32 v[16:17], v[16:17], 1.0 op_sel_hi:[1,0]
	v_div_scale_f32 v14, s[4:5], v11, v11, 1.0
	v_div_scale_f32 v35, s[4:5], v10, v10, 1.0
	v_rcp_f32_e32 v41, v14
	v_div_scale_f32 v37, s[6:7], v17, v17, 1.0
	v_rcp_f32_e32 v42, v35
	v_div_scale_f32 v39, s[8:9], v16, v16, 1.0
	v_rcp_f32_e32 v43, v37
	v_rcp_f32_e32 v44, v39
	v_fma_f32 v45, -v14, v41, 1.0
	v_div_scale_f32 v15, vcc, 1.0, v11, 1.0
	v_fma_f32 v46, -v35, v42, 1.0
	v_fmac_f32_e32 v41, v45, v41
	v_div_scale_f32 v36, s[4:5], 1.0, v10, 1.0
	v_fma_f32 v47, -v37, v43, 1.0
	v_fmac_f32_e32 v42, v46, v42
	v_mul_f32_e32 v45, v15, v41
	v_div_scale_f32 v38, s[6:7], 1.0, v17, 1.0
	v_fma_f32 v48, -v39, v44, 1.0
	v_fmac_f32_e32 v43, v47, v43
	v_mul_f32_e32 v46, v36, v42
	v_fma_f32 v49, -v14, v45, v15
	v_div_scale_f32 v40, s[8:9], 1.0, v16, 1.0
	v_fmac_f32_e32 v44, v48, v44
	v_mul_f32_e32 v47, v38, v43
	v_fma_f32 v50, -v35, v46, v36
	v_fmac_f32_e32 v45, v49, v41
	v_mul_f32_e32 v48, v40, v44
	v_fma_f32 v51, -v37, v47, v38
	v_fmac_f32_e32 v46, v50, v42
	v_fma_f32 v14, -v14, v45, v15
	v_fma_f32 v52, -v39, v48, v40
	v_fmac_f32_e32 v47, v51, v43
	v_fma_f32 v15, -v35, v46, v36
	v_div_fmas_f32 v14, v14, v41, v45
	s_mov_b64 vcc, s[4:5]
	v_fmac_f32_e32 v48, v52, v44
	v_fma_f32 v35, -v37, v47, v38
	v_div_fixup_f32 v11, v14, v11, 1.0
	v_div_fmas_f32 v14, v15, v42, v46
	s_mov_b64 vcc, s[6:7]
	v_fma_f32 v36, -v39, v48, v40
	v_div_fixup_f32 v10, v14, v10, 1.0
	v_div_fmas_f32 v35, v35, v43, v47
	s_mov_b64 vcc, s[8:9]
	v_pk_fma_f32 v[14:15], v[10:11], v[30:31], v[18:19]
	v_div_fmas_f32 v10, v36, v44, v48
	v_and_b32_e32 v29, 0xffff0000, v29
	v_div_fixup_f32 v11, v35, v17, 1.0
	v_div_fixup_f32 v10, v10, v16, 1.0
	v_pk_fma_f32 v[16:17], v[10:11], v[28:29], v[20:21]
	global_store_dwordx4 v[22:23], v[14:17], off
	v_cvt_pk_bf16_f32 v18, v14, v15
	v_cvt_pk_bf16_f32 v19, v16, v17
	s_nop 0
	v_mul_f32_e32 v12, v12, v32
	global_store_dwordx2 v[24:25], v[18:19], off
	s_nop 0
	v_mul_f32_e32 v13, v13, v32
	v_mul_f32_e32 v29, v7, v32
	v_mul_f32_e32 v35, v2, v32
	v_mul_f32_e32 v2, 0xbfb8aa3b, v33
	v_mul_f32_e32 v7, 0xbfb8aa3b, v34
	v_mul_f32_e32 v28, v6, v32
	v_mul_f32_e32 v30, v8, v32
	v_mul_f32_e32 v31, v9, v32
	v_mul_f32_e32 v8, 0xbfb8aa3b, v12
	v_mul_f32_e32 v9, 0xbfb8aa3b, v13
	v_exp_f32_e32 v6, v2
	v_exp_f32_e32 v7, v7
	v_exp_f32_e32 v8, v8
	v_exp_f32_e32 v9, v9
	v_mul_f32_e32 v33, v3, v32
	v_pk_add_f32 v[2:3], v[6:7], 1.0 op_sel_hi:[1,0]
	v_mul_f32_e32 v4, v4, v32
	v_pk_add_f32 v[6:7], v[8:9], 1.0 op_sel_hi:[1,0]
	v_div_scale_f32 v8, s[4:5], v3, v3, 1.0
	v_div_scale_f32 v12, s[4:5], v2, v2, 1.0
	v_rcp_f32_e32 v39, v8
	v_div_scale_f32 v34, s[6:7], v7, v7, 1.0
	v_rcp_f32_e32 v40, v12
	v_div_scale_f32 v37, s[8:9], v6, v6, 1.0
	v_rcp_f32_e32 v41, v34
	v_rcp_f32_e32 v42, v37
	v_fma_f32 v43, -v8, v39, 1.0
	v_div_scale_f32 v9, vcc, 1.0, v3, 1.0
	v_fma_f32 v44, -v12, v40, 1.0
	v_fmac_f32_e32 v39, v43, v39
	v_div_scale_f32 v13, s[4:5], 1.0, v2, 1.0
	v_fma_f32 v45, -v34, v41, 1.0
	v_fmac_f32_e32 v40, v44, v40
	v_mul_f32_e32 v43, v9, v39
	v_div_scale_f32 v36, s[6:7], 1.0, v7, 1.0
	v_fma_f32 v46, -v37, v42, 1.0
	v_fmac_f32_e32 v41, v45, v41
	v_mul_f32_e32 v44, v13, v40
	v_fma_f32 v47, -v8, v43, v9
	v_div_scale_f32 v38, s[8:9], 1.0, v6, 1.0
	v_fmac_f32_e32 v42, v46, v42
	v_mul_f32_e32 v45, v36, v41
	v_fma_f32 v48, -v12, v44, v13
	v_fmac_f32_e32 v43, v47, v39
	v_mul_f32_e32 v46, v38, v42
	v_fma_f32 v49, -v34, v45, v36
	v_fmac_f32_e32 v44, v48, v40
	v_fma_f32 v8, -v8, v43, v9
	v_fma_f32 v50, -v37, v46, v38
	v_fmac_f32_e32 v45, v49, v41
	v_fma_f32 v9, -v12, v44, v13
	v_div_fmas_f32 v8, v8, v39, v43
	s_mov_b64 vcc, s[4:5]
	v_fmac_f32_e32 v46, v50, v42
	v_fma_f32 v12, -v34, v45, v36
	v_div_fixup_f32 v3, v8, v3, 1.0
	v_div_fmas_f32 v8, v9, v40, v44
	s_mov_b64 vcc, s[6:7]
	v_fma_f32 v13, -v37, v46, v38
	v_div_fixup_f32 v2, v8, v2, 1.0
	v_div_fmas_f32 v8, v12, v41, v45
	s_mov_b64 vcc, s[8:9]
	v_div_fixup_f32 v9, v8, v7, 1.0
	v_div_fmas_f32 v7, v13, v42, v46
	v_div_fixup_f32 v8, v7, v6, 1.0
	v_mul_f32_e32 v5, v5, v32
	v_pk_mul_f32 v[14:15], v[14:15], v[14:15]
	s_waitcnt lgkmcnt(0)
	v_mov_b32_e32 v10, v222
	v_mov_b32_e32 v11, v223
	v_mov_b32_e32 v18, v208
	v_mov_b32_e32 v19, v209
	v_mov_b32_e32 v20, v210
	v_mov_b32_e32 v21, v211
	v_lshlrev_b32_e32 v6, 16, v10
	v_and_b32_e32 v7, 0xffff0000, v10
	v_lshlrev_b32_e32 v10, 16, v11
	v_and_b32_e32 v11, 0xffff0000, v11
	v_pk_fma_f32 v[6:7], v[2:3], v[6:7], v[18:19]
	v_pk_fma_f32 v[8:9], v[8:9], v[10:11], v[20:21]
	global_store_dwordx4 v[22:23], v[6:9], off offset:64
	v_cvt_pk_bf16_f32 v10, v6, v7
	v_cvt_pk_bf16_f32 v11, v8, v9
	s_nop 0
	v_mul_f32_e32 v18, 0xbfb8aa3b, v28
	global_store_dwordx2 v[24:25], v[10:11], off offset:32
	s_nop 0
	v_mul_f32_e32 v19, 0xbfb8aa3b, v29
	v_mul_f32_e32 v20, 0xbfb8aa3b, v30
	v_mul_f32_e32 v21, 0xbfb8aa3b, v31
	v_mul_f32_e32 v30, 0xbfb8aa3b, v4
	v_mul_f32_e32 v31, 0xbfb8aa3b, v5
	v_exp_f32_e32 v4, v18
	v_exp_f32_e32 v5, v19
	v_exp_f32_e32 v18, v20
	v_exp_f32_e32 v19, v21
	v_mul_f32_e32 v28, 0xbfb8aa3b, v35
	v_pk_add_f32 v[4:5], v[4:5], 1.0 op_sel_hi:[1,0]
	v_exp_f32_e32 v20, v28
	v_exp_f32_e32 v28, v30
	v_div_scale_f32 v30, s[4:5], v5, v5, 1.0
	v_pk_add_f32 v[18:19], v[18:19], 1.0 op_sel_hi:[1,0]
	v_div_scale_f32 v32, s[4:5], v4, v4, 1.0
	v_rcp_f32_e32 v38, v30
	v_div_scale_f32 v34, s[6:7], v19, v19, 1.0
	v_rcp_f32_e32 v39, v32
	v_div_scale_f32 v36, s[8:9], v18, v18, 1.0
	v_rcp_f32_e32 v40, v34
	v_rcp_f32_e32 v41, v36
	v_mul_f32_e32 v29, 0xbfb8aa3b, v33
	v_fma_f32 v42, -v30, v38, 1.0
	v_exp_f32_e32 v21, v29
	v_exp_f32_e32 v29, v31
	v_div_scale_f32 v31, vcc, 1.0, v5, 1.0
	v_fma_f32 v43, -v32, v39, 1.0
	v_fmac_f32_e32 v38, v42, v38
	v_div_scale_f32 v33, s[4:5], 1.0, v4, 1.0
	v_fma_f32 v44, -v34, v40, 1.0
	v_fmac_f32_e32 v39, v43, v39
	v_mul_f32_e32 v42, v31, v38
	v_div_scale_f32 v35, s[6:7], 1.0, v19, 1.0
	v_fma_f32 v45, -v36, v41, 1.0
	v_fmac_f32_e32 v40, v44, v40
	v_mul_f32_e32 v43, v33, v39
	v_fma_f32 v46, -v30, v42, v31
	v_div_scale_f32 v37, s[8:9], 1.0, v18, 1.0
	v_fmac_f32_e32 v41, v45, v41
	v_mul_f32_e32 v44, v35, v40
	v_fma_f32 v47, -v32, v43, v33
	v_fmac_f32_e32 v42, v46, v38
	v_mul_f32_e32 v45, v37, v41
	v_fma_f32 v48, -v34, v44, v35
	v_fmac_f32_e32 v43, v47, v39
	v_fma_f32 v30, -v30, v42, v31
	v_fma_f32 v49, -v36, v45, v37
	v_fmac_f32_e32 v44, v48, v40
	v_fma_f32 v31, -v32, v43, v33
	v_div_fmas_f32 v30, v30, v38, v42
	s_mov_b64 vcc, s[4:5]
	v_fmac_f32_e32 v45, v49, v41
	v_fma_f32 v32, -v34, v44, v35
	v_div_fixup_f32 v5, v30, v5, 1.0
	v_div_fmas_f32 v30, v31, v39, v43
	s_mov_b64 vcc, s[6:7]
	v_fma_f32 v33, -v36, v45, v37
	v_div_fixup_f32 v4, v30, v4, 1.0
	v_div_fmas_f32 v30, v32, v40, v44
	s_mov_b64 vcc, s[8:9]
	v_div_fixup_f32 v19, v30, v19, 1.0
	v_div_fmas_f32 v30, v33, v41, v45
	v_div_fixup_f32 v18, v30, v18, 1.0
	v_pk_add_f32 v[20:21], v[20:21], 1.0 op_sel_hi:[1,0]
	v_pk_mul_f32 v[6:7], v[6:7], v[6:7]
	v_pk_mul_f32 v[8:9], v[8:9], v[8:9]
	v_add_f32_e32 v6, v6, v7
	s_waitcnt lgkmcnt(0)
	v_mov_b32_e32 v2, v224
	v_mov_b32_e32 v3, v225
	v_mov_b32_e32 v10, v212
	v_mov_b32_e32 v11, v213
	v_mov_b32_e32 v12, v214
	v_mov_b32_e32 v13, v215
	v_lshlrev_b32_e32 v30, 16, v2
	v_and_b32_e32 v31, 0xffff0000, v2
	v_lshlrev_b32_e32 v32, 16, v3
	v_and_b32_e32 v33, 0xffff0000, v3
	v_pk_fma_f32 v[2:3], v[4:5], v[30:31], v[10:11]
	v_pk_fma_f32 v[4:5], v[18:19], v[32:33], v[12:13]
	global_store_dwordx4 v[22:23], v[2:5], off offset:128
	v_cvt_pk_bf16_f32 v10, v2, v3
	v_cvt_pk_bf16_f32 v11, v4, v5
	s_nop 0
	v_pk_add_f32 v[26:27], v[28:29], 1.0 op_sel_hi:[1,0]
	global_store_dwordx2 v[24:25], v[10:11], off offset:64
	s_nop 0
	v_div_scale_f32 v28, s[4:5], v21, v21, 1.0
	v_div_scale_f32 v30, s[4:5], v20, v20, 1.0
	v_div_scale_f32 v32, s[6:7], v27, v27, 1.0
	v_rcp_f32_e32 v36, v28
	v_rcp_f32_e32 v37, v30
	v_rcp_f32_e32 v38, v32
	v_div_scale_f32 v34, s[8:9], v26, v26, 1.0
	v_rcp_f32_e32 v39, v34
	v_fma_f32 v40, -v28, v36, 1.0
	v_fma_f32 v41, -v30, v37, 1.0
	v_fma_f32 v42, -v32, v38, 1.0
	v_div_scale_f32 v29, vcc, 1.0, v21, 1.0
	v_div_scale_f32 v31, s[4:5], 1.0, v20, 1.0
	v_div_scale_f32 v33, s[6:7], 1.0, v27, 1.0
	v_fmac_f32_e32 v36, v40, v36
	v_fmac_f32_e32 v37, v41, v37
	v_fmac_f32_e32 v38, v42, v38
	v_mul_f32_e32 v40, v29, v36
	v_mul_f32_e32 v41, v31, v37
	v_mul_f32_e32 v42, v33, v38
	v_fma_f32 v44, -v28, v40, v29
	v_fma_f32 v45, -v30, v41, v31
	v_fma_f32 v46, -v32, v42, v33
	v_fma_f32 v43, -v34, v39, 1.0
	v_fmac_f32_e32 v40, v44, v36
	v_fmac_f32_e32 v41, v45, v37
	v_fmac_f32_e32 v42, v46, v38
	v_div_scale_f32 v35, s[8:9], 1.0, v26, 1.0
	v_fmac_f32_e32 v39, v43, v39
	v_fma_f32 v28, -v28, v40, v29
	v_fma_f32 v29, -v30, v41, v31
	v_fma_f32 v30, -v32, v42, v33
	v_add_f32_e32 v32, v14, v15
	v_pk_mul_f32 v[14:15], v[16:17], v[16:17]
	v_mul_f32_e32 v43, v35, v39
	v_add_f32_e32 v14, v14, v32
	v_fma_f32 v47, -v34, v43, v35
	v_add_f32_e32 v32, v15, v14
	v_div_fmas_f32 v14, v28, v36, v40
	s_mov_b64 vcc, s[4:5]
	v_pk_mul_f32 v[2:3], v[2:3], v[2:3]
	v_fmac_f32_e32 v43, v47, v39
	v_div_fixup_f32 v15, v14, v21, 1.0
	v_div_fmas_f32 v14, v29, v37, v41
	s_mov_b64 vcc, s[6:7]
	v_pk_mul_f32 v[4:5], v[4:5], v[4:5]
	v_add_f32_e32 v2, v2, v3
	v_fma_f32 v31, -v34, v43, v35
	v_div_fmas_f32 v16, v30, v38, v42
	s_mov_b64 vcc, s[8:9]
	v_add_f32_e32 v6, v8, v6
	v_add_f32_e32 v2, v4, v2
	v_div_fixup_f32 v14, v14, v20, 1.0
	v_div_fixup_f32 v17, v16, v27, 1.0
	v_div_fmas_f32 v16, v31, v39, v43
	v_add_f32_e32 v6, v9, v6
	v_add_f32_e32 v21, v5, v2
	v_div_fixup_f32 v16, v16, v26, 1.0
	v_add_f32_e32 v20, v32, v6
	s_waitcnt lgkmcnt(0)
	v_mov_b32_e32 v18, v226
	v_mov_b32_e32 v19, v227
	v_mov_b32_e32 v10, v216
	v_mov_b32_e32 v11, v217
	v_mov_b32_e32 v12, v218
	v_mov_b32_e32 v13, v219
	v_lshlrev_b32_e32 v2, 16, v18
	v_and_b32_e32 v3, 0xffff0000, v18
	v_lshlrev_b32_e32 v6, 16, v19
	v_and_b32_e32 v7, 0xffff0000, v19
	v_pk_fma_f32 v[4:5], v[14:15], v[2:3], v[10:11]
	v_pk_fma_f32 v[6:7], v[16:17], v[6:7], v[12:13]
	v_pk_mul_f32 v[2:3], v[4:5], v[4:5]
	v_pk_mul_f32 v[8:9], v[6:7], v[6:7]
	v_add_f32_e32 v2, v2, v3
	v_add_f32_e32 v2, v8, v2
	v_add_f32_e32 v10, v20, v21
	v_add_f32_e32 v2, v9, v2
	v_add_f32_e32 v2, v10, v2
	ds_bpermute_b32 v3, v126, v2
	global_store_dwordx4 v[22:23], v[4:7], off offset:192
	s_waitcnt lgkmcnt(0)
	v_add_f32_e32 v2, v2, v3
	ds_bpermute_b32 v3, v127, v2
	v_cvt_pk_bf16_f32 v4, v4, v5
	v_cvt_pk_bf16_f32 v5, v6, v7
	global_store_dwordx2 v[24:25], v[4:5], off offset:96
	s_and_saveexec_b64 s[4:5], s[0:1]
	s_cbranch_execz .LBB0_619
	s_waitcnt lgkmcnt(0)
	v_add_f32_e32 v4, v2, v3
	v_lshl_add_u64 v[2:3], v[140:141], 2, s[20:21]
	global_atomic_add_f32 v[2:3], v4, off
	s_branch .LBB0_619

.LBB0_1356:
	s_mul_i32 s43, s1, 0x6000
	s_add_i32 s50, s43, 0xffffa000
	s_cmp_lg_u32 s1, 0
	s_cselect_b32 s50, s50, 0xc000
	v_add_u32_e32 v148, s50, v141
	v_lshl_add_u64 v[144:145], v[136:137], 0, s[48:49]
	v_readfirstlane_b32 s50, v148
	v_add_u32_e32 v149, 0x1000, v148
	v_lshl_add_u64 v[146:147], v[144:145], 0, s[24:25]
	s_mov_b32 m0, s50
	v_readfirstlane_b32 s50, v149
	v_add_u32_e32 v149, 0x2000, v148
	s_waitcnt vmcnt(6)
	s_barrier
	global_load_lds_dwordx4 v[146:147], off
	v_lshl_add_u64 v[146:147], v[144:145], 0, s[26:27]
	s_mov_b32 m0, s50
	v_readfirstlane_b32 s50, v149
	global_load_lds_dwordx4 v[146:147], off
	v_lshl_add_u64 v[146:147], v[144:145], 0, s[28:29]
	s_mov_b32 m0, s50
	v_lshl_add_u64 v[144:145], v[144:145], 0, s[30:31]
	global_load_lds_dwordx4 v[146:147], off
	v_add_u32_e32 v146, 0x3000, v148
	v_add_u32_e32 v149, 0x4000, v148
	v_readfirstlane_b32 s50, v146
	s_mov_b32 m0, s50
	v_readfirstlane_b32 s50, v149
	global_load_lds_dwordx4 v[144:145], off
	v_lshl_add_u64 v[144:145], v[134:135], 0, s[48:49]
	v_lshl_add_u64 v[146:147], v[144:145], 0, s[34:35]
	s_mov_b32 m0, s50
	v_lshl_add_u64 v[144:145], v[144:145], 0, s[44:45]
	global_load_lds_dwordx4 v[146:147], off
	v_add_u32_e32 v146, 0x5000, v148
	s_add_i32 s43, s43, 0
	v_readfirstlane_b32 s50, v146
	s_mov_b32 m0, s50
	v_add3_u32 v156, s43, v140, v143
	global_load_lds_dwordx4 v[144:145], off
	v_add3_u32 v176, s43, v142, v143
	ds_read_b128 v[144:147], v156 offset:16384
	ds_read_b128 v[148:151], v156 offset:17408
	ds_read_b128 v[152:155], v156 offset:18432
	ds_read_b128 v[156:159], v156 offset:19456
	ds_read_b128 v[160:163], v176
	ds_read_b128 v[164:167], v176 offset:1024
	ds_read_b128 v[168:171], v176 offset:2048
	ds_read_b128 v[172:175], v176 offset:3072
	s_setprio 1
	s_waitcnt lgkmcnt(0)
	v_mfma_f32_16x16x32_bf16 v[126:129], v[144:147], v[160:163], v[126:129]
	v_mfma_f32_16x16x32_bf16 v[122:125], v[148:151], v[160:163], v[122:125]
	v_mfma_f32_16x16x32_bf16 v[118:121], v[152:155], v[160:163], v[118:121]
	v_mfma_f32_16x16x32_bf16 v[114:117], v[156:159], v[160:163], v[114:117]
	v_mfma_f32_16x16x32_bf16 v[110:113], v[144:147], v[164:167], v[110:113]
	v_mfma_f32_16x16x32_bf16 v[106:109], v[148:151], v[164:167], v[106:109]
	v_mfma_f32_16x16x32_bf16 v[102:105], v[152:155], v[164:167], v[102:105]
	v_mfma_f32_16x16x32_bf16 v[98:101], v[156:159], v[164:167], v[98:101]
	v_mfma_f32_16x16x32_bf16 v[94:97], v[144:147], v[168:171], v[94:97]
	v_mfma_f32_16x16x32_bf16 v[90:93], v[148:151], v[168:171], v[90:93]
	v_mfma_f32_16x16x32_bf16 v[86:89], v[152:155], v[168:171], v[86:89]
	v_mfma_f32_16x16x32_bf16 v[82:85], v[156:159], v[168:171], v[82:85]
	v_mfma_f32_16x16x32_bf16 v[78:81], v[144:147], v[172:175], v[78:81]
	v_mfma_f32_16x16x32_bf16 v[74:77], v[148:151], v[172:175], v[74:77]
	v_mfma_f32_16x16x32_bf16 v[70:73], v[152:155], v[172:175], v[70:73]
	v_mfma_f32_16x16x32_bf16 v[66:69], v[156:159], v[172:175], v[66:69]
	s_setprio 0
	ds_read_b128 v[160:163], v176 offset:4096
	ds_read_b128 v[164:167], v176 offset:5120
	ds_read_b128 v[168:171], v176 offset:6144
	ds_read_b128 v[172:175], v176 offset:7168
	s_setprio 1
	s_waitcnt lgkmcnt(0)
	v_mfma_f32_16x16x32_bf16 v[62:65], v[144:147], v[160:163], v[62:65]
	v_mfma_f32_16x16x32_bf16 v[58:61], v[148:151], v[160:163], v[58:61]
	v_mfma_f32_16x16x32_bf16 v[54:57], v[152:155], v[160:163], v[54:57]
	v_mfma_f32_16x16x32_bf16 v[50:53], v[156:159], v[160:163], v[50:53]
	v_mfma_f32_16x16x32_bf16 v[46:49], v[144:147], v[164:167], v[46:49]
	v_mfma_f32_16x16x32_bf16 v[42:45], v[148:151], v[164:167], v[42:45]
	v_mfma_f32_16x16x32_bf16 v[38:41], v[152:155], v[164:167], v[38:41]
	v_mfma_f32_16x16x32_bf16 v[34:37], v[156:159], v[164:167], v[34:37]
	v_mfma_f32_16x16x32_bf16 v[30:33], v[144:147], v[168:171], v[30:33]
	v_mfma_f32_16x16x32_bf16 v[26:29], v[148:151], v[168:171], v[26:29]
	v_mfma_f32_16x16x32_bf16 v[22:25], v[152:155], v[168:171], v[22:25]
	v_mfma_f32_16x16x32_bf16 v[18:21], v[156:159], v[168:171], v[18:21]
	v_mfma_f32_16x16x32_bf16 v[14:17], v[144:147], v[172:175], v[14:17]
	v_mfma_f32_16x16x32_bf16 v[10:13], v[148:151], v[172:175], v[10:13]
	v_mfma_f32_16x16x32_bf16 v[6:9], v[152:155], v[172:175], v[6:9]
	v_mfma_f32_16x16x32_bf16 v[2:5], v[156:159], v[172:175], v[2:5]
	s_setprio 0
	s_add_i32 s43, s1, 1
	s_cmp_lg_u32 s1, 2
	s_cselect_b32 s1, s43, 0
	s_add_u32 s48, s48, 64
	s_addc_u32 s49, s49, 0
	s_cmpk_eq_i32 s48, 0x780
	s_cbranch_scc0 .LBB0_1356
	v_add3_u32 v168, 0, v140, v143
	v_add3_u32 v169, 0, v142, v143
	s_waitcnt vmcnt(6)
	s_barrier
	ds_read_b128 v[134:137], v168 offset:16384
	ds_read_b128 v[144:147], v168 offset:17408
	ds_read_b128 v[148:151], v168 offset:18432
	ds_read_b128 v[152:155], v168 offset:19456
	ds_read_b128 v[140:143], v169
	ds_read_b128 v[156:159], v169 offset:1024
	ds_read_b128 v[160:163], v169 offset:2048
	ds_read_b128 v[164:167], v169 offset:3072
	s_lshl_b64 s[46:47], s[46:47], 8
	s_setprio 1
	s_waitcnt lgkmcnt(0)
	v_mfma_f32_16x16x32_bf16 v[118:121], v[148:151], v[140:143], v[118:121]
	v_mfma_f32_16x16x32_bf16 v[114:117], v[152:155], v[140:143], v[114:117]
	v_mfma_f32_16x16x32_bf16 v[110:113], v[134:137], v[156:159], v[110:113]
	v_mfma_f32_16x16x32_bf16 v[106:109], v[144:147], v[156:159], v[106:109]
	v_mfma_f32_16x16x32_bf16 v[102:105], v[148:151], v[156:159], v[102:105]
	v_mfma_f32_16x16x32_bf16 v[98:101], v[152:155], v[156:159], v[98:101]
	v_mfma_f32_16x16x32_bf16 v[94:97], v[134:137], v[160:163], v[94:97]
	v_mfma_f32_16x16x32_bf16 v[90:93], v[144:147], v[160:163], v[90:93]
	v_mfma_f32_16x16x32_bf16 v[86:89], v[148:151], v[160:163], v[86:89]
	v_mfma_f32_16x16x32_bf16 v[82:85], v[152:155], v[160:163], v[82:85]
	v_mfma_f32_16x16x32_bf16 v[78:81], v[134:137], v[164:167], v[78:81]
	v_mfma_f32_16x16x32_bf16 v[74:77], v[144:147], v[164:167], v[74:77]
	v_mfma_f32_16x16x32_bf16 v[70:73], v[148:151], v[164:167], v[70:73]
	v_mfma_f32_16x16x32_bf16 v[66:69], v[152:155], v[164:167], v[66:69]
	v_mfma_f32_16x16x32_bf16 v[126:129], v[134:137], v[140:143], v[126:129]
	v_mfma_f32_16x16x32_bf16 v[122:125], v[144:147], v[140:143], v[122:125]
	s_setprio 0
	ds_read_b128 v[140:143], v169 offset:4096
	ds_read_b128 v[156:159], v169 offset:5120
	ds_read_b128 v[160:163], v169 offset:6144
	ds_read_b128 v[164:167], v169 offset:7168
	s_setprio 1
	s_waitcnt lgkmcnt(0)
	v_mfma_f32_16x16x32_bf16 v[62:65], v[134:137], v[140:143], v[62:65]
	v_mfma_f32_16x16x32_bf16 v[58:61], v[144:147], v[140:143], v[58:61]
	v_mfma_f32_16x16x32_bf16 v[54:57], v[148:151], v[140:143], v[54:57]
	v_mfma_f32_16x16x32_bf16 v[50:53], v[152:155], v[140:143], v[50:53]
	v_mfma_f32_16x16x32_bf16 v[46:49], v[134:137], v[156:159], v[46:49]
	v_mfma_f32_16x16x32_bf16 v[42:45], v[144:147], v[156:159], v[42:45]
	v_mfma_f32_16x16x32_bf16 v[38:41], v[148:151], v[156:159], v[38:41]
	v_mfma_f32_16x16x32_bf16 v[34:37], v[152:155], v[156:159], v[34:37]
	v_mfma_f32_16x16x32_bf16 v[30:33], v[134:137], v[160:163], v[30:33]
	v_mfma_f32_16x16x32_bf16 v[26:29], v[144:147], v[160:163], v[26:29]
	v_mfma_f32_16x16x32_bf16 v[22:25], v[148:151], v[160:163], v[22:25]
	v_mfma_f32_16x16x32_bf16 v[18:21], v[152:155], v[160:163], v[18:21]
	v_mfma_f32_16x16x32_bf16 v[14:17], v[134:137], v[164:167], v[14:17]
	v_mfma_f32_16x16x32_bf16 v[10:13], v[144:147], v[164:167], v[10:13]
	v_mfma_f32_16x16x32_bf16 v[6:9], v[148:151], v[164:167], v[6:9]
	v_mfma_f32_16x16x32_bf16 v[2:5], v[152:155], v[164:167], v[2:5]
	s_setprio 0
	s_waitcnt vmcnt(0)
	s_barrier
	ds_read_b128 v[134:137], v168 offset:40960
	ds_read_b128 v[140:143], v168 offset:41984
	ds_read_b128 v[144:147], v168 offset:43008
	ds_read_b128 v[148:151], v168 offset:44032
	ds_read_b128 v[152:155], v169 offset:24576
	ds_read_b128 v[156:159], v169 offset:25600
	ds_read_b128 v[160:163], v169 offset:26624
	ds_read_b128 v[164:167], v169 offset:27648
	s_setprio 1
	s_waitcnt lgkmcnt(0)
	v_mfma_f32_16x16x32_bf16 v[118:121], v[144:147], v[152:155], v[118:121]
	v_mfma_f32_16x16x32_bf16 v[110:113], v[134:137], v[156:159], v[110:113]
	v_mfma_f32_16x16x32_bf16 v[106:109], v[140:143], v[156:159], v[106:109]
	v_mfma_f32_16x16x32_bf16 v[102:105], v[144:147], v[156:159], v[102:105]
	v_mfma_f32_16x16x32_bf16 v[98:101], v[148:151], v[156:159], v[98:101]
	v_mfma_f32_16x16x32_bf16 v[94:97], v[134:137], v[160:163], v[94:97]
	v_mfma_f32_16x16x32_bf16 v[90:93], v[140:143], v[160:163], v[90:93]
	v_mfma_f32_16x16x32_bf16 v[86:89], v[144:147], v[160:163], v[86:89]
	v_mfma_f32_16x16x32_bf16 v[82:85], v[148:151], v[160:163], v[82:85]
	v_mfma_f32_16x16x32_bf16 v[78:81], v[134:137], v[164:167], v[78:81]
	v_mfma_f32_16x16x32_bf16 v[74:77], v[140:143], v[164:167], v[74:77]
	v_mfma_f32_16x16x32_bf16 v[70:73], v[144:147], v[164:167], v[70:73]
	v_mfma_f32_16x16x32_bf16 v[66:69], v[148:151], v[164:167], v[66:69]
	v_mfma_f32_16x16x32_bf16 v[126:129], v[134:137], v[152:155], v[126:129]
	v_mfma_f32_16x16x32_bf16 v[122:125], v[140:143], v[152:155], v[122:125]
	v_mfma_f32_16x16x32_bf16 v[152:155], v[148:151], v[152:155], v[114:117]
	s_setprio 0
	s_nop 1
	ds_read_b128 v[114:117], v169 offset:28672
	ds_read_b128 v[156:159], v169 offset:29696
	ds_read_b128 v[160:163], v169 offset:30720
	ds_read_b128 v[164:167], v169 offset:31744
	s_setprio 1
	s_waitcnt lgkmcnt(0)
	v_mfma_f32_16x16x32_bf16 v[62:65], v[134:137], v[114:117], v[62:65]
	v_mfma_f32_16x16x32_bf16 v[58:61], v[140:143], v[114:117], v[58:61]
	v_mfma_f32_16x16x32_bf16 v[54:57], v[144:147], v[114:117], v[54:57]
	v_mfma_f32_16x16x32_bf16 v[50:53], v[148:151], v[114:117], v[50:53]
	v_mfma_f32_16x16x32_bf16 v[46:49], v[134:137], v[156:159], v[46:49]
	v_mfma_f32_16x16x32_bf16 v[42:45], v[140:143], v[156:159], v[42:45]
	v_mfma_f32_16x16x32_bf16 v[38:41], v[144:147], v[156:159], v[38:41]
	v_mfma_f32_16x16x32_bf16 v[34:37], v[148:151], v[156:159], v[34:37]
	v_mfma_f32_16x16x32_bf16 v[30:33], v[134:137], v[160:163], v[30:33]
	v_mfma_f32_16x16x32_bf16 v[26:29], v[140:143], v[160:163], v[26:29]
	v_mfma_f32_16x16x32_bf16 v[22:25], v[144:147], v[160:163], v[22:25]
	v_mfma_f32_16x16x32_bf16 v[18:21], v[148:151], v[160:163], v[18:21]
	v_mfma_f32_16x16x32_bf16 v[14:17], v[134:137], v[164:167], v[14:17]
	v_mfma_f32_16x16x32_bf16 v[10:13], v[140:143], v[164:167], v[10:13]
	v_mfma_f32_16x16x32_bf16 v[6:9], v[144:147], v[164:167], v[6:9]
	v_mfma_f32_16x16x32_bf16 v[2:5], v[148:151], v[164:167], v[2:5]
	s_setprio 0
	v_lshl_add_u64 v[114:115], s[46:47], 0, v[132:133]
	v_lshl_or_b32 v116, s0, 7, v138
	v_lshlrev_b64 v[134:135], 12, v[114:115]
	s_waitcnt vmcnt(0)
	v_lshl_add_u64 v[134:135], v[130:131], 0, v[134:135]
	v_ashrrev_i32_e32 v117, 31, v116
	v_lshl_add_u64 v[144:145], v[116:117], 2, v[134:135]
	s_barrier
	v_mov_b32_e32 v212, v144
	v_mov_b32_e32 v213, v145
	global_load_dwordx4 v[180:183], v[212:213], off
	global_load_dwordx4 v[184:187], v[212:213], off offset:64
	global_load_dwordx4 v[188:191], v[212:213], off offset:128
	global_load_dwordx4 v[192:195], v[212:213], off offset:192
	s_mov_b32 s98, 0x10000
	s_mov_b32 s99, 0
	v_lshl_add_u64 v[214:215], v[212:213], 0, s[98:99]
	global_load_dwordx4 v[196:199], v[214:215], off
	global_load_dwordx4 v[200:203], v[214:215], off offset:64
	global_load_dwordx4 v[204:207], v[214:215], off offset:128
	global_load_dwordx4 v[208:211], v[214:215], off offset:192
	v_lshlrev_b64 v[140:141], 11, v[114:115]
	v_lshl_add_u64 v[140:141], s[8:9], 0, v[140:141]
	v_lshl_add_u64 v[146:147], v[116:117], 1, v[140:141]
	s_waitcnt vmcnt(4) lgkmcnt(0)
	v_mov_b32_e32 v134, v180
	v_mov_b32_e32 v135, v181
	v_mov_b32_e32 v136, v182
	v_mov_b32_e32 v137, v183
	v_pk_add_f32 v[126:127], v[126:127], v[134:135]
	v_pk_add_f32 v[128:129], v[128:129], v[136:137]
	v_cvt_pk_bf16_f32 v134, v126, v127
	v_cvt_pk_bf16_f32 v135, v128, v129
	global_store_dwordx4 v[144:145], v[126:129], off
	global_store_dwordx2 v[146:147], v[134:135], off
	s_nop 0
	s_waitcnt lgkmcnt(0)
	v_mov_b32_e32 v134, v184
	v_mov_b32_e32 v135, v185
	v_mov_b32_e32 v136, v186
	v_mov_b32_e32 v137, v187
	v_pk_add_f32 v[122:123], v[122:123], v[134:135]
	v_pk_add_f32 v[124:125], v[124:125], v[136:137]
	v_cvt_pk_bf16_f32 v134, v122, v123
	v_cvt_pk_bf16_f32 v135, v124, v125
	global_store_dwordx4 v[144:145], v[122:125], off offset:64
	global_store_dwordx2 v[146:147], v[134:135], off offset:32
	s_nop 0
	s_waitcnt lgkmcnt(0)
	v_mov_b32_e32 v134, v188
	v_mov_b32_e32 v135, v189
	v_mov_b32_e32 v136, v190
	v_mov_b32_e32 v137, v191
	v_pk_add_f32 v[134:135], v[118:119], v[134:135]
	v_pk_add_f32 v[136:137], v[120:121], v[136:137]
	v_cvt_pk_bf16_f32 v118, v134, v135
	v_cvt_pk_bf16_f32 v119, v136, v137
	global_store_dwordx4 v[144:145], v[134:137], off offset:128
	global_store_dwordx2 v[146:147], v[118:119], off offset:64
	s_nop 0
	v_and_b32_e32 v119, 64, v139
	v_xor_b32_e32 v118, 16, v139
	v_add_u32_e32 v121, 64, v119
	v_cmp_lt_i32_e64 s[0:1], v118, v121
	s_nop 1
	v_cndmask_b32_e64 v118, v139, v118, s[0:1]
	v_lshlrev_b32_e32 v120, 2, v118
	v_pk_mul_f32 v[118:119], v[126:127], v[126:127]
	v_pk_mul_f32 v[126:127], v[128:129], v[128:129]
	v_add_f32_e32 v118, v118, v119
	v_add_f32_e32 v118, v118, v126
	v_add_f32_e32 v126, v118, v127
	v_pk_mul_f32 v[118:119], v[122:123], v[122:123]
	v_pk_mul_f32 v[122:123], v[124:125], v[124:125]
	v_add_f32_e32 v118, v118, v119
	v_add_f32_e32 v118, v118, v122
	v_add_f32_e32 v118, v118, v123
	v_add_f32_e32 v128, v126, v118
	v_pk_mul_f32 v[118:119], v[134:135], v[134:135]
	v_pk_mul_f32 v[122:123], v[136:137], v[136:137]
	v_add_f32_e32 v118, v118, v119
	v_add_f32_e32 v118, v118, v122
	v_add_f32_e32 v129, v118, v123
	v_add_f32_e32 v128, v128, v129
	s_waitcnt lgkmcnt(0)
	v_mov_b32_e32 v140, v192
	v_mov_b32_e32 v141, v193
	v_mov_b32_e32 v142, v194
	v_mov_b32_e32 v143, v195
	v_pk_add_f32 v[122:123], v[152:153], v[140:141]
	v_pk_add_f32 v[124:125], v[154:155], v[142:143]
	v_pk_mul_f32 v[118:119], v[122:123], v[122:123]
	v_pk_mul_f32 v[126:127], v[124:125], v[124:125]
	v_add_f32_e32 v118, v118, v119
	v_add_f32_e32 v118, v118, v126
	v_add_f32_e32 v118, v118, v127
	v_add_f32_e32 v118, v128, v118
	ds_bpermute_b32 v119, v120, v118
	v_xor_b32_e32 v126, 32, v139
	v_cmp_lt_i32_e64 s[0:1], v126, v121
	global_store_dwordx4 v[144:145], v[122:125], off offset:192
	s_waitcnt lgkmcnt(0)
	v_add_f32_e32 v118, v118, v119
	v_cndmask_b32_e64 v121, v139, v126, s[0:1]
	v_lshlrev_b32_e32 v121, 2, v121
	ds_bpermute_b32 v119, v121, v118
	v_cvt_pk_bf16_f32 v122, v122, v123
	v_cvt_pk_bf16_f32 v123, v124, v125
	global_store_dwordx2 v[146:147], v[122:123], off offset:96
	s_and_saveexec_b64 s[0:1], vcc
	s_cbranch_execz .LBB0_1359
	s_waitcnt lgkmcnt(0)
	v_add_f32_e32 v122, v118, v119
	v_lshl_add_u64 v[118:119], v[114:115], 2, s[10:11]
	global_atomic_add_f32 v[118:119], v122, off

.LBB0_1445:
	s_mul_i32 s51, s7, 0x6000
	s_add_i32 s52, s51, 0xffffa000
	s_cmp_lg_u32 s7, 0
	s_cselect_b32 s52, s52, 0xc000
	v_add_u32_e32 v145, s52, v134
	v_lshl_add_u64 v[146:147], v[138:139], 0, s[4:5]
	v_readfirstlane_b32 s52, v145
	v_add_u32_e32 v150, 0x1000, v145
	v_lshl_add_u64 v[148:149], v[146:147], 0, s[28:29]
	s_mov_b32 m0, s52
	v_readfirstlane_b32 s52, v150
	v_add_u32_e32 v150, 0x2000, v145
	s_waitcnt vmcnt(6)
	s_barrier
	global_load_lds_dwordx4 v[148:149], off
	v_lshl_add_u64 v[148:149], v[146:147], 0, s[30:31]
	s_mov_b32 m0, s52
	v_readfirstlane_b32 s52, v150
	global_load_lds_dwordx4 v[148:149], off
	v_lshl_add_u64 v[148:149], v[146:147], 0, s[34:35]
	s_mov_b32 m0, s52
	v_lshl_add_u64 v[146:147], v[146:147], 0, s[44:45]
	global_load_lds_dwordx4 v[148:149], off
	v_add_u32_e32 v148, 0x3000, v145
	v_add_u32_e32 v150, 0x4000, v145
	v_readfirstlane_b32 s52, v148
	s_mov_b32 m0, s52
	v_readfirstlane_b32 s52, v150
	global_load_lds_dwordx4 v[146:147], off
	v_lshl_add_u64 v[146:147], v[136:137], 0, s[4:5]
	v_add_u32_e32 v145, 0x5000, v145
	v_lshl_add_u64 v[148:149], v[146:147], 0, s[46:47]
	s_mov_b32 m0, s52
	v_readfirstlane_b32 s52, v145
	global_load_lds_dwordx4 v[148:149], off
	v_lshl_add_u64 v[146:147], v[146:147], 0, s[48:49]
	s_mov_b32 m0, s52
	s_add_i32 s51, s51, 0
	global_load_lds_dwordx4 v[146:147], off
	v_add3_u32 v145, s51, v142, v144
	ds_read_b128 v[146:149], v145 offset:16384
	ds_read_b128 v[150:153], v145 offset:17408
	ds_read_b128 v[154:157], v145 offset:18432
	ds_read_b128 v[158:161], v145 offset:19456
	v_add3_u32 v145, s51, v143, v144
	ds_read_b128 v[162:165], v145
	ds_read_b128 v[166:169], v145 offset:1024
	ds_read_b128 v[170:173], v145 offset:2048
	ds_read_b128 v[174:177], v145 offset:3072
	s_setprio 1
	s_waitcnt lgkmcnt(0)
	v_mfma_f32_16x16x32_bf16 v[126:129], v[146:149], v[162:165], v[126:129]
	v_mfma_f32_16x16x32_bf16 v[122:125], v[150:153], v[162:165], v[122:125]
	v_mfma_f32_16x16x32_bf16 v[118:121], v[154:157], v[162:165], v[118:121]
	v_mfma_f32_16x16x32_bf16 v[114:117], v[158:161], v[162:165], v[114:117]
	v_mfma_f32_16x16x32_bf16 v[110:113], v[146:149], v[166:169], v[110:113]
	v_mfma_f32_16x16x32_bf16 v[106:109], v[150:153], v[166:169], v[106:109]
	v_mfma_f32_16x16x32_bf16 v[102:105], v[154:157], v[166:169], v[102:105]
	v_mfma_f32_16x16x32_bf16 v[98:101], v[158:161], v[166:169], v[98:101]
	v_mfma_f32_16x16x32_bf16 v[94:97], v[146:149], v[170:173], v[94:97]
	v_mfma_f32_16x16x32_bf16 v[90:93], v[150:153], v[170:173], v[90:93]
	v_mfma_f32_16x16x32_bf16 v[86:89], v[154:157], v[170:173], v[86:89]
	v_mfma_f32_16x16x32_bf16 v[82:85], v[158:161], v[170:173], v[82:85]
	v_mfma_f32_16x16x32_bf16 v[78:81], v[146:149], v[174:177], v[78:81]
	v_mfma_f32_16x16x32_bf16 v[74:77], v[150:153], v[174:177], v[74:77]
	v_mfma_f32_16x16x32_bf16 v[70:73], v[154:157], v[174:177], v[70:73]
	v_mfma_f32_16x16x32_bf16 v[66:69], v[158:161], v[174:177], v[66:69]
	s_setprio 0
	ds_read_b128 v[162:165], v145 offset:4096
	ds_read_b128 v[166:169], v145 offset:5120
	ds_read_b128 v[170:173], v145 offset:6144
	ds_read_b128 v[174:177], v145 offset:7168
	s_setprio 1
	s_waitcnt lgkmcnt(0)
	v_mfma_f32_16x16x32_bf16 v[62:65], v[146:149], v[162:165], v[62:65]
	v_mfma_f32_16x16x32_bf16 v[58:61], v[150:153], v[162:165], v[58:61]
	v_mfma_f32_16x16x32_bf16 v[54:57], v[154:157], v[162:165], v[54:57]
	v_mfma_f32_16x16x32_bf16 v[50:53], v[158:161], v[162:165], v[50:53]
	v_mfma_f32_16x16x32_bf16 v[46:49], v[146:149], v[166:169], v[46:49]
	v_mfma_f32_16x16x32_bf16 v[42:45], v[150:153], v[166:169], v[42:45]
	v_mfma_f32_16x16x32_bf16 v[38:41], v[154:157], v[166:169], v[38:41]
	v_mfma_f32_16x16x32_bf16 v[34:37], v[158:161], v[166:169], v[34:37]
	v_mfma_f32_16x16x32_bf16 v[30:33], v[146:149], v[170:173], v[30:33]
	v_mfma_f32_16x16x32_bf16 v[26:29], v[150:153], v[170:173], v[26:29]
	v_mfma_f32_16x16x32_bf16 v[22:25], v[154:157], v[170:173], v[22:25]
	v_mfma_f32_16x16x32_bf16 v[18:21], v[158:161], v[170:173], v[18:21]
	v_mfma_f32_16x16x32_bf16 v[14:17], v[146:149], v[174:177], v[14:17]
	v_mfma_f32_16x16x32_bf16 v[10:13], v[150:153], v[174:177], v[10:13]
	v_mfma_f32_16x16x32_bf16 v[6:9], v[154:157], v[174:177], v[6:9]
	v_mfma_f32_16x16x32_bf16 v[2:5], v[158:161], v[174:177], v[2:5]
	s_setprio 0
	s_add_i32 s51, s7, 1
	s_cmp_lg_u32 s7, 2
	s_cselect_b32 s7, s51, 0
	s_add_u32 s4, s4, 64
	s_addc_u32 s5, s5, 0
	s_cmpk_eq_i32 s4, 0x780
	s_cbranch_scc0 .LBB0_1445
	v_add3_u32 v134, 0, v142, v144
	v_add3_u32 v174, 0, v143, v144
	s_waitcnt vmcnt(6)
	s_barrier
	ds_read_b128 v[136:139], v134 offset:16384
	ds_read_b128 v[146:149], v134 offset:17408
	ds_read_b128 v[150:153], v134 offset:18432
	ds_read_b128 v[154:157], v134 offset:19456
	ds_read_b128 v[142:145], v174
	ds_read_b128 v[158:161], v174 offset:1024
	ds_read_b128 v[162:165], v174 offset:2048
	ds_read_b128 v[166:169], v174 offset:3072
	s_setprio 1
	s_waitcnt lgkmcnt(0)
	v_mfma_f32_16x16x32_bf16 v[126:129], v[136:139], v[142:145], v[126:129]
	v_mfma_f32_16x16x32_bf16 v[122:125], v[146:149], v[142:145], v[122:125]
	v_mfma_f32_16x16x32_bf16 v[118:121], v[150:153], v[142:145], v[118:121]
	v_mfma_f32_16x16x32_bf16 v[114:117], v[154:157], v[142:145], v[114:117]
	v_mfma_f32_16x16x32_bf16 v[110:113], v[136:139], v[158:161], v[110:113]
	v_mfma_f32_16x16x32_bf16 v[106:109], v[146:149], v[158:161], v[106:109]
	v_mfma_f32_16x16x32_bf16 v[102:105], v[150:153], v[158:161], v[102:105]
	v_mfma_f32_16x16x32_bf16 v[98:101], v[154:157], v[158:161], v[98:101]
	v_mfma_f32_16x16x32_bf16 v[94:97], v[136:139], v[162:165], v[94:97]
	v_mfma_f32_16x16x32_bf16 v[90:93], v[146:149], v[162:165], v[90:93]
	v_mfma_f32_16x16x32_bf16 v[86:89], v[150:153], v[162:165], v[86:89]
	v_mfma_f32_16x16x32_bf16 v[82:85], v[154:157], v[162:165], v[82:85]
	v_mfma_f32_16x16x32_bf16 v[78:81], v[136:139], v[166:169], v[78:81]
	v_mfma_f32_16x16x32_bf16 v[74:77], v[146:149], v[166:169], v[74:77]
	v_mfma_f32_16x16x32_bf16 v[70:73], v[150:153], v[166:169], v[70:73]
	v_mfma_f32_16x16x32_bf16 v[66:69], v[154:157], v[166:169], v[66:69]
	s_setprio 0
	ds_read_b128 v[142:145], v174 offset:4096
	ds_read_b128 v[158:161], v174 offset:5120
	ds_read_b128 v[162:165], v174 offset:6144
	ds_read_b128 v[166:169], v174 offset:7168
	s_setprio 1
	s_waitcnt lgkmcnt(0)
	v_mfma_f32_16x16x32_bf16 v[62:65], v[136:139], v[142:145], v[62:65]
	v_mfma_f32_16x16x32_bf16 v[58:61], v[146:149], v[142:145], v[58:61]
	v_mfma_f32_16x16x32_bf16 v[54:57], v[150:153], v[142:145], v[54:57]
	v_mfma_f32_16x16x32_bf16 v[50:53], v[154:157], v[142:145], v[50:53]
	v_mfma_f32_16x16x32_bf16 v[46:49], v[136:139], v[158:161], v[46:49]
	v_mfma_f32_16x16x32_bf16 v[42:45], v[146:149], v[158:161], v[42:45]
	v_mfma_f32_16x16x32_bf16 v[38:41], v[150:153], v[158:161], v[38:41]
	v_mfma_f32_16x16x32_bf16 v[34:37], v[154:157], v[158:161], v[34:37]
	v_mfma_f32_16x16x32_bf16 v[30:33], v[136:139], v[162:165], v[30:33]
	v_mfma_f32_16x16x32_bf16 v[26:29], v[146:149], v[162:165], v[26:29]
	v_mfma_f32_16x16x32_bf16 v[22:25], v[150:153], v[162:165], v[22:25]
	v_mfma_f32_16x16x32_bf16 v[18:21], v[154:157], v[162:165], v[18:21]
	v_mfma_f32_16x16x32_bf16 v[14:17], v[136:139], v[166:169], v[14:17]
	v_mfma_f32_16x16x32_bf16 v[10:13], v[146:149], v[166:169], v[10:13]
	v_mfma_f32_16x16x32_bf16 v[6:9], v[150:153], v[166:169], v[6:9]
	v_mfma_f32_16x16x32_bf16 v[2:5], v[154:157], v[166:169], v[2:5]
	s_setprio 0
	s_waitcnt vmcnt(0)
	s_barrier
	ds_read_b128 v[136:139], v134 offset:40960
	ds_read_b128 v[142:145], v134 offset:41984
	ds_read_b128 v[146:149], v134 offset:43008
	ds_read_b128 v[150:153], v134 offset:44032
	ds_read_b128 v[154:157], v174 offset:24576
	ds_read_b128 v[158:161], v174 offset:25600
	ds_read_b128 v[162:165], v174 offset:26624
	ds_read_b128 v[166:169], v174 offset:27648
	s_lshl_b64 s[0:1], s[0:1], 8
	s_setprio 1
	s_waitcnt lgkmcnt(0)
	v_mfma_f32_16x16x32_bf16 v[170:173], v[136:139], v[154:157], v[126:129]
	v_mfma_f32_16x16x32_bf16 v[122:125], v[142:145], v[154:157], v[122:125]
	v_mfma_f32_16x16x32_bf16 v[118:121], v[146:149], v[154:157], v[118:121]
	v_mfma_f32_16x16x32_bf16 v[114:117], v[150:153], v[154:157], v[114:117]
	v_mfma_f32_16x16x32_bf16 v[110:113], v[136:139], v[158:161], v[110:113]
	v_mfma_f32_16x16x32_bf16 v[106:109], v[142:145], v[158:161], v[106:109]
	v_mfma_f32_16x16x32_bf16 v[102:105], v[146:149], v[158:161], v[102:105]
	v_mfma_f32_16x16x32_bf16 v[98:101], v[150:153], v[158:161], v[98:101]
	v_mfma_f32_16x16x32_bf16 v[94:97], v[136:139], v[162:165], v[94:97]
	v_mfma_f32_16x16x32_bf16 v[90:93], v[142:145], v[162:165], v[90:93]
	v_mfma_f32_16x16x32_bf16 v[86:89], v[146:149], v[162:165], v[86:89]
	v_mfma_f32_16x16x32_bf16 v[82:85], v[150:153], v[162:165], v[82:85]
	v_mfma_f32_16x16x32_bf16 v[78:81], v[136:139], v[166:169], v[78:81]
	v_mfma_f32_16x16x32_bf16 v[74:77], v[142:145], v[166:169], v[74:77]
	v_mfma_f32_16x16x32_bf16 v[70:73], v[146:149], v[166:169], v[70:73]
	v_mfma_f32_16x16x32_bf16 v[66:69], v[150:153], v[166:169], v[66:69]
	s_setprio 0
	ds_read_b128 v[126:129], v174 offset:28672
	ds_read_b128 v[154:157], v174 offset:29696
	ds_read_b128 v[158:161], v174 offset:30720
	ds_read_b128 v[162:165], v174 offset:31744
	s_setprio 1
	s_waitcnt lgkmcnt(0)
	v_mfma_f32_16x16x32_bf16 v[62:65], v[136:139], v[126:129], v[62:65]
	v_mfma_f32_16x16x32_bf16 v[58:61], v[142:145], v[126:129], v[58:61]
	v_mfma_f32_16x16x32_bf16 v[54:57], v[146:149], v[126:129], v[54:57]
	v_mfma_f32_16x16x32_bf16 v[50:53], v[150:153], v[126:129], v[50:53]
	v_mfma_f32_16x16x32_bf16 v[46:49], v[136:139], v[154:157], v[46:49]
	v_mfma_f32_16x16x32_bf16 v[42:45], v[142:145], v[154:157], v[42:45]
	v_mfma_f32_16x16x32_bf16 v[38:41], v[146:149], v[154:157], v[38:41]
	v_mfma_f32_16x16x32_bf16 v[34:37], v[150:153], v[154:157], v[34:37]
	v_mfma_f32_16x16x32_bf16 v[30:33], v[136:139], v[158:161], v[30:33]
	v_mfma_f32_16x16x32_bf16 v[26:29], v[142:145], v[158:161], v[26:29]
	v_mfma_f32_16x16x32_bf16 v[22:25], v[146:149], v[158:161], v[22:25]
	v_mfma_f32_16x16x32_bf16 v[18:21], v[150:153], v[158:161], v[18:21]
	v_mfma_f32_16x16x32_bf16 v[14:17], v[136:139], v[162:165], v[14:17]
	v_mfma_f32_16x16x32_bf16 v[10:13], v[142:145], v[162:165], v[10:13]
	v_mfma_f32_16x16x32_bf16 v[6:9], v[146:149], v[162:165], v[6:9]
	v_mfma_f32_16x16x32_bf16 v[2:5], v[150:153], v[162:165], v[2:5]
	s_setprio 0
	v_lshl_add_u64 v[126:127], s[0:1], 0, v[132:133]
	v_lshl_add_u64 v[128:129], v[126:127], 2, s[14:15]
	s_waitcnt vmcnt(0)
	s_barrier
	v_mov_b32_e32 v234, v128
	v_mov_b32_e32 v235, v129
	global_load_dword v228, v[234:235], off
	v_lshl_or_b32 v134, s6, 7, v140
	v_lshlrev_b64 v[128:129], 11, v[126:127]
	v_lshl_add_u64 v[136:137], s[12:13], 0, v[128:129]
	v_lshlrev_b32_e32 v128, 1, v134
	v_mov_b32_e32 v129, v135
	v_lshl_add_u64 v[138:139], v[136:137], 0, v[128:129]
	s_nop 0
	v_lshlrev_b64 v[136:137], 12, v[126:127]
	v_lshlrev_b32_e32 v134, 2, v134
	v_lshl_add_u64 v[136:137], v[130:131], 0, v[136:137]
	v_lshl_add_u64 v[136:137], v[136:137], 0, v[134:135]
	v_mov_b32_e32 v230, v136
	v_mov_b32_e32 v231, v137
	v_mov_b32_e32 v232, v138
	v_mov_b32_e32 v233, v139
	global_load_dwordx4 v[180:183], v[230:231], off
	global_load_dwordx4 v[184:187], v[230:231], off offset:64
	global_load_dwordx4 v[188:191], v[230:231], off offset:128
	global_load_dwordx4 v[192:195], v[230:231], off offset:192
	global_load_dwordx2 v[196:197], v[232:233], off
	global_load_dwordx2 v[198:199], v[232:233], off offset:32
	global_load_dwordx2 v[200:201], v[232:233], off offset:64
	global_load_dwordx2 v[202:203], v[232:233], off offset:96
	s_mov_b32 s99, 0
	s_mov_b32 s98, 0x10000
	v_lshl_add_u64 v[236:237], v[230:231], 0, s[98:99]
	global_load_dwordx4 v[204:207], v[236:237], off
	global_load_dwordx4 v[208:211], v[236:237], off offset:64
	global_load_dwordx4 v[212:215], v[236:237], off offset:128
	global_load_dwordx4 v[216:219], v[236:237], off offset:192
	s_mov_b32 s98, 0x8000
	v_lshl_add_u64 v[236:237], v[232:233], 0, s[98:99]
	global_load_dwordx2 v[220:221], v[236:237], off
	global_load_dwordx2 v[222:223], v[236:237], off offset:32
	global_load_dwordx2 v[224:225], v[236:237], off offset:64
	global_load_dwordx2 v[226:227], v[236:237], off offset:96
	s_mov_b32 s98, 0x40
	v_lshl_add_u64 v[236:237], v[234:235], 0, s[98:99]
	global_load_dword v229, v[236:237], off
	s_waitcnt vmcnt(9) lgkmcnt(0)
	v_mov_b32_e32 v146, v228
	v_mov_b32_e32 v150, v196
	v_mov_b32_e32 v151, v197
	v_mov_b32_e32 v142, v180
	v_mov_b32_e32 v143, v181
	v_mov_b32_e32 v144, v182
	v_mov_b32_e32 v145, v183
	v_fmamk_f32 v146, v146, 0x3a800000, v141
	v_mul_f32_e32 v147, 0x4b800000, v146
	v_cmp_gt_f32_e32 vcc, s50, v146
	v_lshlrev_b32_e32 v152, 16, v150
	s_nop 0
	v_cndmask_b32_e32 v146, v146, v147, vcc
	v_rsq_f32_e32 v154, v146
	v_and_b32_e32 v153, 0xffff0000, v150
	s_nop 0
	v_mul_f32_e32 v150, 0x45800000, v154
	v_cndmask_b32_e32 v158, v154, v150, vcc
	v_mul_f32_e32 v150, v170, v158
	v_mul_f32_e32 v154, v171, v158
	v_mul_f32_e32 v155, v172, v158
	v_mul_f32_e32 v150, 0xbfb8aa3b, v150
	v_mul_f32_e32 v157, 0xbfb8aa3b, v154
	v_mul_f32_e32 v156, v173, v158
	v_mul_f32_e32 v159, 0xbfb8aa3b, v155
	v_exp_f32_e32 v154, v150
	v_exp_f32_e32 v155, v157
	v_mul_f32_e32 v160, 0xbfb8aa3b, v156
	v_exp_f32_e32 v156, v159
	v_exp_f32_e32 v157, v160
	v_pk_add_f32 v[154:155], v[154:155], 1.0 op_sel_hi:[1,0]
	v_lshlrev_b32_e32 v150, 16, v151
	v_div_scale_f32 v159, s[0:1], v155, v155, 1.0
	v_pk_add_f32 v[156:157], v[156:157], 1.0 op_sel_hi:[1,0]
	v_div_scale_f32 v161, s[0:1], v154, v154, 1.0
	v_rcp_f32_e32 v167, v159
	v_div_scale_f32 v163, s[4:5], v157, v157, 1.0
	v_rcp_f32_e32 v168, v161
	v_div_scale_f32 v165, s[6:7], v156, v156, 1.0
	v_rcp_f32_e32 v169, v163
	v_rcp_f32_e32 v170, v165
	v_fma_f32 v171, -v159, v167, 1.0
	v_div_scale_f32 v160, vcc, 1.0, v155, 1.0
	v_fma_f32 v172, -v161, v168, 1.0
	v_fmac_f32_e32 v167, v171, v167
	v_div_scale_f32 v162, s[0:1], 1.0, v154, 1.0
	v_fma_f32 v173, -v163, v169, 1.0
	v_fmac_f32_e32 v168, v172, v168
	v_mul_f32_e32 v171, v160, v167
	v_div_scale_f32 v164, s[4:5], 1.0, v157, 1.0
	v_fma_f32 v174, -v165, v170, 1.0
	v_fmac_f32_e32 v169, v173, v169
	v_mul_f32_e32 v172, v162, v168
	v_fma_f32 v175, -v159, v171, v160
	v_div_scale_f32 v166, s[6:7], 1.0, v156, 1.0
	v_fmac_f32_e32 v170, v174, v170
	v_mul_f32_e32 v173, v164, v169
	v_fma_f32 v176, -v161, v172, v162
	v_fmac_f32_e32 v171, v175, v167
	v_mul_f32_e32 v174, v166, v170
	v_fma_f32 v177, -v163, v173, v164
	v_fmac_f32_e32 v172, v176, v168
	v_fma_f32 v159, -v159, v171, v160
	v_fma_f32 v178, -v165, v174, v166
	v_fmac_f32_e32 v173, v177, v169
	v_fma_f32 v160, -v161, v172, v162
	v_div_fmas_f32 v159, v159, v167, v171
	s_mov_b64 vcc, s[0:1]
	v_fmac_f32_e32 v174, v178, v170
	v_fma_f32 v161, -v163, v173, v164
	v_div_fixup_f32 v155, v159, v155, 1.0
	v_div_fmas_f32 v159, v160, v168, v172
	s_mov_b64 vcc, s[4:5]
	v_fma_f32 v162, -v165, v174, v166
	v_div_fixup_f32 v154, v159, v154, 1.0
	v_div_fmas_f32 v159, v161, v169, v173
	s_mov_b64 vcc, s[6:7]
	v_pk_fma_f32 v[142:143], v[154:155], v[152:153], v[142:143]
	v_div_fmas_f32 v152, v162, v170, v174
	v_and_b32_e32 v151, 0xffff0000, v151
	v_div_fixup_f32 v153, v159, v157, 1.0
	v_div_fixup_f32 v152, v152, v156, 1.0
	v_pk_fma_f32 v[144:145], v[152:153], v[150:151], v[144:145]
	global_store_dwordx4 v[136:137], v[142:145], off
	s_nop 0
	v_mul_f32_e32 v122, v122, v158
	v_mul_f32_e32 v123, v123, v158
	v_mul_f32_e32 v122, 0xbfb8aa3b, v122
	v_mul_f32_e32 v123, 0xbfb8aa3b, v123
	v_mul_f32_e32 v124, v124, v158
	v_mul_f32_e32 v125, v125, v158
	v_exp_f32_e32 v122, v122
	v_exp_f32_e32 v123, v123
	v_mul_f32_e32 v124, 0xbfb8aa3b, v124
	v_mul_f32_e32 v125, 0xbfb8aa3b, v125
	v_exp_f32_e32 v124, v124
	v_exp_f32_e32 v125, v125
	v_pk_add_f32 v[122:123], v[122:123], 1.0 op_sel_hi:[1,0]
	v_mul_f32_e32 v118, v118, v158
	v_div_scale_f32 v144, s[0:1], v123, v123, 1.0
	v_pk_add_f32 v[124:125], v[124:125], 1.0 op_sel_hi:[1,0]
	v_div_scale_f32 v150, s[0:1], v122, v122, 1.0
	v_rcp_f32_e32 v156, v144
	v_div_scale_f32 v152, s[4:5], v125, v125, 1.0
	v_rcp_f32_e32 v157, v150
	v_div_scale_f32 v154, s[6:7], v124, v124, 1.0
	v_rcp_f32_e32 v159, v152
	v_rcp_f32_e32 v160, v154
	v_fma_f32 v161, -v144, v156, 1.0
	v_div_scale_f32 v145, vcc, 1.0, v123, 1.0
	v_fma_f32 v162, -v150, v157, 1.0
	v_fmac_f32_e32 v156, v161, v156
	v_div_scale_f32 v151, s[0:1], 1.0, v122, 1.0
	v_fma_f32 v163, -v152, v159, 1.0
	v_fmac_f32_e32 v157, v162, v157
	v_mul_f32_e32 v161, v145, v156
	v_div_scale_f32 v153, s[4:5], 1.0, v125, 1.0
	v_fma_f32 v164, -v154, v160, 1.0
	v_fmac_f32_e32 v159, v163, v159
	v_mul_f32_e32 v162, v151, v157
	v_fma_f32 v165, -v144, v161, v145
	v_div_scale_f32 v155, s[6:7], 1.0, v124, 1.0
	v_fmac_f32_e32 v160, v164, v160
	v_mul_f32_e32 v163, v153, v159
	v_fma_f32 v166, -v150, v162, v151
	v_fmac_f32_e32 v161, v165, v156
	v_mul_f32_e32 v164, v155, v160
	v_fma_f32 v167, -v152, v163, v153
	v_fmac_f32_e32 v162, v166, v157
	v_fma_f32 v144, -v144, v161, v145
	v_fma_f32 v168, -v154, v164, v155
	v_fmac_f32_e32 v163, v167, v159
	v_fma_f32 v145, -v150, v162, v151
	v_div_fmas_f32 v144, v144, v156, v161
	s_mov_b64 vcc, s[0:1]
	v_fmac_f32_e32 v164, v168, v160
	v_fma_f32 v150, -v152, v163, v153
	v_div_fixup_f32 v123, v144, v123, 1.0
	v_div_fmas_f32 v144, v145, v157, v162
	s_mov_b64 vcc, s[4:5]
	v_fma_f32 v151, -v154, v164, v155
	v_div_fixup_f32 v122, v144, v122, 1.0
	v_div_fmas_f32 v144, v150, v159, v163
	s_mov_b64 vcc, s[6:7]
	v_div_fixup_f32 v125, v144, v125, 1.0
	v_div_fmas_f32 v144, v151, v160, v164
	v_div_fixup_f32 v124, v144, v124, 1.0
	v_mul_f32_e32 v119, v119, v158
	v_mul_f32_e32 v118, 0xbfb8aa3b, v118
	v_mul_f32_e32 v119, 0xbfb8aa3b, v119
	v_mul_f32_e32 v120, v120, v158
	v_mul_f32_e32 v121, v121, v158
	v_mul_f32_e32 v120, 0xbfb8aa3b, v120
	v_mul_f32_e32 v121, 0xbfb8aa3b, v121
	v_mul_f32_e32 v114, v114, v158
	v_mul_f32_e32 v115, v115, v158
	s_waitcnt lgkmcnt(0)
	v_mov_b32_e32 v142, v198
	v_mov_b32_e32 v143, v199
	v_mov_b32_e32 v146, v184
	v_mov_b32_e32 v147, v185
	v_mov_b32_e32 v148, v186
	v_mov_b32_e32 v149, v187
	v_lshlrev_b32_e32 v144, 16, v142
	v_and_b32_e32 v145, 0xffff0000, v142
	v_lshlrev_b32_e32 v142, 16, v143
	v_and_b32_e32 v143, 0xffff0000, v143
	v_pk_fma_f32 v[122:123], v[122:123], v[144:145], v[146:147]
	v_pk_fma_f32 v[124:125], v[124:125], v[142:143], v[148:149]
	global_store_dwordx4 v[136:137], v[122:125], off offset:64
	s_nop 0
	s_nop 0
	s_nop 0
	v_exp_f32_e32 v144, v118
	v_exp_f32_e32 v145, v119
	v_exp_f32_e32 v146, v120
	v_exp_f32_e32 v147, v121
	s_nop 0
	v_pk_add_f32 v[144:145], v[144:145], 1.0 op_sel_hi:[1,0]
	v_mul_f32_e32 v114, 0xbfb8aa3b, v114
	v_div_scale_f32 v148, s[0:1], v145, v145, 1.0
	v_pk_add_f32 v[146:147], v[146:147], 1.0 op_sel_hi:[1,0]
	v_div_scale_f32 v150, s[0:1], v144, v144, 1.0
	v_rcp_f32_e32 v156, v148
	v_div_scale_f32 v152, s[4:5], v147, v147, 1.0
	v_rcp_f32_e32 v157, v150
	v_div_scale_f32 v154, s[6:7], v146, v146, 1.0
	v_rcp_f32_e32 v159, v152
	v_rcp_f32_e32 v160, v154
	v_fma_f32 v161, -v148, v156, 1.0
	v_div_scale_f32 v149, vcc, 1.0, v145, 1.0
	v_fma_f32 v162, -v150, v157, 1.0
	v_fmac_f32_e32 v156, v161, v156
	v_div_scale_f32 v151, s[0:1], 1.0, v144, 1.0
	v_fma_f32 v163, -v152, v159, 1.0
	v_fmac_f32_e32 v157, v162, v157
	v_mul_f32_e32 v161, v149, v156
	v_div_scale_f32 v153, s[4:5], 1.0, v147, 1.0
	v_fma_f32 v164, -v154, v160, 1.0
	v_fmac_f32_e32 v159, v163, v159
	v_mul_f32_e32 v162, v151, v157
	v_fma_f32 v165, -v148, v161, v149
	v_div_scale_f32 v155, s[6:7], 1.0, v146, 1.0
	v_fmac_f32_e32 v160, v164, v160
	v_mul_f32_e32 v163, v153, v159
	v_fma_f32 v166, -v150, v162, v151
	v_fmac_f32_e32 v161, v165, v156
	v_mul_f32_e32 v164, v155, v160
	v_fma_f32 v167, -v152, v163, v153
	v_fmac_f32_e32 v162, v166, v157
	v_fma_f32 v148, -v148, v161, v149
	v_fma_f32 v168, -v154, v164, v155
	v_fmac_f32_e32 v163, v167, v159
	v_fma_f32 v149, -v150, v162, v151
	v_div_fmas_f32 v148, v148, v156, v161
	s_mov_b64 vcc, s[0:1]
	v_fmac_f32_e32 v164, v168, v160
	v_fma_f32 v150, -v152, v163, v153
	v_div_fixup_f32 v145, v148, v145, 1.0
	v_div_fmas_f32 v148, v149, v157, v162
	s_mov_b64 vcc, s[4:5]
	v_fma_f32 v151, -v154, v164, v155
	v_div_fixup_f32 v144, v148, v144, 1.0
	v_div_fmas_f32 v148, v150, v159, v163
	s_mov_b64 vcc, s[6:7]
	v_div_fixup_f32 v147, v148, v147, 1.0
	v_div_fmas_f32 v148, v151, v160, v164
	v_div_fixup_f32 v146, v148, v146, 1.0
	v_mul_f32_e32 v115, 0xbfb8aa3b, v115
	v_mul_f32_e32 v116, v116, v158
	v_mul_f32_e32 v117, v117, v158
	v_exp_f32_e32 v114, v114
	v_exp_f32_e32 v115, v115
	v_mul_f32_e32 v116, 0xbfb8aa3b, v116
	v_mul_f32_e32 v117, 0xbfb8aa3b, v117
	v_exp_f32_e32 v116, v116
	v_exp_f32_e32 v117, v117
	v_pk_add_f32 v[114:115], v[114:115], 1.0 op_sel_hi:[1,0]
	v_pk_add_f32 v[116:117], v[116:117], 1.0 op_sel_hi:[1,0]
	s_waitcnt lgkmcnt(0)
	v_mov_b32_e32 v142, v200
	v_mov_b32_e32 v143, v201
	v_mov_b32_e32 v122, v188
	v_mov_b32_e32 v123, v189
	v_mov_b32_e32 v124, v190
	v_mov_b32_e32 v125, v191
	v_mov_b32_e32 v118, v192
	v_mov_b32_e32 v119, v193
	v_mov_b32_e32 v120, v194
	v_mov_b32_e32 v121, v195
	v_lshlrev_b32_e32 v148, 16, v142
	v_and_b32_e32 v149, 0xffff0000, v142
	v_lshlrev_b32_e32 v142, 16, v143
	v_and_b32_e32 v143, 0xffff0000, v143
	v_pk_fma_f32 v[122:123], v[144:145], v[148:149], v[122:123]
	v_pk_fma_f32 v[124:125], v[146:147], v[142:143], v[124:125]
	global_store_dwordx4 v[136:137], v[122:125], off offset:128
	s_nop 0
	v_div_scale_f32 v138, s[0:1], v114, v114, 1.0
	v_div_scale_f32 v124, s[0:1], v115, v115, 1.0
	v_rcp_f32_e32 v146, v124
	v_div_scale_f32 v142, s[4:5], v117, v117, 1.0
	v_rcp_f32_e32 v147, v138
	v_div_scale_f32 v144, s[6:7], v116, v116, 1.0
	v_rcp_f32_e32 v148, v142
	v_rcp_f32_e32 v149, v144
	v_fma_f32 v150, -v124, v146, 1.0
	v_div_scale_f32 v125, vcc, 1.0, v115, 1.0
	v_fma_f32 v151, -v138, v147, 1.0
	v_fmac_f32_e32 v146, v150, v146
	v_div_scale_f32 v139, s[0:1], 1.0, v114, 1.0
	v_fma_f32 v152, -v142, v148, 1.0
	v_fmac_f32_e32 v147, v151, v147
	v_mul_f32_e32 v150, v125, v146
	v_div_scale_f32 v143, s[4:5], 1.0, v117, 1.0
	v_fma_f32 v153, -v144, v149, 1.0
	v_fmac_f32_e32 v148, v152, v148
	v_mul_f32_e32 v151, v139, v147
	v_fma_f32 v154, -v124, v150, v125
	v_div_scale_f32 v145, s[6:7], 1.0, v116, 1.0
	v_fmac_f32_e32 v149, v153, v149
	v_mul_f32_e32 v152, v143, v148
	v_fma_f32 v155, -v138, v151, v139
	v_fmac_f32_e32 v150, v154, v146
	v_mul_f32_e32 v153, v145, v149
	v_fma_f32 v156, -v142, v152, v143
	v_fmac_f32_e32 v151, v155, v147
	v_fma_f32 v124, -v124, v150, v125
	v_fma_f32 v157, -v144, v153, v145
	v_fmac_f32_e32 v152, v156, v148
	v_fma_f32 v125, -v138, v151, v139
	v_div_fmas_f32 v124, v124, v146, v150
	s_mov_b64 vcc, s[0:1]
	v_fmac_f32_e32 v153, v157, v149
	v_fma_f32 v138, -v142, v152, v143
	v_div_fixup_f32 v115, v124, v115, 1.0
	v_div_fmas_f32 v124, v125, v147, v151
	s_mov_b64 vcc, s[4:5]
	v_fma_f32 v139, -v144, v153, v145
	v_div_fixup_f32 v114, v124, v114, 1.0
	v_div_fmas_f32 v124, v138, v148, v152
	s_mov_b64 vcc, s[6:7]
	v_div_fixup_f32 v117, v124, v117, 1.0
	v_div_fmas_f32 v124, v139, v149, v153
	v_div_fixup_f32 v116, v124, v116, 1.0
	s_waitcnt lgkmcnt(0)
	v_mov_b32_e32 v122, v202
	v_mov_b32_e32 v123, v203
	v_lshlrev_b32_e32 v124, 16, v122
	v_and_b32_e32 v125, 0xffff0000, v122
	v_lshlrev_b32_e32 v122, 16, v123
	v_and_b32_e32 v123, 0xffff0000, v123
	v_pk_fma_f32 v[114:115], v[114:115], v[124:125], v[118:119]
	v_pk_fma_f32 v[116:117], v[116:117], v[122:123], v[120:121]
	global_store_dwordx4 v[136:137], v[114:117], off offset:192
	s_nop 1
	v_or_b32_e32 v114, 16, v126
	v_mov_b32_e32 v115, v127
	v_lshl_add_u64 v[116:117], v[114:115], 2, s[14:15]
	s_mov_b32 s99, 0
	s_mov_b32 s98, 0x20000
	v_lshl_add_u64 v[236:237], v[230:231], 0, s[98:99]
	global_load_dwordx4 v[180:183], v[236:237], off
	global_load_dwordx4 v[184:187], v[236:237], off offset:64
	global_load_dwordx4 v[188:191], v[236:237], off offset:128
	global_load_dwordx4 v[192:195], v[236:237], off offset:192
	s_mov_b32 s98, 0x10000
	v_lshl_add_u64 v[236:237], v[232:233], 0, s[98:99]
	global_load_dwordx2 v[196:197], v[236:237], off
	global_load_dwordx2 v[198:199], v[236:237], off offset:32
	global_load_dwordx2 v[200:201], v[236:237], off offset:64
	global_load_dwordx2 v[202:203], v[236:237], off offset:96
	s_mov_b32 s98, 0x80
	v_lshl_add_u64 v[236:237], v[234:235], 0, s[98:99]
	global_load_dword v228, v[236:237], off
	v_lshlrev_b64 v[116:117], 11, v[114:115]
	v_lshl_add_u64 v[116:117], s[12:13], 0, v[116:117]
	v_lshl_add_u64 v[116:117], v[116:117], 0, v[128:129]
	s_nop 0
	v_lshlrev_b64 v[114:115], 12, v[114:115]
	v_lshl_add_u64 v[114:115], v[130:131], 0, v[114:115]
	v_lshl_add_u64 v[114:115], v[114:115], 0, v[134:135]
	s_nop 0
	s_waitcnt vmcnt(13) lgkmcnt(0)
	v_mov_b32_e32 v122, v229
	v_mov_b32_e32 v136, v220
	v_mov_b32_e32 v137, v221
	v_mov_b32_e32 v118, v204
	v_mov_b32_e32 v119, v205
	v_mov_b32_e32 v120, v206
	v_mov_b32_e32 v121, v207
	v_fmamk_f32 v122, v122, 0x3a800000, v141
	v_mul_f32_e32 v123, 0x4b800000, v122
	v_cmp_gt_f32_e32 vcc, s50, v122
	v_lshlrev_b32_e32 v138, 16, v136
	s_nop 0
	v_cndmask_b32_e32 v122, v122, v123, vcc
	v_rsq_f32_e32 v142, v122
	v_and_b32_e32 v139, 0xffff0000, v136
	s_nop 0
	v_mul_f32_e32 v136, 0x45800000, v142
	v_cndmask_b32_e32 v142, v142, v136, vcc
	v_mul_f32_e32 v110, v110, v142
	v_mul_f32_e32 v111, v111, v142
	v_mul_f32_e32 v110, 0xbfb8aa3b, v110
	v_mul_f32_e32 v111, 0xbfb8aa3b, v111
	v_mul_f32_e32 v112, v112, v142
	v_mul_f32_e32 v113, v113, v142
	v_exp_f32_e32 v110, v110
	v_exp_f32_e32 v111, v111
	v_mul_f32_e32 v112, 0xbfb8aa3b, v112
	v_mul_f32_e32 v113, 0xbfb8aa3b, v113
	v_exp_f32_e32 v112, v112
	v_exp_f32_e32 v113, v113
	v_pk_add_f32 v[110:111], v[110:111], 1.0 op_sel_hi:[1,0]
	v_lshlrev_b32_e32 v136, 16, v137
	v_div_scale_f32 v143, s[0:1], v111, v111, 1.0
	v_pk_add_f32 v[112:113], v[112:113], 1.0 op_sel_hi:[1,0]
	v_div_scale_f32 v145, s[0:1], v110, v110, 1.0
	v_rcp_f32_e32 v151, v143
	v_div_scale_f32 v147, s[4:5], v113, v113, 1.0
	v_rcp_f32_e32 v152, v145
	v_div_scale_f32 v149, s[6:7], v112, v112, 1.0
	v_rcp_f32_e32 v153, v147
	v_rcp_f32_e32 v154, v149
	v_fma_f32 v155, -v143, v151, 1.0
	v_div_scale_f32 v144, vcc, 1.0, v111, 1.0
	v_fma_f32 v156, -v145, v152, 1.0
	v_fmac_f32_e32 v151, v155, v151
	v_div_scale_f32 v146, s[0:1], 1.0, v110, 1.0
	v_fma_f32 v157, -v147, v153, 1.0
	v_fmac_f32_e32 v152, v156, v152
	v_mul_f32_e32 v155, v144, v151
	v_div_scale_f32 v148, s[4:5], 1.0, v113, 1.0
	v_fma_f32 v158, -v149, v154, 1.0
	v_fmac_f32_e32 v153, v157, v153
	v_mul_f32_e32 v156, v146, v152
	v_fma_f32 v159, -v143, v155, v144
	v_div_scale_f32 v150, s[6:7], 1.0, v112, 1.0
	v_fmac_f32_e32 v154, v158, v154
	v_mul_f32_e32 v157, v148, v153
	v_fma_f32 v160, -v145, v156, v146
	v_fmac_f32_e32 v155, v159, v151
	v_mul_f32_e32 v158, v150, v154
	v_fma_f32 v161, -v147, v157, v148
	v_fmac_f32_e32 v156, v160, v152
	v_fma_f32 v143, -v143, v155, v144
	v_fma_f32 v162, -v149, v158, v150
	v_fmac_f32_e32 v157, v161, v153
	v_fma_f32 v144, -v145, v156, v146
	v_div_fmas_f32 v143, v143, v151, v155
	s_mov_b64 vcc, s[0:1]
	v_fmac_f32_e32 v158, v162, v154
	v_fma_f32 v145, -v147, v157, v148
	v_div_fixup_f32 v111, v143, v111, 1.0
	v_div_fmas_f32 v143, v144, v152, v156
	s_mov_b64 vcc, s[4:5]
	v_fma_f32 v146, -v149, v158, v150
	v_div_fixup_f32 v110, v143, v110, 1.0
	v_div_fmas_f32 v143, v145, v153, v157
	s_mov_b64 vcc, s[6:7]
	v_pk_fma_f32 v[110:111], v[110:111], v[138:139], v[118:119]
	v_div_fmas_f32 v118, v146, v154, v158
	v_and_b32_e32 v137, 0xffff0000, v137
	v_div_fixup_f32 v113, v143, v113, 1.0
	v_div_fixup_f32 v112, v118, v112, 1.0
	v_pk_fma_f32 v[112:113], v[112:113], v[136:137], v[120:121]
	global_store_dwordx4 v[114:115], v[110:113], off
	s_nop 0
	v_mul_f32_e32 v106, v106, v142
	v_mul_f32_e32 v107, v107, v142
	v_mul_f32_e32 v106, 0xbfb8aa3b, v106
	v_mul_f32_e32 v107, 0xbfb8aa3b, v107
	v_mul_f32_e32 v108, v108, v142
	v_mul_f32_e32 v109, v109, v142
	v_exp_f32_e32 v106, v106
	v_exp_f32_e32 v107, v107
	v_mul_f32_e32 v108, 0xbfb8aa3b, v108
	v_mul_f32_e32 v109, 0xbfb8aa3b, v109
	v_exp_f32_e32 v108, v108
	v_exp_f32_e32 v109, v109
	v_pk_add_f32 v[106:107], v[106:107], 1.0 op_sel_hi:[1,0]
	v_mul_f32_e32 v102, v102, v142
	v_div_scale_f32 v112, s[0:1], v107, v107, 1.0
	v_pk_add_f32 v[108:109], v[108:109], 1.0 op_sel_hi:[1,0]
	v_div_scale_f32 v118, s[0:1], v106, v106, 1.0
	v_rcp_f32_e32 v138, v112
	v_div_scale_f32 v120, s[4:5], v109, v109, 1.0
	v_rcp_f32_e32 v139, v118
	v_div_scale_f32 v136, s[6:7], v108, v108, 1.0
	v_rcp_f32_e32 v143, v120
	v_rcp_f32_e32 v144, v136
	v_fma_f32 v145, -v112, v138, 1.0
	v_div_scale_f32 v113, vcc, 1.0, v107, 1.0
	v_fma_f32 v146, -v118, v139, 1.0
	v_fmac_f32_e32 v138, v145, v138
	v_div_scale_f32 v119, s[0:1], 1.0, v106, 1.0
	v_fma_f32 v147, -v120, v143, 1.0
	v_fmac_f32_e32 v139, v146, v139
	v_mul_f32_e32 v145, v113, v138
	v_div_scale_f32 v121, s[4:5], 1.0, v109, 1.0
	v_fma_f32 v148, -v136, v144, 1.0
	v_fmac_f32_e32 v143, v147, v143
	v_mul_f32_e32 v146, v119, v139
	v_fma_f32 v149, -v112, v145, v113
	v_div_scale_f32 v137, s[6:7], 1.0, v108, 1.0
	v_fmac_f32_e32 v144, v148, v144
	v_mul_f32_e32 v147, v121, v143
	v_fma_f32 v150, -v118, v146, v119
	v_fmac_f32_e32 v145, v149, v138
	v_mul_f32_e32 v148, v137, v144
	v_fma_f32 v151, -v120, v147, v121
	v_fmac_f32_e32 v146, v150, v139
	v_fma_f32 v112, -v112, v145, v113
	v_fma_f32 v152, -v136, v148, v137
	v_fmac_f32_e32 v147, v151, v143
	v_fma_f32 v113, -v118, v146, v119
	v_div_fmas_f32 v112, v112, v138, v145
	s_mov_b64 vcc, s[0:1]
	v_fmac_f32_e32 v148, v152, v144
	v_fma_f32 v118, -v120, v147, v121
	v_div_fixup_f32 v107, v112, v107, 1.0
	v_div_fmas_f32 v112, v113, v139, v146
	s_mov_b64 vcc, s[4:5]
	v_fma_f32 v119, -v136, v148, v137
	v_div_fixup_f32 v106, v112, v106, 1.0
	v_div_fmas_f32 v112, v118, v143, v147
	s_mov_b64 vcc, s[6:7]
	v_div_fixup_f32 v109, v112, v109, 1.0
	v_div_fmas_f32 v112, v119, v144, v148
	v_div_fixup_f32 v108, v112, v108, 1.0
	v_mul_f32_e32 v103, v103, v142
	v_mul_f32_e32 v102, 0xbfb8aa3b, v102
	v_mul_f32_e32 v103, 0xbfb8aa3b, v103
	v_mul_f32_e32 v104, v104, v142
	v_mul_f32_e32 v105, v105, v142
	v_mul_f32_e32 v104, 0xbfb8aa3b, v104
	v_mul_f32_e32 v105, 0xbfb8aa3b, v105
	v_exp_f32_e32 v118, v104
	v_exp_f32_e32 v119, v105
	s_waitcnt lgkmcnt(0)
	v_mov_b32_e32 v110, v222
	v_mov_b32_e32 v111, v223
	v_mov_b32_e32 v122, v208
	v_mov_b32_e32 v123, v209
	v_mov_b32_e32 v124, v210
	v_mov_b32_e32 v125, v211
	v_lshlrev_b32_e32 v112, 16, v110
	v_and_b32_e32 v113, 0xffff0000, v110
	v_lshlrev_b32_e32 v110, 16, v111
	v_and_b32_e32 v111, 0xffff0000, v111
	v_pk_fma_f32 v[106:107], v[106:107], v[112:113], v[122:123]
	v_pk_fma_f32 v[108:109], v[108:109], v[110:111], v[124:125]
	global_store_dwordx4 v[114:115], v[106:109], off offset:64
	s_nop 0
	s_nop 0
	s_nop 0
	v_exp_f32_e32 v112, v102
	v_exp_f32_e32 v113, v103
	v_pk_add_f32 v[118:119], v[118:119], 1.0 op_sel_hi:[1,0]
	s_nop 0
	v_div_scale_f32 v124, s[4:5], v119, v119, 1.0
	v_pk_add_f32 v[112:113], v[112:113], 1.0 op_sel_hi:[1,0]
	v_div_scale_f32 v136, s[6:7], v118, v118, 1.0
	v_div_scale_f32 v120, s[0:1], v113, v113, 1.0
	v_div_scale_f32 v122, s[0:1], v112, v112, 1.0
	v_rcp_f32_e32 v138, v120
	v_rcp_f32_e32 v139, v122
	v_rcp_f32_e32 v143, v124
	v_rcp_f32_e32 v144, v136
	v_fma_f32 v145, -v120, v138, 1.0
	v_div_scale_f32 v121, vcc, 1.0, v113, 1.0
	v_fma_f32 v146, -v122, v139, 1.0
	v_fmac_f32_e32 v138, v145, v138
	v_div_scale_f32 v123, s[0:1], 1.0, v112, 1.0
	v_fma_f32 v147, -v124, v143, 1.0
	v_fmac_f32_e32 v139, v146, v139
	v_mul_f32_e32 v145, v121, v138
	v_div_scale_f32 v125, s[4:5], 1.0, v119, 1.0
	v_fma_f32 v148, -v136, v144, 1.0
	v_fmac_f32_e32 v143, v147, v143
	v_mul_f32_e32 v146, v123, v139
	v_fma_f32 v149, -v120, v145, v121
	v_div_scale_f32 v137, s[6:7], 1.0, v118, 1.0
	v_fmac_f32_e32 v144, v148, v144
	v_mul_f32_e32 v147, v125, v143
	v_fma_f32 v150, -v122, v146, v123
	v_fmac_f32_e32 v145, v149, v138
	v_mul_f32_e32 v148, v137, v144
	v_fma_f32 v151, -v124, v147, v125
	v_fmac_f32_e32 v146, v150, v139
	v_fma_f32 v120, -v120, v145, v121
	v_fma_f32 v152, -v136, v148, v137
	v_fmac_f32_e32 v147, v151, v143
	v_fma_f32 v121, -v122, v146, v123
	v_div_fmas_f32 v120, v120, v138, v145
	s_mov_b64 vcc, s[0:1]
	v_fmac_f32_e32 v148, v152, v144
	v_fma_f32 v122, -v124, v147, v125
	v_div_fixup_f32 v113, v120, v113, 1.0
	v_div_fmas_f32 v120, v121, v139, v146
	s_mov_b64 vcc, s[4:5]
	v_fma_f32 v123, -v136, v148, v137
	v_div_fixup_f32 v112, v120, v112, 1.0
	v_div_fmas_f32 v120, v122, v143, v147
	s_mov_b64 vcc, s[6:7]
	v_div_fixup_f32 v119, v120, v119, 1.0
	v_div_fmas_f32 v120, v123, v144, v148
	v_div_fixup_f32 v118, v120, v118, 1.0
	v_mul_f32_e32 v98, v98, v142
	v_mul_f32_e32 v99, v99, v142
	v_mul_f32_e32 v98, 0xbfb8aa3b, v98
	v_mul_f32_e32 v99, 0xbfb8aa3b, v99
	v_mul_f32_e32 v100, v100, v142
	v_mul_f32_e32 v101, v101, v142
	v_exp_f32_e32 v98, v98
	v_exp_f32_e32 v99, v99
	v_mul_f32_e32 v100, 0xbfb8aa3b, v100
	v_mul_f32_e32 v101, 0xbfb8aa3b, v101
	v_exp_f32_e32 v100, v100
	v_exp_f32_e32 v101, v101
	v_pk_add_f32 v[98:99], v[98:99], 1.0 op_sel_hi:[1,0]
	v_pk_add_f32 v[100:101], v[100:101], 1.0 op_sel_hi:[1,0]
	s_waitcnt lgkmcnt(0)
	v_mov_b32_e32 v110, v224
	v_mov_b32_e32 v111, v225
	v_mov_b32_e32 v106, v212
	v_mov_b32_e32 v107, v213
	v_mov_b32_e32 v108, v214
	v_mov_b32_e32 v109, v215
	v_mov_b32_e32 v102, v216
	v_mov_b32_e32 v103, v217
	v_mov_b32_e32 v104, v218
	v_mov_b32_e32 v105, v219
	v_lshlrev_b32_e32 v120, 16, v110
	v_and_b32_e32 v121, 0xffff0000, v110
	v_lshlrev_b32_e32 v110, 16, v111
	v_and_b32_e32 v111, 0xffff0000, v111
	v_pk_fma_f32 v[106:107], v[112:113], v[120:121], v[106:107]
	v_pk_fma_f32 v[108:109], v[118:119], v[110:111], v[108:109]
	global_store_dwordx4 v[114:115], v[106:109], off offset:128
	s_nop 0
	v_div_scale_f32 v110, s[0:1], v98, v98, 1.0
	v_div_scale_f32 v108, s[0:1], v99, v99, 1.0
	v_rcp_f32_e32 v118, v108
	v_div_scale_f32 v112, s[4:5], v101, v101, 1.0
	v_rcp_f32_e32 v119, v110
	v_div_scale_f32 v116, s[6:7], v100, v100, 1.0
	v_rcp_f32_e32 v120, v112
	v_rcp_f32_e32 v121, v116
	v_fma_f32 v122, -v108, v118, 1.0
	v_div_scale_f32 v109, vcc, 1.0, v99, 1.0
	v_fma_f32 v123, -v110, v119, 1.0
	v_fmac_f32_e32 v118, v122, v118
	v_div_scale_f32 v111, s[0:1], 1.0, v98, 1.0
	v_fma_f32 v124, -v112, v120, 1.0
	v_fmac_f32_e32 v119, v123, v119
	v_mul_f32_e32 v122, v109, v118
	v_div_scale_f32 v113, s[4:5], 1.0, v101, 1.0
	v_fma_f32 v125, -v116, v121, 1.0
	v_fmac_f32_e32 v120, v124, v120
	v_mul_f32_e32 v123, v111, v119
	v_fma_f32 v136, -v108, v122, v109
	v_div_scale_f32 v117, s[6:7], 1.0, v100, 1.0
	v_fmac_f32_e32 v121, v125, v121
	v_mul_f32_e32 v124, v113, v120
	v_fma_f32 v137, -v110, v123, v111
	v_fmac_f32_e32 v122, v136, v118
	v_mul_f32_e32 v125, v117, v121
	v_fma_f32 v138, -v112, v124, v113
	v_fmac_f32_e32 v123, v137, v119
	v_fma_f32 v108, -v108, v122, v109
	v_fma_f32 v139, -v116, v125, v117
	v_fmac_f32_e32 v124, v138, v120
	v_fma_f32 v109, -v110, v123, v111
	v_div_fmas_f32 v108, v108, v118, v122
	s_mov_b64 vcc, s[0:1]
	v_fmac_f32_e32 v125, v139, v121
	v_fma_f32 v110, -v112, v124, v113
	v_div_fixup_f32 v99, v108, v99, 1.0
	v_div_fmas_f32 v108, v109, v119, v123
	s_mov_b64 vcc, s[4:5]
	v_fma_f32 v111, -v116, v125, v117
	v_div_fixup_f32 v98, v108, v98, 1.0
	v_div_fmas_f32 v108, v110, v120, v124
	s_mov_b64 vcc, s[6:7]
	v_div_fixup_f32 v101, v108, v101, 1.0
	v_div_fmas_f32 v108, v111, v121, v125
	v_div_fixup_f32 v100, v108, v100, 1.0
	s_waitcnt lgkmcnt(0)
	v_mov_b32_e32 v106, v226
	v_mov_b32_e32 v107, v227
	v_lshlrev_b32_e32 v108, 16, v106
	v_and_b32_e32 v109, 0xffff0000, v106
	v_lshlrev_b32_e32 v106, 16, v107
	v_and_b32_e32 v107, 0xffff0000, v107
	v_pk_fma_f32 v[98:99], v[98:99], v[108:109], v[102:103]
	v_pk_fma_f32 v[100:101], v[100:101], v[106:107], v[104:105]
	global_store_dwordx4 v[114:115], v[98:101], off offset:192
	s_nop 1
	v_or_b32_e32 v98, 32, v126
	v_mov_b32_e32 v99, v127
	v_lshl_add_u64 v[100:101], v[98:99], 2, s[14:15]
	s_mov_b32 s99, 0
	s_mov_b32 s98, 0x30000
	v_lshl_add_u64 v[236:237], v[230:231], 0, s[98:99]
	global_load_dwordx4 v[204:207], v[236:237], off
	global_load_dwordx4 v[208:211], v[236:237], off offset:64
	global_load_dwordx4 v[212:215], v[236:237], off offset:128
	global_load_dwordx4 v[216:219], v[236:237], off offset:192
	s_mov_b32 s98, 0x18000
	v_lshl_add_u64 v[236:237], v[232:233], 0, s[98:99]
	global_load_dwordx2 v[220:221], v[236:237], off
	global_load_dwordx2 v[222:223], v[236:237], off offset:32
	global_load_dwordx2 v[224:225], v[236:237], off offset:64
	global_load_dwordx2 v[226:227], v[236:237], off offset:96
	s_mov_b32 s98, 0xc0
	v_lshl_add_u64 v[236:237], v[234:235], 0, s[98:99]
	global_load_dword v229, v[236:237], off
	v_lshlrev_b64 v[100:101], 11, v[98:99]
	v_lshl_add_u64 v[100:101], s[12:13], 0, v[100:101]
	v_lshl_add_u64 v[100:101], v[100:101], 0, v[128:129]
	s_nop 0
	v_lshlrev_b64 v[98:99], 12, v[98:99]
	v_lshl_add_u64 v[98:99], v[130:131], 0, v[98:99]
	v_lshl_add_u64 v[98:99], v[98:99], 0, v[134:135]
	s_nop 0
	s_waitcnt vmcnt(13) lgkmcnt(0)
	v_mov_b32_e32 v106, v228
	v_mov_b32_e32 v110, v196
	v_mov_b32_e32 v111, v197
	v_mov_b32_e32 v102, v180
	v_mov_b32_e32 v103, v181
	v_mov_b32_e32 v104, v182
	v_mov_b32_e32 v105, v183
	v_fmamk_f32 v106, v106, 0x3a800000, v141
	v_mul_f32_e32 v107, 0x4b800000, v106
	v_cmp_gt_f32_e32 vcc, s50, v106
	v_lshlrev_b32_e32 v112, 16, v110
	s_nop 0
	v_cndmask_b32_e32 v106, v106, v107, vcc
	v_rsq_f32_e32 v114, v106
	v_and_b32_e32 v113, 0xffff0000, v110
	s_nop 0
	v_mul_f32_e32 v110, 0x45800000, v114
	v_cndmask_b32_e32 v114, v114, v110, vcc
	v_mul_f32_e32 v94, v94, v114
	v_mul_f32_e32 v95, v95, v114
	v_mul_f32_e32 v94, 0xbfb8aa3b, v94
	v_mul_f32_e32 v95, 0xbfb8aa3b, v95
	v_mul_f32_e32 v96, v96, v114
	v_mul_f32_e32 v97, v97, v114
	v_exp_f32_e32 v94, v94
	v_exp_f32_e32 v95, v95
	v_mul_f32_e32 v96, 0xbfb8aa3b, v96
	v_mul_f32_e32 v97, 0xbfb8aa3b, v97
	v_exp_f32_e32 v96, v96
	v_exp_f32_e32 v97, v97
	v_pk_add_f32 v[94:95], v[94:95], 1.0 op_sel_hi:[1,0]
	v_lshlrev_b32_e32 v110, 16, v111
	v_div_scale_f32 v115, s[0:1], v95, v95, 1.0
	v_pk_add_f32 v[96:97], v[96:97], 1.0 op_sel_hi:[1,0]
	v_div_scale_f32 v117, s[0:1], v94, v94, 1.0
	v_rcp_f32_e32 v123, v115
	v_div_scale_f32 v119, s[4:5], v97, v97, 1.0
	v_rcp_f32_e32 v124, v117
	v_div_scale_f32 v121, s[6:7], v96, v96, 1.0
	v_rcp_f32_e32 v125, v119
	v_rcp_f32_e32 v136, v121
	v_fma_f32 v137, -v115, v123, 1.0
	v_div_scale_f32 v116, vcc, 1.0, v95, 1.0
	v_fma_f32 v138, -v117, v124, 1.0
	v_fmac_f32_e32 v123, v137, v123
	v_div_scale_f32 v118, s[0:1], 1.0, v94, 1.0
	v_fma_f32 v139, -v119, v125, 1.0
	v_fmac_f32_e32 v124, v138, v124
	v_mul_f32_e32 v137, v116, v123
	v_div_scale_f32 v120, s[4:5], 1.0, v97, 1.0
	v_fma_f32 v142, -v121, v136, 1.0
	v_fmac_f32_e32 v125, v139, v125
	v_mul_f32_e32 v138, v118, v124
	v_fma_f32 v143, -v115, v137, v116
	v_div_scale_f32 v122, s[6:7], 1.0, v96, 1.0
	v_fmac_f32_e32 v136, v142, v136
	v_mul_f32_e32 v139, v120, v125
	v_fma_f32 v144, -v117, v138, v118
	v_fmac_f32_e32 v137, v143, v123
	v_mul_f32_e32 v142, v122, v136
	v_fma_f32 v145, -v119, v139, v120
	v_fmac_f32_e32 v138, v144, v124
	v_fma_f32 v115, -v115, v137, v116
	v_fma_f32 v146, -v121, v142, v122
	v_fmac_f32_e32 v139, v145, v125
	v_fma_f32 v116, -v117, v138, v118
	v_div_fmas_f32 v115, v115, v123, v137
	s_mov_b64 vcc, s[0:1]
	v_fmac_f32_e32 v142, v146, v136
	v_fma_f32 v117, -v119, v139, v120
	v_div_fixup_f32 v95, v115, v95, 1.0
	v_div_fmas_f32 v115, v116, v124, v138
	s_mov_b64 vcc, s[4:5]
	v_fma_f32 v118, -v121, v142, v122
	v_div_fixup_f32 v94, v115, v94, 1.0
	v_div_fmas_f32 v115, v117, v125, v139
	s_mov_b64 vcc, s[6:7]
	v_pk_fma_f32 v[94:95], v[94:95], v[112:113], v[102:103]
	v_div_fmas_f32 v102, v118, v136, v142
	v_and_b32_e32 v111, 0xffff0000, v111
	v_div_fixup_f32 v97, v115, v97, 1.0
	v_div_fixup_f32 v96, v102, v96, 1.0
	v_pk_fma_f32 v[96:97], v[96:97], v[110:111], v[104:105]
	global_store_dwordx4 v[98:99], v[94:97], off
	s_nop 0
	v_mul_f32_e32 v90, v90, v114
	v_mul_f32_e32 v91, v91, v114
	v_mul_f32_e32 v90, 0xbfb8aa3b, v90
	v_mul_f32_e32 v91, 0xbfb8aa3b, v91
	v_mul_f32_e32 v92, v92, v114
	v_mul_f32_e32 v93, v93, v114
	v_exp_f32_e32 v90, v90
	v_exp_f32_e32 v91, v91
	v_mul_f32_e32 v92, 0xbfb8aa3b, v92
	v_mul_f32_e32 v93, 0xbfb8aa3b, v93
	v_exp_f32_e32 v92, v92
	v_exp_f32_e32 v93, v93
	v_pk_add_f32 v[90:91], v[90:91], 1.0 op_sel_hi:[1,0]
	v_mul_f32_e32 v86, v86, v114
	v_div_scale_f32 v96, s[0:1], v91, v91, 1.0
	v_pk_add_f32 v[92:93], v[92:93], 1.0 op_sel_hi:[1,0]
	v_div_scale_f32 v102, s[0:1], v90, v90, 1.0
	v_rcp_f32_e32 v112, v96
	v_div_scale_f32 v104, s[4:5], v93, v93, 1.0
	v_rcp_f32_e32 v113, v102
	v_div_scale_f32 v110, s[6:7], v92, v92, 1.0
	v_rcp_f32_e32 v115, v104
	v_rcp_f32_e32 v116, v110
	v_fma_f32 v117, -v96, v112, 1.0
	v_div_scale_f32 v97, vcc, 1.0, v91, 1.0
	v_fma_f32 v118, -v102, v113, 1.0
	v_fmac_f32_e32 v112, v117, v112
	v_div_scale_f32 v103, s[0:1], 1.0, v90, 1.0
	v_fma_f32 v119, -v104, v115, 1.0
	v_fmac_f32_e32 v113, v118, v113
	v_mul_f32_e32 v117, v97, v112
	v_div_scale_f32 v105, s[4:5], 1.0, v93, 1.0
	v_fma_f32 v120, -v110, v116, 1.0
	v_fmac_f32_e32 v115, v119, v115
	v_mul_f32_e32 v118, v103, v113
	v_fma_f32 v121, -v96, v117, v97
	v_div_scale_f32 v111, s[6:7], 1.0, v92, 1.0
	v_fmac_f32_e32 v116, v120, v116
	v_mul_f32_e32 v119, v105, v115
	v_fma_f32 v122, -v102, v118, v103
	v_fmac_f32_e32 v117, v121, v112
	v_mul_f32_e32 v120, v111, v116
	v_fma_f32 v123, -v104, v119, v105
	v_fmac_f32_e32 v118, v122, v113
	v_fma_f32 v96, -v96, v117, v97
	v_fma_f32 v124, -v110, v120, v111
	v_fmac_f32_e32 v119, v123, v115
	v_fma_f32 v97, -v102, v118, v103
	v_div_fmas_f32 v96, v96, v112, v117
	s_mov_b64 vcc, s[0:1]
	v_fmac_f32_e32 v120, v124, v116
	v_fma_f32 v102, -v104, v119, v105
	v_div_fixup_f32 v91, v96, v91, 1.0
	v_div_fmas_f32 v96, v97, v113, v118
	s_mov_b64 vcc, s[4:5]
	v_fma_f32 v103, -v110, v120, v111
	v_div_fixup_f32 v90, v96, v90, 1.0
	v_div_fmas_f32 v96, v102, v115, v119
	s_mov_b64 vcc, s[6:7]
	v_div_fixup_f32 v93, v96, v93, 1.0
	v_div_fmas_f32 v96, v103, v116, v120
	v_div_fixup_f32 v92, v96, v92, 1.0
	v_mul_f32_e32 v87, v87, v114
	v_mul_f32_e32 v86, 0xbfb8aa3b, v86
	v_mul_f32_e32 v87, 0xbfb8aa3b, v87
	v_mul_f32_e32 v88, v88, v114
	v_mul_f32_e32 v89, v89, v114
	v_mul_f32_e32 v88, 0xbfb8aa3b, v88
	v_mul_f32_e32 v89, 0xbfb8aa3b, v89
	v_exp_f32_e32 v102, v88
	v_exp_f32_e32 v103, v89
	s_waitcnt lgkmcnt(0)
	v_mov_b32_e32 v94, v198
	v_mov_b32_e32 v95, v199
	v_mov_b32_e32 v106, v184
	v_mov_b32_e32 v107, v185
	v_mov_b32_e32 v108, v186
	v_mov_b32_e32 v109, v187
	v_lshlrev_b32_e32 v96, 16, v94
	v_and_b32_e32 v97, 0xffff0000, v94
	v_lshlrev_b32_e32 v94, 16, v95
	v_and_b32_e32 v95, 0xffff0000, v95
	v_pk_fma_f32 v[90:91], v[90:91], v[96:97], v[106:107]
	v_pk_fma_f32 v[92:93], v[92:93], v[94:95], v[108:109]
	global_store_dwordx4 v[98:99], v[90:93], off offset:64
	s_nop 0
	s_nop 0
	s_nop 0
	v_exp_f32_e32 v96, v86
	v_exp_f32_e32 v97, v87
	v_pk_add_f32 v[102:103], v[102:103], 1.0 op_sel_hi:[1,0]
	s_nop 0
	v_div_scale_f32 v108, s[4:5], v103, v103, 1.0
	v_pk_add_f32 v[96:97], v[96:97], 1.0 op_sel_hi:[1,0]
	v_div_scale_f32 v110, s[6:7], v102, v102, 1.0
	v_div_scale_f32 v104, s[0:1], v97, v97, 1.0
	v_div_scale_f32 v106, s[0:1], v96, v96, 1.0
	v_rcp_f32_e32 v112, v104
	v_rcp_f32_e32 v113, v106
	v_rcp_f32_e32 v115, v108
	v_rcp_f32_e32 v116, v110
	v_fma_f32 v117, -v104, v112, 1.0
	v_div_scale_f32 v105, vcc, 1.0, v97, 1.0
	v_fma_f32 v118, -v106, v113, 1.0
	v_fmac_f32_e32 v112, v117, v112
	v_div_scale_f32 v107, s[0:1], 1.0, v96, 1.0
	v_fma_f32 v119, -v108, v115, 1.0
	v_fmac_f32_e32 v113, v118, v113
	v_mul_f32_e32 v117, v105, v112
	v_div_scale_f32 v109, s[4:5], 1.0, v103, 1.0
	v_fma_f32 v120, -v110, v116, 1.0
	v_fmac_f32_e32 v115, v119, v115
	v_mul_f32_e32 v118, v107, v113
	v_fma_f32 v121, -v104, v117, v105
	v_div_scale_f32 v111, s[6:7], 1.0, v102, 1.0
	v_fmac_f32_e32 v116, v120, v116
	v_mul_f32_e32 v119, v109, v115
	v_fma_f32 v122, -v106, v118, v107
	v_fmac_f32_e32 v117, v121, v112
	v_mul_f32_e32 v120, v111, v116
	v_fma_f32 v123, -v108, v119, v109
	v_fmac_f32_e32 v118, v122, v113
	v_fma_f32 v104, -v104, v117, v105
	v_fma_f32 v124, -v110, v120, v111
	v_fmac_f32_e32 v119, v123, v115
	v_fma_f32 v105, -v106, v118, v107
	v_div_fmas_f32 v104, v104, v112, v117
	s_mov_b64 vcc, s[0:1]
	v_fmac_f32_e32 v120, v124, v116
	v_fma_f32 v106, -v108, v119, v109
	v_div_fixup_f32 v97, v104, v97, 1.0
	v_div_fmas_f32 v104, v105, v113, v118
	s_mov_b64 vcc, s[4:5]
	v_fma_f32 v107, -v110, v120, v111
	v_div_fixup_f32 v96, v104, v96, 1.0
	v_div_fmas_f32 v104, v106, v115, v119
	s_mov_b64 vcc, s[6:7]
	v_div_fixup_f32 v103, v104, v103, 1.0
	v_div_fmas_f32 v104, v107, v116, v120
	v_div_fixup_f32 v102, v104, v102, 1.0
	v_mul_f32_e32 v82, v82, v114
	v_mul_f32_e32 v83, v83, v114
	v_mul_f32_e32 v82, 0xbfb8aa3b, v82
	v_mul_f32_e32 v83, 0xbfb8aa3b, v83
	v_mul_f32_e32 v84, v84, v114
	v_mul_f32_e32 v85, v85, v114
	v_exp_f32_e32 v82, v82
	v_exp_f32_e32 v83, v83
	v_mul_f32_e32 v84, 0xbfb8aa3b, v84
	v_mul_f32_e32 v85, 0xbfb8aa3b, v85
	v_exp_f32_e32 v84, v84
	v_exp_f32_e32 v85, v85
	v_pk_add_f32 v[82:83], v[82:83], 1.0 op_sel_hi:[1,0]
	v_pk_add_f32 v[84:85], v[84:85], 1.0 op_sel_hi:[1,0]
	s_waitcnt lgkmcnt(0)
	v_mov_b32_e32 v94, v200
	v_mov_b32_e32 v95, v201
	v_mov_b32_e32 v90, v188
	v_mov_b32_e32 v91, v189
	v_mov_b32_e32 v92, v190
	v_mov_b32_e32 v93, v191
	v_mov_b32_e32 v86, v192
	v_mov_b32_e32 v87, v193
	v_mov_b32_e32 v88, v194
	v_mov_b32_e32 v89, v195
	v_lshlrev_b32_e32 v104, 16, v94
	v_and_b32_e32 v105, 0xffff0000, v94
	v_lshlrev_b32_e32 v94, 16, v95
	v_and_b32_e32 v95, 0xffff0000, v95
	v_pk_fma_f32 v[90:91], v[96:97], v[104:105], v[90:91]
	v_pk_fma_f32 v[92:93], v[102:103], v[94:95], v[92:93]
	global_store_dwordx4 v[98:99], v[90:93], off offset:128
	s_nop 0
	v_div_scale_f32 v94, s[0:1], v82, v82, 1.0
	v_div_scale_f32 v92, s[0:1], v83, v83, 1.0
	v_rcp_f32_e32 v102, v92
	v_div_scale_f32 v96, s[4:5], v85, v85, 1.0
	v_rcp_f32_e32 v103, v94
	v_div_scale_f32 v100, s[6:7], v84, v84, 1.0
	v_rcp_f32_e32 v104, v96
	v_rcp_f32_e32 v105, v100
	v_fma_f32 v106, -v92, v102, 1.0
	v_div_scale_f32 v93, vcc, 1.0, v83, 1.0
	v_fma_f32 v107, -v94, v103, 1.0
	v_fmac_f32_e32 v102, v106, v102
	v_div_scale_f32 v95, s[0:1], 1.0, v82, 1.0
	v_fma_f32 v108, -v96, v104, 1.0
	v_fmac_f32_e32 v103, v107, v103
	v_mul_f32_e32 v106, v93, v102
	v_div_scale_f32 v97, s[4:5], 1.0, v85, 1.0
	v_fma_f32 v109, -v100, v105, 1.0
	v_fmac_f32_e32 v104, v108, v104
	v_mul_f32_e32 v107, v95, v103
	v_fma_f32 v110, -v92, v106, v93
	v_div_scale_f32 v101, s[6:7], 1.0, v84, 1.0
	v_fmac_f32_e32 v105, v109, v105
	v_mul_f32_e32 v108, v97, v104
	v_fma_f32 v111, -v94, v107, v95
	v_fmac_f32_e32 v106, v110, v102
	v_mul_f32_e32 v109, v101, v105
	v_fma_f32 v112, -v96, v108, v97
	v_fmac_f32_e32 v107, v111, v103
	v_fma_f32 v92, -v92, v106, v93
	v_fma_f32 v113, -v100, v109, v101
	v_fmac_f32_e32 v108, v112, v104
	v_fma_f32 v93, -v94, v107, v95
	v_div_fmas_f32 v92, v92, v102, v106
	s_mov_b64 vcc, s[0:1]
	v_fmac_f32_e32 v109, v113, v105
	v_fma_f32 v94, -v96, v108, v97
	v_div_fixup_f32 v83, v92, v83, 1.0
	v_div_fmas_f32 v92, v93, v103, v107
	s_mov_b64 vcc, s[4:5]
	v_fma_f32 v95, -v100, v109, v101
	v_div_fixup_f32 v82, v92, v82, 1.0
	v_div_fmas_f32 v92, v94, v104, v108
	s_mov_b64 vcc, s[6:7]
	v_div_fixup_f32 v85, v92, v85, 1.0
	v_div_fmas_f32 v92, v95, v105, v109
	v_div_fixup_f32 v84, v92, v84, 1.0
	s_waitcnt lgkmcnt(0)
	v_mov_b32_e32 v90, v202
	v_mov_b32_e32 v91, v203
	v_lshlrev_b32_e32 v92, 16, v90
	v_and_b32_e32 v93, 0xffff0000, v90
	v_lshlrev_b32_e32 v90, 16, v91
	v_and_b32_e32 v91, 0xffff0000, v91
	v_pk_fma_f32 v[82:83], v[82:83], v[92:93], v[86:87]
	v_pk_fma_f32 v[84:85], v[84:85], v[90:91], v[88:89]
	global_store_dwordx4 v[98:99], v[82:85], off offset:192
	s_nop 1
	v_or_b32_e32 v82, 48, v126
	v_mov_b32_e32 v83, v127
	v_lshl_add_u64 v[84:85], v[82:83], 2, s[14:15]
	s_mov_b32 s99, 0
	s_mov_b32 s98, 0x40000
	v_lshl_add_u64 v[236:237], v[230:231], 0, s[98:99]
	global_load_dwordx4 v[180:183], v[236:237], off
	global_load_dwordx4 v[184:187], v[236:237], off offset:64
	global_load_dwordx4 v[188:191], v[236:237], off offset:128
	global_load_dwordx4 v[192:195], v[236:237], off offset:192
	s_mov_b32 s98, 0x20000
	v_lshl_add_u64 v[236:237], v[232:233], 0, s[98:99]
	global_load_dwordx2 v[196:197], v[236:237], off
	global_load_dwordx2 v[198:199], v[236:237], off offset:32
	global_load_dwordx2 v[200:201], v[236:237], off offset:64
	global_load_dwordx2 v[202:203], v[236:237], off offset:96
	s_mov_b32 s98, 0x100
	v_lshl_add_u64 v[236:237], v[234:235], 0, s[98:99]
	global_load_dword v228, v[236:237], off
	v_lshlrev_b64 v[84:85], 11, v[82:83]
	v_lshl_add_u64 v[84:85], s[12:13], 0, v[84:85]
	v_lshl_add_u64 v[84:85], v[84:85], 0, v[128:129]
	s_nop 0
	v_lshlrev_b64 v[82:83], 12, v[82:83]
	v_lshl_add_u64 v[82:83], v[130:131], 0, v[82:83]
	v_lshl_add_u64 v[82:83], v[82:83], 0, v[134:135]
	s_nop 0
	s_waitcnt vmcnt(13) lgkmcnt(0)
	v_mov_b32_e32 v90, v229
	v_mov_b32_e32 v94, v220
	v_mov_b32_e32 v95, v221
	v_mov_b32_e32 v86, v204
	v_mov_b32_e32 v87, v205
	v_mov_b32_e32 v88, v206
	v_mov_b32_e32 v89, v207
	v_fmamk_f32 v90, v90, 0x3a800000, v141
	v_mul_f32_e32 v91, 0x4b800000, v90
	v_cmp_gt_f32_e32 vcc, s50, v90
	v_lshlrev_b32_e32 v96, 16, v94
	s_nop 0
	v_cndmask_b32_e32 v90, v90, v91, vcc
	v_rsq_f32_e32 v98, v90
	v_and_b32_e32 v97, 0xffff0000, v94
	s_nop 0
	v_mul_f32_e32 v94, 0x45800000, v98
	v_cndmask_b32_e32 v98, v98, v94, vcc
	v_mul_f32_e32 v78, v78, v98
	v_mul_f32_e32 v79, v79, v98
	v_mul_f32_e32 v78, 0xbfb8aa3b, v78
	v_mul_f32_e32 v79, 0xbfb8aa3b, v79
	v_mul_f32_e32 v80, v80, v98
	v_mul_f32_e32 v81, v81, v98
	v_exp_f32_e32 v78, v78
	v_exp_f32_e32 v79, v79
	v_mul_f32_e32 v80, 0xbfb8aa3b, v80
	v_mul_f32_e32 v81, 0xbfb8aa3b, v81
	v_exp_f32_e32 v80, v80
	v_exp_f32_e32 v81, v81
	v_pk_add_f32 v[78:79], v[78:79], 1.0 op_sel_hi:[1,0]
	v_lshlrev_b32_e32 v94, 16, v95
	v_div_scale_f32 v99, s[0:1], v79, v79, 1.0
	v_pk_add_f32 v[80:81], v[80:81], 1.0 op_sel_hi:[1,0]
	v_div_scale_f32 v101, s[0:1], v78, v78, 1.0
	v_rcp_f32_e32 v107, v99
	v_div_scale_f32 v103, s[4:5], v81, v81, 1.0
	v_rcp_f32_e32 v108, v101
	v_div_scale_f32 v105, s[6:7], v80, v80, 1.0
	v_rcp_f32_e32 v109, v103
	v_rcp_f32_e32 v110, v105
	v_fma_f32 v111, -v99, v107, 1.0
	v_div_scale_f32 v100, vcc, 1.0, v79, 1.0
	v_fma_f32 v112, -v101, v108, 1.0
	v_fmac_f32_e32 v107, v111, v107
	v_div_scale_f32 v102, s[0:1], 1.0, v78, 1.0
	v_fma_f32 v113, -v103, v109, 1.0
	v_fmac_f32_e32 v108, v112, v108
	v_mul_f32_e32 v111, v100, v107
	v_div_scale_f32 v104, s[4:5], 1.0, v81, 1.0
	v_fma_f32 v114, -v105, v110, 1.0
	v_fmac_f32_e32 v109, v113, v109
	v_mul_f32_e32 v112, v102, v108
	v_fma_f32 v115, -v99, v111, v100
	v_div_scale_f32 v106, s[6:7], 1.0, v80, 1.0
	v_fmac_f32_e32 v110, v114, v110
	v_mul_f32_e32 v113, v104, v109
	v_fma_f32 v116, -v101, v112, v102
	v_fmac_f32_e32 v111, v115, v107
	v_mul_f32_e32 v114, v106, v110
	v_fma_f32 v117, -v103, v113, v104
	v_fmac_f32_e32 v112, v116, v108
	v_fma_f32 v99, -v99, v111, v100
	v_fma_f32 v118, -v105, v114, v106
	v_fmac_f32_e32 v113, v117, v109
	v_fma_f32 v100, -v101, v112, v102
	v_div_fmas_f32 v99, v99, v107, v111
	s_mov_b64 vcc, s[0:1]
	v_fmac_f32_e32 v114, v118, v110
	v_fma_f32 v101, -v103, v113, v104
	v_div_fixup_f32 v79, v99, v79, 1.0
	v_div_fmas_f32 v99, v100, v108, v112
	s_mov_b64 vcc, s[4:5]
	v_fma_f32 v102, -v105, v114, v106
	v_div_fixup_f32 v78, v99, v78, 1.0
	v_div_fmas_f32 v99, v101, v109, v113
	s_mov_b64 vcc, s[6:7]
	v_pk_fma_f32 v[78:79], v[78:79], v[96:97], v[86:87]
	v_div_fmas_f32 v86, v102, v110, v114
	v_and_b32_e32 v95, 0xffff0000, v95
	v_div_fixup_f32 v81, v99, v81, 1.0
	v_div_fixup_f32 v80, v86, v80, 1.0
	v_pk_fma_f32 v[80:81], v[80:81], v[94:95], v[88:89]
	global_store_dwordx4 v[82:83], v[78:81], off
	s_nop 0
	v_mul_f32_e32 v74, v74, v98
	v_mul_f32_e32 v75, v75, v98
	v_mul_f32_e32 v74, 0xbfb8aa3b, v74
	v_mul_f32_e32 v75, 0xbfb8aa3b, v75
	v_mul_f32_e32 v76, v76, v98
	v_mul_f32_e32 v77, v77, v98
	v_exp_f32_e32 v74, v74
	v_exp_f32_e32 v75, v75
	v_mul_f32_e32 v76, 0xbfb8aa3b, v76
	v_mul_f32_e32 v77, 0xbfb8aa3b, v77
	v_exp_f32_e32 v76, v76
	v_exp_f32_e32 v77, v77
	v_pk_add_f32 v[74:75], v[74:75], 1.0 op_sel_hi:[1,0]
	v_mul_f32_e32 v70, v70, v98
	v_div_scale_f32 v80, s[0:1], v75, v75, 1.0
	v_pk_add_f32 v[76:77], v[76:77], 1.0 op_sel_hi:[1,0]
	v_div_scale_f32 v86, s[0:1], v74, v74, 1.0
	v_rcp_f32_e32 v96, v80
	v_div_scale_f32 v88, s[4:5], v77, v77, 1.0
	v_rcp_f32_e32 v97, v86
	v_div_scale_f32 v94, s[6:7], v76, v76, 1.0
	v_rcp_f32_e32 v99, v88
	v_rcp_f32_e32 v100, v94
	v_fma_f32 v101, -v80, v96, 1.0
	v_div_scale_f32 v81, vcc, 1.0, v75, 1.0
	v_fma_f32 v102, -v86, v97, 1.0
	v_fmac_f32_e32 v96, v101, v96
	v_div_scale_f32 v87, s[0:1], 1.0, v74, 1.0
	v_fma_f32 v103, -v88, v99, 1.0
	v_fmac_f32_e32 v97, v102, v97
	v_mul_f32_e32 v101, v81, v96
	v_div_scale_f32 v89, s[4:5], 1.0, v77, 1.0
	v_fma_f32 v104, -v94, v100, 1.0
	v_fmac_f32_e32 v99, v103, v99
	v_mul_f32_e32 v102, v87, v97
	v_fma_f32 v105, -v80, v101, v81
	v_div_scale_f32 v95, s[6:7], 1.0, v76, 1.0
	v_fmac_f32_e32 v100, v104, v100
	v_mul_f32_e32 v103, v89, v99
	v_fma_f32 v106, -v86, v102, v87
	v_fmac_f32_e32 v101, v105, v96
	v_mul_f32_e32 v104, v95, v100
	v_fma_f32 v107, -v88, v103, v89
	v_fmac_f32_e32 v102, v106, v97
	v_fma_f32 v80, -v80, v101, v81
	v_fma_f32 v108, -v94, v104, v95
	v_fmac_f32_e32 v103, v107, v99
	v_fma_f32 v81, -v86, v102, v87
	v_div_fmas_f32 v80, v80, v96, v101
	s_mov_b64 vcc, s[0:1]
	v_fmac_f32_e32 v104, v108, v100
	v_fma_f32 v86, -v88, v103, v89
	v_div_fixup_f32 v75, v80, v75, 1.0
	v_div_fmas_f32 v80, v81, v97, v102
	s_mov_b64 vcc, s[4:5]
	v_fma_f32 v87, -v94, v104, v95
	v_div_fixup_f32 v74, v80, v74, 1.0
	v_div_fmas_f32 v80, v86, v99, v103
	s_mov_b64 vcc, s[6:7]
	v_div_fixup_f32 v77, v80, v77, 1.0
	v_div_fmas_f32 v80, v87, v100, v104
	v_div_fixup_f32 v76, v80, v76, 1.0
	v_mul_f32_e32 v71, v71, v98
	v_mul_f32_e32 v70, 0xbfb8aa3b, v70
	v_mul_f32_e32 v71, 0xbfb8aa3b, v71
	v_mul_f32_e32 v72, v72, v98
	v_mul_f32_e32 v73, v73, v98
	v_mul_f32_e32 v72, 0xbfb8aa3b, v72
	v_mul_f32_e32 v73, 0xbfb8aa3b, v73
	v_exp_f32_e32 v86, v72
	v_exp_f32_e32 v87, v73
	s_waitcnt lgkmcnt(0)
	v_mov_b32_e32 v78, v222
	v_mov_b32_e32 v79, v223
	v_mov_b32_e32 v90, v208
	v_mov_b32_e32 v91, v209
	v_mov_b32_e32 v92, v210
	v_mov_b32_e32 v93, v211
	v_lshlrev_b32_e32 v80, 16, v78
	v_and_b32_e32 v81, 0xffff0000, v78
	v_lshlrev_b32_e32 v78, 16, v79
	v_and_b32_e32 v79, 0xffff0000, v79
	v_pk_fma_f32 v[74:75], v[74:75], v[80:81], v[90:91]
	v_pk_fma_f32 v[76:77], v[76:77], v[78:79], v[92:93]
	global_store_dwordx4 v[82:83], v[74:77], off offset:64
	s_nop 0
	s_nop 0
	s_nop 0
	v_exp_f32_e32 v80, v70
	v_exp_f32_e32 v81, v71
	v_pk_add_f32 v[86:87], v[86:87], 1.0 op_sel_hi:[1,0]
	s_nop 0
	v_div_scale_f32 v92, s[4:5], v87, v87, 1.0
	v_pk_add_f32 v[80:81], v[80:81], 1.0 op_sel_hi:[1,0]
	v_div_scale_f32 v94, s[6:7], v86, v86, 1.0
	v_div_scale_f32 v88, s[0:1], v81, v81, 1.0
	v_div_scale_f32 v90, s[0:1], v80, v80, 1.0
	v_rcp_f32_e32 v96, v88
	v_rcp_f32_e32 v97, v90
	v_rcp_f32_e32 v99, v92
	v_rcp_f32_e32 v100, v94
	v_fma_f32 v101, -v88, v96, 1.0
	v_div_scale_f32 v89, vcc, 1.0, v81, 1.0
	v_fma_f32 v102, -v90, v97, 1.0
	v_fmac_f32_e32 v96, v101, v96
	v_div_scale_f32 v91, s[0:1], 1.0, v80, 1.0
	v_fma_f32 v103, -v92, v99, 1.0
	v_fmac_f32_e32 v97, v102, v97
	v_mul_f32_e32 v101, v89, v96
	v_div_scale_f32 v93, s[4:5], 1.0, v87, 1.0
	v_fma_f32 v104, -v94, v100, 1.0
	v_fmac_f32_e32 v99, v103, v99
	v_mul_f32_e32 v102, v91, v97
	v_fma_f32 v105, -v88, v101, v89
	v_div_scale_f32 v95, s[6:7], 1.0, v86, 1.0
	v_fmac_f32_e32 v100, v104, v100
	v_mul_f32_e32 v103, v93, v99
	v_fma_f32 v106, -v90, v102, v91
	v_fmac_f32_e32 v101, v105, v96
	v_mul_f32_e32 v104, v95, v100
	v_fma_f32 v107, -v92, v103, v93
	v_fmac_f32_e32 v102, v106, v97
	v_fma_f32 v88, -v88, v101, v89
	v_fma_f32 v108, -v94, v104, v95
	v_fmac_f32_e32 v103, v107, v99
	v_fma_f32 v89, -v90, v102, v91
	v_div_fmas_f32 v88, v88, v96, v101
	s_mov_b64 vcc, s[0:1]
	v_fmac_f32_e32 v104, v108, v100
	v_fma_f32 v90, -v92, v103, v93
	v_div_fixup_f32 v81, v88, v81, 1.0
	v_div_fmas_f32 v88, v89, v97, v102
	s_mov_b64 vcc, s[4:5]
	v_fma_f32 v91, -v94, v104, v95
	v_div_fixup_f32 v80, v88, v80, 1.0
	v_div_fmas_f32 v88, v90, v99, v103
	s_mov_b64 vcc, s[6:7]
	v_div_fixup_f32 v87, v88, v87, 1.0
	v_div_fmas_f32 v88, v91, v100, v104
	v_div_fixup_f32 v86, v88, v86, 1.0
	v_mul_f32_e32 v66, v66, v98
	v_mul_f32_e32 v67, v67, v98
	v_mul_f32_e32 v66, 0xbfb8aa3b, v66
	v_mul_f32_e32 v67, 0xbfb8aa3b, v67
	v_mul_f32_e32 v68, v68, v98
	v_mul_f32_e32 v69, v69, v98
	v_exp_f32_e32 v66, v66
	v_exp_f32_e32 v67, v67
	v_mul_f32_e32 v68, 0xbfb8aa3b, v68
	v_mul_f32_e32 v69, 0xbfb8aa3b, v69
	v_exp_f32_e32 v68, v68
	v_exp_f32_e32 v69, v69
	v_pk_add_f32 v[66:67], v[66:67], 1.0 op_sel_hi:[1,0]
	v_pk_add_f32 v[68:69], v[68:69], 1.0 op_sel_hi:[1,0]
	s_waitcnt lgkmcnt(0)
	v_mov_b32_e32 v78, v224
	v_mov_b32_e32 v79, v225
	v_mov_b32_e32 v74, v212
	v_mov_b32_e32 v75, v213
	v_mov_b32_e32 v76, v214
	v_mov_b32_e32 v77, v215
	v_mov_b32_e32 v70, v216
	v_mov_b32_e32 v71, v217
	v_mov_b32_e32 v72, v218
	v_mov_b32_e32 v73, v219
	v_lshlrev_b32_e32 v88, 16, v78
	v_and_b32_e32 v89, 0xffff0000, v78
	v_lshlrev_b32_e32 v78, 16, v79
	v_and_b32_e32 v79, 0xffff0000, v79
	v_pk_fma_f32 v[74:75], v[80:81], v[88:89], v[74:75]
	v_pk_fma_f32 v[76:77], v[86:87], v[78:79], v[76:77]
	global_store_dwordx4 v[82:83], v[74:77], off offset:128
	s_nop 0
	v_div_scale_f32 v78, s[0:1], v66, v66, 1.0
	v_div_scale_f32 v76, s[0:1], v67, v67, 1.0
	v_rcp_f32_e32 v86, v76
	v_div_scale_f32 v80, s[4:5], v69, v69, 1.0
	v_rcp_f32_e32 v87, v78
	v_div_scale_f32 v84, s[6:7], v68, v68, 1.0
	v_rcp_f32_e32 v88, v80
	v_rcp_f32_e32 v89, v84
	v_fma_f32 v90, -v76, v86, 1.0
	v_div_scale_f32 v77, vcc, 1.0, v67, 1.0
	v_fma_f32 v91, -v78, v87, 1.0
	v_fmac_f32_e32 v86, v90, v86
	v_div_scale_f32 v79, s[0:1], 1.0, v66, 1.0
	v_fma_f32 v92, -v80, v88, 1.0
	v_fmac_f32_e32 v87, v91, v87
	v_mul_f32_e32 v90, v77, v86
	v_div_scale_f32 v81, s[4:5], 1.0, v69, 1.0
	v_fma_f32 v93, -v84, v89, 1.0
	v_fmac_f32_e32 v88, v92, v88
	v_mul_f32_e32 v91, v79, v87
	v_fma_f32 v94, -v76, v90, v77
	v_div_scale_f32 v85, s[6:7], 1.0, v68, 1.0
	v_fmac_f32_e32 v89, v93, v89
	v_mul_f32_e32 v92, v81, v88
	v_fma_f32 v95, -v78, v91, v79
	v_fmac_f32_e32 v90, v94, v86
	v_mul_f32_e32 v93, v85, v89
	v_fma_f32 v96, -v80, v92, v81
	v_fmac_f32_e32 v91, v95, v87
	v_fma_f32 v76, -v76, v90, v77
	v_fma_f32 v97, -v84, v93, v85
	v_fmac_f32_e32 v92, v96, v88
	v_fma_f32 v77, -v78, v91, v79
	v_div_fmas_f32 v76, v76, v86, v90
	s_mov_b64 vcc, s[0:1]
	v_fmac_f32_e32 v93, v97, v89
	v_fma_f32 v78, -v80, v92, v81
	v_div_fixup_f32 v67, v76, v67, 1.0
	v_div_fmas_f32 v76, v77, v87, v91
	s_mov_b64 vcc, s[4:5]
	v_fma_f32 v79, -v84, v93, v85
	v_div_fixup_f32 v66, v76, v66, 1.0
	v_div_fmas_f32 v76, v78, v88, v92
	s_mov_b64 vcc, s[6:7]
	v_div_fixup_f32 v69, v76, v69, 1.0
	v_div_fmas_f32 v76, v79, v89, v93
	v_div_fixup_f32 v68, v76, v68, 1.0
	s_waitcnt lgkmcnt(0)
	v_mov_b32_e32 v74, v226
	v_mov_b32_e32 v75, v227
	v_lshlrev_b32_e32 v76, 16, v74
	v_and_b32_e32 v77, 0xffff0000, v74
	v_lshlrev_b32_e32 v74, 16, v75
	v_and_b32_e32 v75, 0xffff0000, v75
	v_pk_fma_f32 v[66:67], v[66:67], v[76:77], v[70:71]
	v_pk_fma_f32 v[68:69], v[68:69], v[74:75], v[72:73]
	global_store_dwordx4 v[82:83], v[66:69], off offset:192
	s_nop 1
	v_or_b32_e32 v66, 64, v126
	v_mov_b32_e32 v67, v127
	v_lshl_add_u64 v[68:69], v[66:67], 2, s[14:15]
	s_mov_b32 s99, 0
	s_mov_b32 s98, 0x50000
	v_lshl_add_u64 v[236:237], v[230:231], 0, s[98:99]
	global_load_dwordx4 v[204:207], v[236:237], off
	global_load_dwordx4 v[208:211], v[236:237], off offset:64
	global_load_dwordx4 v[212:215], v[236:237], off offset:128
	global_load_dwordx4 v[216:219], v[236:237], off offset:192
	s_mov_b32 s98, 0x28000
	v_lshl_add_u64 v[236:237], v[232:233], 0, s[98:99]
	global_load_dwordx2 v[220:221], v[236:237], off
	global_load_dwordx2 v[222:223], v[236:237], off offset:32
	global_load_dwordx2 v[224:225], v[236:237], off offset:64
	global_load_dwordx2 v[226:227], v[236:237], off offset:96
	s_mov_b32 s98, 0x140
	v_lshl_add_u64 v[236:237], v[234:235], 0, s[98:99]
	global_load_dword v229, v[236:237], off
	v_lshlrev_b64 v[68:69], 11, v[66:67]
	v_lshl_add_u64 v[68:69], s[12:13], 0, v[68:69]
	v_lshl_add_u64 v[68:69], v[68:69], 0, v[128:129]
	s_nop 0
	v_lshlrev_b64 v[66:67], 12, v[66:67]
	v_lshl_add_u64 v[66:67], v[130:131], 0, v[66:67]
	v_lshl_add_u64 v[66:67], v[66:67], 0, v[134:135]
	s_nop 0
	s_waitcnt vmcnt(13) lgkmcnt(0)
	v_mov_b32_e32 v74, v228
	v_mov_b32_e32 v78, v196
	v_mov_b32_e32 v79, v197
	v_mov_b32_e32 v70, v180
	v_mov_b32_e32 v71, v181
	v_mov_b32_e32 v72, v182
	v_mov_b32_e32 v73, v183
	v_fmamk_f32 v74, v74, 0x3a800000, v141
	v_mul_f32_e32 v75, 0x4b800000, v74
	v_cmp_gt_f32_e32 vcc, s50, v74
	v_lshlrev_b32_e32 v80, 16, v78
	s_nop 0
	v_cndmask_b32_e32 v74, v74, v75, vcc
	v_rsq_f32_e32 v82, v74
	v_and_b32_e32 v81, 0xffff0000, v78
	s_nop 0
	v_mul_f32_e32 v78, 0x45800000, v82
	v_cndmask_b32_e32 v82, v82, v78, vcc
	v_mul_f32_e32 v62, v62, v82
	v_mul_f32_e32 v63, v63, v82
	v_mul_f32_e32 v62, 0xbfb8aa3b, v62
	v_mul_f32_e32 v63, 0xbfb8aa3b, v63
	v_mul_f32_e32 v64, v64, v82
	v_mul_f32_e32 v65, v65, v82
	v_exp_f32_e32 v62, v62
	v_exp_f32_e32 v63, v63
	v_mul_f32_e32 v64, 0xbfb8aa3b, v64
	v_mul_f32_e32 v65, 0xbfb8aa3b, v65
	v_exp_f32_e32 v64, v64
	v_exp_f32_e32 v65, v65
	v_pk_add_f32 v[62:63], v[62:63], 1.0 op_sel_hi:[1,0]
	v_lshlrev_b32_e32 v78, 16, v79
	v_div_scale_f32 v83, s[0:1], v63, v63, 1.0
	v_pk_add_f32 v[64:65], v[64:65], 1.0 op_sel_hi:[1,0]
	v_div_scale_f32 v85, s[0:1], v62, v62, 1.0
	v_rcp_f32_e32 v91, v83
	v_div_scale_f32 v87, s[4:5], v65, v65, 1.0
	v_rcp_f32_e32 v92, v85
	v_div_scale_f32 v89, s[6:7], v64, v64, 1.0
	v_rcp_f32_e32 v93, v87
	v_rcp_f32_e32 v94, v89
	v_fma_f32 v95, -v83, v91, 1.0
	v_div_scale_f32 v84, vcc, 1.0, v63, 1.0
	v_fma_f32 v96, -v85, v92, 1.0
	v_fmac_f32_e32 v91, v95, v91
	v_div_scale_f32 v86, s[0:1], 1.0, v62, 1.0
	v_fma_f32 v97, -v87, v93, 1.0
	v_fmac_f32_e32 v92, v96, v92
	v_mul_f32_e32 v95, v84, v91
	v_div_scale_f32 v88, s[4:5], 1.0, v65, 1.0
	v_fma_f32 v98, -v89, v94, 1.0
	v_fmac_f32_e32 v93, v97, v93
	v_mul_f32_e32 v96, v86, v92
	v_fma_f32 v99, -v83, v95, v84
	v_div_scale_f32 v90, s[6:7], 1.0, v64, 1.0
	v_fmac_f32_e32 v94, v98, v94
	v_mul_f32_e32 v97, v88, v93
	v_fma_f32 v100, -v85, v96, v86
	v_fmac_f32_e32 v95, v99, v91
	v_mul_f32_e32 v98, v90, v94
	v_fma_f32 v101, -v87, v97, v88
	v_fmac_f32_e32 v96, v100, v92
	v_fma_f32 v83, -v83, v95, v84
	v_fma_f32 v102, -v89, v98, v90
	v_fmac_f32_e32 v97, v101, v93
	v_fma_f32 v84, -v85, v96, v86
	v_div_fmas_f32 v83, v83, v91, v95
	s_mov_b64 vcc, s[0:1]
	v_fmac_f32_e32 v98, v102, v94
	v_fma_f32 v85, -v87, v97, v88
	v_div_fixup_f32 v63, v83, v63, 1.0
	v_div_fmas_f32 v83, v84, v92, v96
	s_mov_b64 vcc, s[4:5]
	v_fma_f32 v86, -v89, v98, v90
	v_div_fixup_f32 v62, v83, v62, 1.0
	v_div_fmas_f32 v83, v85, v93, v97
	s_mov_b64 vcc, s[6:7]
	v_pk_fma_f32 v[62:63], v[62:63], v[80:81], v[70:71]
	v_div_fmas_f32 v70, v86, v94, v98
	v_and_b32_e32 v79, 0xffff0000, v79
	v_div_fixup_f32 v65, v83, v65, 1.0
	v_div_fixup_f32 v64, v70, v64, 1.0
	v_pk_fma_f32 v[64:65], v[64:65], v[78:79], v[72:73]
	global_store_dwordx4 v[66:67], v[62:65], off
	s_nop 0
	v_mul_f32_e32 v58, v58, v82
	v_mul_f32_e32 v59, v59, v82
	v_mul_f32_e32 v58, 0xbfb8aa3b, v58
	v_mul_f32_e32 v59, 0xbfb8aa3b, v59
	v_mul_f32_e32 v60, v60, v82
	v_mul_f32_e32 v61, v61, v82
	v_exp_f32_e32 v58, v58
	v_exp_f32_e32 v59, v59
	v_mul_f32_e32 v60, 0xbfb8aa3b, v60
	v_mul_f32_e32 v61, 0xbfb8aa3b, v61
	v_exp_f32_e32 v60, v60
	v_exp_f32_e32 v61, v61
	v_pk_add_f32 v[58:59], v[58:59], 1.0 op_sel_hi:[1,0]
	v_mul_f32_e32 v54, v54, v82
	v_div_scale_f32 v64, s[0:1], v59, v59, 1.0
	v_pk_add_f32 v[60:61], v[60:61], 1.0 op_sel_hi:[1,0]
	v_div_scale_f32 v70, s[0:1], v58, v58, 1.0
	v_rcp_f32_e32 v80, v64
	v_div_scale_f32 v72, s[4:5], v61, v61, 1.0
	v_rcp_f32_e32 v81, v70
	v_div_scale_f32 v78, s[6:7], v60, v60, 1.0
	v_rcp_f32_e32 v83, v72
	v_rcp_f32_e32 v84, v78
	v_fma_f32 v85, -v64, v80, 1.0
	v_div_scale_f32 v65, vcc, 1.0, v59, 1.0
	v_fma_f32 v86, -v70, v81, 1.0
	v_fmac_f32_e32 v80, v85, v80
	v_div_scale_f32 v71, s[0:1], 1.0, v58, 1.0
	v_fma_f32 v87, -v72, v83, 1.0
	v_fmac_f32_e32 v81, v86, v81
	v_mul_f32_e32 v85, v65, v80
	v_div_scale_f32 v73, s[4:5], 1.0, v61, 1.0
	v_fma_f32 v88, -v78, v84, 1.0
	v_fmac_f32_e32 v83, v87, v83
	v_mul_f32_e32 v86, v71, v81
	v_fma_f32 v89, -v64, v85, v65
	v_div_scale_f32 v79, s[6:7], 1.0, v60, 1.0
	v_fmac_f32_e32 v84, v88, v84
	v_mul_f32_e32 v87, v73, v83
	v_fma_f32 v90, -v70, v86, v71
	v_fmac_f32_e32 v85, v89, v80
	v_mul_f32_e32 v88, v79, v84
	v_fma_f32 v91, -v72, v87, v73
	v_fmac_f32_e32 v86, v90, v81
	v_fma_f32 v64, -v64, v85, v65
	v_fma_f32 v92, -v78, v88, v79
	v_fmac_f32_e32 v87, v91, v83
	v_fma_f32 v65, -v70, v86, v71
	v_div_fmas_f32 v64, v64, v80, v85
	s_mov_b64 vcc, s[0:1]
	v_fmac_f32_e32 v88, v92, v84
	v_fma_f32 v70, -v72, v87, v73
	v_div_fixup_f32 v59, v64, v59, 1.0
	v_div_fmas_f32 v64, v65, v81, v86
	s_mov_b64 vcc, s[4:5]
	v_fma_f32 v71, -v78, v88, v79
	v_div_fixup_f32 v58, v64, v58, 1.0
	v_div_fmas_f32 v64, v70, v83, v87
	s_mov_b64 vcc, s[6:7]
	v_div_fixup_f32 v61, v64, v61, 1.0
	v_div_fmas_f32 v64, v71, v84, v88
	v_div_fixup_f32 v60, v64, v60, 1.0
	v_mul_f32_e32 v55, v55, v82
	v_mul_f32_e32 v54, 0xbfb8aa3b, v54
	v_mul_f32_e32 v55, 0xbfb8aa3b, v55
	v_mul_f32_e32 v56, v56, v82
	v_mul_f32_e32 v57, v57, v82
	v_mul_f32_e32 v56, 0xbfb8aa3b, v56
	v_mul_f32_e32 v57, 0xbfb8aa3b, v57
	v_exp_f32_e32 v70, v56
	v_exp_f32_e32 v71, v57
	s_waitcnt lgkmcnt(0)
	v_mov_b32_e32 v62, v198
	v_mov_b32_e32 v63, v199
	v_mov_b32_e32 v74, v184
	v_mov_b32_e32 v75, v185
	v_mov_b32_e32 v76, v186
	v_mov_b32_e32 v77, v187
	v_lshlrev_b32_e32 v64, 16, v62
	v_and_b32_e32 v65, 0xffff0000, v62
	v_lshlrev_b32_e32 v62, 16, v63
	v_and_b32_e32 v63, 0xffff0000, v63
	v_pk_fma_f32 v[58:59], v[58:59], v[64:65], v[74:75]
	v_pk_fma_f32 v[60:61], v[60:61], v[62:63], v[76:77]
	global_store_dwordx4 v[66:67], v[58:61], off offset:64
	s_nop 0
	s_nop 0
	s_nop 0
	v_exp_f32_e32 v64, v54
	v_exp_f32_e32 v65, v55
	v_pk_add_f32 v[70:71], v[70:71], 1.0 op_sel_hi:[1,0]
	s_nop 0
	v_div_scale_f32 v76, s[4:5], v71, v71, 1.0
	v_pk_add_f32 v[64:65], v[64:65], 1.0 op_sel_hi:[1,0]
	v_div_scale_f32 v78, s[6:7], v70, v70, 1.0
	v_div_scale_f32 v72, s[0:1], v65, v65, 1.0
	v_div_scale_f32 v74, s[0:1], v64, v64, 1.0
	v_rcp_f32_e32 v80, v72
	v_rcp_f32_e32 v81, v74
	v_rcp_f32_e32 v83, v76
	v_rcp_f32_e32 v84, v78
	v_fma_f32 v85, -v72, v80, 1.0
	v_div_scale_f32 v73, vcc, 1.0, v65, 1.0
	v_fma_f32 v86, -v74, v81, 1.0
	v_fmac_f32_e32 v80, v85, v80
	v_div_scale_f32 v75, s[0:1], 1.0, v64, 1.0
	v_fma_f32 v87, -v76, v83, 1.0
	v_fmac_f32_e32 v81, v86, v81
	v_mul_f32_e32 v85, v73, v80
	v_div_scale_f32 v77, s[4:5], 1.0, v71, 1.0
	v_fma_f32 v88, -v78, v84, 1.0
	v_fmac_f32_e32 v83, v87, v83
	v_mul_f32_e32 v86, v75, v81
	v_fma_f32 v89, -v72, v85, v73
	v_div_scale_f32 v79, s[6:7], 1.0, v70, 1.0
	v_fmac_f32_e32 v84, v88, v84
	v_mul_f32_e32 v87, v77, v83
	v_fma_f32 v90, -v74, v86, v75
	v_fmac_f32_e32 v85, v89, v80
	v_mul_f32_e32 v88, v79, v84
	v_fma_f32 v91, -v76, v87, v77
	v_fmac_f32_e32 v86, v90, v81
	v_fma_f32 v72, -v72, v85, v73
	v_fma_f32 v92, -v78, v88, v79
	v_fmac_f32_e32 v87, v91, v83
	v_fma_f32 v73, -v74, v86, v75
	v_div_fmas_f32 v72, v72, v80, v85
	s_mov_b64 vcc, s[0:1]
	v_fmac_f32_e32 v88, v92, v84
	v_fma_f32 v74, -v76, v87, v77
	v_div_fixup_f32 v65, v72, v65, 1.0
	v_div_fmas_f32 v72, v73, v81, v86
	s_mov_b64 vcc, s[4:5]
	v_fma_f32 v75, -v78, v88, v79
	v_div_fixup_f32 v64, v72, v64, 1.0
	v_div_fmas_f32 v72, v74, v83, v87
	s_mov_b64 vcc, s[6:7]
	v_div_fixup_f32 v71, v72, v71, 1.0
	v_div_fmas_f32 v72, v75, v84, v88
	v_div_fixup_f32 v70, v72, v70, 1.0
	v_mul_f32_e32 v50, v50, v82
	v_mul_f32_e32 v51, v51, v82
	v_mul_f32_e32 v50, 0xbfb8aa3b, v50
	v_mul_f32_e32 v51, 0xbfb8aa3b, v51
	v_mul_f32_e32 v52, v52, v82
	v_mul_f32_e32 v53, v53, v82
	v_exp_f32_e32 v50, v50
	v_exp_f32_e32 v51, v51
	v_mul_f32_e32 v52, 0xbfb8aa3b, v52
	v_mul_f32_e32 v53, 0xbfb8aa3b, v53
	v_exp_f32_e32 v52, v52
	v_exp_f32_e32 v53, v53
	v_pk_add_f32 v[50:51], v[50:51], 1.0 op_sel_hi:[1,0]
	v_pk_add_f32 v[52:53], v[52:53], 1.0 op_sel_hi:[1,0]
	s_waitcnt lgkmcnt(0)
	v_mov_b32_e32 v62, v200
	v_mov_b32_e32 v63, v201
	v_mov_b32_e32 v58, v188
	v_mov_b32_e32 v59, v189
	v_mov_b32_e32 v60, v190
	v_mov_b32_e32 v61, v191
	v_mov_b32_e32 v54, v192
	v_mov_b32_e32 v55, v193
	v_mov_b32_e32 v56, v194
	v_mov_b32_e32 v57, v195
	v_lshlrev_b32_e32 v72, 16, v62
	v_and_b32_e32 v73, 0xffff0000, v62
	v_lshlrev_b32_e32 v62, 16, v63
	v_and_b32_e32 v63, 0xffff0000, v63
	v_pk_fma_f32 v[58:59], v[64:65], v[72:73], v[58:59]
	v_pk_fma_f32 v[60:61], v[70:71], v[62:63], v[60:61]
	global_store_dwordx4 v[66:67], v[58:61], off offset:128
	s_nop 0
	v_div_scale_f32 v62, s[0:1], v50, v50, 1.0
	v_div_scale_f32 v60, s[0:1], v51, v51, 1.0
	v_rcp_f32_e32 v70, v60
	v_div_scale_f32 v64, s[4:5], v53, v53, 1.0
	v_rcp_f32_e32 v71, v62
	v_div_scale_f32 v68, s[6:7], v52, v52, 1.0
	v_rcp_f32_e32 v72, v64
	v_rcp_f32_e32 v73, v68
	v_fma_f32 v74, -v60, v70, 1.0
	v_div_scale_f32 v61, vcc, 1.0, v51, 1.0
	v_fma_f32 v75, -v62, v71, 1.0
	v_fmac_f32_e32 v70, v74, v70
	v_div_scale_f32 v63, s[0:1], 1.0, v50, 1.0
	v_fma_f32 v76, -v64, v72, 1.0
	v_fmac_f32_e32 v71, v75, v71
	v_mul_f32_e32 v74, v61, v70
	v_div_scale_f32 v65, s[4:5], 1.0, v53, 1.0
	v_fma_f32 v77, -v68, v73, 1.0
	v_fmac_f32_e32 v72, v76, v72
	v_mul_f32_e32 v75, v63, v71
	v_fma_f32 v78, -v60, v74, v61
	v_div_scale_f32 v69, s[6:7], 1.0, v52, 1.0
	v_fmac_f32_e32 v73, v77, v73
	v_mul_f32_e32 v76, v65, v72
	v_fma_f32 v79, -v62, v75, v63
	v_fmac_f32_e32 v74, v78, v70
	v_mul_f32_e32 v77, v69, v73
	v_fma_f32 v80, -v64, v76, v65
	v_fmac_f32_e32 v75, v79, v71
	v_fma_f32 v60, -v60, v74, v61
	v_fma_f32 v81, -v68, v77, v69
	v_fmac_f32_e32 v76, v80, v72
	v_fma_f32 v61, -v62, v75, v63
	v_div_fmas_f32 v60, v60, v70, v74
	s_mov_b64 vcc, s[0:1]
	v_fmac_f32_e32 v77, v81, v73
	v_fma_f32 v62, -v64, v76, v65
	v_div_fixup_f32 v51, v60, v51, 1.0
	v_div_fmas_f32 v60, v61, v71, v75
	s_mov_b64 vcc, s[4:5]
	v_fma_f32 v63, -v68, v77, v69
	v_div_fixup_f32 v50, v60, v50, 1.0
	v_div_fmas_f32 v60, v62, v72, v76
	s_mov_b64 vcc, s[6:7]
	v_div_fixup_f32 v53, v60, v53, 1.0
	v_div_fmas_f32 v60, v63, v73, v77
	v_div_fixup_f32 v52, v60, v52, 1.0
	s_waitcnt lgkmcnt(0)
	v_mov_b32_e32 v58, v202
	v_mov_b32_e32 v59, v203
	v_lshlrev_b32_e32 v60, 16, v58
	v_and_b32_e32 v61, 0xffff0000, v58
	v_lshlrev_b32_e32 v58, 16, v59
	v_and_b32_e32 v59, 0xffff0000, v59
	v_pk_fma_f32 v[50:51], v[50:51], v[60:61], v[54:55]
	v_pk_fma_f32 v[52:53], v[52:53], v[58:59], v[56:57]
	global_store_dwordx4 v[66:67], v[50:53], off offset:192
	s_nop 1
	v_or_b32_e32 v50, 0x50, v126
	v_mov_b32_e32 v51, v127
	v_lshl_add_u64 v[52:53], v[50:51], 2, s[14:15]
	s_mov_b32 s99, 0
	s_mov_b32 s98, 0x60000
	v_lshl_add_u64 v[236:237], v[230:231], 0, s[98:99]
	global_load_dwordx4 v[180:183], v[236:237], off
	global_load_dwordx4 v[184:187], v[236:237], off offset:64
	global_load_dwordx4 v[188:191], v[236:237], off offset:128
	global_load_dwordx4 v[192:195], v[236:237], off offset:192
	s_mov_b32 s98, 0x30000
	v_lshl_add_u64 v[236:237], v[232:233], 0, s[98:99]
	global_load_dwordx2 v[196:197], v[236:237], off
	global_load_dwordx2 v[198:199], v[236:237], off offset:32
	global_load_dwordx2 v[200:201], v[236:237], off offset:64
	global_load_dwordx2 v[202:203], v[236:237], off offset:96
	s_mov_b32 s98, 0x180
	v_lshl_add_u64 v[236:237], v[234:235], 0, s[98:99]
	global_load_dword v228, v[236:237], off
	v_lshlrev_b64 v[52:53], 11, v[50:51]
	v_lshl_add_u64 v[52:53], s[12:13], 0, v[52:53]
	v_lshl_add_u64 v[52:53], v[52:53], 0, v[128:129]
	s_nop 0
	v_lshlrev_b64 v[50:51], 12, v[50:51]
	v_lshl_add_u64 v[50:51], v[130:131], 0, v[50:51]
	v_lshl_add_u64 v[50:51], v[50:51], 0, v[134:135]
	s_nop 0
	s_waitcnt vmcnt(13) lgkmcnt(0)
	v_mov_b32_e32 v58, v229
	v_mov_b32_e32 v62, v220
	v_mov_b32_e32 v63, v221
	v_mov_b32_e32 v54, v204
	v_mov_b32_e32 v55, v205
	v_mov_b32_e32 v56, v206
	v_mov_b32_e32 v57, v207
	v_fmamk_f32 v58, v58, 0x3a800000, v141
	v_mul_f32_e32 v59, 0x4b800000, v58
	v_cmp_gt_f32_e32 vcc, s50, v58
	v_lshlrev_b32_e32 v64, 16, v62
	s_nop 0
	v_cndmask_b32_e32 v58, v58, v59, vcc
	v_rsq_f32_e32 v66, v58
	v_and_b32_e32 v65, 0xffff0000, v62
	s_nop 0
	v_mul_f32_e32 v62, 0x45800000, v66
	v_cndmask_b32_e32 v66, v66, v62, vcc
	v_mul_f32_e32 v46, v46, v66
	v_mul_f32_e32 v47, v47, v66
	v_mul_f32_e32 v46, 0xbfb8aa3b, v46
	v_mul_f32_e32 v47, 0xbfb8aa3b, v47
	v_mul_f32_e32 v48, v48, v66
	v_mul_f32_e32 v49, v49, v66
	v_exp_f32_e32 v46, v46
	v_exp_f32_e32 v47, v47
	v_mul_f32_e32 v48, 0xbfb8aa3b, v48
	v_mul_f32_e32 v49, 0xbfb8aa3b, v49
	v_exp_f32_e32 v48, v48
	v_exp_f32_e32 v49, v49
	v_pk_add_f32 v[46:47], v[46:47], 1.0 op_sel_hi:[1,0]
	v_lshlrev_b32_e32 v62, 16, v63
	v_div_scale_f32 v67, s[0:1], v47, v47, 1.0
	v_pk_add_f32 v[48:49], v[48:49], 1.0 op_sel_hi:[1,0]
	v_div_scale_f32 v69, s[0:1], v46, v46, 1.0
	v_rcp_f32_e32 v75, v67
	v_div_scale_f32 v71, s[4:5], v49, v49, 1.0
	v_rcp_f32_e32 v76, v69
	v_div_scale_f32 v73, s[6:7], v48, v48, 1.0
	v_rcp_f32_e32 v77, v71
	v_rcp_f32_e32 v78, v73
	v_fma_f32 v79, -v67, v75, 1.0
	v_div_scale_f32 v68, vcc, 1.0, v47, 1.0
	v_fma_f32 v80, -v69, v76, 1.0
	v_fmac_f32_e32 v75, v79, v75
	v_div_scale_f32 v70, s[0:1], 1.0, v46, 1.0
	v_fma_f32 v81, -v71, v77, 1.0
	v_fmac_f32_e32 v76, v80, v76
	v_mul_f32_e32 v79, v68, v75
	v_div_scale_f32 v72, s[4:5], 1.0, v49, 1.0
	v_fma_f32 v82, -v73, v78, 1.0
	v_fmac_f32_e32 v77, v81, v77
	v_mul_f32_e32 v80, v70, v76
	v_fma_f32 v83, -v67, v79, v68
	v_div_scale_f32 v74, s[6:7], 1.0, v48, 1.0
	v_fmac_f32_e32 v78, v82, v78
	v_mul_f32_e32 v81, v72, v77
	v_fma_f32 v84, -v69, v80, v70
	v_fmac_f32_e32 v79, v83, v75
	v_mul_f32_e32 v82, v74, v78
	v_fma_f32 v85, -v71, v81, v72
	v_fmac_f32_e32 v80, v84, v76
	v_fma_f32 v67, -v67, v79, v68
	v_fma_f32 v86, -v73, v82, v74
	v_fmac_f32_e32 v81, v85, v77
	v_fma_f32 v68, -v69, v80, v70
	v_div_fmas_f32 v67, v67, v75, v79
	s_mov_b64 vcc, s[0:1]
	v_fmac_f32_e32 v82, v86, v78
	v_fma_f32 v69, -v71, v81, v72
	v_div_fixup_f32 v47, v67, v47, 1.0
	v_div_fmas_f32 v67, v68, v76, v80
	s_mov_b64 vcc, s[4:5]
	v_fma_f32 v70, -v73, v82, v74
	v_div_fixup_f32 v46, v67, v46, 1.0
	v_div_fmas_f32 v67, v69, v77, v81
	s_mov_b64 vcc, s[6:7]
	v_pk_fma_f32 v[46:47], v[46:47], v[64:65], v[54:55]
	v_div_fmas_f32 v54, v70, v78, v82
	v_and_b32_e32 v63, 0xffff0000, v63
	v_div_fixup_f32 v49, v67, v49, 1.0
	v_div_fixup_f32 v48, v54, v48, 1.0
	v_pk_fma_f32 v[48:49], v[48:49], v[62:63], v[56:57]
	global_store_dwordx4 v[50:51], v[46:49], off
	s_nop 0
	v_mul_f32_e32 v42, v42, v66
	v_mul_f32_e32 v43, v43, v66
	v_mul_f32_e32 v42, 0xbfb8aa3b, v42
	v_mul_f32_e32 v43, 0xbfb8aa3b, v43
	v_mul_f32_e32 v44, v44, v66
	v_mul_f32_e32 v45, v45, v66
	v_exp_f32_e32 v42, v42
	v_exp_f32_e32 v43, v43
	v_mul_f32_e32 v44, 0xbfb8aa3b, v44
	v_mul_f32_e32 v45, 0xbfb8aa3b, v45
	v_exp_f32_e32 v44, v44
	v_exp_f32_e32 v45, v45
	v_pk_add_f32 v[42:43], v[42:43], 1.0 op_sel_hi:[1,0]
	v_mul_f32_e32 v38, v38, v66
	v_div_scale_f32 v48, s[0:1], v43, v43, 1.0
	v_pk_add_f32 v[44:45], v[44:45], 1.0 op_sel_hi:[1,0]
	v_div_scale_f32 v54, s[0:1], v42, v42, 1.0
	v_rcp_f32_e32 v64, v48
	v_div_scale_f32 v56, s[4:5], v45, v45, 1.0
	v_rcp_f32_e32 v65, v54
	v_div_scale_f32 v62, s[6:7], v44, v44, 1.0
	v_rcp_f32_e32 v67, v56
	v_rcp_f32_e32 v68, v62
	v_fma_f32 v69, -v48, v64, 1.0
	v_div_scale_f32 v49, vcc, 1.0, v43, 1.0
	v_fma_f32 v70, -v54, v65, 1.0
	v_fmac_f32_e32 v64, v69, v64
	v_div_scale_f32 v55, s[0:1], 1.0, v42, 1.0
	v_fma_f32 v71, -v56, v67, 1.0
	v_fmac_f32_e32 v65, v70, v65
	v_mul_f32_e32 v69, v49, v64
	v_div_scale_f32 v57, s[4:5], 1.0, v45, 1.0
	v_fma_f32 v72, -v62, v68, 1.0
	v_fmac_f32_e32 v67, v71, v67
	v_mul_f32_e32 v70, v55, v65
	v_fma_f32 v73, -v48, v69, v49
	v_div_scale_f32 v63, s[6:7], 1.0, v44, 1.0
	v_fmac_f32_e32 v68, v72, v68
	v_mul_f32_e32 v71, v57, v67
	v_fma_f32 v74, -v54, v70, v55
	v_fmac_f32_e32 v69, v73, v64
	v_mul_f32_e32 v72, v63, v68
	v_fma_f32 v75, -v56, v71, v57
	v_fmac_f32_e32 v70, v74, v65
	v_fma_f32 v48, -v48, v69, v49
	v_fma_f32 v76, -v62, v72, v63
	v_fmac_f32_e32 v71, v75, v67
	v_fma_f32 v49, -v54, v70, v55
	v_div_fmas_f32 v48, v48, v64, v69
	s_mov_b64 vcc, s[0:1]
	v_fmac_f32_e32 v72, v76, v68
	v_fma_f32 v54, -v56, v71, v57
	v_div_fixup_f32 v43, v48, v43, 1.0
	v_div_fmas_f32 v48, v49, v65, v70
	s_mov_b64 vcc, s[4:5]
	v_fma_f32 v55, -v62, v72, v63
	v_div_fixup_f32 v42, v48, v42, 1.0
	v_div_fmas_f32 v48, v54, v67, v71
	s_mov_b64 vcc, s[6:7]
	v_div_fixup_f32 v45, v48, v45, 1.0
	v_div_fmas_f32 v48, v55, v68, v72
	v_div_fixup_f32 v44, v48, v44, 1.0
	v_mul_f32_e32 v39, v39, v66
	v_mul_f32_e32 v38, 0xbfb8aa3b, v38
	v_mul_f32_e32 v39, 0xbfb8aa3b, v39
	v_mul_f32_e32 v40, v40, v66
	v_mul_f32_e32 v41, v41, v66
	v_mul_f32_e32 v40, 0xbfb8aa3b, v40
	v_mul_f32_e32 v41, 0xbfb8aa3b, v41
	v_exp_f32_e32 v54, v40
	v_exp_f32_e32 v55, v41
	s_waitcnt lgkmcnt(0)
	v_mov_b32_e32 v46, v222
	v_mov_b32_e32 v47, v223
	v_mov_b32_e32 v58, v208
	v_mov_b32_e32 v59, v209
	v_mov_b32_e32 v60, v210
	v_mov_b32_e32 v61, v211
	v_lshlrev_b32_e32 v48, 16, v46
	v_and_b32_e32 v49, 0xffff0000, v46
	v_lshlrev_b32_e32 v46, 16, v47
	v_and_b32_e32 v47, 0xffff0000, v47
	v_pk_fma_f32 v[42:43], v[42:43], v[48:49], v[58:59]
	v_pk_fma_f32 v[44:45], v[44:45], v[46:47], v[60:61]
	global_store_dwordx4 v[50:51], v[42:45], off offset:64
	s_nop 0
	s_nop 0
	s_nop 0
	v_exp_f32_e32 v48, v38
	v_exp_f32_e32 v49, v39
	v_pk_add_f32 v[54:55], v[54:55], 1.0 op_sel_hi:[1,0]
	s_nop 0
	v_div_scale_f32 v60, s[4:5], v55, v55, 1.0
	v_pk_add_f32 v[48:49], v[48:49], 1.0 op_sel_hi:[1,0]
	v_div_scale_f32 v62, s[6:7], v54, v54, 1.0
	v_div_scale_f32 v56, s[0:1], v49, v49, 1.0
	v_div_scale_f32 v58, s[0:1], v48, v48, 1.0
	v_rcp_f32_e32 v64, v56
	v_rcp_f32_e32 v65, v58
	v_rcp_f32_e32 v67, v60
	v_rcp_f32_e32 v68, v62
	v_fma_f32 v69, -v56, v64, 1.0
	v_div_scale_f32 v57, vcc, 1.0, v49, 1.0
	v_fma_f32 v70, -v58, v65, 1.0
	v_fmac_f32_e32 v64, v69, v64
	v_div_scale_f32 v59, s[0:1], 1.0, v48, 1.0
	v_fma_f32 v71, -v60, v67, 1.0
	v_fmac_f32_e32 v65, v70, v65
	v_mul_f32_e32 v69, v57, v64
	v_div_scale_f32 v61, s[4:5], 1.0, v55, 1.0
	v_fma_f32 v72, -v62, v68, 1.0
	v_fmac_f32_e32 v67, v71, v67
	v_mul_f32_e32 v70, v59, v65
	v_fma_f32 v73, -v56, v69, v57
	v_div_scale_f32 v63, s[6:7], 1.0, v54, 1.0
	v_fmac_f32_e32 v68, v72, v68
	v_mul_f32_e32 v71, v61, v67
	v_fma_f32 v74, -v58, v70, v59
	v_fmac_f32_e32 v69, v73, v64
	v_mul_f32_e32 v72, v63, v68
	v_fma_f32 v75, -v60, v71, v61
	v_fmac_f32_e32 v70, v74, v65
	v_fma_f32 v56, -v56, v69, v57
	v_fma_f32 v76, -v62, v72, v63
	v_fmac_f32_e32 v71, v75, v67
	v_fma_f32 v57, -v58, v70, v59
	v_div_fmas_f32 v56, v56, v64, v69
	s_mov_b64 vcc, s[0:1]
	v_fmac_f32_e32 v72, v76, v68
	v_fma_f32 v58, -v60, v71, v61
	v_div_fixup_f32 v49, v56, v49, 1.0
	v_div_fmas_f32 v56, v57, v65, v70
	s_mov_b64 vcc, s[4:5]
	v_fma_f32 v59, -v62, v72, v63
	v_div_fixup_f32 v48, v56, v48, 1.0
	v_div_fmas_f32 v56, v58, v67, v71
	s_mov_b64 vcc, s[6:7]
	v_div_fixup_f32 v55, v56, v55, 1.0
	v_div_fmas_f32 v56, v59, v68, v72
	v_div_fixup_f32 v54, v56, v54, 1.0
	v_mul_f32_e32 v34, v34, v66
	v_mul_f32_e32 v35, v35, v66
	v_mul_f32_e32 v34, 0xbfb8aa3b, v34
	v_mul_f32_e32 v35, 0xbfb8aa3b, v35
	v_mul_f32_e32 v36, v36, v66
	v_mul_f32_e32 v37, v37, v66
	v_exp_f32_e32 v34, v34
	v_exp_f32_e32 v35, v35
	v_mul_f32_e32 v36, 0xbfb8aa3b, v36
	v_mul_f32_e32 v37, 0xbfb8aa3b, v37
	v_exp_f32_e32 v36, v36
	v_exp_f32_e32 v37, v37
	v_pk_add_f32 v[34:35], v[34:35], 1.0 op_sel_hi:[1,0]
	v_pk_add_f32 v[36:37], v[36:37], 1.0 op_sel_hi:[1,0]
	s_waitcnt lgkmcnt(0)
	v_mov_b32_e32 v46, v224
	v_mov_b32_e32 v47, v225
	v_mov_b32_e32 v42, v212
	v_mov_b32_e32 v43, v213
	v_mov_b32_e32 v44, v214
	v_mov_b32_e32 v45, v215
	v_mov_b32_e32 v38, v216
	v_mov_b32_e32 v39, v217
	v_mov_b32_e32 v40, v218
	v_mov_b32_e32 v41, v219
	v_lshlrev_b32_e32 v56, 16, v46
	v_and_b32_e32 v57, 0xffff0000, v46
	v_lshlrev_b32_e32 v46, 16, v47
	v_and_b32_e32 v47, 0xffff0000, v47
	v_pk_fma_f32 v[42:43], v[48:49], v[56:57], v[42:43]
	v_pk_fma_f32 v[44:45], v[54:55], v[46:47], v[44:45]
	global_store_dwordx4 v[50:51], v[42:45], off offset:128
	s_nop 0
	v_div_scale_f32 v46, s[0:1], v34, v34, 1.0
	v_div_scale_f32 v44, s[0:1], v35, v35, 1.0
	v_rcp_f32_e32 v54, v44
	v_div_scale_f32 v48, s[4:5], v37, v37, 1.0
	v_rcp_f32_e32 v55, v46
	v_div_scale_f32 v52, s[6:7], v36, v36, 1.0
	v_rcp_f32_e32 v56, v48
	v_rcp_f32_e32 v57, v52
	v_fma_f32 v58, -v44, v54, 1.0
	v_div_scale_f32 v45, vcc, 1.0, v35, 1.0
	v_fma_f32 v59, -v46, v55, 1.0
	v_fmac_f32_e32 v54, v58, v54
	v_div_scale_f32 v47, s[0:1], 1.0, v34, 1.0
	v_fma_f32 v60, -v48, v56, 1.0
	v_fmac_f32_e32 v55, v59, v55
	v_mul_f32_e32 v58, v45, v54
	v_div_scale_f32 v49, s[4:5], 1.0, v37, 1.0
	v_fma_f32 v61, -v52, v57, 1.0
	v_fmac_f32_e32 v56, v60, v56
	v_mul_f32_e32 v59, v47, v55
	v_fma_f32 v62, -v44, v58, v45
	v_div_scale_f32 v53, s[6:7], 1.0, v36, 1.0
	v_fmac_f32_e32 v57, v61, v57
	v_mul_f32_e32 v60, v49, v56
	v_fma_f32 v63, -v46, v59, v47
	v_fmac_f32_e32 v58, v62, v54
	v_mul_f32_e32 v61, v53, v57
	v_fma_f32 v64, -v48, v60, v49
	v_fmac_f32_e32 v59, v63, v55
	v_fma_f32 v44, -v44, v58, v45
	v_fma_f32 v65, -v52, v61, v53
	v_fmac_f32_e32 v60, v64, v56
	v_fma_f32 v45, -v46, v59, v47
	v_div_fmas_f32 v44, v44, v54, v58
	s_mov_b64 vcc, s[0:1]
	v_fmac_f32_e32 v61, v65, v57
	v_fma_f32 v46, -v48, v60, v49
	v_div_fixup_f32 v35, v44, v35, 1.0
	v_div_fmas_f32 v44, v45, v55, v59
	s_mov_b64 vcc, s[4:5]
	v_fma_f32 v47, -v52, v61, v53
	v_div_fixup_f32 v34, v44, v34, 1.0
	v_div_fmas_f32 v44, v46, v56, v60
	s_mov_b64 vcc, s[6:7]
	v_div_fixup_f32 v37, v44, v37, 1.0
	v_div_fmas_f32 v44, v47, v57, v61
	v_div_fixup_f32 v36, v44, v36, 1.0
	s_waitcnt lgkmcnt(0)
	v_mov_b32_e32 v42, v226
	v_mov_b32_e32 v43, v227
	v_lshlrev_b32_e32 v44, 16, v42
	v_and_b32_e32 v45, 0xffff0000, v42
	v_lshlrev_b32_e32 v42, 16, v43
	v_and_b32_e32 v43, 0xffff0000, v43
	v_pk_fma_f32 v[34:35], v[34:35], v[44:45], v[38:39]
	v_pk_fma_f32 v[36:37], v[36:37], v[42:43], v[40:41]
	global_store_dwordx4 v[50:51], v[34:37], off offset:192
	s_nop 1
	v_or_b32_e32 v34, 0x60, v126
	v_mov_b32_e32 v35, v127
	v_lshl_add_u64 v[36:37], v[34:35], 2, s[14:15]
	s_mov_b32 s99, 0
	s_mov_b32 s98, 0x70000
	v_lshl_add_u64 v[236:237], v[230:231], 0, s[98:99]
	global_load_dwordx4 v[204:207], v[236:237], off
	global_load_dwordx4 v[208:211], v[236:237], off offset:64
	global_load_dwordx4 v[212:215], v[236:237], off offset:128
	global_load_dwordx4 v[216:219], v[236:237], off offset:192
	s_mov_b32 s98, 0x38000
	v_lshl_add_u64 v[236:237], v[232:233], 0, s[98:99]
	global_load_dwordx2 v[220:221], v[236:237], off
	global_load_dwordx2 v[222:223], v[236:237], off offset:32
	global_load_dwordx2 v[224:225], v[236:237], off offset:64
	global_load_dwordx2 v[226:227], v[236:237], off offset:96
	s_mov_b32 s98, 0x1c0
	v_lshl_add_u64 v[236:237], v[234:235], 0, s[98:99]
	global_load_dword v229, v[236:237], off
	v_lshlrev_b64 v[36:37], 11, v[34:35]
	v_lshl_add_u64 v[36:37], s[12:13], 0, v[36:37]
	v_lshl_add_u64 v[36:37], v[36:37], 0, v[128:129]
	s_nop 0
	v_lshlrev_b64 v[34:35], 12, v[34:35]
	v_lshl_add_u64 v[34:35], v[130:131], 0, v[34:35]
	v_lshl_add_u64 v[34:35], v[34:35], 0, v[134:135]
	s_nop 0
	s_waitcnt vmcnt(13) lgkmcnt(0)
	v_mov_b32_e32 v42, v228
	v_mov_b32_e32 v46, v196
	v_mov_b32_e32 v47, v197
	v_mov_b32_e32 v38, v180
	v_mov_b32_e32 v39, v181
	v_mov_b32_e32 v40, v182
	v_mov_b32_e32 v41, v183
	v_fmamk_f32 v42, v42, 0x3a800000, v141
	v_mul_f32_e32 v43, 0x4b800000, v42
	v_cmp_gt_f32_e32 vcc, s50, v42
	v_lshlrev_b32_e32 v48, 16, v46
	s_nop 0
	v_cndmask_b32_e32 v42, v42, v43, vcc
	v_rsq_f32_e32 v50, v42
	v_and_b32_e32 v49, 0xffff0000, v46
	s_nop 0
	v_mul_f32_e32 v46, 0x45800000, v50
	v_cndmask_b32_e32 v50, v50, v46, vcc
	v_mul_f32_e32 v30, v30, v50
	v_mul_f32_e32 v31, v31, v50
	v_mul_f32_e32 v30, 0xbfb8aa3b, v30
	v_mul_f32_e32 v31, 0xbfb8aa3b, v31
	v_mul_f32_e32 v32, v32, v50
	v_mul_f32_e32 v33, v33, v50
	v_exp_f32_e32 v30, v30
	v_exp_f32_e32 v31, v31
	v_mul_f32_e32 v32, 0xbfb8aa3b, v32
	v_mul_f32_e32 v33, 0xbfb8aa3b, v33
	v_exp_f32_e32 v32, v32
	v_exp_f32_e32 v33, v33
	v_pk_add_f32 v[30:31], v[30:31], 1.0 op_sel_hi:[1,0]
	v_lshlrev_b32_e32 v46, 16, v47
	v_div_scale_f32 v51, s[0:1], v31, v31, 1.0
	v_pk_add_f32 v[32:33], v[32:33], 1.0 op_sel_hi:[1,0]
	v_div_scale_f32 v53, s[0:1], v30, v30, 1.0
	v_rcp_f32_e32 v59, v51
	v_div_scale_f32 v55, s[4:5], v33, v33, 1.0
	v_rcp_f32_e32 v60, v53
	v_div_scale_f32 v57, s[6:7], v32, v32, 1.0
	v_rcp_f32_e32 v61, v55
	v_rcp_f32_e32 v62, v57
	v_fma_f32 v63, -v51, v59, 1.0
	v_div_scale_f32 v52, vcc, 1.0, v31, 1.0
	v_fma_f32 v64, -v53, v60, 1.0
	v_fmac_f32_e32 v59, v63, v59
	v_div_scale_f32 v54, s[0:1], 1.0, v30, 1.0
	v_fma_f32 v65, -v55, v61, 1.0
	v_fmac_f32_e32 v60, v64, v60
	v_mul_f32_e32 v63, v52, v59
	v_div_scale_f32 v56, s[4:5], 1.0, v33, 1.0
	v_fma_f32 v66, -v57, v62, 1.0
	v_fmac_f32_e32 v61, v65, v61
	v_mul_f32_e32 v64, v54, v60
	v_fma_f32 v67, -v51, v63, v52
	v_div_scale_f32 v58, s[6:7], 1.0, v32, 1.0
	v_fmac_f32_e32 v62, v66, v62
	v_mul_f32_e32 v65, v56, v61
	v_fma_f32 v68, -v53, v64, v54
	v_fmac_f32_e32 v63, v67, v59
	v_mul_f32_e32 v66, v58, v62
	v_fma_f32 v69, -v55, v65, v56
	v_fmac_f32_e32 v64, v68, v60
	v_fma_f32 v51, -v51, v63, v52
	v_fma_f32 v70, -v57, v66, v58
	v_fmac_f32_e32 v65, v69, v61
	v_fma_f32 v52, -v53, v64, v54
	v_div_fmas_f32 v51, v51, v59, v63
	s_mov_b64 vcc, s[0:1]
	v_fmac_f32_e32 v66, v70, v62
	v_fma_f32 v53, -v55, v65, v56
	v_div_fixup_f32 v31, v51, v31, 1.0
	v_div_fmas_f32 v51, v52, v60, v64
	s_mov_b64 vcc, s[4:5]
	v_fma_f32 v54, -v57, v66, v58
	v_div_fixup_f32 v30, v51, v30, 1.0
	v_div_fmas_f32 v51, v53, v61, v65
	s_mov_b64 vcc, s[6:7]
	v_pk_fma_f32 v[30:31], v[30:31], v[48:49], v[38:39]
	v_div_fmas_f32 v38, v54, v62, v66
	v_and_b32_e32 v47, 0xffff0000, v47
	v_div_fixup_f32 v33, v51, v33, 1.0
	v_div_fixup_f32 v32, v38, v32, 1.0
	v_pk_fma_f32 v[32:33], v[32:33], v[46:47], v[40:41]
	global_store_dwordx4 v[34:35], v[30:33], off
	s_nop 0
	v_mul_f32_e32 v26, v26, v50
	v_mul_f32_e32 v27, v27, v50
	v_mul_f32_e32 v26, 0xbfb8aa3b, v26
	v_mul_f32_e32 v27, 0xbfb8aa3b, v27
	v_mul_f32_e32 v28, v28, v50
	v_mul_f32_e32 v29, v29, v50
	v_exp_f32_e32 v26, v26
	v_exp_f32_e32 v27, v27
	v_mul_f32_e32 v28, 0xbfb8aa3b, v28
	v_mul_f32_e32 v29, 0xbfb8aa3b, v29
	v_exp_f32_e32 v28, v28
	v_exp_f32_e32 v29, v29
	v_pk_add_f32 v[26:27], v[26:27], 1.0 op_sel_hi:[1,0]
	v_mul_f32_e32 v22, v22, v50
	v_div_scale_f32 v32, s[0:1], v27, v27, 1.0
	v_pk_add_f32 v[28:29], v[28:29], 1.0 op_sel_hi:[1,0]
	v_div_scale_f32 v38, s[0:1], v26, v26, 1.0
	v_rcp_f32_e32 v48, v32
	v_div_scale_f32 v40, s[4:5], v29, v29, 1.0
	v_rcp_f32_e32 v49, v38
	v_div_scale_f32 v46, s[6:7], v28, v28, 1.0
	v_rcp_f32_e32 v51, v40
	v_rcp_f32_e32 v52, v46
	v_fma_f32 v53, -v32, v48, 1.0
	v_div_scale_f32 v33, vcc, 1.0, v27, 1.0
	v_fma_f32 v54, -v38, v49, 1.0
	v_fmac_f32_e32 v48, v53, v48
	v_div_scale_f32 v39, s[0:1], 1.0, v26, 1.0
	v_fma_f32 v55, -v40, v51, 1.0
	v_fmac_f32_e32 v49, v54, v49
	v_mul_f32_e32 v53, v33, v48
	v_div_scale_f32 v41, s[4:5], 1.0, v29, 1.0
	v_fma_f32 v56, -v46, v52, 1.0
	v_fmac_f32_e32 v51, v55, v51
	v_mul_f32_e32 v54, v39, v49
	v_fma_f32 v57, -v32, v53, v33
	v_div_scale_f32 v47, s[6:7], 1.0, v28, 1.0
	v_fmac_f32_e32 v52, v56, v52
	v_mul_f32_e32 v55, v41, v51
	v_fma_f32 v58, -v38, v54, v39
	v_fmac_f32_e32 v53, v57, v48
	v_mul_f32_e32 v56, v47, v52
	v_fma_f32 v59, -v40, v55, v41
	v_fmac_f32_e32 v54, v58, v49
	v_fma_f32 v32, -v32, v53, v33
	v_fma_f32 v60, -v46, v56, v47
	v_fmac_f32_e32 v55, v59, v51
	v_fma_f32 v33, -v38, v54, v39
	v_div_fmas_f32 v32, v32, v48, v53
	s_mov_b64 vcc, s[0:1]
	v_fmac_f32_e32 v56, v60, v52
	v_fma_f32 v38, -v40, v55, v41
	v_div_fixup_f32 v27, v32, v27, 1.0
	v_div_fmas_f32 v32, v33, v49, v54
	s_mov_b64 vcc, s[4:5]
	v_fma_f32 v39, -v46, v56, v47
	v_div_fixup_f32 v26, v32, v26, 1.0
	v_div_fmas_f32 v32, v38, v51, v55
	s_mov_b64 vcc, s[6:7]
	v_div_fixup_f32 v29, v32, v29, 1.0
	v_div_fmas_f32 v32, v39, v52, v56
	v_div_fixup_f32 v28, v32, v28, 1.0
	v_mul_f32_e32 v23, v23, v50
	v_mul_f32_e32 v22, 0xbfb8aa3b, v22
	v_mul_f32_e32 v23, 0xbfb8aa3b, v23
	v_mul_f32_e32 v24, v24, v50
	v_mul_f32_e32 v25, v25, v50
	v_mul_f32_e32 v24, 0xbfb8aa3b, v24
	v_mul_f32_e32 v25, 0xbfb8aa3b, v25
	v_exp_f32_e32 v38, v24
	v_exp_f32_e32 v39, v25
	s_waitcnt lgkmcnt(0)
	v_mov_b32_e32 v30, v198
	v_mov_b32_e32 v31, v199
	v_mov_b32_e32 v42, v184
	v_mov_b32_e32 v43, v185
	v_mov_b32_e32 v44, v186
	v_mov_b32_e32 v45, v187
	v_lshlrev_b32_e32 v32, 16, v30
	v_and_b32_e32 v33, 0xffff0000, v30
	v_lshlrev_b32_e32 v30, 16, v31
	v_and_b32_e32 v31, 0xffff0000, v31
	v_pk_fma_f32 v[26:27], v[26:27], v[32:33], v[42:43]
	v_pk_fma_f32 v[28:29], v[28:29], v[30:31], v[44:45]
	global_store_dwordx4 v[34:35], v[26:29], off offset:64
	s_nop 0
	s_nop 0
	s_nop 0
	v_exp_f32_e32 v32, v22
	v_exp_f32_e32 v33, v23
	v_pk_add_f32 v[38:39], v[38:39], 1.0 op_sel_hi:[1,0]
	s_nop 0
	v_div_scale_f32 v44, s[4:5], v39, v39, 1.0
	v_pk_add_f32 v[32:33], v[32:33], 1.0 op_sel_hi:[1,0]
	v_div_scale_f32 v46, s[6:7], v38, v38, 1.0
	v_div_scale_f32 v40, s[0:1], v33, v33, 1.0
	v_div_scale_f32 v42, s[0:1], v32, v32, 1.0
	v_rcp_f32_e32 v48, v40
	v_rcp_f32_e32 v49, v42
	v_rcp_f32_e32 v51, v44
	v_rcp_f32_e32 v52, v46
	v_fma_f32 v53, -v40, v48, 1.0
	v_div_scale_f32 v41, vcc, 1.0, v33, 1.0
	v_fma_f32 v54, -v42, v49, 1.0
	v_fmac_f32_e32 v48, v53, v48
	v_div_scale_f32 v43, s[0:1], 1.0, v32, 1.0
	v_fma_f32 v55, -v44, v51, 1.0
	v_fmac_f32_e32 v49, v54, v49
	v_mul_f32_e32 v53, v41, v48
	v_div_scale_f32 v45, s[4:5], 1.0, v39, 1.0
	v_fma_f32 v56, -v46, v52, 1.0
	v_fmac_f32_e32 v51, v55, v51
	v_mul_f32_e32 v54, v43, v49
	v_fma_f32 v57, -v40, v53, v41
	v_div_scale_f32 v47, s[6:7], 1.0, v38, 1.0
	v_fmac_f32_e32 v52, v56, v52
	v_mul_f32_e32 v55, v45, v51
	v_fma_f32 v58, -v42, v54, v43
	v_fmac_f32_e32 v53, v57, v48
	v_mul_f32_e32 v56, v47, v52
	v_fma_f32 v59, -v44, v55, v45
	v_fmac_f32_e32 v54, v58, v49
	v_fma_f32 v40, -v40, v53, v41
	v_fma_f32 v60, -v46, v56, v47
	v_fmac_f32_e32 v55, v59, v51
	v_fma_f32 v41, -v42, v54, v43
	v_div_fmas_f32 v40, v40, v48, v53
	s_mov_b64 vcc, s[0:1]
	v_fmac_f32_e32 v56, v60, v52
	v_fma_f32 v42, -v44, v55, v45
	v_div_fixup_f32 v33, v40, v33, 1.0
	v_div_fmas_f32 v40, v41, v49, v54
	s_mov_b64 vcc, s[4:5]
	v_fma_f32 v43, -v46, v56, v47
	v_div_fixup_f32 v32, v40, v32, 1.0
	v_div_fmas_f32 v40, v42, v51, v55
	s_mov_b64 vcc, s[6:7]
	v_div_fixup_f32 v39, v40, v39, 1.0
	v_div_fmas_f32 v40, v43, v52, v56
	v_div_fixup_f32 v38, v40, v38, 1.0
	v_mul_f32_e32 v18, v18, v50
	v_mul_f32_e32 v19, v19, v50
	v_mul_f32_e32 v18, 0xbfb8aa3b, v18
	v_mul_f32_e32 v19, 0xbfb8aa3b, v19
	v_mul_f32_e32 v20, v20, v50
	v_mul_f32_e32 v21, v21, v50
	v_exp_f32_e32 v18, v18
	v_exp_f32_e32 v19, v19
	v_mul_f32_e32 v20, 0xbfb8aa3b, v20
	v_mul_f32_e32 v21, 0xbfb8aa3b, v21
	v_exp_f32_e32 v20, v20
	v_exp_f32_e32 v21, v21
	v_pk_add_f32 v[18:19], v[18:19], 1.0 op_sel_hi:[1,0]
	v_pk_add_f32 v[20:21], v[20:21], 1.0 op_sel_hi:[1,0]
	s_waitcnt lgkmcnt(0)
	v_mov_b32_e32 v30, v200
	v_mov_b32_e32 v31, v201
	v_mov_b32_e32 v26, v188
	v_mov_b32_e32 v27, v189
	v_mov_b32_e32 v28, v190
	v_mov_b32_e32 v29, v191
	v_mov_b32_e32 v22, v192
	v_mov_b32_e32 v23, v193
	v_mov_b32_e32 v24, v194
	v_mov_b32_e32 v25, v195
	v_lshlrev_b32_e32 v40, 16, v30
	v_and_b32_e32 v41, 0xffff0000, v30
	v_lshlrev_b32_e32 v30, 16, v31
	v_and_b32_e32 v31, 0xffff0000, v31
	v_pk_fma_f32 v[26:27], v[32:33], v[40:41], v[26:27]
	v_pk_fma_f32 v[28:29], v[38:39], v[30:31], v[28:29]
	global_store_dwordx4 v[34:35], v[26:29], off offset:128
	s_nop 0
	v_div_scale_f32 v30, s[0:1], v18, v18, 1.0
	v_div_scale_f32 v28, s[0:1], v19, v19, 1.0
	v_rcp_f32_e32 v38, v28
	v_div_scale_f32 v32, s[4:5], v21, v21, 1.0
	v_rcp_f32_e32 v39, v30
	v_div_scale_f32 v36, s[6:7], v20, v20, 1.0
	v_rcp_f32_e32 v40, v32
	v_rcp_f32_e32 v41, v36
	v_fma_f32 v42, -v28, v38, 1.0
	v_div_scale_f32 v29, vcc, 1.0, v19, 1.0
	v_fma_f32 v43, -v30, v39, 1.0
	v_fmac_f32_e32 v38, v42, v38
	v_div_scale_f32 v31, s[0:1], 1.0, v18, 1.0
	v_fma_f32 v44, -v32, v40, 1.0
	v_fmac_f32_e32 v39, v43, v39
	v_mul_f32_e32 v42, v29, v38
	v_div_scale_f32 v33, s[4:5], 1.0, v21, 1.0
	v_fma_f32 v45, -v36, v41, 1.0
	v_fmac_f32_e32 v40, v44, v40
	v_mul_f32_e32 v43, v31, v39
	v_fma_f32 v46, -v28, v42, v29
	v_div_scale_f32 v37, s[6:7], 1.0, v20, 1.0
	v_fmac_f32_e32 v41, v45, v41
	v_mul_f32_e32 v44, v33, v40
	v_fma_f32 v47, -v30, v43, v31
	v_fmac_f32_e32 v42, v46, v38
	v_mul_f32_e32 v45, v37, v41
	v_fma_f32 v48, -v32, v44, v33
	v_fmac_f32_e32 v43, v47, v39
	v_fma_f32 v28, -v28, v42, v29
	v_fma_f32 v49, -v36, v45, v37
	v_fmac_f32_e32 v44, v48, v40
	v_fma_f32 v29, -v30, v43, v31
	v_div_fmas_f32 v28, v28, v38, v42
	s_mov_b64 vcc, s[0:1]
	v_fmac_f32_e32 v45, v49, v41
	v_fma_f32 v30, -v32, v44, v33
	v_div_fixup_f32 v19, v28, v19, 1.0
	v_div_fmas_f32 v28, v29, v39, v43
	s_mov_b64 vcc, s[4:5]
	v_fma_f32 v31, -v36, v45, v37
	v_div_fixup_f32 v18, v28, v18, 1.0
	v_div_fmas_f32 v28, v30, v40, v44
	s_mov_b64 vcc, s[6:7]
	v_div_fixup_f32 v21, v28, v21, 1.0
	v_div_fmas_f32 v28, v31, v41, v45
	v_div_fixup_f32 v20, v28, v20, 1.0
	s_waitcnt lgkmcnt(0)
	v_mov_b32_e32 v26, v202
	v_mov_b32_e32 v27, v203
	v_lshlrev_b32_e32 v28, 16, v26
	v_and_b32_e32 v29, 0xffff0000, v26
	v_lshlrev_b32_e32 v26, 16, v27
	v_and_b32_e32 v27, 0xffff0000, v27
	v_pk_fma_f32 v[18:19], v[18:19], v[28:29], v[22:23]
	v_pk_fma_f32 v[20:21], v[20:21], v[26:27], v[24:25]
	global_store_dwordx4 v[34:35], v[18:21], off offset:192
	v_or_b32_e32 v126, 0x70, v126
	s_nop 0
	v_lshl_add_u64 v[18:19], v[126:127], 2, s[14:15]
	s_nop 0
	v_lshlrev_b64 v[18:19], 11, v[126:127]
	v_lshl_add_u64 v[18:19], s[12:13], 0, v[18:19]
	v_lshl_add_u64 v[20:21], v[18:19], 0, v[128:129]
	s_nop 0
	v_lshlrev_b64 v[18:19], 12, v[126:127]
	v_lshl_add_u64 v[18:19], v[130:131], 0, v[18:19]
	v_lshl_add_u64 v[18:19], v[18:19], 0, v[134:135]
	s_nop 0
	s_waitcnt vmcnt(4) lgkmcnt(0)
	v_mov_b32_e32 v26, v229
	v_mov_b32_e32 v30, v220
	v_mov_b32_e32 v31, v221
	v_mov_b32_e32 v22, v204
	v_mov_b32_e32 v23, v205
	v_mov_b32_e32 v24, v206
	v_mov_b32_e32 v25, v207
	v_fmamk_f32 v26, v26, 0x3a800000, v141
	v_mul_f32_e32 v27, 0x4b800000, v26
	v_cmp_gt_f32_e32 vcc, s50, v26
	v_lshlrev_b32_e32 v32, 16, v30
	s_nop 0
	v_cndmask_b32_e32 v26, v26, v27, vcc
	v_rsq_f32_e32 v34, v26
	v_and_b32_e32 v33, 0xffff0000, v30
	s_nop 0
	v_mul_f32_e32 v30, 0x45800000, v34
	v_cndmask_b32_e32 v34, v34, v30, vcc
	v_mul_f32_e32 v14, v14, v34
	v_mul_f32_e32 v15, v15, v34
	v_mul_f32_e32 v14, 0xbfb8aa3b, v14
	v_mul_f32_e32 v15, 0xbfb8aa3b, v15
	v_mul_f32_e32 v16, v16, v34
	v_mul_f32_e32 v17, v17, v34
	v_exp_f32_e32 v14, v14
	v_exp_f32_e32 v15, v15
	v_mul_f32_e32 v16, 0xbfb8aa3b, v16
	v_mul_f32_e32 v17, 0xbfb8aa3b, v17
	v_exp_f32_e32 v16, v16
	v_exp_f32_e32 v17, v17
	v_pk_add_f32 v[14:15], v[14:15], 1.0 op_sel_hi:[1,0]
	v_lshlrev_b32_e32 v30, 16, v31
	v_div_scale_f32 v35, s[0:1], v15, v15, 1.0
	v_pk_add_f32 v[16:17], v[16:17], 1.0 op_sel_hi:[1,0]
	v_div_scale_f32 v37, s[0:1], v14, v14, 1.0
	v_rcp_f32_e32 v43, v35
	v_div_scale_f32 v39, s[4:5], v17, v17, 1.0
	v_rcp_f32_e32 v44, v37
	v_div_scale_f32 v41, s[6:7], v16, v16, 1.0
	v_rcp_f32_e32 v45, v39
	v_rcp_f32_e32 v46, v41
	v_fma_f32 v47, -v35, v43, 1.0
	v_div_scale_f32 v36, vcc, 1.0, v15, 1.0
	v_fma_f32 v48, -v37, v44, 1.0
	v_fmac_f32_e32 v43, v47, v43
	v_div_scale_f32 v38, s[0:1], 1.0, v14, 1.0
	v_fma_f32 v49, -v39, v45, 1.0
	v_fmac_f32_e32 v44, v48, v44
	v_mul_f32_e32 v47, v36, v43
	v_div_scale_f32 v40, s[4:5], 1.0, v17, 1.0
	v_fma_f32 v50, -v41, v46, 1.0
	v_fmac_f32_e32 v45, v49, v45
	v_mul_f32_e32 v48, v38, v44
	v_fma_f32 v51, -v35, v47, v36
	v_div_scale_f32 v42, s[6:7], 1.0, v16, 1.0
	v_fmac_f32_e32 v46, v50, v46
	v_mul_f32_e32 v49, v40, v45
	v_fma_f32 v52, -v37, v48, v38
	v_fmac_f32_e32 v47, v51, v43
	v_mul_f32_e32 v50, v42, v46
	v_fma_f32 v53, -v39, v49, v40
	v_fmac_f32_e32 v48, v52, v44
	v_fma_f32 v35, -v35, v47, v36
	v_fma_f32 v54, -v41, v50, v42
	v_fmac_f32_e32 v49, v53, v45
	v_fma_f32 v36, -v37, v48, v38
	v_div_fmas_f32 v35, v35, v43, v47
	s_mov_b64 vcc, s[0:1]
	v_fmac_f32_e32 v50, v54, v46
	v_fma_f32 v37, -v39, v49, v40
	v_div_fixup_f32 v15, v35, v15, 1.0
	v_div_fmas_f32 v35, v36, v44, v48
	s_mov_b64 vcc, s[4:5]
	v_fma_f32 v38, -v41, v50, v42
	v_div_fixup_f32 v14, v35, v14, 1.0
	v_div_fmas_f32 v35, v37, v45, v49
	s_mov_b64 vcc, s[6:7]
	v_pk_fma_f32 v[14:15], v[14:15], v[32:33], v[22:23]
	v_div_fmas_f32 v22, v38, v46, v50
	v_and_b32_e32 v31, 0xffff0000, v31
	v_div_fixup_f32 v17, v35, v17, 1.0
	v_div_fixup_f32 v16, v22, v16, 1.0
	v_pk_fma_f32 v[16:17], v[16:17], v[30:31], v[24:25]
	global_store_dwordx4 v[18:19], v[14:17], off
	s_nop 0
	v_mul_f32_e32 v10, v10, v34
	v_mul_f32_e32 v11, v11, v34
	v_mul_f32_e32 v10, 0xbfb8aa3b, v10
	v_mul_f32_e32 v11, 0xbfb8aa3b, v11
	v_mul_f32_e32 v12, v12, v34
	v_mul_f32_e32 v13, v13, v34
	v_exp_f32_e32 v10, v10
	v_exp_f32_e32 v11, v11
	v_mul_f32_e32 v12, 0xbfb8aa3b, v12
	v_mul_f32_e32 v13, 0xbfb8aa3b, v13
	v_exp_f32_e32 v12, v12
	v_exp_f32_e32 v13, v13
	v_pk_add_f32 v[10:11], v[10:11], 1.0 op_sel_hi:[1,0]
	v_mul_f32_e32 v6, v6, v34
	v_div_scale_f32 v16, s[0:1], v11, v11, 1.0
	v_pk_add_f32 v[12:13], v[12:13], 1.0 op_sel_hi:[1,0]
	v_div_scale_f32 v22, s[0:1], v10, v10, 1.0
	v_rcp_f32_e32 v32, v16
	v_div_scale_f32 v24, s[4:5], v13, v13, 1.0
	v_rcp_f32_e32 v33, v22
	v_div_scale_f32 v30, s[6:7], v12, v12, 1.0
	v_rcp_f32_e32 v35, v24
	v_rcp_f32_e32 v36, v30
	v_fma_f32 v37, -v16, v32, 1.0
	v_div_scale_f32 v17, vcc, 1.0, v11, 1.0
	v_fma_f32 v38, -v22, v33, 1.0
	v_fmac_f32_e32 v32, v37, v32
	v_div_scale_f32 v23, s[0:1], 1.0, v10, 1.0
	v_fma_f32 v39, -v24, v35, 1.0
	v_fmac_f32_e32 v33, v38, v33
	v_mul_f32_e32 v37, v17, v32
	v_div_scale_f32 v25, s[4:5], 1.0, v13, 1.0
	v_fma_f32 v40, -v30, v36, 1.0
	v_fmac_f32_e32 v35, v39, v35
	v_mul_f32_e32 v38, v23, v33
	v_fma_f32 v41, -v16, v37, v17
	v_div_scale_f32 v31, s[6:7], 1.0, v12, 1.0
	v_fmac_f32_e32 v36, v40, v36
	v_mul_f32_e32 v39, v25, v35
	v_fma_f32 v42, -v22, v38, v23
	v_fmac_f32_e32 v37, v41, v32
	v_mul_f32_e32 v40, v31, v36
	v_fma_f32 v43, -v24, v39, v25
	v_fmac_f32_e32 v38, v42, v33
	v_fma_f32 v16, -v16, v37, v17
	v_fma_f32 v44, -v30, v40, v31
	v_fmac_f32_e32 v39, v43, v35
	v_fma_f32 v17, -v22, v38, v23
	v_div_fmas_f32 v16, v16, v32, v37
	s_mov_b64 vcc, s[0:1]
	v_fmac_f32_e32 v40, v44, v36
	v_fma_f32 v22, -v24, v39, v25
	v_div_fixup_f32 v11, v16, v11, 1.0
	v_div_fmas_f32 v16, v17, v33, v38
	s_mov_b64 vcc, s[4:5]
	v_fma_f32 v23, -v30, v40, v31
	v_div_fixup_f32 v10, v16, v10, 1.0
	v_div_fmas_f32 v16, v22, v35, v39
	s_mov_b64 vcc, s[6:7]
	v_div_fixup_f32 v13, v16, v13, 1.0
	v_div_fmas_f32 v16, v23, v36, v40
	v_div_fixup_f32 v12, v16, v12, 1.0
	v_mul_f32_e32 v7, v7, v34
	v_mul_f32_e32 v6, 0xbfb8aa3b, v6
	v_mul_f32_e32 v7, 0xbfb8aa3b, v7
	v_mul_f32_e32 v8, v8, v34
	v_mul_f32_e32 v9, v9, v34
	v_mul_f32_e32 v8, 0xbfb8aa3b, v8
	v_mul_f32_e32 v9, 0xbfb8aa3b, v9
	v_exp_f32_e32 v22, v8
	v_exp_f32_e32 v23, v9
	s_waitcnt lgkmcnt(0)
	v_mov_b32_e32 v14, v222
	v_mov_b32_e32 v15, v223
	v_mov_b32_e32 v26, v208
	v_mov_b32_e32 v27, v209
	v_mov_b32_e32 v28, v210
	v_mov_b32_e32 v29, v211
	v_lshlrev_b32_e32 v16, 16, v14
	v_and_b32_e32 v17, 0xffff0000, v14
	v_lshlrev_b32_e32 v14, 16, v15
	v_and_b32_e32 v15, 0xffff0000, v15
	v_pk_fma_f32 v[10:11], v[10:11], v[16:17], v[26:27]
	v_pk_fma_f32 v[12:13], v[12:13], v[14:15], v[28:29]
	global_store_dwordx4 v[18:19], v[10:13], off offset:64
	s_nop 0
	s_nop 0
	s_nop 0
	v_exp_f32_e32 v16, v6
	v_exp_f32_e32 v17, v7
	v_pk_add_f32 v[22:23], v[22:23], 1.0 op_sel_hi:[1,0]
	s_nop 0
	v_div_scale_f32 v28, s[4:5], v23, v23, 1.0
	v_pk_add_f32 v[16:17], v[16:17], 1.0 op_sel_hi:[1,0]
	v_div_scale_f32 v30, s[6:7], v22, v22, 1.0
	v_div_scale_f32 v24, s[0:1], v17, v17, 1.0
	v_div_scale_f32 v26, s[0:1], v16, v16, 1.0
	v_rcp_f32_e32 v32, v24
	v_rcp_f32_e32 v33, v26
	v_rcp_f32_e32 v35, v28
	v_rcp_f32_e32 v36, v30
	v_fma_f32 v37, -v24, v32, 1.0
	v_div_scale_f32 v25, vcc, 1.0, v17, 1.0
	v_fma_f32 v38, -v26, v33, 1.0
	v_fmac_f32_e32 v32, v37, v32
	v_div_scale_f32 v27, s[0:1], 1.0, v16, 1.0
	v_fma_f32 v39, -v28, v35, 1.0
	v_fmac_f32_e32 v33, v38, v33
	v_mul_f32_e32 v37, v25, v32
	v_div_scale_f32 v29, s[4:5], 1.0, v23, 1.0
	v_fma_f32 v40, -v30, v36, 1.0
	v_fmac_f32_e32 v35, v39, v35
	v_mul_f32_e32 v38, v27, v33
	v_fma_f32 v41, -v24, v37, v25
	v_div_scale_f32 v31, s[6:7], 1.0, v22, 1.0
	v_fmac_f32_e32 v36, v40, v36
	v_mul_f32_e32 v39, v29, v35
	v_fma_f32 v42, -v26, v38, v27
	v_fmac_f32_e32 v37, v41, v32
	v_mul_f32_e32 v40, v31, v36
	v_fma_f32 v43, -v28, v39, v29
	v_fmac_f32_e32 v38, v42, v33
	v_fma_f32 v24, -v24, v37, v25
	v_fma_f32 v44, -v30, v40, v31
	v_fmac_f32_e32 v39, v43, v35
	v_fma_f32 v25, -v26, v38, v27
	v_div_fmas_f32 v24, v24, v32, v37
	s_mov_b64 vcc, s[0:1]
	v_fmac_f32_e32 v40, v44, v36
	v_fma_f32 v26, -v28, v39, v29
	v_div_fixup_f32 v17, v24, v17, 1.0
	v_div_fmas_f32 v24, v25, v33, v38
	s_mov_b64 vcc, s[4:5]
	v_fma_f32 v27, -v30, v40, v31
	v_div_fixup_f32 v16, v24, v16, 1.0
	v_div_fmas_f32 v24, v26, v35, v39
	s_mov_b64 vcc, s[6:7]
	v_div_fixup_f32 v23, v24, v23, 1.0
	v_div_fmas_f32 v24, v27, v36, v40
	v_div_fixup_f32 v22, v24, v22, 1.0
	v_mul_f32_e32 v2, v2, v34
	v_mul_f32_e32 v3, v3, v34
	v_mul_f32_e32 v2, 0xbfb8aa3b, v2
	v_mul_f32_e32 v3, 0xbfb8aa3b, v3
	v_mul_f32_e32 v4, v4, v34
	v_mul_f32_e32 v5, v5, v34
	v_exp_f32_e32 v2, v2
	v_exp_f32_e32 v3, v3
	v_mul_f32_e32 v4, 0xbfb8aa3b, v4
	v_mul_f32_e32 v5, 0xbfb8aa3b, v5
	v_exp_f32_e32 v4, v4
	v_exp_f32_e32 v5, v5
	v_pk_add_f32 v[2:3], v[2:3], 1.0 op_sel_hi:[1,0]
	v_pk_add_f32 v[4:5], v[4:5], 1.0 op_sel_hi:[1,0]
	s_waitcnt lgkmcnt(0)
	v_mov_b32_e32 v14, v224
	v_mov_b32_e32 v15, v225
	v_mov_b32_e32 v10, v212
	v_mov_b32_e32 v11, v213
	v_mov_b32_e32 v12, v214
	v_mov_b32_e32 v13, v215
	v_mov_b32_e32 v6, v216
	v_mov_b32_e32 v7, v217
	v_mov_b32_e32 v8, v218
	v_mov_b32_e32 v9, v219
	v_lshlrev_b32_e32 v24, 16, v14
	v_and_b32_e32 v25, 0xffff0000, v14
	v_lshlrev_b32_e32 v14, 16, v15
	v_and_b32_e32 v15, 0xffff0000, v15
	v_pk_fma_f32 v[10:11], v[16:17], v[24:25], v[10:11]
	v_pk_fma_f32 v[12:13], v[22:23], v[14:15], v[12:13]
	global_store_dwordx4 v[18:19], v[10:13], off offset:128
	s_nop 0
	v_div_scale_f32 v14, s[0:1], v2, v2, 1.0
	v_div_scale_f32 v12, s[0:1], v3, v3, 1.0
	v_rcp_f32_e32 v22, v12
	v_div_scale_f32 v16, s[4:5], v5, v5, 1.0
	v_rcp_f32_e32 v23, v14
	v_div_scale_f32 v20, s[6:7], v4, v4, 1.0
	v_rcp_f32_e32 v24, v16
	v_rcp_f32_e32 v25, v20
	v_fma_f32 v26, -v12, v22, 1.0
	v_div_scale_f32 v13, vcc, 1.0, v3, 1.0
	v_fma_f32 v27, -v14, v23, 1.0
	v_fmac_f32_e32 v22, v26, v22
	v_div_scale_f32 v15, s[0:1], 1.0, v2, 1.0
	v_fma_f32 v28, -v16, v24, 1.0
	v_fmac_f32_e32 v23, v27, v23
	v_mul_f32_e32 v26, v13, v22
	v_div_scale_f32 v17, s[4:5], 1.0, v5, 1.0
	v_fma_f32 v29, -v20, v25, 1.0
	v_fmac_f32_e32 v24, v28, v24
	v_mul_f32_e32 v27, v15, v23
	v_fma_f32 v30, -v12, v26, v13
	v_div_scale_f32 v21, s[6:7], 1.0, v4, 1.0
	v_fmac_f32_e32 v25, v29, v25
	v_mul_f32_e32 v28, v17, v24
	v_fma_f32 v31, -v14, v27, v15
	v_fmac_f32_e32 v26, v30, v22
	v_mul_f32_e32 v29, v21, v25
	v_fma_f32 v32, -v16, v28, v17
	v_fmac_f32_e32 v27, v31, v23
	v_fma_f32 v12, -v12, v26, v13
	v_fma_f32 v33, -v20, v29, v21
	v_fmac_f32_e32 v28, v32, v24
	v_fma_f32 v13, -v14, v27, v15
	v_div_fmas_f32 v12, v12, v22, v26
	s_mov_b64 vcc, s[0:1]
	v_fmac_f32_e32 v29, v33, v25
	v_fma_f32 v14, -v16, v28, v17
	v_div_fixup_f32 v3, v12, v3, 1.0
	v_div_fmas_f32 v12, v13, v23, v27
	s_mov_b64 vcc, s[4:5]
	v_fma_f32 v15, -v20, v29, v21
	v_div_fixup_f32 v2, v12, v2, 1.0
	v_div_fmas_f32 v12, v14, v24, v28
	s_mov_b64 vcc, s[6:7]
	v_div_fixup_f32 v5, v12, v5, 1.0
	v_div_fmas_f32 v12, v15, v25, v29
	v_div_fixup_f32 v4, v12, v4, 1.0
	s_waitcnt lgkmcnt(0)
	v_mov_b32_e32 v10, v226
	v_mov_b32_e32 v11, v227
	v_lshlrev_b32_e32 v12, 16, v10
	v_and_b32_e32 v13, 0xffff0000, v10
	v_lshlrev_b32_e32 v10, 16, v11
	v_and_b32_e32 v11, 0xffff0000, v11
	v_pk_fma_f32 v[2:3], v[2:3], v[12:13], v[6:7]
	v_pk_fma_f32 v[4:5], v[4:5], v[10:11], v[8:9]
	global_store_dwordx4 v[18:19], v[2:5], off offset:192
	s_add_i32 s2, s2, s40
	s_add_i32 s41, s41, s40
	s_cmpk_gt_i32 s2, 0x7ff
	s_cbranch_scc0 .LBB0_1444
